# GEMM MFMA sweeps reordered boustrophedon-wise (consecutive MFMAs share one operand fragment) - operand-reuse / power experiment
# baseline (speedup 1.0000x reference)
; #define PG8_STAGE(bufoff, gbase, voff) do { _Pragma("unroll") for (int _i = 0; _i < 2; ++_i) \
;         __builtin_amdgcn_global_load_lds((const unsigned*)((const char*)(gbase) + (voff)[_i]), (PG8_LAS unsigned*)(lds + (bufoff) + ldsw + _i * 8192), 16, 0, 0); } while (0)
; #define PG8_LDA(dst, b, h) do { _Pragma("unroll") for (int m = 0; m < 4; ++m) _Pragma("unroll") for (int k = 0; k < 2; ++k) dst[m][k] = *(const PG8_LAS bf16x8*)(lds + PG8_SA(b, h) + aoff + m * 2048 + k * 1024); } while (0)
; #define PG8_LDB(dst, b, h) do { _Pragma("unroll") for (int n = 0; n < 2; ++n) _Pragma("unroll") for (int k = 0; k < 2; ++k) dst[n][k] = *(const PG8_LAS bf16x8*)(lds + PG8_SB(b, h) + boff + n * 2048 + k * 1024); } while (0)
; #define PG8_MMA(ai, bj, At, Bt) do { __builtin_amdgcn_s_setprio(1); _Pragma("unroll") for (int m = 0; m < 4; ++m) _Pragma("unroll") for (int n = 0; n < 2; ++n) _Pragma("unroll") for (int k = 0; k < 2; ++k) \
;         acc[ai][bj][m][n] = __builtin_amdgcn_mfma_f32_16x16x32_bf16(Bt[n][k], At[m][k], acc[ai][bj][m][n], 0, 0, 0); __builtin_amdgcn_s_setprio(0); } while (0)
; #define PG8_WAIT_V(n) asm volatile("s_waitcnt vmcnt(" #n ")" ::: "memory")
; #define PG8_BAR __builtin_amdgcn_s_barrier()
; template <class Epi, class Sched, bool ALIGN_EPI = false, bool SP2 = false>
; __device__ __forceinline__ void gemm_phase(PG8_LAS unsigned char* lds, const Gemm g, const Sched& S, const Epi& E) {
;     ...
;         for (int t = 0; t < nt; t += 2) {
;             const bool last = (t == nt - 2);
;             const char* a1 = cA + (size_t)(t + 1) * kstA;
;             const char* a2 = last ? nA : cA + (size_t)(t + 2) * kstA; const char* b2 = last ? nB : cB + (size_t)(t + 2) * kstep;
;             const char* a3 = a2 + kstA; const char* b3 = b2 + kstep;
;             if (last && has_next) S.a_ready(nxt);
;             if constexpr (SP2) {
;             PG8_LDB(B0, 0, 0); PG8_LDB(B1, 0, 1); PG8_SCHED; PG8_LDA(At, 0, 0); PG8_STAGE(PG8_SA(1, 1), a1 + hstepA, voffA);
;             PG8_WAIT_V(8); PG8_WAIT_L(0); PG8_BAR; PG8_MMA(0, 0, At, B0); PG8_MMA(0, 1, At, B1); PG8_BAR; PG8_SCHED;
;             PG8_LDA(At, 0, 1); PG8_STAGE(PG8_SB(0, 0), b2, voffB); PG8_STAGE(PG8_SB(0, 1), b2 + hstepB, voffB); PG8_STAGE(PG8_SA(0, 0), a2, voffA);
;             PG8_WAIT_V(8); PG8_WAIT_L(0); PG8_BAR; PG8_MMA(1, 0, At, B0); PG8_MMA(1, 1, At, B1); PG8_BAR; PG8_SCHED;
.LBB0_299:
	s_ashr_i32 s43, s42, 31
	s_lshl_b64 s[4:5], s[42:43], 20
	v_readlane_b32 s12, v254, 41
	v_readlane_b32 s13, v254, 42
	s_add_u32 s46, s12, s4
	s_addc_u32 s47, s13, s5
	s_and_b64 s[4:5], s[34:35], exec
	s_cselect_b32 s4, s47, s51
	s_cselect_b32 s5, s46, s50
	s_ashr_i32 s41, s40, 31
	s_lshl_b64 s[12:13], s[40:41], 20
	v_readlane_b32 s14, v253, 24
	s_add_u32 s48, s14, s12
	v_readlane_b32 s12, v253, 25
	s_addc_u32 s49, s12, s13
	s_and_b64 s[12:13], s[34:35], exec
	s_cselect_b32 s12, s49, s57
	s_cselect_b32 s13, s48, s56
	s_add_u32 s50, s50, 0x80080
	s_addc_u32 s51, s51, 0
	s_add_u32 s41, s56, 0x100
	s_addc_u32 s43, s57, 0
	s_mov_b32 s61, -2
	ds_read_b128 v[156:159], v152
	ds_read_b128 v[160:163], v152 offset:1024
	ds_read_b128 v[164:167], v152 offset:2048
	ds_read_b128 v[168:171], v152 offset:3072
	ds_read_b128 v[172:175], v153
	ds_read_b128 v[176:179], v153 offset:1024
	ds_read_b128 v[180:183], v153 offset:2048
	ds_read_b128 v[186:189], v153 offset:3072
	s_add_u32 s56, s50, 0xfff80080
	s_addc_u32 s57, s51, -1
	s_cmp_eq_u32 s61, 28
	s_cselect_b32 s59, s4, s57
	s_cselect_b32 s58, s5, s56
	s_cselect_b32 s57, s12, s43
	s_cselect_b32 s56, s13, s41
	v_lshl_add_u64 v[222:223], s[50:51], 0, v[142:143]
	s_add_i32 m0, s6, 0xc000
	ds_read_b128 v[190:193], v154
	ds_read_b128 v[194:197], v154 offset:1024
	ds_read_b128 v[198:201], v154 offset:2048
	ds_read_b128 v[202:205], v154 offset:3072
	ds_read_b128 v[206:209], v154 offset:4096
	ds_read_b128 v[210:213], v154 offset:5120
	ds_read_b128 v[214:217], v154 offset:6144
	ds_read_b128 v[218:221], v154 offset:7168
	global_load_lds_dwordx4 v[222:223], off
	v_lshl_add_u64 v[222:223], s[50:51], 0, v[144:145]
	s_add_i32 m0, s6, 0xe000
	s_nop 0
	global_load_lds_dwordx4 v[222:223], off
	s_waitcnt vmcnt(8)
	s_waitcnt lgkmcnt(0)
	s_setprio 1
	s_barrier
	v_mfma_f32_16x16x32_bf16 v[124:127], v[156:159], v[190:193], 0
	v_mfma_f32_16x16x32_bf16 v[120:123], v[164:167], v[190:193], 0
	v_mfma_f32_16x16x32_bf16 v[104:107], v[164:167], v[198:201], 0
	v_mfma_f32_16x16x32_bf16 v[108:111], v[156:159], v[198:201], 0
	v_mfma_f32_16x16x32_bf16 v[92:95], v[156:159], v[206:209], 0
	v_mfma_f32_16x16x32_bf16 v[88:91], v[164:167], v[206:209], 0
	v_mfma_f32_16x16x32_bf16 v[72:75], v[164:167], v[214:217], 0
	v_mfma_f32_16x16x32_bf16 v[76:79], v[156:159], v[214:217], 0
	v_mfma_f32_16x16x32_bf16 v[124:127], v[160:163], v[194:197], v[124:127]
	v_mfma_f32_16x16x32_bf16 v[120:123], v[168:171], v[194:197], v[120:123]
	v_mfma_f32_16x16x32_bf16 v[104:107], v[168:171], v[202:205], v[104:107]
	v_mfma_f32_16x16x32_bf16 v[108:111], v[160:163], v[202:205], v[108:111]
	v_mfma_f32_16x16x32_bf16 v[92:95], v[160:163], v[210:213], v[92:95]
	v_mfma_f32_16x16x32_bf16 v[88:91], v[168:171], v[210:213], v[88:91]
	v_mfma_f32_16x16x32_bf16 v[72:75], v[168:171], v[218:221], v[72:75]
	v_mfma_f32_16x16x32_bf16 v[76:79], v[160:163], v[218:221], v[76:79]
	s_setprio 0
	s_setprio 1
	v_mfma_f32_16x16x32_bf16 v[116:119], v[172:175], v[190:193], 0
	v_mfma_f32_16x16x32_bf16 v[112:115], v[180:183], v[190:193], 0
	v_mfma_f32_16x16x32_bf16 v[96:99], v[180:183], v[198:201], 0
	v_mfma_f32_16x16x32_bf16 v[100:103], v[172:175], v[198:201], 0
	v_mfma_f32_16x16x32_bf16 v[84:87], v[172:175], v[206:209], 0
	v_mfma_f32_16x16x32_bf16 v[80:83], v[180:183], v[206:209], 0
	v_mfma_f32_16x16x32_bf16 v[64:67], v[180:183], v[214:217], 0
	v_mfma_f32_16x16x32_bf16 v[68:71], v[172:175], v[214:217], 0
	v_mfma_f32_16x16x32_bf16 v[116:119], v[176:179], v[194:197], v[116:119]
	v_mfma_f32_16x16x32_bf16 v[112:115], v[186:189], v[194:197], v[112:115]
	v_mfma_f32_16x16x32_bf16 v[96:99], v[186:189], v[202:205], v[96:99]
	v_mfma_f32_16x16x32_bf16 v[100:103], v[176:179], v[202:205], v[100:103]
	v_mfma_f32_16x16x32_bf16 v[84:87], v[176:179], v[210:213], v[84:87]
	v_mfma_f32_16x16x32_bf16 v[80:83], v[186:189], v[210:213], v[80:83]
	v_mfma_f32_16x16x32_bf16 v[64:67], v[186:189], v[218:221], v[64:67]
	v_mfma_f32_16x16x32_bf16 v[68:71], v[176:179], v[218:221], v[68:71]
	s_barrier
	s_setprio 0
	s_add_i32 s62, s53, s3
	v_lshl_add_u64 v[222:223], s[56:57], 0, v[130:131]
	s_mov_b32 m0, s62
	ds_read_b128 v[190:193], v154 offset:16384
	ds_read_b128 v[194:197], v154 offset:17408
	ds_read_b128 v[198:201], v154 offset:18432
	ds_read_b128 v[202:205], v154 offset:19456
	ds_read_b128 v[206:209], v154 offset:20480
	ds_read_b128 v[210:213], v154 offset:21504
	ds_read_b128 v[214:217], v154 offset:22528
	ds_read_b128 v[218:221], v154 offset:23552
	global_load_lds_dwordx4 v[222:223], off
	s_add_i32 m0, s62, 0x2000
	s_add_u32 s62, s56, 0x80000
	v_lshl_add_u64 v[224:225], s[56:57], 0, v[134:135]
	s_addc_u32 s63, s57, 0
	s_add_i32 s64, s55, s3
	global_load_lds_dwordx4 v[224:225], off
	v_lshl_add_u64 v[226:227], s[62:63], 0, v[130:131]
	s_mov_b32 m0, s64
	v_lshl_add_u64 v[228:229], s[58:59], 0, v[132:133]
	global_load_lds_dwordx4 v[226:227], off
	v_lshl_add_u64 v[226:227], s[62:63], 0, v[134:135]
	s_add_i32 m0, s64, 0x2000
	s_nop 0
	global_load_lds_dwordx4 v[226:227], off
	v_lshl_add_u64 v[226:227], s[58:59], 0, v[128:129]
	s_mov_b32 m0, s6
	s_nop 0
	global_load_lds_dwordx4 v[226:227], off
	s_mov_b32 m0, s7
	s_nop 0
	global_load_lds_dwordx4 v[228:229], off
	s_waitcnt vmcnt(8)
	s_waitcnt lgkmcnt(0)
	s_setprio 1
	s_barrier
; #define PG8_STAGE(bufoff, gbase, voff) do { _Pragma("unroll") for (int _i = 0; _i < 2; ++_i) \
;         __builtin_amdgcn_global_load_lds((const unsigned*)((const char*)(gbase) + (voff)[_i]), (PG8_LAS unsigned*)(lds + (bufoff) + ldsw + _i * 8192), 16, 0, 0); } while (0)
; #define PG8_LDA(dst, b, h) do { _Pragma("unroll") for (int m = 0; m < 4; ++m) _Pragma("unroll") for (int k = 0; k < 2; ++k) dst[m][k] = *(const PG8_LAS bf16x8*)(lds + PG8_SA(b, h) + aoff + m * 2048 + k * 1024); } while (0)
; #define PG8_LDB(dst, b, h) do { _Pragma("unroll") for (int n = 0; n < 2; ++n) _Pragma("unroll") for (int k = 0; k < 2; ++k) dst[n][k] = *(const PG8_LAS bf16x8*)(lds + PG8_SB(b, h) + boff + n * 2048 + k * 1024); } while (0)
; #define PG8_MMA(ai, bj, At, Bt) do { __builtin_amdgcn_s_setprio(1); _Pragma("unroll") for (int m = 0; m < 4; ++m) _Pragma("unroll") for (int n = 0; n < 2; ++n) _Pragma("unroll") for (int k = 0; k < 2; ++k) \
;         acc[ai][bj][m][n] = __builtin_amdgcn_mfma_f32_16x16x32_bf16(Bt[n][k], At[m][k], acc[ai][bj][m][n], 0, 0, 0); __builtin_amdgcn_s_setprio(0); } while (0)
; #define PG8_WAIT_V(n) asm volatile("s_waitcnt vmcnt(" #n ")" ::: "memory")
; #define PG8_WAIT_L(n) asm volatile("s_waitcnt lgkmcnt(" #n ")" ::: "memory")
; #define PG8_BAR __builtin_amdgcn_s_barrier()
; #define PG8_SCHED __builtin_amdgcn_sched_barrier(0)
; template <class Epi, class Sched, bool ALIGN_EPI = false, bool SP2 = false>
; __device__ __forceinline__ void gemm_phase(PG8_LAS unsigned char* lds, const Gemm g, const Sched& S, const Epi& E) {
;     ...
;             PG8_WAIT_V(8); PG8_WAIT_L(0); PG8_BAR; PG8_MMA(0, 0, At, B0); PG8_MMA(0, 1, At, B1); PG8_BAR; PG8_SCHED;
;             PG8_LDA(At, 0, 1); PG8_STAGE(PG8_SB(0, 0), b2, voffB); PG8_STAGE(PG8_SB(0, 1), b2 + hstepB, voffB); PG8_STAGE(PG8_SA(0, 0), a2, voffA);
;             PG8_WAIT_V(8); PG8_WAIT_L(0); PG8_BAR; PG8_MMA(1, 0, At, B0); PG8_MMA(1, 1, At, B1); PG8_BAR; PG8_SCHED;
;             PG8_LDB(B0, 1, 0); PG8_LDB(B1, 1, 1); PG8_SCHED; PG8_LDA(At, 1, 0); PG8_STAGE(PG8_SA(0, 1), a2 + hstepA, voffA);
;             PG8_WAIT_V(8); PG8_WAIT_L(0); PG8_BAR; PG8_MMA(0, 0, At, B0); PG8_MMA(0, 1, At, B1); PG8_BAR; PG8_SCHED;
	v_mfma_f32_16x16x32_bf16 v[60:63], v[156:159], v[190:193], 0
	v_mfma_f32_16x16x32_bf16 v[56:59], v[164:167], v[190:193], 0
	v_mfma_f32_16x16x32_bf16 v[40:43], v[164:167], v[198:201], 0
	v_mfma_f32_16x16x32_bf16 v[44:47], v[156:159], v[198:201], 0
	v_mfma_f32_16x16x32_bf16 v[28:31], v[156:159], v[206:209], 0
	v_mfma_f32_16x16x32_bf16 v[24:27], v[164:167], v[206:209], 0
	v_mfma_f32_16x16x32_bf16 v[8:11], v[164:167], v[214:217], 0
	v_mfma_f32_16x16x32_bf16 v[12:15], v[156:159], v[214:217], 0
	v_mfma_f32_16x16x32_bf16 v[60:63], v[160:163], v[194:197], v[60:63]
	v_mfma_f32_16x16x32_bf16 v[56:59], v[168:171], v[194:197], v[56:59]
	v_mfma_f32_16x16x32_bf16 v[40:43], v[168:171], v[202:205], v[40:43]
	v_mfma_f32_16x16x32_bf16 v[44:47], v[160:163], v[202:205], v[44:47]
	v_mfma_f32_16x16x32_bf16 v[28:31], v[160:163], v[210:213], v[28:31]
	v_mfma_f32_16x16x32_bf16 v[24:27], v[168:171], v[210:213], v[24:27]
	v_mfma_f32_16x16x32_bf16 v[8:11], v[168:171], v[218:221], v[8:11]
	v_mfma_f32_16x16x32_bf16 v[12:15], v[160:163], v[218:221], v[12:15]
	s_setprio 0
	s_setprio 1
	v_mfma_f32_16x16x32_bf16 v[52:55], v[172:175], v[190:193], 0
	v_mfma_f32_16x16x32_bf16 v[48:51], v[180:183], v[190:193], 0
	v_mfma_f32_16x16x32_bf16 v[32:35], v[180:183], v[198:201], 0
	v_mfma_f32_16x16x32_bf16 v[36:39], v[172:175], v[198:201], 0
	v_mfma_f32_16x16x32_bf16 v[20:23], v[172:175], v[206:209], 0
	v_mfma_f32_16x16x32_bf16 v[16:19], v[180:183], v[206:209], 0
	v_mfma_f32_16x16x32_bf16 v[0:3], v[180:183], v[214:217], 0
	v_mfma_f32_16x16x32_bf16 v[4:7], v[172:175], v[214:217], 0
	v_mfma_f32_16x16x32_bf16 v[52:55], v[176:179], v[194:197], v[52:55]
	v_mfma_f32_16x16x32_bf16 v[48:51], v[186:189], v[194:197], v[48:51]
	v_mfma_f32_16x16x32_bf16 v[32:35], v[186:189], v[202:205], v[32:35]
	v_mfma_f32_16x16x32_bf16 v[36:39], v[176:179], v[202:205], v[36:39]
	v_mfma_f32_16x16x32_bf16 v[20:23], v[176:179], v[210:213], v[20:23]
	v_mfma_f32_16x16x32_bf16 v[16:19], v[186:189], v[210:213], v[16:19]
	v_mfma_f32_16x16x32_bf16 v[0:3], v[186:189], v[218:221], v[0:3]
	v_mfma_f32_16x16x32_bf16 v[4:7], v[176:179], v[218:221], v[4:7]
	s_barrier
	s_setprio 0
	s_add_i32 s62, 0, 0x18000
	v_add_u32_e32 v155, s62, v150
	s_add_i32 s63, 0, 0x1c000
	ds_read_b128 v[156:159], v155
	ds_read_b128 v[160:163], v155 offset:1024
	ds_read_b128 v[164:167], v155 offset:2048
	ds_read_b128 v[168:171], v155 offset:3072
	v_add_u32_e32 v155, s63, v150
	ds_read_b128 v[172:175], v155
	ds_read_b128 v[176:179], v155 offset:1024
	ds_read_b128 v[180:183], v155 offset:2048
	ds_read_b128 v[186:189], v155 offset:3072
	s_add_u32 s58, s58, 0x80000
	s_addc_u32 s59, s59, 0
	s_mov_b32 m0, s8
	v_lshl_add_u64 v[230:231], s[58:59], 0, v[128:129]
	ds_read_b128 v[190:193], v154 offset:32768
	ds_read_b128 v[194:197], v154 offset:33792
	ds_read_b128 v[198:201], v154 offset:34816
	ds_read_b128 v[202:205], v154 offset:35840
	ds_read_b128 v[206:209], v154 offset:36864
	ds_read_b128 v[210:213], v154 offset:37888
	ds_read_b128 v[214:217], v154 offset:38912
	ds_read_b128 v[218:221], v154 offset:39936
	global_load_lds_dwordx4 v[230:231], off
	v_lshl_add_u64 v[230:231], s[58:59], 0, v[132:133]
	s_mov_b32 m0, s9
	s_nop 0
	global_load_lds_dwordx4 v[230:231], off
	s_waitcnt vmcnt(8)
	s_waitcnt lgkmcnt(0)
	s_setprio 1
	s_barrier
	v_mfma_f32_16x16x32_bf16 v[124:127], v[156:159], v[190:193], v[124:127]
	v_mfma_f32_16x16x32_bf16 v[120:123], v[164:167], v[190:193], v[120:123]
	v_mfma_f32_16x16x32_bf16 v[104:107], v[164:167], v[198:201], v[104:107]
	v_mfma_f32_16x16x32_bf16 v[108:111], v[156:159], v[198:201], v[108:111]
	v_mfma_f32_16x16x32_bf16 v[92:95], v[156:159], v[206:209], v[92:95]
	v_mfma_f32_16x16x32_bf16 v[88:91], v[164:167], v[206:209], v[88:91]
	v_mfma_f32_16x16x32_bf16 v[72:75], v[164:167], v[214:217], v[72:75]
	v_mfma_f32_16x16x32_bf16 v[76:79], v[156:159], v[214:217], v[76:79]
	v_mfma_f32_16x16x32_bf16 v[124:127], v[160:163], v[194:197], v[124:127]
	v_mfma_f32_16x16x32_bf16 v[120:123], v[168:171], v[194:197], v[120:123]
	v_mfma_f32_16x16x32_bf16 v[104:107], v[168:171], v[202:205], v[104:107]
	v_mfma_f32_16x16x32_bf16 v[108:111], v[160:163], v[202:205], v[108:111]
	v_mfma_f32_16x16x32_bf16 v[92:95], v[160:163], v[210:213], v[92:95]
	v_mfma_f32_16x16x32_bf16 v[88:91], v[168:171], v[210:213], v[88:91]
	v_mfma_f32_16x16x32_bf16 v[72:75], v[168:171], v[218:221], v[72:75]
	v_mfma_f32_16x16x32_bf16 v[76:79], v[160:163], v[218:221], v[76:79]
	s_setprio 0
	s_setprio 1
	v_mfma_f32_16x16x32_bf16 v[116:119], v[172:175], v[190:193], v[116:119]
	v_mfma_f32_16x16x32_bf16 v[112:115], v[180:183], v[190:193], v[112:115]
	v_mfma_f32_16x16x32_bf16 v[96:99], v[180:183], v[198:201], v[96:99]
	v_mfma_f32_16x16x32_bf16 v[100:103], v[172:175], v[198:201], v[100:103]
	v_mfma_f32_16x16x32_bf16 v[84:87], v[172:175], v[206:209], v[84:87]
	v_mfma_f32_16x16x32_bf16 v[80:83], v[180:183], v[206:209], v[80:83]
	v_mfma_f32_16x16x32_bf16 v[64:67], v[180:183], v[214:217], v[64:67]
	v_mfma_f32_16x16x32_bf16 v[68:71], v[172:175], v[214:217], v[68:71]
	v_mfma_f32_16x16x32_bf16 v[116:119], v[176:179], v[194:197], v[116:119]
	v_mfma_f32_16x16x32_bf16 v[112:115], v[186:189], v[194:197], v[112:115]
	v_mfma_f32_16x16x32_bf16 v[96:99], v[186:189], v[202:205], v[96:99]
	v_mfma_f32_16x16x32_bf16 v[100:103], v[176:179], v[202:205], v[100:103]
	v_mfma_f32_16x16x32_bf16 v[84:87], v[176:179], v[210:213], v[84:87]
	v_mfma_f32_16x16x32_bf16 v[80:83], v[186:189], v[210:213], v[80:83]
	v_mfma_f32_16x16x32_bf16 v[64:67], v[186:189], v[218:221], v[64:67]
	v_mfma_f32_16x16x32_bf16 v[68:71], v[176:179], v[218:221], v[68:71]
	s_barrier
; #define PG8_STAGE(bufoff, gbase, voff) do { _Pragma("unroll") for (int _i = 0; _i < 2; ++_i) \
;         __builtin_amdgcn_global_load_lds((const unsigned*)((const char*)(gbase) + (voff)[_i]), (PG8_LAS unsigned*)(lds + (bufoff) + ldsw + _i * 8192), 16, 0, 0); } while (0)
; #define PG8_LDA(dst, b, h) do { _Pragma("unroll") for (int m = 0; m < 4; ++m) _Pragma("unroll") for (int k = 0; k < 2; ++k) dst[m][k] = *(const PG8_LAS bf16x8*)(lds + PG8_SA(b, h) + aoff + m * 2048 + k * 1024); } while (0)
; #define PG8_LDB(dst, b, h) do { _Pragma("unroll") for (int n = 0; n < 2; ++n) _Pragma("unroll") for (int k = 0; k < 2; ++k) dst[n][k] = *(const PG8_LAS bf16x8*)(lds + PG8_SB(b, h) + boff + n * 2048 + k * 1024); } while (0)
; #define PG8_MMA(ai, bj, At, Bt) do { __builtin_amdgcn_s_setprio(1); _Pragma("unroll") for (int m = 0; m < 4; ++m) _Pragma("unroll") for (int n = 0; n < 2; ++n) _Pragma("unroll") for (int k = 0; k < 2; ++k) \
;         acc[ai][bj][m][n] = __builtin_amdgcn_mfma_f32_16x16x32_bf16(Bt[n][k], At[m][k], acc[ai][bj][m][n], 0, 0, 0); __builtin_amdgcn_s_setprio(0); } while (0)
; #define PG8_WAIT_V(n) asm volatile("s_waitcnt vmcnt(" #n ")" ::: "memory")
; #define PG8_WAIT_L(n) asm volatile("s_waitcnt lgkmcnt(" #n ")" ::: "memory")
; #define PG8_BAR __builtin_amdgcn_s_barrier()
; #define PG8_SCHED __builtin_amdgcn_sched_barrier(0)
; template <class Epi, class Sched, bool ALIGN_EPI = false, bool SP2 = false>
; __device__ __forceinline__ void gemm_phase(PG8_LAS unsigned char* lds, const Gemm g, const Sched& S, const Epi& E) {
;     ...
;             PG8_LDB(B0, 0, 0); PG8_LDB(B1, 0, 1); PG8_SCHED; PG8_LDA(At, 0, 0); PG8_STAGE(PG8_SA(1, 1), a1 + hstepA, voffA);
;             PG8_WAIT_V(8); PG8_WAIT_L(0); PG8_BAR; PG8_MMA(0, 0, At, B0); PG8_MMA(0, 1, At, B1); PG8_BAR; PG8_SCHED;
;     ...
;             PG8_LDA(At, 1, 1); PG8_STAGE(PG8_SB(1, 0), b3, voffB); PG8_STAGE(PG8_SB(1, 1), b3 + hstepB, voffB); PG8_STAGE(PG8_SA(1, 0), a3, voffA);
;             PG8_WAIT_V(8); PG8_WAIT_L(0); PG8_BAR; PG8_MMA(1, 0, At, B0); PG8_MMA(1, 1, At, B1); PG8_BAR; PG8_SCHED;
	s_setprio 0
	s_add_i32 s58, s62, s3
	v_lshl_add_u64 v[222:223], v[222:223], 0, s[36:37]
	s_mov_b32 m0, s58
	ds_read_b128 v[190:193], v154 offset:49152
	ds_read_b128 v[194:197], v154 offset:50176
	ds_read_b128 v[198:201], v154 offset:51200
	ds_read_b128 v[202:205], v154 offset:52224
	ds_read_b128 v[206:209], v154 offset:53248
	ds_read_b128 v[210:213], v154 offset:54272
	ds_read_b128 v[214:217], v154 offset:55296
	ds_read_b128 v[218:221], v154 offset:56320
	global_load_lds_dwordx4 v[222:223], off
	s_add_i32 m0, s58, 0x2000
	s_add_u32 s56, s56, 0x80080
	v_lshl_add_u64 v[222:223], v[224:225], 0, s[36:37]
	s_addc_u32 s57, s57, 0
	s_add_i32 s58, s63, s3
	global_load_lds_dwordx4 v[222:223], off
	v_lshl_add_u64 v[222:223], s[56:57], 0, v[130:131]
	s_mov_b32 m0, s58
	s_nop 0
	global_load_lds_dwordx4 v[222:223], off
	v_lshl_add_u64 v[222:223], s[56:57], 0, v[134:135]
	s_add_i32 m0, s58, 0x2000
	s_nop 0
	global_load_lds_dwordx4 v[222:223], off
	v_lshl_add_u64 v[222:223], v[226:227], 0, s[36:37]
	s_mov_b32 m0, s44
	s_nop 0
	global_load_lds_dwordx4 v[222:223], off
	v_lshl_add_u64 v[222:223], v[228:229], 0, s[36:37]
	s_mov_b32 m0, s45
	s_nop 0
	global_load_lds_dwordx4 v[222:223], off
	s_waitcnt vmcnt(8)
	s_waitcnt lgkmcnt(0)
	s_setprio 1
	s_barrier
	v_mfma_f32_16x16x32_bf16 v[60:63], v[156:159], v[190:193], v[60:63]
	v_mfma_f32_16x16x32_bf16 v[56:59], v[164:167], v[190:193], v[56:59]
	v_mfma_f32_16x16x32_bf16 v[40:43], v[164:167], v[198:201], v[40:43]
	v_mfma_f32_16x16x32_bf16 v[44:47], v[156:159], v[198:201], v[44:47]
	v_mfma_f32_16x16x32_bf16 v[28:31], v[156:159], v[206:209], v[28:31]
	v_mfma_f32_16x16x32_bf16 v[24:27], v[164:167], v[206:209], v[24:27]
	v_mfma_f32_16x16x32_bf16 v[8:11], v[164:167], v[214:217], v[8:11]
	v_mfma_f32_16x16x32_bf16 v[12:15], v[156:159], v[214:217], v[12:15]
	v_mfma_f32_16x16x32_bf16 v[60:63], v[160:163], v[194:197], v[60:63]
	v_mfma_f32_16x16x32_bf16 v[56:59], v[168:171], v[194:197], v[56:59]
	v_mfma_f32_16x16x32_bf16 v[40:43], v[168:171], v[202:205], v[40:43]
	v_mfma_f32_16x16x32_bf16 v[44:47], v[160:163], v[202:205], v[44:47]
	v_mfma_f32_16x16x32_bf16 v[28:31], v[160:163], v[210:213], v[28:31]
	v_mfma_f32_16x16x32_bf16 v[24:27], v[168:171], v[210:213], v[24:27]
	v_mfma_f32_16x16x32_bf16 v[8:11], v[168:171], v[218:221], v[8:11]
	v_mfma_f32_16x16x32_bf16 v[12:15], v[160:163], v[218:221], v[12:15]
	s_setprio 0
	s_setprio 1
	v_mfma_f32_16x16x32_bf16 v[52:55], v[172:175], v[190:193], v[52:55]
	v_mfma_f32_16x16x32_bf16 v[48:51], v[180:183], v[190:193], v[48:51]
	v_mfma_f32_16x16x32_bf16 v[32:35], v[180:183], v[198:201], v[32:35]
	v_mfma_f32_16x16x32_bf16 v[36:39], v[172:175], v[198:201], v[36:39]
	v_mfma_f32_16x16x32_bf16 v[20:23], v[172:175], v[206:209], v[20:23]
	v_mfma_f32_16x16x32_bf16 v[16:19], v[180:183], v[206:209], v[16:19]
	v_mfma_f32_16x16x32_bf16 v[0:3], v[180:183], v[214:217], v[0:3]
	v_mfma_f32_16x16x32_bf16 v[4:7], v[172:175], v[214:217], v[4:7]
	v_mfma_f32_16x16x32_bf16 v[52:55], v[176:179], v[194:197], v[52:55]
	v_mfma_f32_16x16x32_bf16 v[48:51], v[186:189], v[194:197], v[48:51]
	v_mfma_f32_16x16x32_bf16 v[32:35], v[186:189], v[202:205], v[32:35]
	v_mfma_f32_16x16x32_bf16 v[36:39], v[176:179], v[202:205], v[36:39]
	v_mfma_f32_16x16x32_bf16 v[20:23], v[176:179], v[210:213], v[20:23]
	v_mfma_f32_16x16x32_bf16 v[16:19], v[186:189], v[210:213], v[16:19]
	v_mfma_f32_16x16x32_bf16 v[0:3], v[186:189], v[218:221], v[0:3]
	v_mfma_f32_16x16x32_bf16 v[4:7], v[176:179], v[218:221], v[4:7]
	s_barrier
	s_setprio 0
	s_add_i32 s61, s61, 2
	s_add_u32 s50, s50, 0x100
	s_addc_u32 s51, s51, 0
	s_add_u32 s41, s41, 0x100
	s_addc_u32 s43, s43, 0
	s_cmp_gt_u32 s61, 29
	s_cbranch_scc1 .Lmy_peel_0_exit
.LBB0_300:
	ds_read_b128 v[156:159], v152
	ds_read_b128 v[160:163], v152 offset:1024
	ds_read_b128 v[164:167], v152 offset:2048
	ds_read_b128 v[168:171], v152 offset:3072
	ds_read_b128 v[172:175], v153
	ds_read_b128 v[176:179], v153 offset:1024
	ds_read_b128 v[180:183], v153 offset:2048
	ds_read_b128 v[186:189], v153 offset:3072
	s_add_u32 s56, s50, 0xfff80080
	s_addc_u32 s57, s51, -1
	s_cmp_eq_u32 s61, 28
	s_cselect_b32 s59, s4, s57
	s_cselect_b32 s58, s5, s56
	s_cselect_b32 s57, s12, s43
	s_cselect_b32 s56, s13, s41
	v_lshl_add_u64 v[222:223], s[50:51], 0, v[142:143]
	s_add_i32 m0, s6, 0xc000
	ds_read_b128 v[190:193], v154
	ds_read_b128 v[194:197], v154 offset:1024
	ds_read_b128 v[198:201], v154 offset:2048
	ds_read_b128 v[202:205], v154 offset:3072
	ds_read_b128 v[206:209], v154 offset:4096
	ds_read_b128 v[210:213], v154 offset:5120
	ds_read_b128 v[214:217], v154 offset:6144
	ds_read_b128 v[218:221], v154 offset:7168
	global_load_lds_dwordx4 v[222:223], off
	v_lshl_add_u64 v[222:223], s[50:51], 0, v[144:145]
	s_add_i32 m0, s6, 0xe000
	s_nop 0
	global_load_lds_dwordx4 v[222:223], off
	s_waitcnt vmcnt(8)
	s_waitcnt lgkmcnt(0)
	s_setprio 1
	s_barrier
; #define PG8_STAGE(bufoff, gbase, voff) do { _Pragma("unroll") for (int _i = 0; _i < 2; ++_i) \
;         __builtin_amdgcn_global_load_lds((const unsigned*)((const char*)(gbase) + (voff)[_i]), (PG8_LAS unsigned*)(lds + (bufoff) + ldsw + _i * 8192), 16, 0, 0); } while (0)
; #define PG8_LDA(dst, b, h) do { _Pragma("unroll") for (int m = 0; m < 4; ++m) _Pragma("unroll") for (int k = 0; k < 2; ++k) dst[m][k] = *(const PG8_LAS bf16x8*)(lds + PG8_SA(b, h) + aoff + m * 2048 + k * 1024); } while (0)
; #define PG8_LDB(dst, b, h) do { _Pragma("unroll") for (int n = 0; n < 2; ++n) _Pragma("unroll") for (int k = 0; k < 2; ++k) dst[n][k] = *(const PG8_LAS bf16x8*)(lds + PG8_SB(b, h) + boff + n * 2048 + k * 1024); } while (0)
; #define PG8_MMA(ai, bj, At, Bt) do { __builtin_amdgcn_s_setprio(1); _Pragma("unroll") for (int m = 0; m < 4; ++m) _Pragma("unroll") for (int n = 0; n < 2; ++n) _Pragma("unroll") for (int k = 0; k < 2; ++k) \
;         acc[ai][bj][m][n] = __builtin_amdgcn_mfma_f32_16x16x32_bf16(Bt[n][k], At[m][k], acc[ai][bj][m][n], 0, 0, 0); __builtin_amdgcn_s_setprio(0); } while (0)
; #define PG8_WAIT_V(n) asm volatile("s_waitcnt vmcnt(" #n ")" ::: "memory")
; #define PG8_WAIT_L(n) asm volatile("s_waitcnt lgkmcnt(" #n ")" ::: "memory")
; #define PG8_BAR __builtin_amdgcn_s_barrier()
; #define PG8_SCHED __builtin_amdgcn_sched_barrier(0)
; template <class Epi, class Sched, bool ALIGN_EPI = false, bool SP2 = false>
; __device__ __forceinline__ void gemm_phase(PG8_LAS unsigned char* lds, const Gemm g, const Sched& S, const Epi& E) {
;     ...
;             PG8_WAIT_V(8); PG8_WAIT_L(0); PG8_BAR; PG8_MMA(0, 0, At, B0); PG8_MMA(0, 1, At, B1); PG8_BAR; PG8_SCHED;
;             PG8_LDA(At, 0, 1); PG8_STAGE(PG8_SB(0, 0), b2, voffB); PG8_STAGE(PG8_SB(0, 1), b2 + hstepB, voffB); PG8_STAGE(PG8_SA(0, 0), a2, voffA);
;             PG8_WAIT_V(8); PG8_WAIT_L(0); PG8_BAR; PG8_MMA(1, 0, At, B0); PG8_MMA(1, 1, At, B1); PG8_BAR; PG8_SCHED;
;             PG8_LDB(B0, 1, 0); PG8_LDB(B1, 1, 1); PG8_SCHED; PG8_LDA(At, 1, 0); PG8_STAGE(PG8_SA(0, 1), a2 + hstepA, voffA);
;             PG8_WAIT_V(8); PG8_WAIT_L(0); PG8_BAR; PG8_MMA(0, 0, At, B0); PG8_MMA(0, 1, At, B1); PG8_BAR; PG8_SCHED;
	v_mfma_f32_16x16x32_bf16 v[124:127], v[156:159], v[190:193], v[124:127]
	v_mfma_f32_16x16x32_bf16 v[120:123], v[164:167], v[190:193], v[120:123]
	v_mfma_f32_16x16x32_bf16 v[104:107], v[164:167], v[198:201], v[104:107]
	v_mfma_f32_16x16x32_bf16 v[108:111], v[156:159], v[198:201], v[108:111]
	v_mfma_f32_16x16x32_bf16 v[92:95], v[156:159], v[206:209], v[92:95]
	v_mfma_f32_16x16x32_bf16 v[88:91], v[164:167], v[206:209], v[88:91]
	v_mfma_f32_16x16x32_bf16 v[72:75], v[164:167], v[214:217], v[72:75]
	v_mfma_f32_16x16x32_bf16 v[76:79], v[156:159], v[214:217], v[76:79]
	v_mfma_f32_16x16x32_bf16 v[124:127], v[160:163], v[194:197], v[124:127]
	v_mfma_f32_16x16x32_bf16 v[120:123], v[168:171], v[194:197], v[120:123]
	v_mfma_f32_16x16x32_bf16 v[104:107], v[168:171], v[202:205], v[104:107]
	v_mfma_f32_16x16x32_bf16 v[108:111], v[160:163], v[202:205], v[108:111]
	v_mfma_f32_16x16x32_bf16 v[92:95], v[160:163], v[210:213], v[92:95]
	v_mfma_f32_16x16x32_bf16 v[88:91], v[168:171], v[210:213], v[88:91]
	v_mfma_f32_16x16x32_bf16 v[72:75], v[168:171], v[218:221], v[72:75]
	v_mfma_f32_16x16x32_bf16 v[76:79], v[160:163], v[218:221], v[76:79]
	s_setprio 0
	s_setprio 1
	v_mfma_f32_16x16x32_bf16 v[116:119], v[172:175], v[190:193], v[116:119]
	v_mfma_f32_16x16x32_bf16 v[112:115], v[180:183], v[190:193], v[112:115]
	v_mfma_f32_16x16x32_bf16 v[96:99], v[180:183], v[198:201], v[96:99]
	v_mfma_f32_16x16x32_bf16 v[100:103], v[172:175], v[198:201], v[100:103]
	v_mfma_f32_16x16x32_bf16 v[84:87], v[172:175], v[206:209], v[84:87]
	v_mfma_f32_16x16x32_bf16 v[80:83], v[180:183], v[206:209], v[80:83]
	v_mfma_f32_16x16x32_bf16 v[64:67], v[180:183], v[214:217], v[64:67]
	v_mfma_f32_16x16x32_bf16 v[68:71], v[172:175], v[214:217], v[68:71]
	v_mfma_f32_16x16x32_bf16 v[116:119], v[176:179], v[194:197], v[116:119]
	v_mfma_f32_16x16x32_bf16 v[112:115], v[186:189], v[194:197], v[112:115]
	v_mfma_f32_16x16x32_bf16 v[96:99], v[186:189], v[202:205], v[96:99]
	v_mfma_f32_16x16x32_bf16 v[100:103], v[176:179], v[202:205], v[100:103]
	v_mfma_f32_16x16x32_bf16 v[84:87], v[176:179], v[210:213], v[84:87]
	v_mfma_f32_16x16x32_bf16 v[80:83], v[186:189], v[210:213], v[80:83]
	v_mfma_f32_16x16x32_bf16 v[64:67], v[186:189], v[218:221], v[64:67]
	v_mfma_f32_16x16x32_bf16 v[68:71], v[176:179], v[218:221], v[68:71]
	s_barrier
	s_setprio 0
	s_add_i32 s62, s53, s3
	v_lshl_add_u64 v[222:223], s[56:57], 0, v[130:131]
	s_mov_b32 m0, s62
	ds_read_b128 v[190:193], v154 offset:16384
	ds_read_b128 v[194:197], v154 offset:17408
	ds_read_b128 v[198:201], v154 offset:18432
	ds_read_b128 v[202:205], v154 offset:19456
	ds_read_b128 v[206:209], v154 offset:20480
	ds_read_b128 v[210:213], v154 offset:21504
	ds_read_b128 v[214:217], v154 offset:22528
	ds_read_b128 v[218:221], v154 offset:23552
	global_load_lds_dwordx4 v[222:223], off
	s_add_i32 m0, s62, 0x2000
	s_add_u32 s62, s56, 0x80000
	v_lshl_add_u64 v[224:225], s[56:57], 0, v[134:135]
	s_addc_u32 s63, s57, 0
	s_add_i32 s64, s55, s3
	global_load_lds_dwordx4 v[224:225], off
	v_lshl_add_u64 v[226:227], s[62:63], 0, v[130:131]
	s_mov_b32 m0, s64
	v_lshl_add_u64 v[228:229], s[58:59], 0, v[132:133]
	global_load_lds_dwordx4 v[226:227], off
	v_lshl_add_u64 v[226:227], s[62:63], 0, v[134:135]
	s_add_i32 m0, s64, 0x2000
	s_nop 0
	global_load_lds_dwordx4 v[226:227], off
	v_lshl_add_u64 v[226:227], s[58:59], 0, v[128:129]
	s_mov_b32 m0, s6
	s_nop 0
	global_load_lds_dwordx4 v[226:227], off
	s_mov_b32 m0, s7
	s_nop 0
	global_load_lds_dwordx4 v[228:229], off
	s_waitcnt vmcnt(8)
	s_waitcnt lgkmcnt(0)
	s_setprio 1
	s_barrier
	v_mfma_f32_16x16x32_bf16 v[60:63], v[156:159], v[190:193], v[60:63]
	v_mfma_f32_16x16x32_bf16 v[56:59], v[164:167], v[190:193], v[56:59]
	v_mfma_f32_16x16x32_bf16 v[40:43], v[164:167], v[198:201], v[40:43]
	v_mfma_f32_16x16x32_bf16 v[44:47], v[156:159], v[198:201], v[44:47]
	v_mfma_f32_16x16x32_bf16 v[28:31], v[156:159], v[206:209], v[28:31]
	v_mfma_f32_16x16x32_bf16 v[24:27], v[164:167], v[206:209], v[24:27]
	v_mfma_f32_16x16x32_bf16 v[8:11], v[164:167], v[214:217], v[8:11]
	v_mfma_f32_16x16x32_bf16 v[12:15], v[156:159], v[214:217], v[12:15]
	v_mfma_f32_16x16x32_bf16 v[60:63], v[160:163], v[194:197], v[60:63]
	v_mfma_f32_16x16x32_bf16 v[56:59], v[168:171], v[194:197], v[56:59]
	v_mfma_f32_16x16x32_bf16 v[40:43], v[168:171], v[202:205], v[40:43]
	v_mfma_f32_16x16x32_bf16 v[44:47], v[160:163], v[202:205], v[44:47]
	v_mfma_f32_16x16x32_bf16 v[28:31], v[160:163], v[210:213], v[28:31]
	v_mfma_f32_16x16x32_bf16 v[24:27], v[168:171], v[210:213], v[24:27]
	v_mfma_f32_16x16x32_bf16 v[8:11], v[168:171], v[218:221], v[8:11]
	v_mfma_f32_16x16x32_bf16 v[12:15], v[160:163], v[218:221], v[12:15]
	s_setprio 0
	s_setprio 1
	v_mfma_f32_16x16x32_bf16 v[52:55], v[172:175], v[190:193], v[52:55]
	v_mfma_f32_16x16x32_bf16 v[48:51], v[180:183], v[190:193], v[48:51]
	v_mfma_f32_16x16x32_bf16 v[32:35], v[180:183], v[198:201], v[32:35]
	v_mfma_f32_16x16x32_bf16 v[36:39], v[172:175], v[198:201], v[36:39]
	v_mfma_f32_16x16x32_bf16 v[20:23], v[172:175], v[206:209], v[20:23]
	v_mfma_f32_16x16x32_bf16 v[16:19], v[180:183], v[206:209], v[16:19]
	v_mfma_f32_16x16x32_bf16 v[0:3], v[180:183], v[214:217], v[0:3]
	v_mfma_f32_16x16x32_bf16 v[4:7], v[172:175], v[214:217], v[4:7]
	v_mfma_f32_16x16x32_bf16 v[52:55], v[176:179], v[194:197], v[52:55]
	v_mfma_f32_16x16x32_bf16 v[48:51], v[186:189], v[194:197], v[48:51]
	v_mfma_f32_16x16x32_bf16 v[32:35], v[186:189], v[202:205], v[32:35]
	v_mfma_f32_16x16x32_bf16 v[36:39], v[176:179], v[202:205], v[36:39]
	v_mfma_f32_16x16x32_bf16 v[20:23], v[176:179], v[210:213], v[20:23]
	v_mfma_f32_16x16x32_bf16 v[16:19], v[186:189], v[210:213], v[16:19]
	v_mfma_f32_16x16x32_bf16 v[0:3], v[186:189], v[218:221], v[0:3]
	v_mfma_f32_16x16x32_bf16 v[4:7], v[176:179], v[218:221], v[4:7]
	s_barrier
; #define PG8_STAGE(bufoff, gbase, voff) do { _Pragma("unroll") for (int _i = 0; _i < 2; ++_i) \
;         __builtin_amdgcn_global_load_lds((const unsigned*)((const char*)(gbase) + (voff)[_i]), (PG8_LAS unsigned*)(lds + (bufoff) + ldsw + _i * 8192), 16, 0, 0); } while (0)
; #define PG8_LDA(dst, b, h) do { _Pragma("unroll") for (int m = 0; m < 4; ++m) _Pragma("unroll") for (int k = 0; k < 2; ++k) dst[m][k] = *(const PG8_LAS bf16x8*)(lds + PG8_SA(b, h) + aoff + m * 2048 + k * 1024); } while (0)
; #define PG8_LDB(dst, b, h) do { _Pragma("unroll") for (int n = 0; n < 2; ++n) _Pragma("unroll") for (int k = 0; k < 2; ++k) dst[n][k] = *(const PG8_LAS bf16x8*)(lds + PG8_SB(b, h) + boff + n * 2048 + k * 1024); } while (0)
; #define PG8_MMA(ai, bj, At, Bt) do { __builtin_amdgcn_s_setprio(1); _Pragma("unroll") for (int m = 0; m < 4; ++m) _Pragma("unroll") for (int n = 0; n < 2; ++n) _Pragma("unroll") for (int k = 0; k < 2; ++k) \
;         acc[ai][bj][m][n] = __builtin_amdgcn_mfma_f32_16x16x32_bf16(Bt[n][k], At[m][k], acc[ai][bj][m][n], 0, 0, 0); __builtin_amdgcn_s_setprio(0); } while (0)
; #define PG8_WAIT_V(n) asm volatile("s_waitcnt vmcnt(" #n ")" ::: "memory")
; #define PG8_WAIT_L(n) asm volatile("s_waitcnt lgkmcnt(" #n ")" ::: "memory")
; #define PG8_BAR __builtin_amdgcn_s_barrier()
; #define PG8_SCHED __builtin_amdgcn_sched_barrier(0)
; template <class Epi, class Sched, bool ALIGN_EPI = false, bool SP2 = false>
; __device__ __forceinline__ void gemm_phase(PG8_LAS unsigned char* lds, const Gemm g, const Sched& S, const Epi& E) {
;     ...
;             PG8_LDB(B0, 1, 0); PG8_LDB(B1, 1, 1); PG8_SCHED; PG8_LDA(At, 1, 0); PG8_STAGE(PG8_SA(0, 1), a2 + hstepA, voffA);
;             PG8_WAIT_V(8); PG8_WAIT_L(0); PG8_BAR; PG8_MMA(0, 0, At, B0); PG8_MMA(0, 1, At, B1); PG8_BAR; PG8_SCHED;
	s_setprio 0
	s_add_i32 s62, 0, 0x18000
	v_add_u32_e32 v155, s62, v150
	s_add_i32 s63, 0, 0x1c000
	ds_read_b128 v[156:159], v155
	ds_read_b128 v[160:163], v155 offset:1024
	ds_read_b128 v[164:167], v155 offset:2048
	ds_read_b128 v[168:171], v155 offset:3072
	v_add_u32_e32 v155, s63, v150
	ds_read_b128 v[172:175], v155
	ds_read_b128 v[176:179], v155 offset:1024
	ds_read_b128 v[180:183], v155 offset:2048
	ds_read_b128 v[186:189], v155 offset:3072
	s_add_u32 s58, s58, 0x80000
	s_addc_u32 s59, s59, 0
	s_mov_b32 m0, s8
	v_lshl_add_u64 v[230:231], s[58:59], 0, v[128:129]
	ds_read_b128 v[190:193], v154 offset:32768
	ds_read_b128 v[194:197], v154 offset:33792
	ds_read_b128 v[198:201], v154 offset:34816
	ds_read_b128 v[202:205], v154 offset:35840
	ds_read_b128 v[206:209], v154 offset:36864
	ds_read_b128 v[210:213], v154 offset:37888
	ds_read_b128 v[214:217], v154 offset:38912
	ds_read_b128 v[218:221], v154 offset:39936
	global_load_lds_dwordx4 v[230:231], off
	v_lshl_add_u64 v[230:231], s[58:59], 0, v[132:133]
	s_mov_b32 m0, s9
	s_nop 0
	global_load_lds_dwordx4 v[230:231], off
	s_waitcnt vmcnt(8)
	s_waitcnt lgkmcnt(0)
	s_setprio 1
	s_barrier
	v_mfma_f32_16x16x32_bf16 v[124:127], v[156:159], v[190:193], v[124:127]
	v_mfma_f32_16x16x32_bf16 v[120:123], v[164:167], v[190:193], v[120:123]
	v_mfma_f32_16x16x32_bf16 v[104:107], v[164:167], v[198:201], v[104:107]
	v_mfma_f32_16x16x32_bf16 v[108:111], v[156:159], v[198:201], v[108:111]
	v_mfma_f32_16x16x32_bf16 v[92:95], v[156:159], v[206:209], v[92:95]
	v_mfma_f32_16x16x32_bf16 v[88:91], v[164:167], v[206:209], v[88:91]
	v_mfma_f32_16x16x32_bf16 v[72:75], v[164:167], v[214:217], v[72:75]
	v_mfma_f32_16x16x32_bf16 v[76:79], v[156:159], v[214:217], v[76:79]
	v_mfma_f32_16x16x32_bf16 v[124:127], v[160:163], v[194:197], v[124:127]
	v_mfma_f32_16x16x32_bf16 v[120:123], v[168:171], v[194:197], v[120:123]
	v_mfma_f32_16x16x32_bf16 v[104:107], v[168:171], v[202:205], v[104:107]
	v_mfma_f32_16x16x32_bf16 v[108:111], v[160:163], v[202:205], v[108:111]
	v_mfma_f32_16x16x32_bf16 v[92:95], v[160:163], v[210:213], v[92:95]
	v_mfma_f32_16x16x32_bf16 v[88:91], v[168:171], v[210:213], v[88:91]
	v_mfma_f32_16x16x32_bf16 v[72:75], v[168:171], v[218:221], v[72:75]
	v_mfma_f32_16x16x32_bf16 v[76:79], v[160:163], v[218:221], v[76:79]
	s_setprio 0
	s_setprio 1
	v_mfma_f32_16x16x32_bf16 v[116:119], v[172:175], v[190:193], v[116:119]
	v_mfma_f32_16x16x32_bf16 v[112:115], v[180:183], v[190:193], v[112:115]
	v_mfma_f32_16x16x32_bf16 v[96:99], v[180:183], v[198:201], v[96:99]
	v_mfma_f32_16x16x32_bf16 v[100:103], v[172:175], v[198:201], v[100:103]
	v_mfma_f32_16x16x32_bf16 v[84:87], v[172:175], v[206:209], v[84:87]
	v_mfma_f32_16x16x32_bf16 v[80:83], v[180:183], v[206:209], v[80:83]
	v_mfma_f32_16x16x32_bf16 v[64:67], v[180:183], v[214:217], v[64:67]
	v_mfma_f32_16x16x32_bf16 v[68:71], v[172:175], v[214:217], v[68:71]
	v_mfma_f32_16x16x32_bf16 v[116:119], v[176:179], v[194:197], v[116:119]
	v_mfma_f32_16x16x32_bf16 v[112:115], v[186:189], v[194:197], v[112:115]
	v_mfma_f32_16x16x32_bf16 v[96:99], v[186:189], v[202:205], v[96:99]
	v_mfma_f32_16x16x32_bf16 v[100:103], v[176:179], v[202:205], v[100:103]
	v_mfma_f32_16x16x32_bf16 v[84:87], v[176:179], v[210:213], v[84:87]
	v_mfma_f32_16x16x32_bf16 v[80:83], v[186:189], v[210:213], v[80:83]
	v_mfma_f32_16x16x32_bf16 v[64:67], v[186:189], v[218:221], v[64:67]
	v_mfma_f32_16x16x32_bf16 v[68:71], v[176:179], v[218:221], v[68:71]
	s_barrier
; #define PG8_STAGE(bufoff, gbase, voff) do { _Pragma("unroll") for (int _i = 0; _i < 2; ++_i) \
;         __builtin_amdgcn_global_load_lds((const unsigned*)((const char*)(gbase) + (voff)[_i]), (PG8_LAS unsigned*)(lds + (bufoff) + ldsw + _i * 8192), 16, 0, 0); } while (0)
; #define PG8_LDA(dst, b, h) do { _Pragma("unroll") for (int m = 0; m < 4; ++m) _Pragma("unroll") for (int k = 0; k < 2; ++k) dst[m][k] = *(const PG8_LAS bf16x8*)(lds + PG8_SA(b, h) + aoff + m * 2048 + k * 1024); } while (0)
; #define PG8_MMA(ai, bj, At, Bt) do { __builtin_amdgcn_s_setprio(1); _Pragma("unroll") for (int m = 0; m < 4; ++m) _Pragma("unroll") for (int n = 0; n < 2; ++n) _Pragma("unroll") for (int k = 0; k < 2; ++k) \
;         acc[ai][bj][m][n] = __builtin_amdgcn_mfma_f32_16x16x32_bf16(Bt[n][k], At[m][k], acc[ai][bj][m][n], 0, 0, 0); __builtin_amdgcn_s_setprio(0); } while (0)
; #define PG8_WAIT_V(n) asm volatile("s_waitcnt vmcnt(" #n ")" ::: "memory")
; #define PG8_WAIT_L(n) asm volatile("s_waitcnt lgkmcnt(" #n ")" ::: "memory")
; #define PG8_BAR __builtin_amdgcn_s_barrier()
; #define PG8_SCHED __builtin_amdgcn_sched_barrier(0)
; template <class Epi, class Sched, bool ALIGN_EPI = false, bool SP2 = false>
; __device__ __forceinline__ void gemm_phase(PG8_LAS unsigned char* lds, const Gemm g, const Sched& S, const Epi& E) {
;     ...
;             PG8_LDA(At, 1, 1); PG8_STAGE(PG8_SB(1, 0), b3, voffB); PG8_STAGE(PG8_SB(1, 1), b3 + hstepB, voffB); PG8_STAGE(PG8_SA(1, 0), a3, voffA);
;             PG8_WAIT_V(8); PG8_WAIT_L(0); PG8_BAR; PG8_MMA(1, 0, At, B0); PG8_MMA(1, 1, At, B1); PG8_BAR; PG8_SCHED;
	s_setprio 0
	s_add_i32 s58, s62, s3
	v_lshl_add_u64 v[222:223], v[222:223], 0, s[36:37]
	s_mov_b32 m0, s58
	ds_read_b128 v[190:193], v154 offset:49152
	ds_read_b128 v[194:197], v154 offset:50176
	ds_read_b128 v[198:201], v154 offset:51200
	ds_read_b128 v[202:205], v154 offset:52224
	ds_read_b128 v[206:209], v154 offset:53248
	ds_read_b128 v[210:213], v154 offset:54272
	ds_read_b128 v[214:217], v154 offset:55296
	ds_read_b128 v[218:221], v154 offset:56320
	global_load_lds_dwordx4 v[222:223], off
	s_add_i32 m0, s58, 0x2000
	s_add_u32 s56, s56, 0x80080
	v_lshl_add_u64 v[222:223], v[224:225], 0, s[36:37]
	s_addc_u32 s57, s57, 0
	s_add_i32 s58, s63, s3
	global_load_lds_dwordx4 v[222:223], off
	v_lshl_add_u64 v[222:223], s[56:57], 0, v[130:131]
	s_mov_b32 m0, s58
	s_nop 0
	global_load_lds_dwordx4 v[222:223], off
	v_lshl_add_u64 v[222:223], s[56:57], 0, v[134:135]
	s_add_i32 m0, s58, 0x2000
	s_nop 0
	global_load_lds_dwordx4 v[222:223], off
	v_lshl_add_u64 v[222:223], v[226:227], 0, s[36:37]
	s_mov_b32 m0, s44
	s_nop 0
	global_load_lds_dwordx4 v[222:223], off
	v_lshl_add_u64 v[222:223], v[228:229], 0, s[36:37]
	s_mov_b32 m0, s45
	s_nop 0
	global_load_lds_dwordx4 v[222:223], off
	s_waitcnt vmcnt(8)
	s_waitcnt lgkmcnt(0)
	s_setprio 1
	s_barrier
	v_mfma_f32_16x16x32_bf16 v[60:63], v[156:159], v[190:193], v[60:63]
	v_mfma_f32_16x16x32_bf16 v[56:59], v[164:167], v[190:193], v[56:59]
	v_mfma_f32_16x16x32_bf16 v[40:43], v[164:167], v[198:201], v[40:43]
	v_mfma_f32_16x16x32_bf16 v[44:47], v[156:159], v[198:201], v[44:47]
	v_mfma_f32_16x16x32_bf16 v[28:31], v[156:159], v[206:209], v[28:31]
	v_mfma_f32_16x16x32_bf16 v[24:27], v[164:167], v[206:209], v[24:27]
	v_mfma_f32_16x16x32_bf16 v[8:11], v[164:167], v[214:217], v[8:11]
	v_mfma_f32_16x16x32_bf16 v[12:15], v[156:159], v[214:217], v[12:15]
	v_mfma_f32_16x16x32_bf16 v[60:63], v[160:163], v[194:197], v[60:63]
	v_mfma_f32_16x16x32_bf16 v[56:59], v[168:171], v[194:197], v[56:59]
	v_mfma_f32_16x16x32_bf16 v[40:43], v[168:171], v[202:205], v[40:43]
	v_mfma_f32_16x16x32_bf16 v[44:47], v[160:163], v[202:205], v[44:47]
	v_mfma_f32_16x16x32_bf16 v[28:31], v[160:163], v[210:213], v[28:31]
	v_mfma_f32_16x16x32_bf16 v[24:27], v[168:171], v[210:213], v[24:27]
	v_mfma_f32_16x16x32_bf16 v[8:11], v[168:171], v[218:221], v[8:11]
	v_mfma_f32_16x16x32_bf16 v[12:15], v[160:163], v[218:221], v[12:15]
	s_setprio 0
	s_setprio 1
	v_mfma_f32_16x16x32_bf16 v[52:55], v[172:175], v[190:193], v[52:55]
	v_mfma_f32_16x16x32_bf16 v[48:51], v[180:183], v[190:193], v[48:51]
	v_mfma_f32_16x16x32_bf16 v[32:35], v[180:183], v[198:201], v[32:35]
	v_mfma_f32_16x16x32_bf16 v[36:39], v[172:175], v[198:201], v[36:39]
	v_mfma_f32_16x16x32_bf16 v[20:23], v[172:175], v[206:209], v[20:23]
	v_mfma_f32_16x16x32_bf16 v[16:19], v[180:183], v[206:209], v[16:19]
	v_mfma_f32_16x16x32_bf16 v[0:3], v[180:183], v[214:217], v[0:3]
	v_mfma_f32_16x16x32_bf16 v[4:7], v[172:175], v[214:217], v[4:7]
	v_mfma_f32_16x16x32_bf16 v[52:55], v[176:179], v[194:197], v[52:55]
	v_mfma_f32_16x16x32_bf16 v[48:51], v[186:189], v[194:197], v[48:51]
	v_mfma_f32_16x16x32_bf16 v[32:35], v[186:189], v[202:205], v[32:35]
	v_mfma_f32_16x16x32_bf16 v[36:39], v[176:179], v[202:205], v[36:39]
	v_mfma_f32_16x16x32_bf16 v[20:23], v[176:179], v[210:213], v[20:23]
	v_mfma_f32_16x16x32_bf16 v[16:19], v[186:189], v[210:213], v[16:19]
	v_mfma_f32_16x16x32_bf16 v[0:3], v[186:189], v[218:221], v[0:3]
	v_mfma_f32_16x16x32_bf16 v[4:7], v[176:179], v[218:221], v[4:7]
	s_barrier
	s_setprio 0
	s_add_i32 s61, s61, 2
	s_add_u32 s50, s50, 0x100
	s_addc_u32 s51, s51, 0
	s_add_u32 s41, s41, 0x100
	s_addc_u32 s43, s43, 0
	s_cmp_gt_u32 s61, 29
	s_cbranch_scc0 .LBB0_300

; #define PG8_STAGE(bufoff, gbase, voff) do { _Pragma("unroll") for (int _i = 0; _i < 2; ++_i) \
;         __builtin_amdgcn_global_load_lds((const unsigned*)((const char*)(gbase) + (voff)[_i]), (PG8_LAS unsigned*)(lds + (bufoff) + ldsw + _i * 8192), 16, 0, 0); } while (0)
; #define PG8_LDA(dst, b, h) do { _Pragma("unroll") for (int m = 0; m < 4; ++m) _Pragma("unroll") for (int k = 0; k < 2; ++k) dst[m][k] = *(const PG8_LAS bf16x8*)(lds + PG8_SA(b, h) + aoff + m * 2048 + k * 1024); } while (0)
; #define PG8_LDB(dst, b, h) do { _Pragma("unroll") for (int n = 0; n < 2; ++n) _Pragma("unroll") for (int k = 0; k < 2; ++k) dst[n][k] = *(const PG8_LAS bf16x8*)(lds + PG8_SB(b, h) + boff + n * 2048 + k * 1024); } while (0)
; #define PG8_MMA(ai, bj, At, Bt) do { __builtin_amdgcn_s_setprio(1); _Pragma("unroll") for (int m = 0; m < 4; ++m) _Pragma("unroll") for (int n = 0; n < 2; ++n) _Pragma("unroll") for (int k = 0; k < 2; ++k) \
;         acc[ai][bj][m][n] = __builtin_amdgcn_mfma_f32_16x16x32_bf16(Bt[n][k], At[m][k], acc[ai][bj][m][n], 0, 0, 0); __builtin_amdgcn_s_setprio(0); } while (0)
; #define PG8_WAIT_V(n) asm volatile("s_waitcnt vmcnt(" #n ")" ::: "memory")
; #define PG8_WAIT_L(n) asm volatile("s_waitcnt lgkmcnt(" #n ")" ::: "memory")
; #define PG8_BAR __builtin_amdgcn_s_barrier()
; template <class Epi, class Sched, bool ALIGN_EPI = false, bool SP2 = false>
; __device__ __forceinline__ void gemm_phase(PG8_LAS unsigned char* lds, const Gemm g, const Sched& S, const Epi& E) {
;     ...
;             const char* a1 = cA + (size_t)(t + 1) * kstA;
;             const char* a2 = last ? nA : cA + (size_t)(t + 2) * kstA; const char* b2 = last ? nB : cB + (size_t)(t + 2) * kstep;
;             const char* a3 = a2 + kstA; const char* b3 = b2 + kstep;
;             if (last && has_next) S.a_ready(nxt);
;             if constexpr (SP2) {
;             PG8_LDB(B0, 0, 0); PG8_LDB(B1, 0, 1); PG8_SCHED; PG8_LDA(At, 0, 0); PG8_STAGE(PG8_SA(1, 1), a1 + hstepA, voffA);
;             PG8_WAIT_V(8); PG8_WAIT_L(0); PG8_BAR; PG8_MMA(0, 0, At, B0); PG8_MMA(0, 1, At, B1); PG8_BAR; PG8_SCHED;
;             PG8_LDA(At, 0, 1); PG8_STAGE(PG8_SB(0, 0), b2, voffB); PG8_STAGE(PG8_SB(0, 1), b2 + hstepB, voffB); PG8_STAGE(PG8_SA(0, 0), a2, voffA);
;             PG8_WAIT_V(8); PG8_WAIT_L(0); PG8_BAR; PG8_MMA(1, 0, At, B0); PG8_MMA(1, 1, At, B1); PG8_BAR; PG8_SCHED;
.LBB0_397:
	s_or_b32 s42, s74, 1
	s_add_i32 s74, s74, 2
	s_mov_b32 s75, s43
	s_lshl_b64 s[4:5], s[42:43], 15
	s_lshl_b64 s[12:13], s[74:75], 15
	s_add_u32 s42, s38, s12
	v_add_u32_e32 v170, s10, v177
	v_add_u32_e32 v174, s11, v177
	s_addc_u32 s46, s39, s13
	ds_read_b128 v[158:161], v170
	ds_read_b128 v[162:165], v170 offset:1024
	ds_read_b128 v[166:169], v170 offset:2048
	ds_read_b128 v[170:173], v170 offset:3072
	ds_read_b128 v[180:183], v174
	ds_read_b128 v[186:189], v174 offset:1024
	ds_read_b128 v[190:193], v174 offset:2048
	ds_read_b128 v[194:197], v174 offset:3072
	s_and_b64 s[12:13], s[50:51], exec
	s_cselect_b32 s59, s46, s61
	s_cselect_b32 s58, s42, s60
	s_lshl_b64 s[12:13], s[74:75], 7
	s_add_u32 s42, s40, s12
	s_addc_u32 s46, s41, s13
	s_and_b64 s[12:13], s[50:51], exec
	s_cselect_b32 s53, s46, s63
	s_cselect_b32 s52, s42, s62
	s_add_u32 s50, s58, 0x8000
	s_addc_u32 s51, s59, 0
	s_add_u32 s4, s35, s4
	s_addc_u32 s5, s65, s5
	v_lshl_add_u64 v[174:175], s[4:5], 0, v[128:129]
	s_add_i32 m0, s66, 0xc000
	ds_read_b128 v[198:201], v179
	ds_read_b128 v[202:205], v179 offset:1024
	ds_read_b128 v[206:209], v179 offset:2048
	ds_read_b128 v[210:213], v179 offset:3072
	ds_read_b128 v[214:217], v179 offset:4096
	ds_read_b128 v[218:221], v179 offset:5120
	ds_read_b128 v[222:225], v179 offset:6144
	ds_read_b128 v[226:229], v179 offset:7168
	global_load_lds_dwordx4 v[174:175], off
	v_lshl_add_u64 v[174:175], s[4:5], 0, v[132:133]
	s_add_i32 m0, s66, 0xe000
	s_nop 0
	global_load_lds_dwordx4 v[174:175], off
	s_waitcnt vmcnt(8)
	s_waitcnt lgkmcnt(0)
	s_setprio 1
	s_barrier
	v_mfma_f32_16x16x32_bf16 v[124:127], v[158:161], v[198:201], v[124:127]
	v_mfma_f32_16x16x32_bf16 v[120:123], v[166:169], v[198:201], v[120:123]
	v_mfma_f32_16x16x32_bf16 v[112:115], v[166:169], v[206:209], v[112:115]
	v_mfma_f32_16x16x32_bf16 v[116:119], v[158:161], v[206:209], v[116:119]
	v_mfma_f32_16x16x32_bf16 v[108:111], v[158:161], v[214:217], v[108:111]
	v_mfma_f32_16x16x32_bf16 v[104:107], v[166:169], v[214:217], v[104:107]
	v_mfma_f32_16x16x32_bf16 v[96:99], v[166:169], v[222:225], v[96:99]
	v_mfma_f32_16x16x32_bf16 v[100:103], v[158:161], v[222:225], v[100:103]
	v_mfma_f32_16x16x32_bf16 v[124:127], v[162:165], v[202:205], v[124:127]
	v_mfma_f32_16x16x32_bf16 v[120:123], v[170:173], v[202:205], v[120:123]
	v_mfma_f32_16x16x32_bf16 v[112:115], v[170:173], v[210:213], v[112:115]
	v_mfma_f32_16x16x32_bf16 v[116:119], v[162:165], v[210:213], v[116:119]
	v_mfma_f32_16x16x32_bf16 v[108:111], v[162:165], v[218:221], v[108:111]
	v_mfma_f32_16x16x32_bf16 v[104:107], v[170:173], v[218:221], v[104:107]
	v_mfma_f32_16x16x32_bf16 v[96:99], v[170:173], v[226:229], v[96:99]
	v_mfma_f32_16x16x32_bf16 v[100:103], v[162:165], v[226:229], v[100:103]
	s_setprio 0
	s_setprio 1
	v_mfma_f32_16x16x32_bf16 v[92:95], v[180:183], v[198:201], v[92:95]
	v_mfma_f32_16x16x32_bf16 v[88:91], v[190:193], v[198:201], v[88:91]
	v_mfma_f32_16x16x32_bf16 v[80:83], v[190:193], v[206:209], v[80:83]
	v_mfma_f32_16x16x32_bf16 v[84:87], v[180:183], v[206:209], v[84:87]
	v_mfma_f32_16x16x32_bf16 v[76:79], v[180:183], v[214:217], v[76:79]
	v_mfma_f32_16x16x32_bf16 v[72:75], v[190:193], v[214:217], v[72:75]
	v_mfma_f32_16x16x32_bf16 v[64:67], v[190:193], v[222:225], v[64:67]
	v_mfma_f32_16x16x32_bf16 v[68:71], v[180:183], v[222:225], v[68:71]
	v_mfma_f32_16x16x32_bf16 v[92:95], v[186:189], v[202:205], v[92:95]
	v_mfma_f32_16x16x32_bf16 v[88:91], v[194:197], v[202:205], v[88:91]
	v_mfma_f32_16x16x32_bf16 v[80:83], v[194:197], v[210:213], v[80:83]
	v_mfma_f32_16x16x32_bf16 v[84:87], v[186:189], v[210:213], v[84:87]
	v_mfma_f32_16x16x32_bf16 v[76:79], v[186:189], v[218:221], v[76:79]
	v_mfma_f32_16x16x32_bf16 v[72:75], v[194:197], v[218:221], v[72:75]
	v_mfma_f32_16x16x32_bf16 v[64:67], v[194:197], v[226:229], v[64:67]
	v_mfma_f32_16x16x32_bf16 v[68:71], v[186:189], v[226:229], v[68:71]
	s_barrier
	s_setprio 0
	s_add_i32 s4, s10, s9
	v_lshl_add_u64 v[174:175], s[52:53], 0, v[130:131]
	s_mov_b32 m0, s4
	ds_read_b128 v[198:201], v179 offset:16384
	ds_read_b128 v[202:205], v179 offset:17408
	ds_read_b128 v[206:209], v179 offset:18432
	ds_read_b128 v[210:213], v179 offset:19456
	ds_read_b128 v[214:217], v179 offset:20480
	ds_read_b128 v[218:221], v179 offset:21504
	ds_read_b128 v[222:225], v179 offset:22528
	ds_read_b128 v[226:229], v179 offset:23552
	global_load_lds_dwordx4 v[174:175], off
	s_add_i32 m0, s4, 0x2000
	s_add_u32 s4, s52, 0x160000
	v_lshl_add_u64 v[230:231], s[52:53], 0, v[134:135]
	s_addc_u32 s5, s53, 0
	s_add_i32 s12, s11, s9
	global_load_lds_dwordx4 v[230:231], off
	v_lshl_add_u64 v[232:233], s[4:5], 0, v[130:131]
	s_mov_b32 m0, s12
	s_nop 0
	global_load_lds_dwordx4 v[232:233], off
	v_lshl_add_u64 v[232:233], s[4:5], 0, v[134:135]
	s_add_i32 m0, s12, 0x2000
	s_nop 0
	global_load_lds_dwordx4 v[232:233], off
	v_lshl_add_u64 v[232:233], s[58:59], 0, v[128:129]
	s_mov_b32 m0, s66
	s_nop 0
	global_load_lds_dwordx4 v[232:233], off
	v_lshl_add_u64 v[232:233], s[58:59], 0, v[132:133]
	s_mov_b32 m0, s67
	s_nop 0
	global_load_lds_dwordx4 v[232:233], off
	s_waitcnt vmcnt(8)
	s_waitcnt lgkmcnt(0)
	s_setprio 1
	s_barrier
; #define PG8_STAGE(bufoff, gbase, voff) do { _Pragma("unroll") for (int _i = 0; _i < 2; ++_i) \
;         __builtin_amdgcn_global_load_lds((const unsigned*)((const char*)(gbase) + (voff)[_i]), (PG8_LAS unsigned*)(lds + (bufoff) + ldsw + _i * 8192), 16, 0, 0); } while (0)
; #define PG8_LDA(dst, b, h) do { _Pragma("unroll") for (int m = 0; m < 4; ++m) _Pragma("unroll") for (int k = 0; k < 2; ++k) dst[m][k] = *(const PG8_LAS bf16x8*)(lds + PG8_SA(b, h) + aoff + m * 2048 + k * 1024); } while (0)
; #define PG8_LDB(dst, b, h) do { _Pragma("unroll") for (int n = 0; n < 2; ++n) _Pragma("unroll") for (int k = 0; k < 2; ++k) dst[n][k] = *(const PG8_LAS bf16x8*)(lds + PG8_SB(b, h) + boff + n * 2048 + k * 1024); } while (0)
; #define PG8_MMA(ai, bj, At, Bt) do { __builtin_amdgcn_s_setprio(1); _Pragma("unroll") for (int m = 0; m < 4; ++m) _Pragma("unroll") for (int n = 0; n < 2; ++n) _Pragma("unroll") for (int k = 0; k < 2; ++k) \
;         acc[ai][bj][m][n] = __builtin_amdgcn_mfma_f32_16x16x32_bf16(Bt[n][k], At[m][k], acc[ai][bj][m][n], 0, 0, 0); __builtin_amdgcn_s_setprio(0); } while (0)
; #define PG8_WAIT_V(n) asm volatile("s_waitcnt vmcnt(" #n ")" ::: "memory")
; #define PG8_WAIT_L(n) asm volatile("s_waitcnt lgkmcnt(" #n ")" ::: "memory")
; #define PG8_BAR __builtin_amdgcn_s_barrier()
; #define PG8_SCHED __builtin_amdgcn_sched_barrier(0)
; template <class Epi, class Sched, bool ALIGN_EPI = false, bool SP2 = false>
; __device__ __forceinline__ void gemm_phase(PG8_LAS unsigned char* lds, const Gemm g, const Sched& S, const Epi& E) {
;     ...
;             PG8_WAIT_V(8); PG8_WAIT_L(0); PG8_BAR; PG8_MMA(0, 0, At, B0); PG8_MMA(0, 1, At, B1); PG8_BAR; PG8_SCHED;
;             PG8_LDA(At, 0, 1); PG8_STAGE(PG8_SB(0, 0), b2, voffB); PG8_STAGE(PG8_SB(0, 1), b2 + hstepB, voffB); PG8_STAGE(PG8_SA(0, 0), a2, voffA);
;             PG8_WAIT_V(8); PG8_WAIT_L(0); PG8_BAR; PG8_MMA(1, 0, At, B0); PG8_MMA(1, 1, At, B1); PG8_BAR; PG8_SCHED;
;             PG8_LDB(B0, 1, 0); PG8_LDB(B1, 1, 1); PG8_SCHED; PG8_LDA(At, 1, 0); PG8_STAGE(PG8_SA(0, 1), a2 + hstepA, voffA);
;             PG8_WAIT_V(8); PG8_WAIT_L(0); PG8_BAR; PG8_MMA(0, 0, At, B0); PG8_MMA(0, 1, At, B1); PG8_BAR; PG8_SCHED;
	v_mfma_f32_16x16x32_bf16 v[60:63], v[158:161], v[198:201], v[60:63]
	v_mfma_f32_16x16x32_bf16 v[56:59], v[166:169], v[198:201], v[56:59]
	v_mfma_f32_16x16x32_bf16 v[48:51], v[166:169], v[206:209], v[48:51]
	v_mfma_f32_16x16x32_bf16 v[52:55], v[158:161], v[206:209], v[52:55]
	v_mfma_f32_16x16x32_bf16 v[44:47], v[158:161], v[214:217], v[44:47]
	v_mfma_f32_16x16x32_bf16 v[40:43], v[166:169], v[214:217], v[40:43]
	v_mfma_f32_16x16x32_bf16 v[32:35], v[166:169], v[222:225], v[32:35]
	v_mfma_f32_16x16x32_bf16 v[36:39], v[158:161], v[222:225], v[36:39]
	v_mfma_f32_16x16x32_bf16 v[60:63], v[162:165], v[202:205], v[60:63]
	v_mfma_f32_16x16x32_bf16 v[56:59], v[170:173], v[202:205], v[56:59]
	v_mfma_f32_16x16x32_bf16 v[48:51], v[170:173], v[210:213], v[48:51]
	v_mfma_f32_16x16x32_bf16 v[52:55], v[162:165], v[210:213], v[52:55]
	v_mfma_f32_16x16x32_bf16 v[44:47], v[162:165], v[218:221], v[44:47]
	v_mfma_f32_16x16x32_bf16 v[40:43], v[170:173], v[218:221], v[40:43]
	v_mfma_f32_16x16x32_bf16 v[32:35], v[170:173], v[226:229], v[32:35]
	v_mfma_f32_16x16x32_bf16 v[36:39], v[162:165], v[226:229], v[36:39]
	s_setprio 0
	s_setprio 1
	v_mfma_f32_16x16x32_bf16 v[28:31], v[180:183], v[198:201], v[28:31]
	v_mfma_f32_16x16x32_bf16 v[24:27], v[190:193], v[198:201], v[24:27]
	v_mfma_f32_16x16x32_bf16 v[16:19], v[190:193], v[206:209], v[16:19]
	v_mfma_f32_16x16x32_bf16 v[20:23], v[180:183], v[206:209], v[20:23]
	v_mfma_f32_16x16x32_bf16 v[12:15], v[180:183], v[214:217], v[12:15]
	v_mfma_f32_16x16x32_bf16 v[8:11], v[190:193], v[214:217], v[8:11]
	v_mfma_f32_16x16x32_bf16 v[0:3], v[190:193], v[222:225], v[0:3]
	v_mfma_f32_16x16x32_bf16 v[4:7], v[180:183], v[222:225], v[4:7]
	v_mfma_f32_16x16x32_bf16 v[28:31], v[186:189], v[202:205], v[28:31]
	v_mfma_f32_16x16x32_bf16 v[24:27], v[194:197], v[202:205], v[24:27]
	v_mfma_f32_16x16x32_bf16 v[16:19], v[194:197], v[210:213], v[16:19]
	v_mfma_f32_16x16x32_bf16 v[20:23], v[186:189], v[210:213], v[20:23]
	v_mfma_f32_16x16x32_bf16 v[12:15], v[186:189], v[218:221], v[12:15]
	v_mfma_f32_16x16x32_bf16 v[8:11], v[194:197], v[218:221], v[8:11]
	v_mfma_f32_16x16x32_bf16 v[0:3], v[194:197], v[226:229], v[0:3]
	v_mfma_f32_16x16x32_bf16 v[4:7], v[186:189], v[226:229], v[4:7]
	s_barrier
	s_setprio 0
	s_add_i32 s12, 0, 0x18000
	s_add_i32 s13, 0, 0x1c000
	v_add_u32_e32 v170, s12, v177
	v_add_u32_e32 v185, s13, v177
	ds_read_b128 v[158:161], v170
	ds_read_b128 v[162:165], v170 offset:1024
	ds_read_b128 v[166:169], v170 offset:2048
	ds_read_b128 v[170:173], v170 offset:3072
	ds_read_b128 v[180:183], v185
	ds_read_b128 v[186:189], v185 offset:1024
	ds_read_b128 v[190:193], v185 offset:2048
	ds_read_b128 v[194:197], v185 offset:3072
	s_add_u32 s4, s58, 0x4000
	s_addc_u32 s5, s59, 0
	s_mov_b32 m0, s76
	v_lshl_add_u64 v[232:233], s[4:5], 0, v[128:129]
	ds_read_b128 v[198:201], v179 offset:32768
	ds_read_b128 v[202:205], v179 offset:33792
	ds_read_b128 v[206:209], v179 offset:34816
	ds_read_b128 v[210:213], v179 offset:35840
	ds_read_b128 v[214:217], v179 offset:36864
	ds_read_b128 v[218:221], v179 offset:37888
	ds_read_b128 v[222:225], v179 offset:38912
	ds_read_b128 v[226:229], v179 offset:39936
	global_load_lds_dwordx4 v[232:233], off
	v_lshl_add_u64 v[232:233], s[4:5], 0, v[132:133]
	s_mov_b32 m0, s77
	s_nop 0
	global_load_lds_dwordx4 v[232:233], off
	s_waitcnt vmcnt(8)
	s_waitcnt lgkmcnt(0)
	s_setprio 1
	s_barrier
	v_mfma_f32_16x16x32_bf16 v[124:127], v[158:161], v[198:201], v[124:127]
	v_mfma_f32_16x16x32_bf16 v[120:123], v[166:169], v[198:201], v[120:123]
	v_mfma_f32_16x16x32_bf16 v[112:115], v[166:169], v[206:209], v[112:115]
	v_mfma_f32_16x16x32_bf16 v[116:119], v[158:161], v[206:209], v[116:119]
	v_mfma_f32_16x16x32_bf16 v[108:111], v[158:161], v[214:217], v[108:111]
	v_mfma_f32_16x16x32_bf16 v[104:107], v[166:169], v[214:217], v[104:107]
	v_mfma_f32_16x16x32_bf16 v[96:99], v[166:169], v[222:225], v[96:99]
	v_mfma_f32_16x16x32_bf16 v[100:103], v[158:161], v[222:225], v[100:103]
	v_mfma_f32_16x16x32_bf16 v[124:127], v[162:165], v[202:205], v[124:127]
	v_mfma_f32_16x16x32_bf16 v[120:123], v[170:173], v[202:205], v[120:123]
	v_mfma_f32_16x16x32_bf16 v[112:115], v[170:173], v[210:213], v[112:115]
	v_mfma_f32_16x16x32_bf16 v[116:119], v[162:165], v[210:213], v[116:119]
	v_mfma_f32_16x16x32_bf16 v[108:111], v[162:165], v[218:221], v[108:111]
	v_mfma_f32_16x16x32_bf16 v[104:107], v[170:173], v[218:221], v[104:107]
	v_mfma_f32_16x16x32_bf16 v[96:99], v[170:173], v[226:229], v[96:99]
	v_mfma_f32_16x16x32_bf16 v[100:103], v[162:165], v[226:229], v[100:103]
	s_setprio 0
	s_setprio 1
	v_mfma_f32_16x16x32_bf16 v[92:95], v[180:183], v[198:201], v[92:95]
	v_mfma_f32_16x16x32_bf16 v[88:91], v[190:193], v[198:201], v[88:91]
	v_mfma_f32_16x16x32_bf16 v[80:83], v[190:193], v[206:209], v[80:83]
	v_mfma_f32_16x16x32_bf16 v[84:87], v[180:183], v[206:209], v[84:87]
	v_mfma_f32_16x16x32_bf16 v[76:79], v[180:183], v[214:217], v[76:79]
	v_mfma_f32_16x16x32_bf16 v[72:75], v[190:193], v[214:217], v[72:75]
	v_mfma_f32_16x16x32_bf16 v[64:67], v[190:193], v[222:225], v[64:67]
	v_mfma_f32_16x16x32_bf16 v[68:71], v[180:183], v[222:225], v[68:71]
	v_mfma_f32_16x16x32_bf16 v[92:95], v[186:189], v[202:205], v[92:95]
	v_mfma_f32_16x16x32_bf16 v[88:91], v[194:197], v[202:205], v[88:91]
	v_mfma_f32_16x16x32_bf16 v[80:83], v[194:197], v[210:213], v[80:83]
	v_mfma_f32_16x16x32_bf16 v[84:87], v[186:189], v[210:213], v[84:87]
	v_mfma_f32_16x16x32_bf16 v[76:79], v[186:189], v[218:221], v[76:79]
	v_mfma_f32_16x16x32_bf16 v[72:75], v[194:197], v[218:221], v[72:75]
	v_mfma_f32_16x16x32_bf16 v[64:67], v[194:197], v[226:229], v[64:67]
	v_mfma_f32_16x16x32_bf16 v[68:71], v[186:189], v[226:229], v[68:71]
	s_barrier
; #define PG8_STAGE(bufoff, gbase, voff) do { _Pragma("unroll") for (int _i = 0; _i < 2; ++_i) \
;         __builtin_amdgcn_global_load_lds((const unsigned*)((const char*)(gbase) + (voff)[_i]), (PG8_LAS unsigned*)(lds + (bufoff) + ldsw + _i * 8192), 16, 0, 0); } while (0)
; #define PG8_LDA(dst, b, h) do { _Pragma("unroll") for (int m = 0; m < 4; ++m) _Pragma("unroll") for (int k = 0; k < 2; ++k) dst[m][k] = *(const PG8_LAS bf16x8*)(lds + PG8_SA(b, h) + aoff + m * 2048 + k * 1024); } while (0)
; #define PG8_MMA(ai, bj, At, Bt) do { __builtin_amdgcn_s_setprio(1); _Pragma("unroll") for (int m = 0; m < 4; ++m) _Pragma("unroll") for (int n = 0; n < 2; ++n) _Pragma("unroll") for (int k = 0; k < 2; ++k) \
;         acc[ai][bj][m][n] = __builtin_amdgcn_mfma_f32_16x16x32_bf16(Bt[n][k], At[m][k], acc[ai][bj][m][n], 0, 0, 0); __builtin_amdgcn_s_setprio(0); } while (0)
; #define PG8_WAIT_V(n) asm volatile("s_waitcnt vmcnt(" #n ")" ::: "memory")
; #define PG8_WAIT_L(n) asm volatile("s_waitcnt lgkmcnt(" #n ")" ::: "memory")
; #define PG8_BAR __builtin_amdgcn_s_barrier()
; #define PG8_SCHED __builtin_amdgcn_sched_barrier(0)
; template <class Epi, class Sched, bool ALIGN_EPI = false, bool SP2 = false>
; __device__ __forceinline__ void gemm_phase(PG8_LAS unsigned char* lds, const Gemm g, const Sched& S, const Epi& E) {
;     ...
;             PG8_LDA(At, 1, 1); PG8_STAGE(PG8_SB(1, 0), b3, voffB); PG8_STAGE(PG8_SB(1, 1), b3 + hstepB, voffB); PG8_STAGE(PG8_SA(1, 0), a3, voffA);
;             PG8_WAIT_V(8); PG8_WAIT_L(0); PG8_BAR; PG8_MMA(1, 0, At, B0); PG8_MMA(1, 1, At, B1); PG8_BAR; PG8_SCHED;
	s_setprio 0
	s_add_i32 s4, s12, s9
	v_lshl_add_u64 v[174:175], v[174:175], 0, s[54:55]
	s_mov_b32 m0, s4
	ds_read_b128 v[198:201], v179 offset:49152
	ds_read_b128 v[202:205], v179 offset:50176
	ds_read_b128 v[206:209], v179 offset:51200
	ds_read_b128 v[210:213], v179 offset:52224
	ds_read_b128 v[214:217], v179 offset:53248
	ds_read_b128 v[218:221], v179 offset:54272
	ds_read_b128 v[222:225], v179 offset:55296
	ds_read_b128 v[226:229], v179 offset:56320
	global_load_lds_dwordx4 v[174:175], off
	s_add_i32 m0, s4, 0x2000
	s_add_u32 s4, s52, 0x160080
	v_lshl_add_u64 v[174:175], v[230:231], 0, s[54:55]
	s_addc_u32 s5, s53, 0
	s_add_i32 s12, s13, s9
	global_load_lds_dwordx4 v[174:175], off
	v_lshl_add_u64 v[174:175], s[4:5], 0, v[130:131]
	s_mov_b32 m0, s12
	s_nop 0
	global_load_lds_dwordx4 v[174:175], off
	v_lshl_add_u64 v[174:175], s[4:5], 0, v[134:135]
	s_add_i32 m0, s12, 0x2000
	s_nop 0
	global_load_lds_dwordx4 v[174:175], off
	v_lshl_add_u64 v[174:175], s[50:51], 0, v[128:129]
	s_mov_b32 m0, s45
	s_nop 0
	global_load_lds_dwordx4 v[174:175], off
	v_lshl_add_u64 v[174:175], s[50:51], 0, v[132:133]
	s_mov_b32 m0, s56
	s_nop 0
	global_load_lds_dwordx4 v[174:175], off
	s_waitcnt vmcnt(8)
	s_waitcnt lgkmcnt(0)
	s_setprio 1
	s_barrier
	v_mfma_f32_16x16x32_bf16 v[60:63], v[158:161], v[198:201], v[60:63]
	v_mfma_f32_16x16x32_bf16 v[56:59], v[166:169], v[198:201], v[56:59]
	v_mfma_f32_16x16x32_bf16 v[48:51], v[166:169], v[206:209], v[48:51]
	v_mfma_f32_16x16x32_bf16 v[52:55], v[158:161], v[206:209], v[52:55]
	v_mfma_f32_16x16x32_bf16 v[44:47], v[158:161], v[214:217], v[44:47]
	v_mfma_f32_16x16x32_bf16 v[40:43], v[166:169], v[214:217], v[40:43]
	v_mfma_f32_16x16x32_bf16 v[32:35], v[166:169], v[222:225], v[32:35]
	v_mfma_f32_16x16x32_bf16 v[36:39], v[158:161], v[222:225], v[36:39]
	v_mfma_f32_16x16x32_bf16 v[60:63], v[162:165], v[202:205], v[60:63]
	v_mfma_f32_16x16x32_bf16 v[56:59], v[170:173], v[202:205], v[56:59]
	v_mfma_f32_16x16x32_bf16 v[48:51], v[170:173], v[210:213], v[48:51]
	v_mfma_f32_16x16x32_bf16 v[52:55], v[162:165], v[210:213], v[52:55]
	v_mfma_f32_16x16x32_bf16 v[44:47], v[162:165], v[218:221], v[44:47]
	v_mfma_f32_16x16x32_bf16 v[40:43], v[170:173], v[218:221], v[40:43]
	v_mfma_f32_16x16x32_bf16 v[32:35], v[170:173], v[226:229], v[32:35]
	v_mfma_f32_16x16x32_bf16 v[36:39], v[162:165], v[226:229], v[36:39]
	s_setprio 0
	s_setprio 1
	v_mfma_f32_16x16x32_bf16 v[28:31], v[180:183], v[198:201], v[28:31]
	v_mfma_f32_16x16x32_bf16 v[24:27], v[190:193], v[198:201], v[24:27]
	v_mfma_f32_16x16x32_bf16 v[16:19], v[190:193], v[206:209], v[16:19]
	v_mfma_f32_16x16x32_bf16 v[20:23], v[180:183], v[206:209], v[20:23]
	v_mfma_f32_16x16x32_bf16 v[12:15], v[180:183], v[214:217], v[12:15]
	v_mfma_f32_16x16x32_bf16 v[8:11], v[190:193], v[214:217], v[8:11]
	v_mfma_f32_16x16x32_bf16 v[0:3], v[190:193], v[222:225], v[0:3]
	v_mfma_f32_16x16x32_bf16 v[4:7], v[180:183], v[222:225], v[4:7]
	v_mfma_f32_16x16x32_bf16 v[28:31], v[186:189], v[202:205], v[28:31]
	v_mfma_f32_16x16x32_bf16 v[24:27], v[194:197], v[202:205], v[24:27]
	v_mfma_f32_16x16x32_bf16 v[16:19], v[194:197], v[210:213], v[16:19]
	v_mfma_f32_16x16x32_bf16 v[20:23], v[186:189], v[210:213], v[20:23]
	v_mfma_f32_16x16x32_bf16 v[12:15], v[186:189], v[218:221], v[12:15]
	v_mfma_f32_16x16x32_bf16 v[8:11], v[194:197], v[218:221], v[8:11]
	v_mfma_f32_16x16x32_bf16 v[0:3], v[194:197], v[226:229], v[0:3]
	v_mfma_f32_16x16x32_bf16 v[4:7], v[186:189], v[226:229], v[4:7]
	s_barrier
	s_setprio 0
	s_cmp_ge_i32 s74, s57
	s_cbranch_scc1 .LBB0_409

; #define PG8_STAGE(bufoff, gbase, voff) do { _Pragma("unroll") for (int _i = 0; _i < 2; ++_i) \
;         __builtin_amdgcn_global_load_lds((const unsigned*)((const char*)(gbase) + (voff)[_i]), (PG8_LAS unsigned*)(lds + (bufoff) + ldsw + _i * 8192), 16, 0, 0); } while (0)
; #define PG8_LDA(dst, b, h) do { _Pragma("unroll") for (int m = 0; m < 4; ++m) _Pragma("unroll") for (int k = 0; k < 2; ++k) dst[m][k] = *(const PG8_LAS bf16x8*)(lds + PG8_SA(b, h) + aoff + m * 2048 + k * 1024); } while (0)
; #define PG8_LDB(dst, b, h) do { _Pragma("unroll") for (int n = 0; n < 2; ++n) _Pragma("unroll") for (int k = 0; k < 2; ++k) dst[n][k] = *(const PG8_LAS bf16x8*)(lds + PG8_SB(b, h) + boff + n * 2048 + k * 1024); } while (0)
; #define PG8_MMA(ai, bj, At, Bt) do { __builtin_amdgcn_s_setprio(1); _Pragma("unroll") for (int m = 0; m < 4; ++m) _Pragma("unroll") for (int n = 0; n < 2; ++n) _Pragma("unroll") for (int k = 0; k < 2; ++k) \
;         acc[ai][bj][m][n] = __builtin_amdgcn_mfma_f32_16x16x32_bf16(Bt[n][k], At[m][k], acc[ai][bj][m][n], 0, 0, 0); __builtin_amdgcn_s_setprio(0); } while (0)
; #define PG8_WAIT_V(n) asm volatile("s_waitcnt vmcnt(" #n ")" ::: "memory")
; #define PG8_BAR __builtin_amdgcn_s_barrier()
; template <class Epi, class Sched, bool ALIGN_EPI = false, bool SP2 = false>
; __device__ __forceinline__ void gemm_phase(PG8_LAS unsigned char* lds, const Gemm g, const Sched& S, const Epi& E) {
;     ...
;         for (int t = 0; t < nt; t += 2) {
;             const bool last = (t == nt - 2);
;             const char* a1 = cA + (size_t)(t + 1) * kstA;
;             const char* a2 = last ? nA : cA + (size_t)(t + 2) * kstA; const char* b2 = last ? nB : cB + (size_t)(t + 2) * kstep;
;             const char* a3 = a2 + kstA; const char* b3 = b2 + kstep;
;             if (last && has_next) S.a_ready(nxt);
;             if constexpr (SP2) {
;             PG8_LDB(B0, 0, 0); PG8_LDB(B1, 0, 1); PG8_SCHED; PG8_LDA(At, 0, 0); PG8_STAGE(PG8_SA(1, 1), a1 + hstepA, voffA);
;             PG8_WAIT_V(8); PG8_WAIT_L(0); PG8_BAR; PG8_MMA(0, 0, At, B0); PG8_MMA(0, 1, At, B1); PG8_BAR; PG8_SCHED;
;             PG8_LDA(At, 0, 1); PG8_STAGE(PG8_SB(0, 0), b2, voffB); PG8_STAGE(PG8_SB(0, 1), b2 + hstepB, voffB); PG8_STAGE(PG8_SA(0, 0), a2, voffA);
;             PG8_WAIT_V(8); PG8_WAIT_L(0); PG8_BAR; PG8_MMA(1, 0, At, B0); PG8_MMA(1, 1, At, B1); PG8_BAR; PG8_SCHED;
.LBB0_655:
	s_add_u32 s50, s50, 0x80080
	s_addc_u32 s51, s51, 0
	s_add_u32 s4, s52, 0x100
	s_addc_u32 s5, s53, 0
	s_mov_b32 s46, -2
	ds_read_b128 v[166:169], v163
	ds_read_b128 v[170:173], v163 offset:1024
	ds_read_b128 v[174:177], v163 offset:2048
	ds_read_b128 v[178:181], v163 offset:3072
	ds_read_b128 v[186:189], v164
	ds_read_b128 v[190:193], v164 offset:1024
	ds_read_b128 v[194:197], v164 offset:2048
	ds_read_b128 v[198:201], v164 offset:3072
	s_add_u32 s47, s50, 0xfff80080
	s_addc_u32 s52, s51, -1
	s_cmp_eq_u32 s46, 28
	s_cselect_b32 s59, s63, s52
	s_cselect_b32 s58, s62, s47
	s_cselect_b32 s53, s65, s5
	s_cselect_b32 s52, s64, s4
	v_lshl_add_u64 v[158:159], s[50:51], 0, v[152:153]
	s_add_i32 m0, s9, 0xc000
	ds_read_b128 v[202:205], v165
	ds_read_b128 v[206:209], v165 offset:1024
	ds_read_b128 v[210:213], v165 offset:2048
	ds_read_b128 v[214:217], v165 offset:3072
	ds_read_b128 v[218:221], v165 offset:4096
	ds_read_b128 v[222:225], v165 offset:5120
	ds_read_b128 v[226:229], v165 offset:6144
	ds_read_b128 v[230:233], v165 offset:7168
	global_load_lds_dwordx4 v[158:159], off
	v_lshl_add_u64 v[158:159], s[50:51], 0, v[154:155]
	s_add_i32 m0, s9, 0xe000
	s_nop 0
	global_load_lds_dwordx4 v[158:159], off
	s_waitcnt vmcnt(8)
	s_waitcnt lgkmcnt(0)
	s_setprio 1
	s_barrier
	v_mfma_f32_16x16x32_bf16 v[124:127], v[166:169], v[202:205], 0
	v_mfma_f32_16x16x32_bf16 v[120:123], v[174:177], v[202:205], 0
	v_mfma_f32_16x16x32_bf16 v[104:107], v[174:177], v[210:213], 0
	v_mfma_f32_16x16x32_bf16 v[112:115], v[166:169], v[210:213], 0
	v_mfma_f32_16x16x32_bf16 v[96:99], v[166:169], v[218:221], 0
	v_mfma_f32_16x16x32_bf16 v[88:91], v[174:177], v[218:221], 0
	v_mfma_f32_16x16x32_bf16 v[72:75], v[174:177], v[226:229], 0
	v_mfma_f32_16x16x32_bf16 v[80:83], v[166:169], v[226:229], 0
	v_mfma_f32_16x16x32_bf16 v[124:127], v[170:173], v[206:209], v[124:127]
	v_mfma_f32_16x16x32_bf16 v[120:123], v[178:181], v[206:209], v[120:123]
	v_mfma_f32_16x16x32_bf16 v[104:107], v[178:181], v[214:217], v[104:107]
	v_mfma_f32_16x16x32_bf16 v[112:115], v[170:173], v[214:217], v[112:115]
	v_mfma_f32_16x16x32_bf16 v[96:99], v[170:173], v[222:225], v[96:99]
	v_mfma_f32_16x16x32_bf16 v[88:91], v[178:181], v[222:225], v[88:91]
	v_mfma_f32_16x16x32_bf16 v[72:75], v[178:181], v[230:233], v[72:75]
	v_mfma_f32_16x16x32_bf16 v[80:83], v[170:173], v[230:233], v[80:83]
	s_setprio 0
	s_setprio 1
	v_mfma_f32_16x16x32_bf16 v[116:119], v[186:189], v[202:205], 0
	v_mfma_f32_16x16x32_bf16 v[108:111], v[194:197], v[202:205], 0
	v_mfma_f32_16x16x32_bf16 v[92:95], v[194:197], v[210:213], 0
	v_mfma_f32_16x16x32_bf16 v[100:103], v[186:189], v[210:213], 0
	v_mfma_f32_16x16x32_bf16 v[84:87], v[186:189], v[218:221], 0
	v_mfma_f32_16x16x32_bf16 v[76:79], v[194:197], v[218:221], 0
	v_mfma_f32_16x16x32_bf16 v[64:67], v[194:197], v[226:229], 0
	v_mfma_f32_16x16x32_bf16 v[68:71], v[186:189], v[226:229], 0
	v_mfma_f32_16x16x32_bf16 v[116:119], v[190:193], v[206:209], v[116:119]
	v_mfma_f32_16x16x32_bf16 v[108:111], v[198:201], v[206:209], v[108:111]
	v_mfma_f32_16x16x32_bf16 v[92:95], v[198:201], v[214:217], v[92:95]
	v_mfma_f32_16x16x32_bf16 v[100:103], v[190:193], v[214:217], v[100:103]
	v_mfma_f32_16x16x32_bf16 v[84:87], v[190:193], v[222:225], v[84:87]
	v_mfma_f32_16x16x32_bf16 v[76:79], v[198:201], v[222:225], v[76:79]
	v_mfma_f32_16x16x32_bf16 v[64:67], v[198:201], v[230:233], v[64:67]
	v_mfma_f32_16x16x32_bf16 v[68:71], v[190:193], v[230:233], v[68:71]
	s_barrier
	s_setprio 0
	s_add_i32 s47, s44, s8
	v_lshl_add_u64 v[158:159], s[52:53], 0, v[130:131]
	s_mov_b32 m0, s47
	ds_read_b128 v[202:205], v165 offset:16384
	ds_read_b128 v[206:209], v165 offset:17408
	ds_read_b128 v[210:213], v165 offset:18432
	ds_read_b128 v[214:217], v165 offset:19456
	ds_read_b128 v[218:221], v165 offset:20480
	ds_read_b128 v[222:225], v165 offset:21504
	ds_read_b128 v[226:229], v165 offset:22528
	ds_read_b128 v[230:233], v165 offset:23552
	global_load_lds_dwordx4 v[158:159], off
	s_add_i32 m0, s47, 0x2000
	s_add_u32 s66, s52, 0x80000
	v_lshl_add_u64 v[182:183], s[52:53], 0, v[134:135]
	s_addc_u32 s67, s53, 0
	s_add_i32 s47, s45, s8
	global_load_lds_dwordx4 v[182:183], off
	v_lshl_add_u64 v[234:235], s[66:67], 0, v[130:131]
	s_mov_b32 m0, s47
	v_lshl_add_u64 v[236:237], s[58:59], 0, v[132:133]
	global_load_lds_dwordx4 v[234:235], off
	v_lshl_add_u64 v[234:235], s[66:67], 0, v[134:135]
	s_add_i32 m0, s47, 0x2000
	s_nop 0
	global_load_lds_dwordx4 v[234:235], off
	v_lshl_add_u64 v[234:235], s[58:59], 0, v[128:129]
	s_mov_b32 m0, s9
	s_nop 0
	global_load_lds_dwordx4 v[234:235], off
	s_mov_b32 m0, s10
	s_nop 0
	global_load_lds_dwordx4 v[236:237], off
	s_waitcnt vmcnt(8)
	s_waitcnt lgkmcnt(0)
	s_setprio 1
	s_barrier
; #define PG8_STAGE(bufoff, gbase, voff) do { _Pragma("unroll") for (int _i = 0; _i < 2; ++_i) \
;         __builtin_amdgcn_global_load_lds((const unsigned*)((const char*)(gbase) + (voff)[_i]), (PG8_LAS unsigned*)(lds + (bufoff) + ldsw + _i * 8192), 16, 0, 0); } while (0)
; #define PG8_LDA(dst, b, h) do { _Pragma("unroll") for (int m = 0; m < 4; ++m) _Pragma("unroll") for (int k = 0; k < 2; ++k) dst[m][k] = *(const PG8_LAS bf16x8*)(lds + PG8_SA(b, h) + aoff + m * 2048 + k * 1024); } while (0)
; #define PG8_LDB(dst, b, h) do { _Pragma("unroll") for (int n = 0; n < 2; ++n) _Pragma("unroll") for (int k = 0; k < 2; ++k) dst[n][k] = *(const PG8_LAS bf16x8*)(lds + PG8_SB(b, h) + boff + n * 2048 + k * 1024); } while (0)
; #define PG8_MMA(ai, bj, At, Bt) do { __builtin_amdgcn_s_setprio(1); _Pragma("unroll") for (int m = 0; m < 4; ++m) _Pragma("unroll") for (int n = 0; n < 2; ++n) _Pragma("unroll") for (int k = 0; k < 2; ++k) \
;         acc[ai][bj][m][n] = __builtin_amdgcn_mfma_f32_16x16x32_bf16(Bt[n][k], At[m][k], acc[ai][bj][m][n], 0, 0, 0); __builtin_amdgcn_s_setprio(0); } while (0)
; #define PG8_WAIT_V(n) asm volatile("s_waitcnt vmcnt(" #n ")" ::: "memory")
; #define PG8_WAIT_L(n) asm volatile("s_waitcnt lgkmcnt(" #n ")" ::: "memory")
; #define PG8_BAR __builtin_amdgcn_s_barrier()
; #define PG8_SCHED __builtin_amdgcn_sched_barrier(0)
; template <class Epi, class Sched, bool ALIGN_EPI = false, bool SP2 = false>
; __device__ __forceinline__ void gemm_phase(PG8_LAS unsigned char* lds, const Gemm g, const Sched& S, const Epi& E) {
;     ...
;             PG8_WAIT_V(8); PG8_WAIT_L(0); PG8_BAR; PG8_MMA(0, 0, At, B0); PG8_MMA(0, 1, At, B1); PG8_BAR; PG8_SCHED;
;             PG8_LDA(At, 0, 1); PG8_STAGE(PG8_SB(0, 0), b2, voffB); PG8_STAGE(PG8_SB(0, 1), b2 + hstepB, voffB); PG8_STAGE(PG8_SA(0, 0), a2, voffA);
;             PG8_WAIT_V(8); PG8_WAIT_L(0); PG8_BAR; PG8_MMA(1, 0, At, B0); PG8_MMA(1, 1, At, B1); PG8_BAR; PG8_SCHED;
;             PG8_LDB(B0, 1, 0); PG8_LDB(B1, 1, 1); PG8_SCHED; PG8_LDA(At, 1, 0); PG8_STAGE(PG8_SA(0, 1), a2 + hstepA, voffA);
;             PG8_WAIT_V(8); PG8_WAIT_L(0); PG8_BAR; PG8_MMA(0, 0, At, B0); PG8_MMA(0, 1, At, B1); PG8_BAR; PG8_SCHED;
	v_mfma_f32_16x16x32_bf16 v[60:63], v[166:169], v[202:205], 0
	v_mfma_f32_16x16x32_bf16 v[56:59], v[174:177], v[202:205], 0
	v_mfma_f32_16x16x32_bf16 v[40:43], v[174:177], v[210:213], 0
	v_mfma_f32_16x16x32_bf16 v[48:51], v[166:169], v[210:213], 0
	v_mfma_f32_16x16x32_bf16 v[32:35], v[166:169], v[218:221], 0
	v_mfma_f32_16x16x32_bf16 v[24:27], v[174:177], v[218:221], 0
	v_mfma_f32_16x16x32_bf16 v[8:11], v[174:177], v[226:229], 0
	v_mfma_f32_16x16x32_bf16 v[16:19], v[166:169], v[226:229], 0
	v_mfma_f32_16x16x32_bf16 v[60:63], v[170:173], v[206:209], v[60:63]
	v_mfma_f32_16x16x32_bf16 v[56:59], v[178:181], v[206:209], v[56:59]
	v_mfma_f32_16x16x32_bf16 v[40:43], v[178:181], v[214:217], v[40:43]
	v_mfma_f32_16x16x32_bf16 v[48:51], v[170:173], v[214:217], v[48:51]
	v_mfma_f32_16x16x32_bf16 v[32:35], v[170:173], v[222:225], v[32:35]
	v_mfma_f32_16x16x32_bf16 v[24:27], v[178:181], v[222:225], v[24:27]
	v_mfma_f32_16x16x32_bf16 v[8:11], v[178:181], v[230:233], v[8:11]
	v_mfma_f32_16x16x32_bf16 v[16:19], v[170:173], v[230:233], v[16:19]
	s_setprio 0
	s_setprio 1
	v_mfma_f32_16x16x32_bf16 v[52:55], v[186:189], v[202:205], 0
	v_mfma_f32_16x16x32_bf16 v[44:47], v[194:197], v[202:205], 0
	v_mfma_f32_16x16x32_bf16 v[28:31], v[194:197], v[210:213], 0
	v_mfma_f32_16x16x32_bf16 v[36:39], v[186:189], v[210:213], 0
	v_mfma_f32_16x16x32_bf16 v[20:23], v[186:189], v[218:221], 0
	v_mfma_f32_16x16x32_bf16 v[12:15], v[194:197], v[218:221], 0
	v_mfma_f32_16x16x32_bf16 v[0:3], v[194:197], v[226:229], 0
	v_mfma_f32_16x16x32_bf16 v[4:7], v[186:189], v[226:229], 0
	v_mfma_f32_16x16x32_bf16 v[52:55], v[190:193], v[206:209], v[52:55]
	v_mfma_f32_16x16x32_bf16 v[44:47], v[198:201], v[206:209], v[44:47]
	v_mfma_f32_16x16x32_bf16 v[28:31], v[198:201], v[214:217], v[28:31]
	v_mfma_f32_16x16x32_bf16 v[36:39], v[190:193], v[214:217], v[36:39]
	v_mfma_f32_16x16x32_bf16 v[20:23], v[190:193], v[222:225], v[20:23]
	v_mfma_f32_16x16x32_bf16 v[12:15], v[198:201], v[222:225], v[12:15]
	v_mfma_f32_16x16x32_bf16 v[0:3], v[198:201], v[230:233], v[0:3]
	v_mfma_f32_16x16x32_bf16 v[4:7], v[190:193], v[230:233], v[4:7]
	s_barrier
	s_setprio 0
	s_add_i32 s47, 0, 0x18000
	s_add_i32 s55, 0, 0x1c000
	v_add_u32_e32 v178, s47, v160
	v_add_u32_e32 v185, s55, v160
	ds_read_b128 v[166:169], v178
	ds_read_b128 v[170:173], v178 offset:1024
	ds_read_b128 v[174:177], v178 offset:2048
	ds_read_b128 v[178:181], v178 offset:3072
	ds_read_b128 v[186:189], v185
	ds_read_b128 v[190:193], v185 offset:1024
	ds_read_b128 v[194:197], v185 offset:2048
	ds_read_b128 v[198:201], v185 offset:3072
	s_add_u32 s58, s58, 0x80000
	s_addc_u32 s59, s59, 0
	s_mov_b32 m0, s11
	v_lshl_add_u64 v[238:239], s[58:59], 0, v[128:129]
	ds_read_b128 v[202:205], v165 offset:32768
	ds_read_b128 v[206:209], v165 offset:33792
	ds_read_b128 v[210:213], v165 offset:34816
	ds_read_b128 v[214:217], v165 offset:35840
	ds_read_b128 v[218:221], v165 offset:36864
	ds_read_b128 v[222:225], v165 offset:37888
	ds_read_b128 v[226:229], v165 offset:38912
	ds_read_b128 v[230:233], v165 offset:39936
	global_load_lds_dwordx4 v[238:239], off
	v_lshl_add_u64 v[238:239], s[58:59], 0, v[132:133]
	s_mov_b32 m0, s12
	s_nop 0
	global_load_lds_dwordx4 v[238:239], off
	s_waitcnt vmcnt(8)
	s_waitcnt lgkmcnt(0)
	s_setprio 1
	s_barrier
	v_mfma_f32_16x16x32_bf16 v[124:127], v[166:169], v[202:205], v[124:127]
	v_mfma_f32_16x16x32_bf16 v[120:123], v[174:177], v[202:205], v[120:123]
	v_mfma_f32_16x16x32_bf16 v[104:107], v[174:177], v[210:213], v[104:107]
	v_mfma_f32_16x16x32_bf16 v[112:115], v[166:169], v[210:213], v[112:115]
	v_mfma_f32_16x16x32_bf16 v[96:99], v[166:169], v[218:221], v[96:99]
	v_mfma_f32_16x16x32_bf16 v[88:91], v[174:177], v[218:221], v[88:91]
	v_mfma_f32_16x16x32_bf16 v[72:75], v[174:177], v[226:229], v[72:75]
	v_mfma_f32_16x16x32_bf16 v[80:83], v[166:169], v[226:229], v[80:83]
	v_mfma_f32_16x16x32_bf16 v[124:127], v[170:173], v[206:209], v[124:127]
	v_mfma_f32_16x16x32_bf16 v[120:123], v[178:181], v[206:209], v[120:123]
	v_mfma_f32_16x16x32_bf16 v[104:107], v[178:181], v[214:217], v[104:107]
	v_mfma_f32_16x16x32_bf16 v[112:115], v[170:173], v[214:217], v[112:115]
	v_mfma_f32_16x16x32_bf16 v[96:99], v[170:173], v[222:225], v[96:99]
	v_mfma_f32_16x16x32_bf16 v[88:91], v[178:181], v[222:225], v[88:91]
	v_mfma_f32_16x16x32_bf16 v[72:75], v[178:181], v[230:233], v[72:75]
	v_mfma_f32_16x16x32_bf16 v[80:83], v[170:173], v[230:233], v[80:83]
	s_setprio 0
	s_setprio 1
	v_mfma_f32_16x16x32_bf16 v[116:119], v[186:189], v[202:205], v[116:119]
	v_mfma_f32_16x16x32_bf16 v[108:111], v[194:197], v[202:205], v[108:111]
	v_mfma_f32_16x16x32_bf16 v[92:95], v[194:197], v[210:213], v[92:95]
	v_mfma_f32_16x16x32_bf16 v[100:103], v[186:189], v[210:213], v[100:103]
	v_mfma_f32_16x16x32_bf16 v[84:87], v[186:189], v[218:221], v[84:87]
	v_mfma_f32_16x16x32_bf16 v[76:79], v[194:197], v[218:221], v[76:79]
	v_mfma_f32_16x16x32_bf16 v[64:67], v[194:197], v[226:229], v[64:67]
	v_mfma_f32_16x16x32_bf16 v[68:71], v[186:189], v[226:229], v[68:71]
	v_mfma_f32_16x16x32_bf16 v[116:119], v[190:193], v[206:209], v[116:119]
	v_mfma_f32_16x16x32_bf16 v[108:111], v[198:201], v[206:209], v[108:111]
	v_mfma_f32_16x16x32_bf16 v[92:95], v[198:201], v[214:217], v[92:95]
	v_mfma_f32_16x16x32_bf16 v[100:103], v[190:193], v[214:217], v[100:103]
	v_mfma_f32_16x16x32_bf16 v[84:87], v[190:193], v[222:225], v[84:87]
	v_mfma_f32_16x16x32_bf16 v[76:79], v[198:201], v[222:225], v[76:79]
	v_mfma_f32_16x16x32_bf16 v[64:67], v[198:201], v[230:233], v[64:67]
	v_mfma_f32_16x16x32_bf16 v[68:71], v[190:193], v[230:233], v[68:71]
	s_barrier
; #define PG8_STAGE(bufoff, gbase, voff) do { _Pragma("unroll") for (int _i = 0; _i < 2; ++_i) \
;         __builtin_amdgcn_global_load_lds((const unsigned*)((const char*)(gbase) + (voff)[_i]), (PG8_LAS unsigned*)(lds + (bufoff) + ldsw + _i * 8192), 16, 0, 0); } while (0)
; #define PG8_LDA(dst, b, h) do { _Pragma("unroll") for (int m = 0; m < 4; ++m) _Pragma("unroll") for (int k = 0; k < 2; ++k) dst[m][k] = *(const PG8_LAS bf16x8*)(lds + PG8_SA(b, h) + aoff + m * 2048 + k * 1024); } while (0)
; #define PG8_LDB(dst, b, h) do { _Pragma("unroll") for (int n = 0; n < 2; ++n) _Pragma("unroll") for (int k = 0; k < 2; ++k) dst[n][k] = *(const PG8_LAS bf16x8*)(lds + PG8_SB(b, h) + boff + n * 2048 + k * 1024); } while (0)
; template <class Epi, class Sched, bool ALIGN_EPI = false, bool SP2 = false>
; __device__ __forceinline__ void gemm_phase(PG8_LAS unsigned char* lds, const Gemm g, const Sched& S, const Epi& E) {
;     ...
;         for (int t = 0; t < nt; t += 2) {
;             const bool last = (t == nt - 2);
;             const char* a1 = cA + (size_t)(t + 1) * kstA;
;             const char* a2 = last ? nA : cA + (size_t)(t + 2) * kstA; const char* b2 = last ? nB : cB + (size_t)(t + 2) * kstep;
;             const char* a3 = a2 + kstA; const char* b3 = b2 + kstep;
;             if (last && has_next) S.a_ready(nxt);
;             if constexpr (SP2) {
;             PG8_LDB(B0, 0, 0); PG8_LDB(B1, 0, 1); PG8_SCHED; PG8_LDA(At, 0, 0); PG8_STAGE(PG8_SA(1, 1), a1 + hstepA, voffA);
;             PG8_WAIT_V(8); PG8_WAIT_L(0); PG8_BAR; PG8_MMA(0, 0, At, B0); PG8_MMA(0, 1, At, B1); PG8_BAR; PG8_SCHED;
;             PG8_LDA(At, 0, 1); PG8_STAGE(PG8_SB(0, 0), b2, voffB); PG8_STAGE(PG8_SB(0, 1), b2 + hstepB, voffB); PG8_STAGE(PG8_SA(0, 0), a2, voffA);
;             PG8_WAIT_V(8); PG8_WAIT_L(0); PG8_BAR; PG8_MMA(1, 0, At, B0); PG8_MMA(1, 1, At, B1); PG8_BAR; PG8_SCHED;
;             PG8_LDB(B0, 1, 0); PG8_LDB(B1, 1, 1); PG8_SCHED; PG8_LDA(At, 1, 0); PG8_STAGE(PG8_SA(0, 1), a2 + hstepA, voffA);
;             PG8_WAIT_V(8); PG8_WAIT_L(0); PG8_BAR; PG8_MMA(0, 0, At, B0); PG8_MMA(0, 1, At, B1); PG8_BAR; PG8_SCHED;
;             PG8_LDA(At, 1, 1); PG8_STAGE(PG8_SB(1, 0), b3, voffB); PG8_STAGE(PG8_SB(1, 1), b3 + hstepB, voffB); PG8_STAGE(PG8_SA(1, 0), a3, voffA);
;             PG8_WAIT_V(8); PG8_WAIT_L(0); PG8_BAR; PG8_MMA(1, 0, At, B0); PG8_MMA(1, 1, At, B1); PG8_BAR; PG8_SCHED;
	s_setprio 0
	s_add_i32 s47, s47, s8
	v_lshl_add_u64 v[158:159], v[158:159], 0, s[38:39]
	s_mov_b32 m0, s47
	ds_read_b128 v[202:205], v165 offset:49152
	ds_read_b128 v[206:209], v165 offset:50176
	ds_read_b128 v[210:213], v165 offset:51200
	ds_read_b128 v[214:217], v165 offset:52224
	ds_read_b128 v[218:221], v165 offset:53248
	ds_read_b128 v[222:225], v165 offset:54272
	ds_read_b128 v[226:229], v165 offset:55296
	ds_read_b128 v[230:233], v165 offset:56320
	global_load_lds_dwordx4 v[158:159], off
	s_add_i32 m0, s47, 0x2000
	s_add_u32 s52, s52, 0x80080
	v_lshl_add_u64 v[158:159], v[182:183], 0, s[38:39]
	s_addc_u32 s53, s53, 0
	s_add_i32 s47, s55, s8
	global_load_lds_dwordx4 v[158:159], off
	v_lshl_add_u64 v[158:159], s[52:53], 0, v[130:131]
	s_mov_b32 m0, s47
	s_nop 0
	global_load_lds_dwordx4 v[158:159], off
	v_lshl_add_u64 v[158:159], s[52:53], 0, v[134:135]
	s_add_i32 m0, s47, 0x2000
	s_nop 0
	global_load_lds_dwordx4 v[158:159], off
	v_lshl_add_u64 v[158:159], v[234:235], 0, s[38:39]
	s_mov_b32 m0, s13
	s_nop 0
	global_load_lds_dwordx4 v[158:159], off
	v_lshl_add_u64 v[158:159], v[236:237], 0, s[38:39]
	s_mov_b32 m0, s33
	s_nop 0
	global_load_lds_dwordx4 v[158:159], off
	s_waitcnt vmcnt(8)
	s_waitcnt lgkmcnt(0)
	s_setprio 1
	s_barrier
	v_mfma_f32_16x16x32_bf16 v[60:63], v[166:169], v[202:205], v[60:63]
	v_mfma_f32_16x16x32_bf16 v[56:59], v[174:177], v[202:205], v[56:59]
	v_mfma_f32_16x16x32_bf16 v[40:43], v[174:177], v[210:213], v[40:43]
	v_mfma_f32_16x16x32_bf16 v[48:51], v[166:169], v[210:213], v[48:51]
	v_mfma_f32_16x16x32_bf16 v[32:35], v[166:169], v[218:221], v[32:35]
	v_mfma_f32_16x16x32_bf16 v[24:27], v[174:177], v[218:221], v[24:27]
	v_mfma_f32_16x16x32_bf16 v[8:11], v[174:177], v[226:229], v[8:11]
	v_mfma_f32_16x16x32_bf16 v[16:19], v[166:169], v[226:229], v[16:19]
	v_mfma_f32_16x16x32_bf16 v[60:63], v[170:173], v[206:209], v[60:63]
	v_mfma_f32_16x16x32_bf16 v[56:59], v[178:181], v[206:209], v[56:59]
	v_mfma_f32_16x16x32_bf16 v[40:43], v[178:181], v[214:217], v[40:43]
	v_mfma_f32_16x16x32_bf16 v[48:51], v[170:173], v[214:217], v[48:51]
	v_mfma_f32_16x16x32_bf16 v[32:35], v[170:173], v[222:225], v[32:35]
	v_mfma_f32_16x16x32_bf16 v[24:27], v[178:181], v[222:225], v[24:27]
	v_mfma_f32_16x16x32_bf16 v[8:11], v[178:181], v[230:233], v[8:11]
	v_mfma_f32_16x16x32_bf16 v[16:19], v[170:173], v[230:233], v[16:19]
	s_setprio 0
	s_setprio 1
	v_mfma_f32_16x16x32_bf16 v[52:55], v[186:189], v[202:205], v[52:55]
	v_mfma_f32_16x16x32_bf16 v[44:47], v[194:197], v[202:205], v[44:47]
	v_mfma_f32_16x16x32_bf16 v[28:31], v[194:197], v[210:213], v[28:31]
	v_mfma_f32_16x16x32_bf16 v[36:39], v[186:189], v[210:213], v[36:39]
	v_mfma_f32_16x16x32_bf16 v[20:23], v[186:189], v[218:221], v[20:23]
	v_mfma_f32_16x16x32_bf16 v[12:15], v[194:197], v[218:221], v[12:15]
	v_mfma_f32_16x16x32_bf16 v[0:3], v[194:197], v[226:229], v[0:3]
	v_mfma_f32_16x16x32_bf16 v[4:7], v[186:189], v[226:229], v[4:7]
	v_mfma_f32_16x16x32_bf16 v[52:55], v[190:193], v[206:209], v[52:55]
	v_mfma_f32_16x16x32_bf16 v[44:47], v[198:201], v[206:209], v[44:47]
	v_mfma_f32_16x16x32_bf16 v[28:31], v[198:201], v[214:217], v[28:31]
	v_mfma_f32_16x16x32_bf16 v[36:39], v[190:193], v[214:217], v[36:39]
	v_mfma_f32_16x16x32_bf16 v[20:23], v[190:193], v[222:225], v[20:23]
	v_mfma_f32_16x16x32_bf16 v[12:15], v[198:201], v[222:225], v[12:15]
	v_mfma_f32_16x16x32_bf16 v[0:3], v[198:201], v[230:233], v[0:3]
	v_mfma_f32_16x16x32_bf16 v[4:7], v[190:193], v[230:233], v[4:7]
	s_barrier
	s_setprio 0
	s_add_i32 s46, s46, 2
	s_add_u32 s50, s50, 0x100
	s_addc_u32 s51, s51, 0
	s_add_u32 s4, s4, 0x100
	s_addc_u32 s5, s5, 0
	s_cmp_gt_u32 s46, 29
	s_cbranch_scc1 .Lmy_peel_2_exit
.LBB0_656:
	ds_read_b128 v[166:169], v163
	ds_read_b128 v[170:173], v163 offset:1024
	ds_read_b128 v[174:177], v163 offset:2048
	ds_read_b128 v[178:181], v163 offset:3072
	ds_read_b128 v[186:189], v164
	ds_read_b128 v[190:193], v164 offset:1024
	ds_read_b128 v[194:197], v164 offset:2048
	ds_read_b128 v[198:201], v164 offset:3072
	s_add_u32 s47, s50, 0xfff80080
	s_addc_u32 s52, s51, -1
	s_cmp_eq_u32 s46, 28
	s_cselect_b32 s59, s63, s52
	s_cselect_b32 s58, s62, s47
	s_cselect_b32 s53, s65, s5
	s_cselect_b32 s52, s64, s4
	v_lshl_add_u64 v[158:159], s[50:51], 0, v[152:153]
	s_add_i32 m0, s9, 0xc000
	ds_read_b128 v[202:205], v165
	ds_read_b128 v[206:209], v165 offset:1024
	ds_read_b128 v[210:213], v165 offset:2048
	ds_read_b128 v[214:217], v165 offset:3072
	ds_read_b128 v[218:221], v165 offset:4096
	ds_read_b128 v[222:225], v165 offset:5120
	ds_read_b128 v[226:229], v165 offset:6144
	ds_read_b128 v[230:233], v165 offset:7168
	global_load_lds_dwordx4 v[158:159], off
	v_lshl_add_u64 v[158:159], s[50:51], 0, v[154:155]
	s_add_i32 m0, s9, 0xe000
	s_nop 0
	global_load_lds_dwordx4 v[158:159], off
	s_waitcnt vmcnt(8)
	s_waitcnt lgkmcnt(0)
	s_setprio 1
	s_barrier
; #define PG8_STAGE(bufoff, gbase, voff) do { _Pragma("unroll") for (int _i = 0; _i < 2; ++_i) \
;         __builtin_amdgcn_global_load_lds((const unsigned*)((const char*)(gbase) + (voff)[_i]), (PG8_LAS unsigned*)(lds + (bufoff) + ldsw + _i * 8192), 16, 0, 0); } while (0)
; #define PG8_LDA(dst, b, h) do { _Pragma("unroll") for (int m = 0; m < 4; ++m) _Pragma("unroll") for (int k = 0; k < 2; ++k) dst[m][k] = *(const PG8_LAS bf16x8*)(lds + PG8_SA(b, h) + aoff + m * 2048 + k * 1024); } while (0)
; #define PG8_LDB(dst, b, h) do { _Pragma("unroll") for (int n = 0; n < 2; ++n) _Pragma("unroll") for (int k = 0; k < 2; ++k) dst[n][k] = *(const PG8_LAS bf16x8*)(lds + PG8_SB(b, h) + boff + n * 2048 + k * 1024); } while (0)
; #define PG8_MMA(ai, bj, At, Bt) do { __builtin_amdgcn_s_setprio(1); _Pragma("unroll") for (int m = 0; m < 4; ++m) _Pragma("unroll") for (int n = 0; n < 2; ++n) _Pragma("unroll") for (int k = 0; k < 2; ++k) \
;         acc[ai][bj][m][n] = __builtin_amdgcn_mfma_f32_16x16x32_bf16(Bt[n][k], At[m][k], acc[ai][bj][m][n], 0, 0, 0); __builtin_amdgcn_s_setprio(0); } while (0)
; #define PG8_WAIT_V(n) asm volatile("s_waitcnt vmcnt(" #n ")" ::: "memory")
; #define PG8_WAIT_L(n) asm volatile("s_waitcnt lgkmcnt(" #n ")" ::: "memory")
; #define PG8_BAR __builtin_amdgcn_s_barrier()
; #define PG8_SCHED __builtin_amdgcn_sched_barrier(0)
; template <class Epi, class Sched, bool ALIGN_EPI = false, bool SP2 = false>
; __device__ __forceinline__ void gemm_phase(PG8_LAS unsigned char* lds, const Gemm g, const Sched& S, const Epi& E) {
;     ...
;             PG8_LDB(B0, 0, 0); PG8_LDB(B1, 0, 1); PG8_SCHED; PG8_LDA(At, 0, 0); PG8_STAGE(PG8_SA(1, 1), a1 + hstepA, voffA);
;             PG8_WAIT_V(8); PG8_WAIT_L(0); PG8_BAR; PG8_MMA(0, 0, At, B0); PG8_MMA(0, 1, At, B1); PG8_BAR; PG8_SCHED;
;             PG8_LDA(At, 0, 1); PG8_STAGE(PG8_SB(0, 0), b2, voffB); PG8_STAGE(PG8_SB(0, 1), b2 + hstepB, voffB); PG8_STAGE(PG8_SA(0, 0), a2, voffA);
;             PG8_WAIT_V(8); PG8_WAIT_L(0); PG8_BAR; PG8_MMA(1, 0, At, B0); PG8_MMA(1, 1, At, B1); PG8_BAR; PG8_SCHED;
	v_mfma_f32_16x16x32_bf16 v[124:127], v[166:169], v[202:205], v[124:127]
	v_mfma_f32_16x16x32_bf16 v[120:123], v[174:177], v[202:205], v[120:123]
	v_mfma_f32_16x16x32_bf16 v[104:107], v[174:177], v[210:213], v[104:107]
	v_mfma_f32_16x16x32_bf16 v[112:115], v[166:169], v[210:213], v[112:115]
	v_mfma_f32_16x16x32_bf16 v[96:99], v[166:169], v[218:221], v[96:99]
	v_mfma_f32_16x16x32_bf16 v[88:91], v[174:177], v[218:221], v[88:91]
	v_mfma_f32_16x16x32_bf16 v[72:75], v[174:177], v[226:229], v[72:75]
	v_mfma_f32_16x16x32_bf16 v[80:83], v[166:169], v[226:229], v[80:83]
	v_mfma_f32_16x16x32_bf16 v[124:127], v[170:173], v[206:209], v[124:127]
	v_mfma_f32_16x16x32_bf16 v[120:123], v[178:181], v[206:209], v[120:123]
	v_mfma_f32_16x16x32_bf16 v[104:107], v[178:181], v[214:217], v[104:107]
	v_mfma_f32_16x16x32_bf16 v[112:115], v[170:173], v[214:217], v[112:115]
	v_mfma_f32_16x16x32_bf16 v[96:99], v[170:173], v[222:225], v[96:99]
	v_mfma_f32_16x16x32_bf16 v[88:91], v[178:181], v[222:225], v[88:91]
	v_mfma_f32_16x16x32_bf16 v[72:75], v[178:181], v[230:233], v[72:75]
	v_mfma_f32_16x16x32_bf16 v[80:83], v[170:173], v[230:233], v[80:83]
	s_setprio 0
	s_setprio 1
	v_mfma_f32_16x16x32_bf16 v[116:119], v[186:189], v[202:205], v[116:119]
	v_mfma_f32_16x16x32_bf16 v[108:111], v[194:197], v[202:205], v[108:111]
	v_mfma_f32_16x16x32_bf16 v[92:95], v[194:197], v[210:213], v[92:95]
	v_mfma_f32_16x16x32_bf16 v[100:103], v[186:189], v[210:213], v[100:103]
	v_mfma_f32_16x16x32_bf16 v[84:87], v[186:189], v[218:221], v[84:87]
	v_mfma_f32_16x16x32_bf16 v[76:79], v[194:197], v[218:221], v[76:79]
	v_mfma_f32_16x16x32_bf16 v[64:67], v[194:197], v[226:229], v[64:67]
	v_mfma_f32_16x16x32_bf16 v[68:71], v[186:189], v[226:229], v[68:71]
	v_mfma_f32_16x16x32_bf16 v[116:119], v[190:193], v[206:209], v[116:119]
	v_mfma_f32_16x16x32_bf16 v[108:111], v[198:201], v[206:209], v[108:111]
	v_mfma_f32_16x16x32_bf16 v[92:95], v[198:201], v[214:217], v[92:95]
	v_mfma_f32_16x16x32_bf16 v[100:103], v[190:193], v[214:217], v[100:103]
	v_mfma_f32_16x16x32_bf16 v[84:87], v[190:193], v[222:225], v[84:87]
	v_mfma_f32_16x16x32_bf16 v[76:79], v[198:201], v[222:225], v[76:79]
	v_mfma_f32_16x16x32_bf16 v[64:67], v[198:201], v[230:233], v[64:67]
	v_mfma_f32_16x16x32_bf16 v[68:71], v[190:193], v[230:233], v[68:71]
	s_barrier
	s_setprio 0
	s_add_i32 s47, s44, s8
	v_lshl_add_u64 v[158:159], s[52:53], 0, v[130:131]
	s_mov_b32 m0, s47
	ds_read_b128 v[202:205], v165 offset:16384
	ds_read_b128 v[206:209], v165 offset:17408
	ds_read_b128 v[210:213], v165 offset:18432
	ds_read_b128 v[214:217], v165 offset:19456
	ds_read_b128 v[218:221], v165 offset:20480
	ds_read_b128 v[222:225], v165 offset:21504
	ds_read_b128 v[226:229], v165 offset:22528
	ds_read_b128 v[230:233], v165 offset:23552
	global_load_lds_dwordx4 v[158:159], off
	s_add_i32 m0, s47, 0x2000
	s_add_u32 s66, s52, 0x80000
	v_lshl_add_u64 v[182:183], s[52:53], 0, v[134:135]
	s_addc_u32 s67, s53, 0
	s_add_i32 s47, s45, s8
	global_load_lds_dwordx4 v[182:183], off
	v_lshl_add_u64 v[234:235], s[66:67], 0, v[130:131]
	s_mov_b32 m0, s47
	v_lshl_add_u64 v[236:237], s[58:59], 0, v[132:133]
	global_load_lds_dwordx4 v[234:235], off
	v_lshl_add_u64 v[234:235], s[66:67], 0, v[134:135]
	s_add_i32 m0, s47, 0x2000
	s_nop 0
	global_load_lds_dwordx4 v[234:235], off
	v_lshl_add_u64 v[234:235], s[58:59], 0, v[128:129]
	s_mov_b32 m0, s9
	s_nop 0
	global_load_lds_dwordx4 v[234:235], off
	s_mov_b32 m0, s10
	s_nop 0
	global_load_lds_dwordx4 v[236:237], off
	s_waitcnt vmcnt(8)
	s_waitcnt lgkmcnt(0)
	s_setprio 1
	s_barrier
	v_mfma_f32_16x16x32_bf16 v[60:63], v[166:169], v[202:205], v[60:63]
	v_mfma_f32_16x16x32_bf16 v[56:59], v[174:177], v[202:205], v[56:59]
	v_mfma_f32_16x16x32_bf16 v[40:43], v[174:177], v[210:213], v[40:43]
	v_mfma_f32_16x16x32_bf16 v[48:51], v[166:169], v[210:213], v[48:51]
	v_mfma_f32_16x16x32_bf16 v[32:35], v[166:169], v[218:221], v[32:35]
	v_mfma_f32_16x16x32_bf16 v[24:27], v[174:177], v[218:221], v[24:27]
	v_mfma_f32_16x16x32_bf16 v[8:11], v[174:177], v[226:229], v[8:11]
	v_mfma_f32_16x16x32_bf16 v[16:19], v[166:169], v[226:229], v[16:19]
	v_mfma_f32_16x16x32_bf16 v[60:63], v[170:173], v[206:209], v[60:63]
	v_mfma_f32_16x16x32_bf16 v[56:59], v[178:181], v[206:209], v[56:59]
	v_mfma_f32_16x16x32_bf16 v[40:43], v[178:181], v[214:217], v[40:43]
	v_mfma_f32_16x16x32_bf16 v[48:51], v[170:173], v[214:217], v[48:51]
	v_mfma_f32_16x16x32_bf16 v[32:35], v[170:173], v[222:225], v[32:35]
	v_mfma_f32_16x16x32_bf16 v[24:27], v[178:181], v[222:225], v[24:27]
	v_mfma_f32_16x16x32_bf16 v[8:11], v[178:181], v[230:233], v[8:11]
	v_mfma_f32_16x16x32_bf16 v[16:19], v[170:173], v[230:233], v[16:19]
	s_setprio 0
	s_setprio 1
	v_mfma_f32_16x16x32_bf16 v[52:55], v[186:189], v[202:205], v[52:55]
	v_mfma_f32_16x16x32_bf16 v[44:47], v[194:197], v[202:205], v[44:47]
	v_mfma_f32_16x16x32_bf16 v[28:31], v[194:197], v[210:213], v[28:31]
	v_mfma_f32_16x16x32_bf16 v[36:39], v[186:189], v[210:213], v[36:39]
	v_mfma_f32_16x16x32_bf16 v[20:23], v[186:189], v[218:221], v[20:23]
	v_mfma_f32_16x16x32_bf16 v[12:15], v[194:197], v[218:221], v[12:15]
	v_mfma_f32_16x16x32_bf16 v[0:3], v[194:197], v[226:229], v[0:3]
	v_mfma_f32_16x16x32_bf16 v[4:7], v[186:189], v[226:229], v[4:7]
	v_mfma_f32_16x16x32_bf16 v[52:55], v[190:193], v[206:209], v[52:55]
	v_mfma_f32_16x16x32_bf16 v[44:47], v[198:201], v[206:209], v[44:47]
	v_mfma_f32_16x16x32_bf16 v[28:31], v[198:201], v[214:217], v[28:31]
	v_mfma_f32_16x16x32_bf16 v[36:39], v[190:193], v[214:217], v[36:39]
	v_mfma_f32_16x16x32_bf16 v[20:23], v[190:193], v[222:225], v[20:23]
	v_mfma_f32_16x16x32_bf16 v[12:15], v[198:201], v[222:225], v[12:15]
	v_mfma_f32_16x16x32_bf16 v[0:3], v[198:201], v[230:233], v[0:3]
	v_mfma_f32_16x16x32_bf16 v[4:7], v[190:193], v[230:233], v[4:7]
	s_barrier
; #define PG8_STAGE(bufoff, gbase, voff) do { _Pragma("unroll") for (int _i = 0; _i < 2; ++_i) \
;         __builtin_amdgcn_global_load_lds((const unsigned*)((const char*)(gbase) + (voff)[_i]), (PG8_LAS unsigned*)(lds + (bufoff) + ldsw + _i * 8192), 16, 0, 0); } while (0)
; #define PG8_LDA(dst, b, h) do { _Pragma("unroll") for (int m = 0; m < 4; ++m) _Pragma("unroll") for (int k = 0; k < 2; ++k) dst[m][k] = *(const PG8_LAS bf16x8*)(lds + PG8_SA(b, h) + aoff + m * 2048 + k * 1024); } while (0)
; #define PG8_LDB(dst, b, h) do { _Pragma("unroll") for (int n = 0; n < 2; ++n) _Pragma("unroll") for (int k = 0; k < 2; ++k) dst[n][k] = *(const PG8_LAS bf16x8*)(lds + PG8_SB(b, h) + boff + n * 2048 + k * 1024); } while (0)
; #define PG8_MMA(ai, bj, At, Bt) do { __builtin_amdgcn_s_setprio(1); _Pragma("unroll") for (int m = 0; m < 4; ++m) _Pragma("unroll") for (int n = 0; n < 2; ++n) _Pragma("unroll") for (int k = 0; k < 2; ++k) \
;         acc[ai][bj][m][n] = __builtin_amdgcn_mfma_f32_16x16x32_bf16(Bt[n][k], At[m][k], acc[ai][bj][m][n], 0, 0, 0); __builtin_amdgcn_s_setprio(0); } while (0)
; #define PG8_WAIT_V(n) asm volatile("s_waitcnt vmcnt(" #n ")" ::: "memory")
; #define PG8_WAIT_L(n) asm volatile("s_waitcnt lgkmcnt(" #n ")" ::: "memory")
; #define PG8_BAR __builtin_amdgcn_s_barrier()
; #define PG8_SCHED __builtin_amdgcn_sched_barrier(0)
; template <class Epi, class Sched, bool ALIGN_EPI = false, bool SP2 = false>
; __device__ __forceinline__ void gemm_phase(PG8_LAS unsigned char* lds, const Gemm g, const Sched& S, const Epi& E) {
;     ...
;             PG8_LDB(B0, 1, 0); PG8_LDB(B1, 1, 1); PG8_SCHED; PG8_LDA(At, 1, 0); PG8_STAGE(PG8_SA(0, 1), a2 + hstepA, voffA);
;             PG8_WAIT_V(8); PG8_WAIT_L(0); PG8_BAR; PG8_MMA(0, 0, At, B0); PG8_MMA(0, 1, At, B1); PG8_BAR; PG8_SCHED;
	s_setprio 0
	s_add_i32 s47, 0, 0x18000
	s_add_i32 s55, 0, 0x1c000
	v_add_u32_e32 v178, s47, v160
	v_add_u32_e32 v185, s55, v160
	ds_read_b128 v[166:169], v178
	ds_read_b128 v[170:173], v178 offset:1024
	ds_read_b128 v[174:177], v178 offset:2048
	ds_read_b128 v[178:181], v178 offset:3072
	ds_read_b128 v[186:189], v185
	ds_read_b128 v[190:193], v185 offset:1024
	ds_read_b128 v[194:197], v185 offset:2048
	ds_read_b128 v[198:201], v185 offset:3072
	s_add_u32 s58, s58, 0x80000
	s_addc_u32 s59, s59, 0
	s_mov_b32 m0, s11
	v_lshl_add_u64 v[238:239], s[58:59], 0, v[128:129]
	ds_read_b128 v[202:205], v165 offset:32768
	ds_read_b128 v[206:209], v165 offset:33792
	ds_read_b128 v[210:213], v165 offset:34816
	ds_read_b128 v[214:217], v165 offset:35840
	ds_read_b128 v[218:221], v165 offset:36864
	ds_read_b128 v[222:225], v165 offset:37888
	ds_read_b128 v[226:229], v165 offset:38912
	ds_read_b128 v[230:233], v165 offset:39936
	global_load_lds_dwordx4 v[238:239], off
	v_lshl_add_u64 v[238:239], s[58:59], 0, v[132:133]
	s_mov_b32 m0, s12
	s_nop 0
	global_load_lds_dwordx4 v[238:239], off
	s_waitcnt vmcnt(8)
	s_waitcnt lgkmcnt(0)
	s_setprio 1
	s_barrier
	v_mfma_f32_16x16x32_bf16 v[124:127], v[166:169], v[202:205], v[124:127]
	v_mfma_f32_16x16x32_bf16 v[120:123], v[174:177], v[202:205], v[120:123]
	v_mfma_f32_16x16x32_bf16 v[104:107], v[174:177], v[210:213], v[104:107]
	v_mfma_f32_16x16x32_bf16 v[112:115], v[166:169], v[210:213], v[112:115]
	v_mfma_f32_16x16x32_bf16 v[96:99], v[166:169], v[218:221], v[96:99]
	v_mfma_f32_16x16x32_bf16 v[88:91], v[174:177], v[218:221], v[88:91]
	v_mfma_f32_16x16x32_bf16 v[72:75], v[174:177], v[226:229], v[72:75]
	v_mfma_f32_16x16x32_bf16 v[80:83], v[166:169], v[226:229], v[80:83]
	v_mfma_f32_16x16x32_bf16 v[124:127], v[170:173], v[206:209], v[124:127]
	v_mfma_f32_16x16x32_bf16 v[120:123], v[178:181], v[206:209], v[120:123]
	v_mfma_f32_16x16x32_bf16 v[104:107], v[178:181], v[214:217], v[104:107]
	v_mfma_f32_16x16x32_bf16 v[112:115], v[170:173], v[214:217], v[112:115]
	v_mfma_f32_16x16x32_bf16 v[96:99], v[170:173], v[222:225], v[96:99]
	v_mfma_f32_16x16x32_bf16 v[88:91], v[178:181], v[222:225], v[88:91]
	v_mfma_f32_16x16x32_bf16 v[72:75], v[178:181], v[230:233], v[72:75]
	v_mfma_f32_16x16x32_bf16 v[80:83], v[170:173], v[230:233], v[80:83]
	s_setprio 0
	s_setprio 1
	v_mfma_f32_16x16x32_bf16 v[116:119], v[186:189], v[202:205], v[116:119]
	v_mfma_f32_16x16x32_bf16 v[108:111], v[194:197], v[202:205], v[108:111]
	v_mfma_f32_16x16x32_bf16 v[92:95], v[194:197], v[210:213], v[92:95]
	v_mfma_f32_16x16x32_bf16 v[100:103], v[186:189], v[210:213], v[100:103]
	v_mfma_f32_16x16x32_bf16 v[84:87], v[186:189], v[218:221], v[84:87]
	v_mfma_f32_16x16x32_bf16 v[76:79], v[194:197], v[218:221], v[76:79]
	v_mfma_f32_16x16x32_bf16 v[64:67], v[194:197], v[226:229], v[64:67]
	v_mfma_f32_16x16x32_bf16 v[68:71], v[186:189], v[226:229], v[68:71]
	v_mfma_f32_16x16x32_bf16 v[116:119], v[190:193], v[206:209], v[116:119]
	v_mfma_f32_16x16x32_bf16 v[108:111], v[198:201], v[206:209], v[108:111]
	v_mfma_f32_16x16x32_bf16 v[92:95], v[198:201], v[214:217], v[92:95]
	v_mfma_f32_16x16x32_bf16 v[100:103], v[190:193], v[214:217], v[100:103]
	v_mfma_f32_16x16x32_bf16 v[84:87], v[190:193], v[222:225], v[84:87]
	v_mfma_f32_16x16x32_bf16 v[76:79], v[198:201], v[222:225], v[76:79]
	v_mfma_f32_16x16x32_bf16 v[64:67], v[198:201], v[230:233], v[64:67]
	v_mfma_f32_16x16x32_bf16 v[68:71], v[190:193], v[230:233], v[68:71]
	s_barrier
; #define PG8_STAGE(bufoff, gbase, voff) do { _Pragma("unroll") for (int _i = 0; _i < 2; ++_i) \
;         __builtin_amdgcn_global_load_lds((const unsigned*)((const char*)(gbase) + (voff)[_i]), (PG8_LAS unsigned*)(lds + (bufoff) + ldsw + _i * 8192), 16, 0, 0); } while (0)
; #define PG8_LDA(dst, b, h) do { _Pragma("unroll") for (int m = 0; m < 4; ++m) _Pragma("unroll") for (int k = 0; k < 2; ++k) dst[m][k] = *(const PG8_LAS bf16x8*)(lds + PG8_SA(b, h) + aoff + m * 2048 + k * 1024); } while (0)
; #define PG8_MMA(ai, bj, At, Bt) do { __builtin_amdgcn_s_setprio(1); _Pragma("unroll") for (int m = 0; m < 4; ++m) _Pragma("unroll") for (int n = 0; n < 2; ++n) _Pragma("unroll") for (int k = 0; k < 2; ++k) \
;         acc[ai][bj][m][n] = __builtin_amdgcn_mfma_f32_16x16x32_bf16(Bt[n][k], At[m][k], acc[ai][bj][m][n], 0, 0, 0); __builtin_amdgcn_s_setprio(0); } while (0)
; #define PG8_WAIT_V(n) asm volatile("s_waitcnt vmcnt(" #n ")" ::: "memory")
; #define PG8_WAIT_L(n) asm volatile("s_waitcnt lgkmcnt(" #n ")" ::: "memory")
; #define PG8_BAR __builtin_amdgcn_s_barrier()
; #define PG8_SCHED __builtin_amdgcn_sched_barrier(0)
; template <class Epi, class Sched, bool ALIGN_EPI = false, bool SP2 = false>
; __device__ __forceinline__ void gemm_phase(PG8_LAS unsigned char* lds, const Gemm g, const Sched& S, const Epi& E) {
;     ...
;             PG8_LDA(At, 1, 1); PG8_STAGE(PG8_SB(1, 0), b3, voffB); PG8_STAGE(PG8_SB(1, 1), b3 + hstepB, voffB); PG8_STAGE(PG8_SA(1, 0), a3, voffA);
;             PG8_WAIT_V(8); PG8_WAIT_L(0); PG8_BAR; PG8_MMA(1, 0, At, B0); PG8_MMA(1, 1, At, B1); PG8_BAR; PG8_SCHED;
	s_setprio 0
	s_add_i32 s47, s47, s8
	v_lshl_add_u64 v[158:159], v[158:159], 0, s[38:39]
	s_mov_b32 m0, s47
	ds_read_b128 v[202:205], v165 offset:49152
	ds_read_b128 v[206:209], v165 offset:50176
	ds_read_b128 v[210:213], v165 offset:51200
	ds_read_b128 v[214:217], v165 offset:52224
	ds_read_b128 v[218:221], v165 offset:53248
	ds_read_b128 v[222:225], v165 offset:54272
	ds_read_b128 v[226:229], v165 offset:55296
	ds_read_b128 v[230:233], v165 offset:56320
	global_load_lds_dwordx4 v[158:159], off
	s_add_i32 m0, s47, 0x2000
	s_add_u32 s52, s52, 0x80080
	v_lshl_add_u64 v[158:159], v[182:183], 0, s[38:39]
	s_addc_u32 s53, s53, 0
	s_add_i32 s47, s55, s8
	global_load_lds_dwordx4 v[158:159], off
	v_lshl_add_u64 v[158:159], s[52:53], 0, v[130:131]
	s_mov_b32 m0, s47
	s_nop 0
	global_load_lds_dwordx4 v[158:159], off
	v_lshl_add_u64 v[158:159], s[52:53], 0, v[134:135]
	s_add_i32 m0, s47, 0x2000
	s_nop 0
	global_load_lds_dwordx4 v[158:159], off
	v_lshl_add_u64 v[158:159], v[234:235], 0, s[38:39]
	s_mov_b32 m0, s13
	s_nop 0
	global_load_lds_dwordx4 v[158:159], off
	v_lshl_add_u64 v[158:159], v[236:237], 0, s[38:39]
	s_mov_b32 m0, s33
	s_nop 0
	global_load_lds_dwordx4 v[158:159], off
	s_waitcnt vmcnt(8)
	s_waitcnt lgkmcnt(0)
	s_setprio 1
	s_barrier
	v_mfma_f32_16x16x32_bf16 v[60:63], v[166:169], v[202:205], v[60:63]
	v_mfma_f32_16x16x32_bf16 v[56:59], v[174:177], v[202:205], v[56:59]
	v_mfma_f32_16x16x32_bf16 v[40:43], v[174:177], v[210:213], v[40:43]
	v_mfma_f32_16x16x32_bf16 v[48:51], v[166:169], v[210:213], v[48:51]
	v_mfma_f32_16x16x32_bf16 v[32:35], v[166:169], v[218:221], v[32:35]
	v_mfma_f32_16x16x32_bf16 v[24:27], v[174:177], v[218:221], v[24:27]
	v_mfma_f32_16x16x32_bf16 v[8:11], v[174:177], v[226:229], v[8:11]
	v_mfma_f32_16x16x32_bf16 v[16:19], v[166:169], v[226:229], v[16:19]
	v_mfma_f32_16x16x32_bf16 v[60:63], v[170:173], v[206:209], v[60:63]
	v_mfma_f32_16x16x32_bf16 v[56:59], v[178:181], v[206:209], v[56:59]
	v_mfma_f32_16x16x32_bf16 v[40:43], v[178:181], v[214:217], v[40:43]
	v_mfma_f32_16x16x32_bf16 v[48:51], v[170:173], v[214:217], v[48:51]
	v_mfma_f32_16x16x32_bf16 v[32:35], v[170:173], v[222:225], v[32:35]
	v_mfma_f32_16x16x32_bf16 v[24:27], v[178:181], v[222:225], v[24:27]
	v_mfma_f32_16x16x32_bf16 v[8:11], v[178:181], v[230:233], v[8:11]
	v_mfma_f32_16x16x32_bf16 v[16:19], v[170:173], v[230:233], v[16:19]
	s_setprio 0
	s_setprio 1
	v_mfma_f32_16x16x32_bf16 v[52:55], v[186:189], v[202:205], v[52:55]
	v_mfma_f32_16x16x32_bf16 v[44:47], v[194:197], v[202:205], v[44:47]
	v_mfma_f32_16x16x32_bf16 v[28:31], v[194:197], v[210:213], v[28:31]
	v_mfma_f32_16x16x32_bf16 v[36:39], v[186:189], v[210:213], v[36:39]
	v_mfma_f32_16x16x32_bf16 v[20:23], v[186:189], v[218:221], v[20:23]
	v_mfma_f32_16x16x32_bf16 v[12:15], v[194:197], v[218:221], v[12:15]
	v_mfma_f32_16x16x32_bf16 v[0:3], v[194:197], v[226:229], v[0:3]
	v_mfma_f32_16x16x32_bf16 v[4:7], v[186:189], v[226:229], v[4:7]
	v_mfma_f32_16x16x32_bf16 v[52:55], v[190:193], v[206:209], v[52:55]
	v_mfma_f32_16x16x32_bf16 v[44:47], v[198:201], v[206:209], v[44:47]
	v_mfma_f32_16x16x32_bf16 v[28:31], v[198:201], v[214:217], v[28:31]
	v_mfma_f32_16x16x32_bf16 v[36:39], v[190:193], v[214:217], v[36:39]
	v_mfma_f32_16x16x32_bf16 v[20:23], v[190:193], v[222:225], v[20:23]
	v_mfma_f32_16x16x32_bf16 v[12:15], v[198:201], v[222:225], v[12:15]
	v_mfma_f32_16x16x32_bf16 v[0:3], v[198:201], v[230:233], v[0:3]
	v_mfma_f32_16x16x32_bf16 v[4:7], v[190:193], v[230:233], v[4:7]
	s_barrier
	s_setprio 0
	s_add_i32 s46, s46, 2
	s_add_u32 s50, s50, 0x100
	s_addc_u32 s51, s51, 0
	s_add_u32 s4, s4, 0x100
	s_addc_u32 s5, s5, 0
	s_cmp_gt_u32 s46, 29
	s_cbranch_scc0 .LBB0_656

; #define PG8_STAGE(bufoff, gbase, voff) do { _Pragma("unroll") for (int _i = 0; _i < 2; ++_i) \
;         __builtin_amdgcn_global_load_lds((const unsigned*)((const char*)(gbase) + (voff)[_i]), (PG8_LAS unsigned*)(lds + (bufoff) + ldsw + _i * 8192), 16, 0, 0); } while (0)
; #define PG8_LDA(dst, b, h) do { _Pragma("unroll") for (int m = 0; m < 4; ++m) _Pragma("unroll") for (int k = 0; k < 2; ++k) dst[m][k] = *(const PG8_LAS bf16x8*)(lds + PG8_SA(b, h) + aoff + m * 2048 + k * 1024); } while (0)
; #define PG8_LDB(dst, b, h) do { _Pragma("unroll") for (int n = 0; n < 2; ++n) _Pragma("unroll") for (int k = 0; k < 2; ++k) dst[n][k] = *(const PG8_LAS bf16x8*)(lds + PG8_SB(b, h) + boff + n * 2048 + k * 1024); } while (0)
; #define PG8_MMA(ai, bj, At, Bt) do { __builtin_amdgcn_s_setprio(1); _Pragma("unroll") for (int m = 0; m < 4; ++m) _Pragma("unroll") for (int n = 0; n < 2; ++n) _Pragma("unroll") for (int k = 0; k < 2; ++k) \
;         acc[ai][bj][m][n] = __builtin_amdgcn_mfma_f32_16x16x32_bf16(Bt[n][k], At[m][k], acc[ai][bj][m][n], 0, 0, 0); __builtin_amdgcn_s_setprio(0); } while (0)
; #define PG8_WAIT_V(n) asm volatile("s_waitcnt vmcnt(" #n ")" ::: "memory")
; #define PG8_WAIT_L(n) asm volatile("s_waitcnt lgkmcnt(" #n ")" ::: "memory")
; #define PG8_BAR __builtin_amdgcn_s_barrier()
; #define PG8_SCHED __builtin_amdgcn_sched_barrier(0)
; template <class Epi, class Sched, bool ALIGN_EPI = false, bool SP2 = false>
; __device__ __forceinline__ void gemm_phase(PG8_LAS unsigned char* lds, const Gemm g, const Sched& S, const Epi& E) {
;     ...
;             PG8_LDB(B0, 0, 0); PG8_LDB(B1, 0, 1); PG8_SCHED; PG8_LDA(At, 0, 0); PG8_STAGE(PG8_SA(1, 1), a1 + hstepA, voffA);
;             PG8_WAIT_V(8); PG8_WAIT_L(0); PG8_BAR; PG8_MMA(0, 0, At, B0); PG8_MMA(0, 1, At, B1); PG8_BAR; PG8_SCHED;
;             PG8_LDA(At, 0, 1); PG8_STAGE(PG8_SB(0, 0), b2, voffB); PG8_STAGE(PG8_SB(0, 1), b2 + hstepB, voffB); PG8_STAGE(PG8_SA(0, 0), a2, voffA);
;             PG8_WAIT_V(8); PG8_WAIT_L(0); PG8_BAR; PG8_MMA(1, 0, At, B0); PG8_MMA(1, 1, At, B1); PG8_BAR; PG8_SCHED;
.LBB0_929:
	ds_read_b128 v[152:155], v148
	ds_read_b128 v[156:159], v148 offset:1024
	ds_read_b128 v[160:163], v148 offset:2048
	ds_read_b128 v[164:167], v148 offset:3072
	ds_read_b128 v[168:171], v149
	ds_read_b128 v[172:175], v149 offset:1024
	ds_read_b128 v[176:179], v149 offset:2048
	ds_read_b128 v[180:183], v149 offset:3072
	s_add_u32 s52, s50, 0xfff80080
	s_addc_u32 s53, s51, -1
	s_cmp_eq_u32 s57, 28
	s_cselect_b32 s59, s45, s53
	s_cselect_b32 s58, s46, s52
	s_cselect_b32 s53, s47, s56
	s_cselect_b32 s52, s49, s55
	v_lshl_add_u64 v[142:143], s[50:51], 0, v[138:139]
	s_add_i32 m0, s8, 0xc000
	ds_read_b128 v[190:193], v150
	ds_read_b128 v[194:197], v150 offset:1024
	ds_read_b128 v[198:201], v150 offset:2048
	ds_read_b128 v[202:205], v150 offset:3072
	ds_read_b128 v[206:209], v150 offset:4096
	ds_read_b128 v[210:213], v150 offset:5120
	ds_read_b128 v[214:217], v150 offset:6144
	ds_read_b128 v[218:221], v150 offset:7168
	global_load_lds_dwordx4 v[142:143], off
	v_lshl_add_u64 v[142:143], s[50:51], 0, v[140:141]
	s_add_i32 m0, s8, 0xe000
	s_nop 0
	global_load_lds_dwordx4 v[142:143], off
	s_waitcnt vmcnt(8)
	s_waitcnt lgkmcnt(0)
	s_barrier
	s_setprio 1
	s_waitcnt lgkmcnt(0)
	v_mfma_f32_16x16x32_bf16 v[124:127], v[152:155], v[190:193], v[124:127]
	v_mfma_f32_16x16x32_bf16 v[120:123], v[160:163], v[190:193], v[120:123]
	v_mfma_f32_16x16x32_bf16 v[104:107], v[160:163], v[198:201], v[104:107]
	v_mfma_f32_16x16x32_bf16 v[108:111], v[152:155], v[198:201], v[108:111]
	v_mfma_f32_16x16x32_bf16 v[92:95], v[152:155], v[206:209], v[92:95]
	v_mfma_f32_16x16x32_bf16 v[88:91], v[160:163], v[206:209], v[88:91]
	v_mfma_f32_16x16x32_bf16 v[72:75], v[160:163], v[214:217], v[72:75]
	v_mfma_f32_16x16x32_bf16 v[76:79], v[152:155], v[214:217], v[76:79]
	v_mfma_f32_16x16x32_bf16 v[124:127], v[156:159], v[194:197], v[124:127]
	v_mfma_f32_16x16x32_bf16 v[120:123], v[164:167], v[194:197], v[120:123]
	v_mfma_f32_16x16x32_bf16 v[104:107], v[164:167], v[202:205], v[104:107]
	v_mfma_f32_16x16x32_bf16 v[108:111], v[156:159], v[202:205], v[108:111]
	v_mfma_f32_16x16x32_bf16 v[92:95], v[156:159], v[210:213], v[92:95]
	v_mfma_f32_16x16x32_bf16 v[88:91], v[164:167], v[210:213], v[88:91]
	v_mfma_f32_16x16x32_bf16 v[72:75], v[164:167], v[218:221], v[72:75]
	v_mfma_f32_16x16x32_bf16 v[76:79], v[156:159], v[218:221], v[76:79]
	s_setprio 0
	s_setprio 1
	v_mfma_f32_16x16x32_bf16 v[116:119], v[168:171], v[190:193], v[116:119]
	v_mfma_f32_16x16x32_bf16 v[112:115], v[176:179], v[190:193], v[112:115]
	v_mfma_f32_16x16x32_bf16 v[96:99], v[176:179], v[198:201], v[96:99]
	v_mfma_f32_16x16x32_bf16 v[100:103], v[168:171], v[198:201], v[100:103]
	v_mfma_f32_16x16x32_bf16 v[84:87], v[168:171], v[206:209], v[84:87]
	v_mfma_f32_16x16x32_bf16 v[80:83], v[176:179], v[206:209], v[80:83]
	v_mfma_f32_16x16x32_bf16 v[64:67], v[176:179], v[214:217], v[64:67]
	v_mfma_f32_16x16x32_bf16 v[68:71], v[168:171], v[214:217], v[68:71]
	v_mfma_f32_16x16x32_bf16 v[116:119], v[172:175], v[194:197], v[116:119]
	v_mfma_f32_16x16x32_bf16 v[112:115], v[180:183], v[194:197], v[112:115]
	v_mfma_f32_16x16x32_bf16 v[96:99], v[180:183], v[202:205], v[96:99]
	v_mfma_f32_16x16x32_bf16 v[100:103], v[172:175], v[202:205], v[100:103]
	v_mfma_f32_16x16x32_bf16 v[84:87], v[172:175], v[210:213], v[84:87]
	v_mfma_f32_16x16x32_bf16 v[80:83], v[180:183], v[210:213], v[80:83]
	v_mfma_f32_16x16x32_bf16 v[64:67], v[180:183], v[218:221], v[64:67]
	v_mfma_f32_16x16x32_bf16 v[68:71], v[172:175], v[218:221], v[68:71]
	s_setprio 0
	s_barrier
	s_add_i32 s70, s41, s7
	v_lshl_add_u64 v[142:143], s[52:53], 0, v[132:133]
	s_mov_b32 m0, s70
	ds_read_b128 v[190:193], v150 offset:16384
	ds_read_b128 v[194:197], v150 offset:17408
	ds_read_b128 v[198:201], v150 offset:18432
	ds_read_b128 v[202:205], v150 offset:19456
	ds_read_b128 v[206:209], v150 offset:20480
	ds_read_b128 v[210:213], v150 offset:21504
	ds_read_b128 v[214:217], v150 offset:22528
	ds_read_b128 v[218:221], v150 offset:23552
	global_load_lds_dwordx4 v[142:143], off
	s_add_i32 m0, s70, 0x2000
	s_add_u32 s70, s52, 0x80000
	v_lshl_add_u64 v[222:223], s[52:53], 0, v[128:129]
	s_addc_u32 s71, s53, 0
	s_add_i32 s72, s44, s7
	global_load_lds_dwordx4 v[222:223], off
	v_lshl_add_u64 v[224:225], s[70:71], 0, v[132:133]
	s_mov_b32 m0, s72
	v_lshl_add_u64 v[226:227], s[58:59], 0, v[130:131]
	global_load_lds_dwordx4 v[224:225], off
	v_lshl_add_u64 v[224:225], s[70:71], 0, v[128:129]
	s_add_i32 m0, s72, 0x2000
	s_nop 0
	global_load_lds_dwordx4 v[224:225], off
	v_lshl_add_u64 v[224:225], s[58:59], 0, v[134:135]
	s_mov_b32 m0, s8
	s_nop 0
	global_load_lds_dwordx4 v[224:225], off
	s_mov_b32 m0, s9
	s_nop 0
	global_load_lds_dwordx4 v[226:227], off
	s_waitcnt vmcnt(8)
	s_waitcnt lgkmcnt(0)
	s_barrier
; #define PG8_STAGE(bufoff, gbase, voff) do { _Pragma("unroll") for (int _i = 0; _i < 2; ++_i) \
;         __builtin_amdgcn_global_load_lds((const unsigned*)((const char*)(gbase) + (voff)[_i]), (PG8_LAS unsigned*)(lds + (bufoff) + ldsw + _i * 8192), 16, 0, 0); } while (0)
; #define PG8_LDA(dst, b, h) do { _Pragma("unroll") for (int m = 0; m < 4; ++m) _Pragma("unroll") for (int k = 0; k < 2; ++k) dst[m][k] = *(const PG8_LAS bf16x8*)(lds + PG8_SA(b, h) + aoff + m * 2048 + k * 1024); } while (0)
; #define PG8_LDB(dst, b, h) do { _Pragma("unroll") for (int n = 0; n < 2; ++n) _Pragma("unroll") for (int k = 0; k < 2; ++k) dst[n][k] = *(const PG8_LAS bf16x8*)(lds + PG8_SB(b, h) + boff + n * 2048 + k * 1024); } while (0)
; #define PG8_MMA(ai, bj, At, Bt) do { __builtin_amdgcn_s_setprio(1); _Pragma("unroll") for (int m = 0; m < 4; ++m) _Pragma("unroll") for (int n = 0; n < 2; ++n) _Pragma("unroll") for (int k = 0; k < 2; ++k) \
;         acc[ai][bj][m][n] = __builtin_amdgcn_mfma_f32_16x16x32_bf16(Bt[n][k], At[m][k], acc[ai][bj][m][n], 0, 0, 0); __builtin_amdgcn_s_setprio(0); } while (0)
; #define PG8_WAIT_V(n) asm volatile("s_waitcnt vmcnt(" #n ")" ::: "memory")
; #define PG8_WAIT_L(n) asm volatile("s_waitcnt lgkmcnt(" #n ")" ::: "memory")
; #define PG8_BAR __builtin_amdgcn_s_barrier()
; #define PG8_SCHED __builtin_amdgcn_sched_barrier(0)
; template <class Epi, class Sched, bool ALIGN_EPI = false, bool SP2 = false>
; __device__ __forceinline__ void gemm_phase(PG8_LAS unsigned char* lds, const Gemm g, const Sched& S, const Epi& E) {
;     ...
;             PG8_WAIT_V(8); PG8_WAIT_L(0); PG8_BAR; PG8_MMA(1, 0, At, B0); PG8_MMA(1, 1, At, B1); PG8_BAR; PG8_SCHED;
;             PG8_LDB(B0, 1, 0); PG8_LDB(B1, 1, 1); PG8_SCHED; PG8_LDA(At, 1, 0); PG8_STAGE(PG8_SA(0, 1), a2 + hstepA, voffA);
;             PG8_WAIT_V(8); PG8_WAIT_L(0); PG8_BAR; PG8_MMA(0, 0, At, B0); PG8_MMA(0, 1, At, B1); PG8_BAR; PG8_SCHED;
	s_setprio 1
	s_waitcnt lgkmcnt(0)
	v_mfma_f32_16x16x32_bf16 v[60:63], v[152:155], v[190:193], v[60:63]
	v_mfma_f32_16x16x32_bf16 v[56:59], v[160:163], v[190:193], v[56:59]
	v_mfma_f32_16x16x32_bf16 v[40:43], v[160:163], v[198:201], v[40:43]
	v_mfma_f32_16x16x32_bf16 v[44:47], v[152:155], v[198:201], v[44:47]
	v_mfma_f32_16x16x32_bf16 v[28:31], v[152:155], v[206:209], v[28:31]
	v_mfma_f32_16x16x32_bf16 v[24:27], v[160:163], v[206:209], v[24:27]
	v_mfma_f32_16x16x32_bf16 v[8:11], v[160:163], v[214:217], v[8:11]
	v_mfma_f32_16x16x32_bf16 v[12:15], v[152:155], v[214:217], v[12:15]
	v_mfma_f32_16x16x32_bf16 v[60:63], v[156:159], v[194:197], v[60:63]
	v_mfma_f32_16x16x32_bf16 v[56:59], v[164:167], v[194:197], v[56:59]
	v_mfma_f32_16x16x32_bf16 v[40:43], v[164:167], v[202:205], v[40:43]
	v_mfma_f32_16x16x32_bf16 v[44:47], v[156:159], v[202:205], v[44:47]
	v_mfma_f32_16x16x32_bf16 v[28:31], v[156:159], v[210:213], v[28:31]
	v_mfma_f32_16x16x32_bf16 v[24:27], v[164:167], v[210:213], v[24:27]
	v_mfma_f32_16x16x32_bf16 v[8:11], v[164:167], v[218:221], v[8:11]
	v_mfma_f32_16x16x32_bf16 v[12:15], v[156:159], v[218:221], v[12:15]
	s_setprio 0
	s_setprio 1
	v_mfma_f32_16x16x32_bf16 v[52:55], v[168:171], v[190:193], v[52:55]
	v_mfma_f32_16x16x32_bf16 v[48:51], v[176:179], v[190:193], v[48:51]
	v_mfma_f32_16x16x32_bf16 v[32:35], v[176:179], v[198:201], v[32:35]
	v_mfma_f32_16x16x32_bf16 v[36:39], v[168:171], v[198:201], v[36:39]
	v_mfma_f32_16x16x32_bf16 v[20:23], v[168:171], v[206:209], v[20:23]
	v_mfma_f32_16x16x32_bf16 v[16:19], v[176:179], v[206:209], v[16:19]
	v_mfma_f32_16x16x32_bf16 v[0:3], v[176:179], v[214:217], v[0:3]
	v_mfma_f32_16x16x32_bf16 v[4:7], v[168:171], v[214:217], v[4:7]
	v_mfma_f32_16x16x32_bf16 v[52:55], v[172:175], v[194:197], v[52:55]
	v_mfma_f32_16x16x32_bf16 v[48:51], v[180:183], v[194:197], v[48:51]
	v_mfma_f32_16x16x32_bf16 v[32:35], v[180:183], v[202:205], v[32:35]
	v_mfma_f32_16x16x32_bf16 v[36:39], v[172:175], v[202:205], v[36:39]
	v_mfma_f32_16x16x32_bf16 v[20:23], v[172:175], v[210:213], v[20:23]
	v_mfma_f32_16x16x32_bf16 v[16:19], v[180:183], v[210:213], v[16:19]
	v_mfma_f32_16x16x32_bf16 v[0:3], v[180:183], v[218:221], v[0:3]
	v_mfma_f32_16x16x32_bf16 v[4:7], v[172:175], v[218:221], v[4:7]
	s_setprio 0
	s_barrier
	s_add_i32 s70, 0, 0x18000
	v_add_u32_e32 v136, s70, v145
	s_add_i32 s71, 0, 0x1c000
	ds_read_b128 v[152:155], v136
	ds_read_b128 v[156:159], v136 offset:1024
	ds_read_b128 v[160:163], v136 offset:2048
	ds_read_b128 v[164:167], v136 offset:3072
	v_add_u32_e32 v136, s71, v145
	ds_read_b128 v[168:171], v136
	ds_read_b128 v[172:175], v136 offset:1024
	ds_read_b128 v[176:179], v136 offset:2048
	ds_read_b128 v[180:183], v136 offset:3072
	s_add_u32 s58, s58, 0x80000
	s_addc_u32 s59, s59, 0
	s_mov_b32 m0, s10
	v_lshl_add_u64 v[228:229], s[58:59], 0, v[134:135]
	ds_read_b128 v[190:193], v150 offset:32768
	ds_read_b128 v[194:197], v150 offset:33792
	ds_read_b128 v[198:201], v150 offset:34816
	ds_read_b128 v[202:205], v150 offset:35840
	ds_read_b128 v[206:209], v150 offset:36864
	ds_read_b128 v[210:213], v150 offset:37888
	ds_read_b128 v[214:217], v150 offset:38912
	ds_read_b128 v[218:221], v150 offset:39936
	global_load_lds_dwordx4 v[228:229], off
	v_lshl_add_u64 v[228:229], s[58:59], 0, v[130:131]
	s_mov_b32 m0, s11
	s_nop 0
	global_load_lds_dwordx4 v[228:229], off
	s_waitcnt vmcnt(8)
	s_waitcnt lgkmcnt(0)
	s_barrier
	s_setprio 1
	s_waitcnt lgkmcnt(0)
	v_mfma_f32_16x16x32_bf16 v[124:127], v[152:155], v[190:193], v[124:127]
	v_mfma_f32_16x16x32_bf16 v[120:123], v[160:163], v[190:193], v[120:123]
	v_mfma_f32_16x16x32_bf16 v[104:107], v[160:163], v[198:201], v[104:107]
	v_mfma_f32_16x16x32_bf16 v[108:111], v[152:155], v[198:201], v[108:111]
	v_mfma_f32_16x16x32_bf16 v[92:95], v[152:155], v[206:209], v[92:95]
	v_mfma_f32_16x16x32_bf16 v[88:91], v[160:163], v[206:209], v[88:91]
	v_mfma_f32_16x16x32_bf16 v[72:75], v[160:163], v[214:217], v[72:75]
	v_mfma_f32_16x16x32_bf16 v[76:79], v[152:155], v[214:217], v[76:79]
	v_mfma_f32_16x16x32_bf16 v[124:127], v[156:159], v[194:197], v[124:127]
	v_mfma_f32_16x16x32_bf16 v[120:123], v[164:167], v[194:197], v[120:123]
	v_mfma_f32_16x16x32_bf16 v[104:107], v[164:167], v[202:205], v[104:107]
	v_mfma_f32_16x16x32_bf16 v[108:111], v[156:159], v[202:205], v[108:111]
	v_mfma_f32_16x16x32_bf16 v[92:95], v[156:159], v[210:213], v[92:95]
	v_mfma_f32_16x16x32_bf16 v[88:91], v[164:167], v[210:213], v[88:91]
	v_mfma_f32_16x16x32_bf16 v[72:75], v[164:167], v[218:221], v[72:75]
	v_mfma_f32_16x16x32_bf16 v[76:79], v[156:159], v[218:221], v[76:79]
	s_setprio 0
	s_setprio 1
	v_mfma_f32_16x16x32_bf16 v[116:119], v[168:171], v[190:193], v[116:119]
	v_mfma_f32_16x16x32_bf16 v[112:115], v[176:179], v[190:193], v[112:115]
	v_mfma_f32_16x16x32_bf16 v[96:99], v[176:179], v[198:201], v[96:99]
	v_mfma_f32_16x16x32_bf16 v[100:103], v[168:171], v[198:201], v[100:103]
	v_mfma_f32_16x16x32_bf16 v[84:87], v[168:171], v[206:209], v[84:87]
	v_mfma_f32_16x16x32_bf16 v[80:83], v[176:179], v[206:209], v[80:83]
	v_mfma_f32_16x16x32_bf16 v[64:67], v[176:179], v[214:217], v[64:67]
	v_mfma_f32_16x16x32_bf16 v[68:71], v[168:171], v[214:217], v[68:71]
	v_mfma_f32_16x16x32_bf16 v[116:119], v[172:175], v[194:197], v[116:119]
	v_mfma_f32_16x16x32_bf16 v[112:115], v[180:183], v[194:197], v[112:115]
	v_mfma_f32_16x16x32_bf16 v[96:99], v[180:183], v[202:205], v[96:99]
	v_mfma_f32_16x16x32_bf16 v[100:103], v[172:175], v[202:205], v[100:103]
	v_mfma_f32_16x16x32_bf16 v[84:87], v[172:175], v[210:213], v[84:87]
	v_mfma_f32_16x16x32_bf16 v[80:83], v[180:183], v[210:213], v[80:83]
	v_mfma_f32_16x16x32_bf16 v[64:67], v[180:183], v[218:221], v[64:67]
	v_mfma_f32_16x16x32_bf16 v[68:71], v[172:175], v[218:221], v[68:71]
	s_setprio 0
	s_barrier
; #define PG8_STAGE(bufoff, gbase, voff) do { _Pragma("unroll") for (int _i = 0; _i < 2; ++_i) \
;         __builtin_amdgcn_global_load_lds((const unsigned*)((const char*)(gbase) + (voff)[_i]), (PG8_LAS unsigned*)(lds + (bufoff) + ldsw + _i * 8192), 16, 0, 0); } while (0)
; #define PG8_LDA(dst, b, h) do { _Pragma("unroll") for (int m = 0; m < 4; ++m) _Pragma("unroll") for (int k = 0; k < 2; ++k) dst[m][k] = *(const PG8_LAS bf16x8*)(lds + PG8_SA(b, h) + aoff + m * 2048 + k * 1024); } while (0)
; #define PG8_MMA(ai, bj, At, Bt) do { __builtin_amdgcn_s_setprio(1); _Pragma("unroll") for (int m = 0; m < 4; ++m) _Pragma("unroll") for (int n = 0; n < 2; ++n) _Pragma("unroll") for (int k = 0; k < 2; ++k) \
;         acc[ai][bj][m][n] = __builtin_amdgcn_mfma_f32_16x16x32_bf16(Bt[n][k], At[m][k], acc[ai][bj][m][n], 0, 0, 0); __builtin_amdgcn_s_setprio(0); } while (0)
; #define PG8_WAIT_V(n) asm volatile("s_waitcnt vmcnt(" #n ")" ::: "memory")
; #define PG8_WAIT_L(n) asm volatile("s_waitcnt lgkmcnt(" #n ")" ::: "memory")
; #define PG8_BAR __builtin_amdgcn_s_barrier()
; #define PG8_SCHED __builtin_amdgcn_sched_barrier(0)
; template <class Epi, class Sched, bool ALIGN_EPI = false, bool SP2 = false>
; __device__ __forceinline__ void gemm_phase(PG8_LAS unsigned char* lds, const Gemm g, const Sched& S, const Epi& E) {
;     ...
;             PG8_LDA(At, 1, 1); PG8_STAGE(PG8_SB(1, 0), b3, voffB); PG8_STAGE(PG8_SB(1, 1), b3 + hstepB, voffB); PG8_STAGE(PG8_SA(1, 0), a3, voffA);
;             PG8_WAIT_V(8); PG8_WAIT_L(0); PG8_BAR; PG8_MMA(1, 0, At, B0); PG8_MMA(1, 1, At, B1); PG8_BAR; PG8_SCHED;
	s_add_i32 s58, s70, s7
	v_lshl_add_u64 v[142:143], v[142:143], 0, s[34:35]
	s_mov_b32 m0, s58
	ds_read_b128 v[190:193], v150 offset:49152
	ds_read_b128 v[194:197], v150 offset:50176
	ds_read_b128 v[198:201], v150 offset:51200
	ds_read_b128 v[202:205], v150 offset:52224
	ds_read_b128 v[206:209], v150 offset:53248
	ds_read_b128 v[210:213], v150 offset:54272
	ds_read_b128 v[214:217], v150 offset:55296
	ds_read_b128 v[218:221], v150 offset:56320
	global_load_lds_dwordx4 v[142:143], off
	s_add_i32 m0, s58, 0x2000
	s_add_u32 s52, s52, 0x80080
	v_lshl_add_u64 v[142:143], v[222:223], 0, s[34:35]
	s_addc_u32 s53, s53, 0
	s_add_i32 s58, s71, s7
	global_load_lds_dwordx4 v[142:143], off
	v_lshl_add_u64 v[142:143], s[52:53], 0, v[132:133]
	s_mov_b32 m0, s58
	s_nop 0
	global_load_lds_dwordx4 v[142:143], off
	v_lshl_add_u64 v[142:143], s[52:53], 0, v[128:129]
	s_add_i32 m0, s58, 0x2000
	s_nop 0
	global_load_lds_dwordx4 v[142:143], off
	v_lshl_add_u64 v[142:143], v[224:225], 0, s[34:35]
	s_mov_b32 m0, s13
	s_nop 0
	global_load_lds_dwordx4 v[142:143], off
	v_lshl_add_u64 v[142:143], v[226:227], 0, s[34:35]
	s_mov_b32 m0, s33
	s_nop 0
	global_load_lds_dwordx4 v[142:143], off
	s_waitcnt vmcnt(8)
	s_waitcnt lgkmcnt(0)
	s_barrier
	s_setprio 1
	s_waitcnt lgkmcnt(0)
	v_mfma_f32_16x16x32_bf16 v[60:63], v[152:155], v[190:193], v[60:63]
	v_mfma_f32_16x16x32_bf16 v[56:59], v[160:163], v[190:193], v[56:59]
	v_mfma_f32_16x16x32_bf16 v[40:43], v[160:163], v[198:201], v[40:43]
	v_mfma_f32_16x16x32_bf16 v[44:47], v[152:155], v[198:201], v[44:47]
	v_mfma_f32_16x16x32_bf16 v[28:31], v[152:155], v[206:209], v[28:31]
	v_mfma_f32_16x16x32_bf16 v[24:27], v[160:163], v[206:209], v[24:27]
	v_mfma_f32_16x16x32_bf16 v[8:11], v[160:163], v[214:217], v[8:11]
	v_mfma_f32_16x16x32_bf16 v[12:15], v[152:155], v[214:217], v[12:15]
	v_mfma_f32_16x16x32_bf16 v[60:63], v[156:159], v[194:197], v[60:63]
	v_mfma_f32_16x16x32_bf16 v[56:59], v[164:167], v[194:197], v[56:59]
	v_mfma_f32_16x16x32_bf16 v[40:43], v[164:167], v[202:205], v[40:43]
	v_mfma_f32_16x16x32_bf16 v[44:47], v[156:159], v[202:205], v[44:47]
	v_mfma_f32_16x16x32_bf16 v[28:31], v[156:159], v[210:213], v[28:31]
	v_mfma_f32_16x16x32_bf16 v[24:27], v[164:167], v[210:213], v[24:27]
	v_mfma_f32_16x16x32_bf16 v[8:11], v[164:167], v[218:221], v[8:11]
	v_mfma_f32_16x16x32_bf16 v[12:15], v[156:159], v[218:221], v[12:15]
	s_setprio 0
	s_setprio 1
	v_mfma_f32_16x16x32_bf16 v[52:55], v[168:171], v[190:193], v[52:55]
	v_mfma_f32_16x16x32_bf16 v[48:51], v[176:179], v[190:193], v[48:51]
	v_mfma_f32_16x16x32_bf16 v[32:35], v[176:179], v[198:201], v[32:35]
	v_mfma_f32_16x16x32_bf16 v[36:39], v[168:171], v[198:201], v[36:39]
	v_mfma_f32_16x16x32_bf16 v[20:23], v[168:171], v[206:209], v[20:23]
	v_mfma_f32_16x16x32_bf16 v[16:19], v[176:179], v[206:209], v[16:19]
	v_mfma_f32_16x16x32_bf16 v[0:3], v[176:179], v[214:217], v[0:3]
	v_mfma_f32_16x16x32_bf16 v[4:7], v[168:171], v[214:217], v[4:7]
	v_mfma_f32_16x16x32_bf16 v[52:55], v[172:175], v[194:197], v[52:55]
	v_mfma_f32_16x16x32_bf16 v[48:51], v[180:183], v[194:197], v[48:51]
	v_mfma_f32_16x16x32_bf16 v[32:35], v[180:183], v[202:205], v[32:35]
	v_mfma_f32_16x16x32_bf16 v[36:39], v[172:175], v[202:205], v[36:39]
	v_mfma_f32_16x16x32_bf16 v[20:23], v[172:175], v[210:213], v[20:23]
	v_mfma_f32_16x16x32_bf16 v[16:19], v[180:183], v[210:213], v[16:19]
	v_mfma_f32_16x16x32_bf16 v[0:3], v[180:183], v[218:221], v[0:3]
	v_mfma_f32_16x16x32_bf16 v[4:7], v[172:175], v[218:221], v[4:7]
	s_setprio 0
	s_barrier
	s_add_i32 s57, s57, 2
	s_add_u32 s50, s50, 0x100
	s_addc_u32 s51, s51, 0
	s_add_u32 s55, s55, 0x100
	s_addc_u32 s56, s56, 0
	s_cmp_gt_u32 s57, 29
	s_cbranch_scc0 .LBB0_929
	s_and_b64 vcc, exec, s[38:39]
	s_cbranch_vccz .LBB0_932
	s_barrier

; #define PG8_STAGE(bufoff, gbase, voff) do { _Pragma("unroll") for (int _i = 0; _i < 2; ++_i) \
;         __builtin_amdgcn_global_load_lds((const unsigned*)((const char*)(gbase) + (voff)[_i]), (PG8_LAS unsigned*)(lds + (bufoff) + ldsw + _i * 8192), 16, 0, 0); } while (0)
; #define PG8_LDA(dst, b, h) do { _Pragma("unroll") for (int m = 0; m < 4; ++m) _Pragma("unroll") for (int k = 0; k < 2; ++k) dst[m][k] = *(const PG8_LAS bf16x8*)(lds + PG8_SA(b, h) + aoff + m * 2048 + k * 1024); } while (0)
; #define PG8_LDB(dst, b, h) do { _Pragma("unroll") for (int n = 0; n < 2; ++n) _Pragma("unroll") for (int k = 0; k < 2; ++k) dst[n][k] = *(const PG8_LAS bf16x8*)(lds + PG8_SB(b, h) + boff + n * 2048 + k * 1024); } while (0)
; #define PG8_WAIT_V(n) asm volatile("s_waitcnt vmcnt(" #n ")" ::: "memory")
; #define PG8_WAIT_L(n) asm volatile("s_waitcnt lgkmcnt(" #n ")" ::: "memory")
; template <class Epi, class Sched, bool ALIGN_EPI = false, bool SP2 = false>
; __device__ __forceinline__ void gemm_phase(PG8_LAS unsigned char* lds, const Gemm g, const Sched& S, const Epi& E) {
;     ...
;         const bool has_next = S.next(ui + 1, nxt);
;         const char* nA = has_next ? (const char*)g.A + (size_t)nxt.pm * tstepA + (size_t)nxt.z * g.azs + (size_t)(nxt.k0 >> 6) * kstA : cA; const char* nB = has_next ? (const char*)g.Bt + (size_t)nxt.pn * tstepB + (size_t)nxt.z * g.bzs + (size_t)nxt.k0 * 2 : cB;
;         const int nt = cur.nt;
;         for (int t = 0; t < nt; t += 2) {
;             const bool last = (t == nt - 2);
;             const char* a1 = cA + (size_t)(t + 1) * kstA;
;             const char* a2 = last ? nA : cA + (size_t)(t + 2) * kstA; const char* b2 = last ? nB : cB + (size_t)(t + 2) * kstep;
;             const char* a3 = a2 + kstA; const char* b3 = b2 + kstep;
;             if (last && has_next) S.a_ready(nxt);
;             if constexpr (SP2) {
;             PG8_LDB(B0, 0, 0); PG8_LDB(B1, 0, 1); PG8_SCHED; PG8_LDA(At, 0, 0); PG8_STAGE(PG8_SA(1, 1), a1 + hstepA, voffA);
;             PG8_WAIT_V(8); PG8_WAIT_L(0); PG8_BAR; PG8_MMA(0, 0, At, B0); PG8_MMA(0, 1, At, B1); PG8_BAR; PG8_SCHED;
;             PG8_LDA(At, 0, 1); PG8_STAGE(PG8_SB(0, 0), b2, voffB); PG8_STAGE(PG8_SB(0, 1), b2 + hstepB, voffB); PG8_STAGE(PG8_SA(0, 0), a2, voffA);
;             PG8_WAIT_V(8); PG8_WAIT_L(0); PG8_BAR; PG8_MMA(1, 0, At, B0); PG8_MMA(1, 1, At, B1); PG8_BAR; PG8_SCHED;
.LBB0_1048:
	s_or_b32 s58, s66, 1
	s_add_i32 s66, s66, 2
	s_mov_b32 s67, s59
	v_add_u32_e32 v140, s10, v179
	v_add_u32_e32 v182, s11, v179
	s_lshl_b64 s[4:5], s[58:59], 7
	s_lshl_b64 s[6:7], s[66:67], 7
	ds_read_b128 v[128:131], v140
	ds_read_b128 v[132:135], v140 offset:1024
	ds_read_b128 v[136:139], v140 offset:2048
	ds_read_b128 v[140:143], v140 offset:3072
	ds_read_b128 v[174:177], v182
	ds_read_b128 v[190:193], v182 offset:1024
	ds_read_b128 v[194:197], v182 offset:2048
	ds_read_b128 v[198:201], v182 offset:3072
	s_add_u32 s46, s60, s6
	s_addc_u32 s47, s61, s7
	s_and_b64 s[12:13], s[76:77], exec
	s_cselect_b32 vcc_hi, s47, s49
	s_cselect_b32 vcc_lo, s46, s48
	s_add_u32 s12, s62, s6
	s_addc_u32 s13, s63, s7
	s_and_b64 s[6:7], s[76:77], exec
	s_cselect_b32 s77, s13, s55
	s_cselect_b32 s76, s12, s54
	s_add_u32 s4, s35, s4
	s_addc_u32 s5, s39, s5
	v_lshl_add_u64 v[182:183], s[4:5], 0, v[144:145]
	s_add_i32 m0, s21, 0xc000
	ds_read_b128 v[202:205], v181
	ds_read_b128 v[206:209], v181 offset:1024
	ds_read_b128 v[210:213], v181 offset:2048
	ds_read_b128 v[214:217], v181 offset:3072
	ds_read_b128 v[218:221], v181 offset:4096
	ds_read_b128 v[222:225], v181 offset:5120
	ds_read_b128 v[226:229], v181 offset:6144
	ds_read_b128 v[230:233], v181 offset:7168
	global_load_lds_dwordx4 v[182:183], off
	v_lshl_add_u64 v[182:183], s[4:5], 0, v[148:149]
	s_add_i32 m0, s21, 0xe000
	s_nop 0
	global_load_lds_dwordx4 v[182:183], off
	s_waitcnt vmcnt(8)
	s_waitcnt lgkmcnt(0)
	s_setprio 1
	s_barrier
	v_mfma_f32_16x16x32_bf16 v[124:127], v[128:131], v[202:205], v[124:127]
	v_mfma_f32_16x16x32_bf16 v[120:123], v[136:139], v[202:205], v[120:123]
	v_mfma_f32_16x16x32_bf16 v[112:115], v[136:139], v[210:213], v[112:115]
	v_mfma_f32_16x16x32_bf16 v[116:119], v[128:131], v[210:213], v[116:119]
	v_mfma_f32_16x16x32_bf16 v[108:111], v[128:131], v[218:221], v[108:111]
	v_mfma_f32_16x16x32_bf16 v[104:107], v[136:139], v[218:221], v[104:107]
	v_mfma_f32_16x16x32_bf16 v[96:99], v[136:139], v[226:229], v[96:99]
	v_mfma_f32_16x16x32_bf16 v[100:103], v[128:131], v[226:229], v[100:103]
	v_mfma_f32_16x16x32_bf16 v[124:127], v[132:135], v[206:209], v[124:127]
	v_mfma_f32_16x16x32_bf16 v[120:123], v[140:143], v[206:209], v[120:123]
	v_mfma_f32_16x16x32_bf16 v[112:115], v[140:143], v[214:217], v[112:115]
	v_mfma_f32_16x16x32_bf16 v[116:119], v[132:135], v[214:217], v[116:119]
	v_mfma_f32_16x16x32_bf16 v[108:111], v[132:135], v[222:225], v[108:111]
	v_mfma_f32_16x16x32_bf16 v[104:107], v[140:143], v[222:225], v[104:107]
	v_mfma_f32_16x16x32_bf16 v[96:99], v[140:143], v[230:233], v[96:99]
	v_mfma_f32_16x16x32_bf16 v[100:103], v[132:135], v[230:233], v[100:103]
	s_setprio 0
	s_setprio 1
	v_mfma_f32_16x16x32_bf16 v[92:95], v[174:177], v[202:205], v[92:95]
	v_mfma_f32_16x16x32_bf16 v[88:91], v[194:197], v[202:205], v[88:91]
	v_mfma_f32_16x16x32_bf16 v[80:83], v[194:197], v[210:213], v[80:83]
	v_mfma_f32_16x16x32_bf16 v[84:87], v[174:177], v[210:213], v[84:87]
	v_mfma_f32_16x16x32_bf16 v[76:79], v[174:177], v[218:221], v[76:79]
	v_mfma_f32_16x16x32_bf16 v[72:75], v[194:197], v[218:221], v[72:75]
	v_mfma_f32_16x16x32_bf16 v[64:67], v[194:197], v[226:229], v[64:67]
	v_mfma_f32_16x16x32_bf16 v[68:71], v[174:177], v[226:229], v[68:71]
	v_mfma_f32_16x16x32_bf16 v[92:95], v[190:193], v[206:209], v[92:95]
	v_mfma_f32_16x16x32_bf16 v[88:91], v[198:201], v[206:209], v[88:91]
	v_mfma_f32_16x16x32_bf16 v[80:83], v[198:201], v[214:217], v[80:83]
	v_mfma_f32_16x16x32_bf16 v[84:87], v[190:193], v[214:217], v[84:87]
	v_mfma_f32_16x16x32_bf16 v[76:79], v[190:193], v[222:225], v[76:79]
	v_mfma_f32_16x16x32_bf16 v[72:75], v[198:201], v[222:225], v[72:75]
	v_mfma_f32_16x16x32_bf16 v[64:67], v[198:201], v[230:233], v[64:67]
	v_mfma_f32_16x16x32_bf16 v[68:71], v[190:193], v[230:233], v[68:71]
	s_barrier
	s_setprio 0
	s_add_i32 s4, s10, s94
	v_lshl_add_u64 v[182:183], s[76:77], 0, v[146:147]
	s_mov_b32 m0, s4
	ds_read_b128 v[202:205], v181 offset:16384
	ds_read_b128 v[206:209], v181 offset:17408
	ds_read_b128 v[210:213], v181 offset:18432
	ds_read_b128 v[214:217], v181 offset:19456
	ds_read_b128 v[218:221], v181 offset:20480
	ds_read_b128 v[222:225], v181 offset:21504
	ds_read_b128 v[226:229], v181 offset:22528
	ds_read_b128 v[230:233], v181 offset:23552
	global_load_lds_dwordx4 v[182:183], off
	s_add_i32 m0, s4, 0x2000
	s_add_u32 s4, s76, 0x80000
	v_lshl_add_u64 v[234:235], s[76:77], 0, v[150:151]
	s_addc_u32 s5, s77, 0
	s_add_i32 s6, s11, s94
	global_load_lds_dwordx4 v[234:235], off
	v_lshl_add_u64 v[236:237], s[4:5], 0, v[146:147]
	s_mov_b32 m0, s6
	v_lshl_add_u64 v[238:239], vcc, 0, v[148:149]
	global_load_lds_dwordx4 v[236:237], off
	v_lshl_add_u64 v[236:237], s[4:5], 0, v[150:151]
	s_add_i32 m0, s6, 0x2000
	s_nop 0
	global_load_lds_dwordx4 v[236:237], off
	v_lshl_add_u64 v[236:237], vcc, 0, v[144:145]
	s_mov_b32 m0, s21
	s_nop 0
	global_load_lds_dwordx4 v[236:237], off
	s_mov_b32 m0, s95
	s_nop 0
	global_load_lds_dwordx4 v[238:239], off
	s_waitcnt vmcnt(8)
	s_waitcnt lgkmcnt(0)
	s_setprio 1
	s_barrier
; #define PG8_STAGE(bufoff, gbase, voff) do { _Pragma("unroll") for (int _i = 0; _i < 2; ++_i) \
;         __builtin_amdgcn_global_load_lds((const unsigned*)((const char*)(gbase) + (voff)[_i]), (PG8_LAS unsigned*)(lds + (bufoff) + ldsw + _i * 8192), 16, 0, 0); } while (0)
; #define PG8_LDA(dst, b, h) do { _Pragma("unroll") for (int m = 0; m < 4; ++m) _Pragma("unroll") for (int k = 0; k < 2; ++k) dst[m][k] = *(const PG8_LAS bf16x8*)(lds + PG8_SA(b, h) + aoff + m * 2048 + k * 1024); } while (0)
; #define PG8_LDB(dst, b, h) do { _Pragma("unroll") for (int n = 0; n < 2; ++n) _Pragma("unroll") for (int k = 0; k < 2; ++k) dst[n][k] = *(const PG8_LAS bf16x8*)(lds + PG8_SB(b, h) + boff + n * 2048 + k * 1024); } while (0)
; #define PG8_MMA(ai, bj, At, Bt) do { __builtin_amdgcn_s_setprio(1); _Pragma("unroll") for (int m = 0; m < 4; ++m) _Pragma("unroll") for (int n = 0; n < 2; ++n) _Pragma("unroll") for (int k = 0; k < 2; ++k) \
;         acc[ai][bj][m][n] = __builtin_amdgcn_mfma_f32_16x16x32_bf16(Bt[n][k], At[m][k], acc[ai][bj][m][n], 0, 0, 0); __builtin_amdgcn_s_setprio(0); } while (0)
; #define PG8_WAIT_V(n) asm volatile("s_waitcnt vmcnt(" #n ")" ::: "memory")
; #define PG8_WAIT_L(n) asm volatile("s_waitcnt lgkmcnt(" #n ")" ::: "memory")
; #define PG8_BAR __builtin_amdgcn_s_barrier()
; #define PG8_SCHED __builtin_amdgcn_sched_barrier(0)
; template <class Epi, class Sched, bool ALIGN_EPI = false, bool SP2 = false>
; __device__ __forceinline__ void gemm_phase(PG8_LAS unsigned char* lds, const Gemm g, const Sched& S, const Epi& E) {
;     ...
;             PG8_WAIT_V(8); PG8_WAIT_L(0); PG8_BAR; PG8_MMA(1, 0, At, B0); PG8_MMA(1, 1, At, B1); PG8_BAR; PG8_SCHED;
;             PG8_LDB(B0, 1, 0); PG8_LDB(B1, 1, 1); PG8_SCHED; PG8_LDA(At, 1, 0); PG8_STAGE(PG8_SA(0, 1), a2 + hstepA, voffA);
;             PG8_WAIT_V(8); PG8_WAIT_L(0); PG8_BAR; PG8_MMA(0, 0, At, B0); PG8_MMA(0, 1, At, B1); PG8_BAR; PG8_SCHED;
	v_mfma_f32_16x16x32_bf16 v[60:63], v[128:131], v[202:205], v[60:63]
	v_mfma_f32_16x16x32_bf16 v[56:59], v[136:139], v[202:205], v[56:59]
	v_mfma_f32_16x16x32_bf16 v[48:51], v[136:139], v[210:213], v[48:51]
	v_mfma_f32_16x16x32_bf16 v[52:55], v[128:131], v[210:213], v[52:55]
	v_mfma_f32_16x16x32_bf16 v[44:47], v[128:131], v[218:221], v[44:47]
	v_mfma_f32_16x16x32_bf16 v[40:43], v[136:139], v[218:221], v[40:43]
	v_mfma_f32_16x16x32_bf16 v[32:35], v[136:139], v[226:229], v[32:35]
	v_mfma_f32_16x16x32_bf16 v[36:39], v[128:131], v[226:229], v[36:39]
	v_mfma_f32_16x16x32_bf16 v[60:63], v[132:135], v[206:209], v[60:63]
	v_mfma_f32_16x16x32_bf16 v[56:59], v[140:143], v[206:209], v[56:59]
	v_mfma_f32_16x16x32_bf16 v[48:51], v[140:143], v[214:217], v[48:51]
	v_mfma_f32_16x16x32_bf16 v[52:55], v[132:135], v[214:217], v[52:55]
	v_mfma_f32_16x16x32_bf16 v[44:47], v[132:135], v[222:225], v[44:47]
	v_mfma_f32_16x16x32_bf16 v[40:43], v[140:143], v[222:225], v[40:43]
	v_mfma_f32_16x16x32_bf16 v[32:35], v[140:143], v[230:233], v[32:35]
	v_mfma_f32_16x16x32_bf16 v[36:39], v[132:135], v[230:233], v[36:39]
	s_setprio 0
	s_setprio 1
	v_mfma_f32_16x16x32_bf16 v[28:31], v[174:177], v[202:205], v[28:31]
	v_mfma_f32_16x16x32_bf16 v[24:27], v[194:197], v[202:205], v[24:27]
	v_mfma_f32_16x16x32_bf16 v[16:19], v[194:197], v[210:213], v[16:19]
	v_mfma_f32_16x16x32_bf16 v[20:23], v[174:177], v[210:213], v[20:23]
	v_mfma_f32_16x16x32_bf16 v[12:15], v[174:177], v[218:221], v[12:15]
	v_mfma_f32_16x16x32_bf16 v[8:11], v[194:197], v[218:221], v[8:11]
	v_mfma_f32_16x16x32_bf16 v[0:3], v[194:197], v[226:229], v[0:3]
	v_mfma_f32_16x16x32_bf16 v[4:7], v[174:177], v[226:229], v[4:7]
	v_mfma_f32_16x16x32_bf16 v[28:31], v[190:193], v[206:209], v[28:31]
	v_mfma_f32_16x16x32_bf16 v[24:27], v[198:201], v[206:209], v[24:27]
	v_mfma_f32_16x16x32_bf16 v[16:19], v[198:201], v[214:217], v[16:19]
	v_mfma_f32_16x16x32_bf16 v[20:23], v[190:193], v[214:217], v[20:23]
	v_mfma_f32_16x16x32_bf16 v[12:15], v[190:193], v[222:225], v[12:15]
	v_mfma_f32_16x16x32_bf16 v[8:11], v[198:201], v[222:225], v[8:11]
	v_mfma_f32_16x16x32_bf16 v[0:3], v[198:201], v[230:233], v[0:3]
	v_mfma_f32_16x16x32_bf16 v[4:7], v[190:193], v[230:233], v[4:7]
	s_barrier
	s_setprio 0
	s_add_i32 s6, 0, 0x18000
	s_add_i32 s7, 0, 0x1c000
	v_add_u32_e32 v140, s6, v179
	v_add_u32_e32 v198, s7, v179
	ds_read_b128 v[128:131], v140
	ds_read_b128 v[132:135], v140 offset:1024
	ds_read_b128 v[136:139], v140 offset:2048
	ds_read_b128 v[140:143], v140 offset:3072
	ds_read_b128 v[174:177], v198
	ds_read_b128 v[190:193], v198 offset:1024
	ds_read_b128 v[194:197], v198 offset:2048
	ds_read_b128 v[198:201], v198 offset:3072
	s_add_u32 s4, vcc_lo, 0x80000
	s_addc_u32 s5, vcc_hi, 0
	s_mov_b32 m0, s96
	v_lshl_add_u64 v[240:241], s[4:5], 0, v[144:145]
	ds_read_b128 v[202:205], v181 offset:32768
	ds_read_b128 v[206:209], v181 offset:33792
	ds_read_b128 v[210:213], v181 offset:34816
	ds_read_b128 v[214:217], v181 offset:35840
	ds_read_b128 v[218:221], v181 offset:36864
	ds_read_b128 v[222:225], v181 offset:37888
	ds_read_b128 v[226:229], v181 offset:38912
	ds_read_b128 v[230:233], v181 offset:39936
	global_load_lds_dwordx4 v[240:241], off
	v_lshl_add_u64 v[240:241], s[4:5], 0, v[148:149]
	s_mov_b32 m0, s97
	s_nop 0
	global_load_lds_dwordx4 v[240:241], off
	s_waitcnt vmcnt(8)
	s_waitcnt lgkmcnt(0)
	s_setprio 1
	s_barrier
	v_mfma_f32_16x16x32_bf16 v[124:127], v[128:131], v[202:205], v[124:127]
	v_mfma_f32_16x16x32_bf16 v[120:123], v[136:139], v[202:205], v[120:123]
	v_mfma_f32_16x16x32_bf16 v[112:115], v[136:139], v[210:213], v[112:115]
	v_mfma_f32_16x16x32_bf16 v[116:119], v[128:131], v[210:213], v[116:119]
	v_mfma_f32_16x16x32_bf16 v[108:111], v[128:131], v[218:221], v[108:111]
	v_mfma_f32_16x16x32_bf16 v[104:107], v[136:139], v[218:221], v[104:107]
	v_mfma_f32_16x16x32_bf16 v[96:99], v[136:139], v[226:229], v[96:99]
	v_mfma_f32_16x16x32_bf16 v[100:103], v[128:131], v[226:229], v[100:103]
	v_mfma_f32_16x16x32_bf16 v[124:127], v[132:135], v[206:209], v[124:127]
	v_mfma_f32_16x16x32_bf16 v[120:123], v[140:143], v[206:209], v[120:123]
	v_mfma_f32_16x16x32_bf16 v[112:115], v[140:143], v[214:217], v[112:115]
	v_mfma_f32_16x16x32_bf16 v[116:119], v[132:135], v[214:217], v[116:119]
	v_mfma_f32_16x16x32_bf16 v[108:111], v[132:135], v[222:225], v[108:111]
	v_mfma_f32_16x16x32_bf16 v[104:107], v[140:143], v[222:225], v[104:107]
	v_mfma_f32_16x16x32_bf16 v[96:99], v[140:143], v[230:233], v[96:99]
	v_mfma_f32_16x16x32_bf16 v[100:103], v[132:135], v[230:233], v[100:103]
	s_setprio 0
	s_setprio 1
	v_mfma_f32_16x16x32_bf16 v[92:95], v[174:177], v[202:205], v[92:95]
	v_mfma_f32_16x16x32_bf16 v[88:91], v[194:197], v[202:205], v[88:91]
	v_mfma_f32_16x16x32_bf16 v[80:83], v[194:197], v[210:213], v[80:83]
	v_mfma_f32_16x16x32_bf16 v[84:87], v[174:177], v[210:213], v[84:87]
	v_mfma_f32_16x16x32_bf16 v[76:79], v[174:177], v[218:221], v[76:79]
	v_mfma_f32_16x16x32_bf16 v[72:75], v[194:197], v[218:221], v[72:75]
	v_mfma_f32_16x16x32_bf16 v[64:67], v[194:197], v[226:229], v[64:67]
	v_mfma_f32_16x16x32_bf16 v[68:71], v[174:177], v[226:229], v[68:71]
	v_mfma_f32_16x16x32_bf16 v[92:95], v[190:193], v[206:209], v[92:95]
	v_mfma_f32_16x16x32_bf16 v[88:91], v[198:201], v[206:209], v[88:91]
	v_mfma_f32_16x16x32_bf16 v[80:83], v[198:201], v[214:217], v[80:83]
	v_mfma_f32_16x16x32_bf16 v[84:87], v[190:193], v[214:217], v[84:87]
	v_mfma_f32_16x16x32_bf16 v[76:79], v[190:193], v[222:225], v[76:79]
	v_mfma_f32_16x16x32_bf16 v[72:75], v[198:201], v[222:225], v[72:75]
	v_mfma_f32_16x16x32_bf16 v[64:67], v[198:201], v[230:233], v[64:67]
	v_mfma_f32_16x16x32_bf16 v[68:71], v[190:193], v[230:233], v[68:71]
	s_barrier
; #define PG8_STAGE(bufoff, gbase, voff) do { _Pragma("unroll") for (int _i = 0; _i < 2; ++_i) \
;         __builtin_amdgcn_global_load_lds((const unsigned*)((const char*)(gbase) + (voff)[_i]), (PG8_LAS unsigned*)(lds + (bufoff) + ldsw + _i * 8192), 16, 0, 0); } while (0)
; #define PG8_LDA(dst, b, h) do { _Pragma("unroll") for (int m = 0; m < 4; ++m) _Pragma("unroll") for (int k = 0; k < 2; ++k) dst[m][k] = *(const PG8_LAS bf16x8*)(lds + PG8_SA(b, h) + aoff + m * 2048 + k * 1024); } while (0)
; #define PG8_MMA(ai, bj, At, Bt) do { __builtin_amdgcn_s_setprio(1); _Pragma("unroll") for (int m = 0; m < 4; ++m) _Pragma("unroll") for (int n = 0; n < 2; ++n) _Pragma("unroll") for (int k = 0; k < 2; ++k) \
;         acc[ai][bj][m][n] = __builtin_amdgcn_mfma_f32_16x16x32_bf16(Bt[n][k], At[m][k], acc[ai][bj][m][n], 0, 0, 0); __builtin_amdgcn_s_setprio(0); } while (0)
; #define PG8_WAIT_V(n) asm volatile("s_waitcnt vmcnt(" #n ")" ::: "memory")
; #define PG8_WAIT_L(n) asm volatile("s_waitcnt lgkmcnt(" #n ")" ::: "memory")
; #define PG8_BAR __builtin_amdgcn_s_barrier()
; #define PG8_SCHED __builtin_amdgcn_sched_barrier(0)
; template <class Epi, class Sched, bool ALIGN_EPI = false, bool SP2 = false>
; __device__ __forceinline__ void gemm_phase(PG8_LAS unsigned char* lds, const Gemm g, const Sched& S, const Epi& E) {
;     ...
;             PG8_LDA(At, 1, 1); PG8_STAGE(PG8_SB(1, 0), b3, voffB); PG8_STAGE(PG8_SB(1, 1), b3 + hstepB, voffB); PG8_STAGE(PG8_SA(1, 0), a3, voffA);
;             PG8_WAIT_V(8); PG8_WAIT_L(0); PG8_BAR; PG8_MMA(1, 0, At, B0); PG8_MMA(1, 1, At, B1); PG8_BAR; PG8_SCHED;
	s_setprio 0
	s_add_i32 s4, s6, s94
	v_lshl_add_u64 v[182:183], v[182:183], 0, s[70:71]
	s_mov_b32 m0, s4
	ds_read_b128 v[202:205], v181 offset:49152
	ds_read_b128 v[206:209], v181 offset:50176
	ds_read_b128 v[210:213], v181 offset:51200
	ds_read_b128 v[214:217], v181 offset:52224
	ds_read_b128 v[218:221], v181 offset:53248
	ds_read_b128 v[222:225], v181 offset:54272
	ds_read_b128 v[226:229], v181 offset:55296
	ds_read_b128 v[230:233], v181 offset:56320
	global_load_lds_dwordx4 v[182:183], off
	s_add_i32 m0, s4, 0x2000
	s_add_u32 s4, s76, 0x80080
	v_lshl_add_u64 v[182:183], v[234:235], 0, s[70:71]
	s_addc_u32 s5, s77, 0
	s_add_i32 s6, s7, s94
	global_load_lds_dwordx4 v[182:183], off
	v_lshl_add_u64 v[182:183], s[4:5], 0, v[146:147]
	s_mov_b32 m0, s6
	s_nop 0
	global_load_lds_dwordx4 v[182:183], off
	v_lshl_add_u64 v[182:183], s[4:5], 0, v[150:151]
	s_add_i32 m0, s6, 0x2000
	s_nop 0
	global_load_lds_dwordx4 v[182:183], off
	v_lshl_add_u64 v[182:183], v[236:237], 0, s[70:71]
	s_mov_b32 m0, s56
	s_nop 0
	global_load_lds_dwordx4 v[182:183], off
	v_lshl_add_u64 v[182:183], v[238:239], 0, s[70:71]
	s_mov_b32 m0, s57
	s_nop 0
	global_load_lds_dwordx4 v[182:183], off
	s_waitcnt vmcnt(8)
	s_waitcnt lgkmcnt(0)
	s_setprio 1
	s_barrier
	v_mfma_f32_16x16x32_bf16 v[60:63], v[128:131], v[202:205], v[60:63]
	v_mfma_f32_16x16x32_bf16 v[56:59], v[136:139], v[202:205], v[56:59]
	v_mfma_f32_16x16x32_bf16 v[48:51], v[136:139], v[210:213], v[48:51]
	v_mfma_f32_16x16x32_bf16 v[52:55], v[128:131], v[210:213], v[52:55]
	v_mfma_f32_16x16x32_bf16 v[44:47], v[128:131], v[218:221], v[44:47]
	v_mfma_f32_16x16x32_bf16 v[40:43], v[136:139], v[218:221], v[40:43]
	v_mfma_f32_16x16x32_bf16 v[32:35], v[136:139], v[226:229], v[32:35]
	v_mfma_f32_16x16x32_bf16 v[36:39], v[128:131], v[226:229], v[36:39]
	v_mfma_f32_16x16x32_bf16 v[60:63], v[132:135], v[206:209], v[60:63]
	v_mfma_f32_16x16x32_bf16 v[56:59], v[140:143], v[206:209], v[56:59]
	v_mfma_f32_16x16x32_bf16 v[48:51], v[140:143], v[214:217], v[48:51]
	v_mfma_f32_16x16x32_bf16 v[52:55], v[132:135], v[214:217], v[52:55]
	v_mfma_f32_16x16x32_bf16 v[44:47], v[132:135], v[222:225], v[44:47]
	v_mfma_f32_16x16x32_bf16 v[40:43], v[140:143], v[222:225], v[40:43]
	v_mfma_f32_16x16x32_bf16 v[32:35], v[140:143], v[230:233], v[32:35]
	v_mfma_f32_16x16x32_bf16 v[36:39], v[132:135], v[230:233], v[36:39]
	s_setprio 0
	s_setprio 1
	v_mfma_f32_16x16x32_bf16 v[28:31], v[174:177], v[202:205], v[28:31]
	v_mfma_f32_16x16x32_bf16 v[24:27], v[194:197], v[202:205], v[24:27]
	v_mfma_f32_16x16x32_bf16 v[16:19], v[194:197], v[210:213], v[16:19]
	v_mfma_f32_16x16x32_bf16 v[20:23], v[174:177], v[210:213], v[20:23]
	v_mfma_f32_16x16x32_bf16 v[12:15], v[174:177], v[218:221], v[12:15]
	v_mfma_f32_16x16x32_bf16 v[8:11], v[194:197], v[218:221], v[8:11]
	v_mfma_f32_16x16x32_bf16 v[0:3], v[194:197], v[226:229], v[0:3]
	v_mfma_f32_16x16x32_bf16 v[4:7], v[174:177], v[226:229], v[4:7]
	v_mfma_f32_16x16x32_bf16 v[28:31], v[190:193], v[206:209], v[28:31]
	v_mfma_f32_16x16x32_bf16 v[24:27], v[198:201], v[206:209], v[24:27]
	v_mfma_f32_16x16x32_bf16 v[16:19], v[198:201], v[214:217], v[16:19]
	v_mfma_f32_16x16x32_bf16 v[20:23], v[190:193], v[214:217], v[20:23]
	v_mfma_f32_16x16x32_bf16 v[12:15], v[190:193], v[222:225], v[12:15]
	v_mfma_f32_16x16x32_bf16 v[8:11], v[198:201], v[222:225], v[8:11]
	v_mfma_f32_16x16x32_bf16 v[0:3], v[198:201], v[230:233], v[0:3]
	v_mfma_f32_16x16x32_bf16 v[4:7], v[190:193], v[230:233], v[4:7]
	s_barrier
	s_setprio 0
	s_cmp_ge_i32 s66, s44
	s_cbranch_scc1 .LBB0_1066

; #define PG8_STAGE(bufoff, gbase, voff) do { _Pragma("unroll") for (int _i = 0; _i < 2; ++_i) \
;         __builtin_amdgcn_global_load_lds((const unsigned*)((const char*)(gbase) + (voff)[_i]), (PG8_LAS unsigned*)(lds + (bufoff) + ldsw + _i * 8192), 16, 0, 0); } while (0)
; #define PG8_LDA(dst, b, h) do { _Pragma("unroll") for (int m = 0; m < 4; ++m) _Pragma("unroll") for (int k = 0; k < 2; ++k) dst[m][k] = *(const PG8_LAS bf16x8*)(lds + PG8_SA(b, h) + aoff + m * 2048 + k * 1024); } while (0)
; #define PG8_LDB(dst, b, h) do { _Pragma("unroll") for (int n = 0; n < 2; ++n) _Pragma("unroll") for (int k = 0; k < 2; ++k) dst[n][k] = *(const PG8_LAS bf16x8*)(lds + PG8_SB(b, h) + boff + n * 2048 + k * 1024); } while (0)
; #define PG8_WAIT_V(n) asm volatile("s_waitcnt vmcnt(" #n ")" ::: "memory")
; #define PG8_WAIT_L(n) asm volatile("s_waitcnt lgkmcnt(" #n ")" ::: "memory")
; template <class Epi, class Sched, bool ALIGN_EPI = false, bool SP2 = false>
; __device__ __forceinline__ void gemm_phase(PG8_LAS unsigned char* lds, const Gemm g, const Sched& S, const Epi& E) {
;     ...
;         const bool has_next = S.next(ui + 1, nxt);
;         const char* nA = has_next ? (const char*)g.A + (size_t)nxt.pm * tstepA + (size_t)nxt.z * g.azs + (size_t)(nxt.k0 >> 6) * kstA : cA; const char* nB = has_next ? (const char*)g.Bt + (size_t)nxt.pn * tstepB + (size_t)nxt.z * g.bzs + (size_t)nxt.k0 * 2 : cB;
;         const int nt = cur.nt;
;         for (int t = 0; t < nt; t += 2) {
;             const bool last = (t == nt - 2);
;             const char* a1 = cA + (size_t)(t + 1) * kstA;
;             const char* a2 = last ? nA : cA + (size_t)(t + 2) * kstA; const char* b2 = last ? nB : cB + (size_t)(t + 2) * kstep;
;             const char* a3 = a2 + kstA; const char* b3 = b2 + kstep;
;             if (last && has_next) S.a_ready(nxt);
;             if constexpr (SP2) {
;             PG8_LDB(B0, 0, 0); PG8_LDB(B1, 0, 1); PG8_SCHED; PG8_LDA(At, 0, 0); PG8_STAGE(PG8_SA(1, 1), a1 + hstepA, voffA);
;             PG8_WAIT_V(8); PG8_WAIT_L(0); PG8_BAR; PG8_MMA(0, 0, At, B0); PG8_MMA(0, 1, At, B1); PG8_BAR; PG8_SCHED;
;             PG8_LDA(At, 0, 1); PG8_STAGE(PG8_SB(0, 0), b2, voffB); PG8_STAGE(PG8_SB(0, 1), b2 + hstepB, voffB); PG8_STAGE(PG8_SA(0, 0), a2, voffA);
;             PG8_WAIT_V(8); PG8_WAIT_L(0); PG8_BAR; PG8_MMA(1, 0, At, B0); PG8_MMA(1, 1, At, B1); PG8_BAR; PG8_SCHED;
.LBB0_1306:
	s_ashr_i32 s41, s40, 31
	s_lshl_b64 s[4:5], s[40:41], 20
	v_readlane_b32 s12, v254, 41
	v_readlane_b32 s13, v254, 42
	s_add_u32 s44, s12, s4
	s_addc_u32 s45, s13, s5
	s_and_b64 s[4:5], s[42:43], exec
	s_cselect_b32 s4, s45, s51
	s_cselect_b32 s5, s44, s50
	s_ashr_i32 s39, s38, 31
	s_lshl_b64 s[12:13], s[38:39], 20
	s_add_u32 s48, s3, s12
	s_addc_u32 s49, s10, s13
	s_and_b64 s[12:13], s[42:43], exec
	s_cselect_b32 s12, s49, s53
	s_cselect_b32 s13, s48, s52
	s_add_u32 s50, s50, 0x80080
	s_addc_u32 s51, s51, 0
	s_add_u32 s39, s52, 0x100
	s_addc_u32 s41, s53, 0
	s_mov_b32 s63, -2
	ds_read_b128 v[156:159], v152
	ds_read_b128 v[160:163], v152 offset:1024
	ds_read_b128 v[164:167], v152 offset:2048
	ds_read_b128 v[168:171], v152 offset:3072
	ds_read_b128 v[172:175], v153
	ds_read_b128 v[176:179], v153 offset:1024
	ds_read_b128 v[180:183], v153 offset:2048
	ds_read_b128 v[190:193], v153 offset:3072
	s_add_u32 s52, s50, 0xfff80080
	s_addc_u32 s53, s51, -1
	s_cmp_eq_u32 s63, 28
	s_cselect_b32 s59, s4, s53
	s_cselect_b32 s58, s5, s52
	s_cselect_b32 s53, s12, s41
	s_cselect_b32 s52, s13, s39
	v_lshl_add_u64 v[226:227], s[50:51], 0, v[142:143]
	s_add_i32 m0, s7, 0xc000
	ds_read_b128 v[194:197], v154
	ds_read_b128 v[198:201], v154 offset:1024
	ds_read_b128 v[202:205], v154 offset:2048
	ds_read_b128 v[206:209], v154 offset:3072
	ds_read_b128 v[210:213], v154 offset:4096
	ds_read_b128 v[214:217], v154 offset:5120
	ds_read_b128 v[218:221], v154 offset:6144
	ds_read_b128 v[222:225], v154 offset:7168
	global_load_lds_dwordx4 v[226:227], off
	v_lshl_add_u64 v[226:227], s[50:51], 0, v[144:145]
	s_add_i32 m0, s7, 0xe000
	s_nop 0
	global_load_lds_dwordx4 v[226:227], off
	s_waitcnt vmcnt(8)
	s_waitcnt lgkmcnt(0)
	s_setprio 1
	s_barrier
	v_mfma_f32_16x16x32_bf16 v[124:127], v[156:159], v[194:197], 0
	v_mfma_f32_16x16x32_bf16 v[120:123], v[164:167], v[194:197], 0
	v_mfma_f32_16x16x32_bf16 v[104:107], v[164:167], v[202:205], 0
	v_mfma_f32_16x16x32_bf16 v[108:111], v[156:159], v[202:205], 0
	v_mfma_f32_16x16x32_bf16 v[92:95], v[156:159], v[210:213], 0
	v_mfma_f32_16x16x32_bf16 v[88:91], v[164:167], v[210:213], 0
	v_mfma_f32_16x16x32_bf16 v[72:75], v[164:167], v[218:221], 0
	v_mfma_f32_16x16x32_bf16 v[76:79], v[156:159], v[218:221], 0
	v_mfma_f32_16x16x32_bf16 v[124:127], v[160:163], v[198:201], v[124:127]
	v_mfma_f32_16x16x32_bf16 v[120:123], v[168:171], v[198:201], v[120:123]
	v_mfma_f32_16x16x32_bf16 v[104:107], v[168:171], v[206:209], v[104:107]
	v_mfma_f32_16x16x32_bf16 v[108:111], v[160:163], v[206:209], v[108:111]
	v_mfma_f32_16x16x32_bf16 v[92:95], v[160:163], v[214:217], v[92:95]
	v_mfma_f32_16x16x32_bf16 v[88:91], v[168:171], v[214:217], v[88:91]
	v_mfma_f32_16x16x32_bf16 v[72:75], v[168:171], v[222:225], v[72:75]
	v_mfma_f32_16x16x32_bf16 v[76:79], v[160:163], v[222:225], v[76:79]
	s_setprio 0
	s_setprio 1
	v_mfma_f32_16x16x32_bf16 v[116:119], v[172:175], v[194:197], 0
	v_mfma_f32_16x16x32_bf16 v[112:115], v[180:183], v[194:197], 0
	v_mfma_f32_16x16x32_bf16 v[96:99], v[180:183], v[202:205], 0
	v_mfma_f32_16x16x32_bf16 v[100:103], v[172:175], v[202:205], 0
	v_mfma_f32_16x16x32_bf16 v[84:87], v[172:175], v[210:213], 0
	v_mfma_f32_16x16x32_bf16 v[80:83], v[180:183], v[210:213], 0
	v_mfma_f32_16x16x32_bf16 v[64:67], v[180:183], v[218:221], 0
	v_mfma_f32_16x16x32_bf16 v[68:71], v[172:175], v[218:221], 0
	v_mfma_f32_16x16x32_bf16 v[116:119], v[176:179], v[198:201], v[116:119]
	v_mfma_f32_16x16x32_bf16 v[112:115], v[190:193], v[198:201], v[112:115]
	v_mfma_f32_16x16x32_bf16 v[96:99], v[190:193], v[206:209], v[96:99]
	v_mfma_f32_16x16x32_bf16 v[100:103], v[176:179], v[206:209], v[100:103]
	v_mfma_f32_16x16x32_bf16 v[84:87], v[176:179], v[214:217], v[84:87]
	v_mfma_f32_16x16x32_bf16 v[80:83], v[190:193], v[214:217], v[80:83]
	v_mfma_f32_16x16x32_bf16 v[64:67], v[190:193], v[222:225], v[64:67]
	v_mfma_f32_16x16x32_bf16 v[68:71], v[176:179], v[222:225], v[68:71]
	s_barrier
	s_setprio 0
	s_add_i32 s64, s57, s6
	v_lshl_add_u64 v[226:227], s[52:53], 0, v[130:131]
	s_mov_b32 m0, s64
	ds_read_b128 v[194:197], v154 offset:16384
	ds_read_b128 v[198:201], v154 offset:17408
	ds_read_b128 v[202:205], v154 offset:18432
	ds_read_b128 v[206:209], v154 offset:19456
	ds_read_b128 v[210:213], v154 offset:20480
	ds_read_b128 v[214:217], v154 offset:21504
	ds_read_b128 v[218:221], v154 offset:22528
	ds_read_b128 v[222:225], v154 offset:23552
	global_load_lds_dwordx4 v[226:227], off
	s_add_i32 m0, s64, 0x2000
	s_add_u32 s64, s52, 0x80000
	v_lshl_add_u64 v[228:229], s[52:53], 0, v[134:135]
	s_addc_u32 s65, s53, 0
	s_add_i32 s66, s61, s6
	global_load_lds_dwordx4 v[228:229], off
	v_lshl_add_u64 v[230:231], s[64:65], 0, v[130:131]
	s_mov_b32 m0, s66
	v_lshl_add_u64 v[232:233], s[58:59], 0, v[132:133]
	global_load_lds_dwordx4 v[230:231], off
	v_lshl_add_u64 v[230:231], s[64:65], 0, v[134:135]
	s_add_i32 m0, s66, 0x2000
	s_nop 0
	global_load_lds_dwordx4 v[230:231], off
	v_lshl_add_u64 v[230:231], s[58:59], 0, v[128:129]
	s_mov_b32 m0, s7
	s_nop 0
	global_load_lds_dwordx4 v[230:231], off
	s_mov_b32 m0, s8
	s_nop 0
	global_load_lds_dwordx4 v[232:233], off
	s_waitcnt vmcnt(8)
	s_waitcnt lgkmcnt(0)
	s_setprio 1
	s_barrier
; #define PG8_STAGE(bufoff, gbase, voff) do { _Pragma("unroll") for (int _i = 0; _i < 2; ++_i) \
;         __builtin_amdgcn_global_load_lds((const unsigned*)((const char*)(gbase) + (voff)[_i]), (PG8_LAS unsigned*)(lds + (bufoff) + ldsw + _i * 8192), 16, 0, 0); } while (0)
; #define PG8_LDA(dst, b, h) do { _Pragma("unroll") for (int m = 0; m < 4; ++m) _Pragma("unroll") for (int k = 0; k < 2; ++k) dst[m][k] = *(const PG8_LAS bf16x8*)(lds + PG8_SA(b, h) + aoff + m * 2048 + k * 1024); } while (0)
; #define PG8_LDB(dst, b, h) do { _Pragma("unroll") for (int n = 0; n < 2; ++n) _Pragma("unroll") for (int k = 0; k < 2; ++k) dst[n][k] = *(const PG8_LAS bf16x8*)(lds + PG8_SB(b, h) + boff + n * 2048 + k * 1024); } while (0)
; #define PG8_MMA(ai, bj, At, Bt) do { __builtin_amdgcn_s_setprio(1); _Pragma("unroll") for (int m = 0; m < 4; ++m) _Pragma("unroll") for (int n = 0; n < 2; ++n) _Pragma("unroll") for (int k = 0; k < 2; ++k) \
;         acc[ai][bj][m][n] = __builtin_amdgcn_mfma_f32_16x16x32_bf16(Bt[n][k], At[m][k], acc[ai][bj][m][n], 0, 0, 0); __builtin_amdgcn_s_setprio(0); } while (0)
; #define PG8_WAIT_V(n) asm volatile("s_waitcnt vmcnt(" #n ")" ::: "memory")
; #define PG8_WAIT_L(n) asm volatile("s_waitcnt lgkmcnt(" #n ")" ::: "memory")
; #define PG8_BAR __builtin_amdgcn_s_barrier()
; #define PG8_SCHED __builtin_amdgcn_sched_barrier(0)
; template <class Epi, class Sched, bool ALIGN_EPI = false, bool SP2 = false>
; __device__ __forceinline__ void gemm_phase(PG8_LAS unsigned char* lds, const Gemm g, const Sched& S, const Epi& E) {
;     ...
;             PG8_WAIT_V(8); PG8_WAIT_L(0); PG8_BAR; PG8_MMA(1, 0, At, B0); PG8_MMA(1, 1, At, B1); PG8_BAR; PG8_SCHED;
;             PG8_LDB(B0, 1, 0); PG8_LDB(B1, 1, 1); PG8_SCHED; PG8_LDA(At, 1, 0); PG8_STAGE(PG8_SA(0, 1), a2 + hstepA, voffA);
;             PG8_WAIT_V(8); PG8_WAIT_L(0); PG8_BAR; PG8_MMA(0, 0, At, B0); PG8_MMA(0, 1, At, B1); PG8_BAR; PG8_SCHED;
	v_mfma_f32_16x16x32_bf16 v[60:63], v[156:159], v[194:197], 0
	v_mfma_f32_16x16x32_bf16 v[56:59], v[164:167], v[194:197], 0
	v_mfma_f32_16x16x32_bf16 v[40:43], v[164:167], v[202:205], 0
	v_mfma_f32_16x16x32_bf16 v[44:47], v[156:159], v[202:205], 0
	v_mfma_f32_16x16x32_bf16 v[28:31], v[156:159], v[210:213], 0
	v_mfma_f32_16x16x32_bf16 v[24:27], v[164:167], v[210:213], 0
	v_mfma_f32_16x16x32_bf16 v[8:11], v[164:167], v[218:221], 0
	v_mfma_f32_16x16x32_bf16 v[12:15], v[156:159], v[218:221], 0
	v_mfma_f32_16x16x32_bf16 v[60:63], v[160:163], v[198:201], v[60:63]
	v_mfma_f32_16x16x32_bf16 v[56:59], v[168:171], v[198:201], v[56:59]
	v_mfma_f32_16x16x32_bf16 v[40:43], v[168:171], v[206:209], v[40:43]
	v_mfma_f32_16x16x32_bf16 v[44:47], v[160:163], v[206:209], v[44:47]
	v_mfma_f32_16x16x32_bf16 v[28:31], v[160:163], v[214:217], v[28:31]
	v_mfma_f32_16x16x32_bf16 v[24:27], v[168:171], v[214:217], v[24:27]
	v_mfma_f32_16x16x32_bf16 v[8:11], v[168:171], v[222:225], v[8:11]
	v_mfma_f32_16x16x32_bf16 v[12:15], v[160:163], v[222:225], v[12:15]
	s_setprio 0
	s_setprio 1
	v_mfma_f32_16x16x32_bf16 v[52:55], v[172:175], v[194:197], 0
	v_mfma_f32_16x16x32_bf16 v[48:51], v[180:183], v[194:197], 0
	v_mfma_f32_16x16x32_bf16 v[32:35], v[180:183], v[202:205], 0
	v_mfma_f32_16x16x32_bf16 v[36:39], v[172:175], v[202:205], 0
	v_mfma_f32_16x16x32_bf16 v[20:23], v[172:175], v[210:213], 0
	v_mfma_f32_16x16x32_bf16 v[16:19], v[180:183], v[210:213], 0
	v_mfma_f32_16x16x32_bf16 v[0:3], v[180:183], v[218:221], 0
	v_mfma_f32_16x16x32_bf16 v[4:7], v[172:175], v[218:221], 0
	v_mfma_f32_16x16x32_bf16 v[52:55], v[176:179], v[198:201], v[52:55]
	v_mfma_f32_16x16x32_bf16 v[48:51], v[190:193], v[198:201], v[48:51]
	v_mfma_f32_16x16x32_bf16 v[32:35], v[190:193], v[206:209], v[32:35]
	v_mfma_f32_16x16x32_bf16 v[36:39], v[176:179], v[206:209], v[36:39]
	v_mfma_f32_16x16x32_bf16 v[20:23], v[176:179], v[214:217], v[20:23]
	v_mfma_f32_16x16x32_bf16 v[16:19], v[190:193], v[214:217], v[16:19]
	v_mfma_f32_16x16x32_bf16 v[0:3], v[190:193], v[222:225], v[0:3]
	v_mfma_f32_16x16x32_bf16 v[4:7], v[176:179], v[222:225], v[4:7]
	s_barrier
	s_setprio 0
	s_add_i32 s64, 0, 0x18000
	v_add_u32_e32 v155, s64, v150
	s_add_i32 s65, 0, 0x1c000
	ds_read_b128 v[156:159], v155
	ds_read_b128 v[160:163], v155 offset:1024
	ds_read_b128 v[164:167], v155 offset:2048
	ds_read_b128 v[168:171], v155 offset:3072
	v_add_u32_e32 v155, s65, v150
	ds_read_b128 v[172:175], v155
	ds_read_b128 v[176:179], v155 offset:1024
	ds_read_b128 v[180:183], v155 offset:2048
	ds_read_b128 v[190:193], v155 offset:3072
	s_add_u32 s58, s58, 0x80000
	s_addc_u32 s59, s59, 0
	s_mov_b32 m0, s9
	v_lshl_add_u64 v[234:235], s[58:59], 0, v[128:129]
	ds_read_b128 v[194:197], v154 offset:32768
	ds_read_b128 v[198:201], v154 offset:33792
	ds_read_b128 v[202:205], v154 offset:34816
	ds_read_b128 v[206:209], v154 offset:35840
	ds_read_b128 v[210:213], v154 offset:36864
	ds_read_b128 v[214:217], v154 offset:37888
	ds_read_b128 v[218:221], v154 offset:38912
	ds_read_b128 v[222:225], v154 offset:39936
	global_load_lds_dwordx4 v[234:235], off
	v_lshl_add_u64 v[234:235], s[58:59], 0, v[132:133]
	s_mov_b32 m0, s11
	s_nop 0
	global_load_lds_dwordx4 v[234:235], off
	s_waitcnt vmcnt(8)
	s_waitcnt lgkmcnt(0)
	s_setprio 1
	s_barrier
	v_mfma_f32_16x16x32_bf16 v[124:127], v[156:159], v[194:197], v[124:127]
	v_mfma_f32_16x16x32_bf16 v[120:123], v[164:167], v[194:197], v[120:123]
	v_mfma_f32_16x16x32_bf16 v[104:107], v[164:167], v[202:205], v[104:107]
	v_mfma_f32_16x16x32_bf16 v[108:111], v[156:159], v[202:205], v[108:111]
	v_mfma_f32_16x16x32_bf16 v[92:95], v[156:159], v[210:213], v[92:95]
	v_mfma_f32_16x16x32_bf16 v[88:91], v[164:167], v[210:213], v[88:91]
	v_mfma_f32_16x16x32_bf16 v[72:75], v[164:167], v[218:221], v[72:75]
	v_mfma_f32_16x16x32_bf16 v[76:79], v[156:159], v[218:221], v[76:79]
	v_mfma_f32_16x16x32_bf16 v[124:127], v[160:163], v[198:201], v[124:127]
	v_mfma_f32_16x16x32_bf16 v[120:123], v[168:171], v[198:201], v[120:123]
	v_mfma_f32_16x16x32_bf16 v[104:107], v[168:171], v[206:209], v[104:107]
	v_mfma_f32_16x16x32_bf16 v[108:111], v[160:163], v[206:209], v[108:111]
	v_mfma_f32_16x16x32_bf16 v[92:95], v[160:163], v[214:217], v[92:95]
	v_mfma_f32_16x16x32_bf16 v[88:91], v[168:171], v[214:217], v[88:91]
	v_mfma_f32_16x16x32_bf16 v[72:75], v[168:171], v[222:225], v[72:75]
	v_mfma_f32_16x16x32_bf16 v[76:79], v[160:163], v[222:225], v[76:79]
	s_setprio 0
	s_setprio 1
	v_mfma_f32_16x16x32_bf16 v[116:119], v[172:175], v[194:197], v[116:119]
	v_mfma_f32_16x16x32_bf16 v[112:115], v[180:183], v[194:197], v[112:115]
	v_mfma_f32_16x16x32_bf16 v[96:99], v[180:183], v[202:205], v[96:99]
	v_mfma_f32_16x16x32_bf16 v[100:103], v[172:175], v[202:205], v[100:103]
	v_mfma_f32_16x16x32_bf16 v[84:87], v[172:175], v[210:213], v[84:87]
	v_mfma_f32_16x16x32_bf16 v[80:83], v[180:183], v[210:213], v[80:83]
	v_mfma_f32_16x16x32_bf16 v[64:67], v[180:183], v[218:221], v[64:67]
	v_mfma_f32_16x16x32_bf16 v[68:71], v[172:175], v[218:221], v[68:71]
	v_mfma_f32_16x16x32_bf16 v[116:119], v[176:179], v[198:201], v[116:119]
	v_mfma_f32_16x16x32_bf16 v[112:115], v[190:193], v[198:201], v[112:115]
	v_mfma_f32_16x16x32_bf16 v[96:99], v[190:193], v[206:209], v[96:99]
	v_mfma_f32_16x16x32_bf16 v[100:103], v[176:179], v[206:209], v[100:103]
	v_mfma_f32_16x16x32_bf16 v[84:87], v[176:179], v[214:217], v[84:87]
	v_mfma_f32_16x16x32_bf16 v[80:83], v[190:193], v[214:217], v[80:83]
	v_mfma_f32_16x16x32_bf16 v[64:67], v[190:193], v[222:225], v[64:67]
	v_mfma_f32_16x16x32_bf16 v[68:71], v[176:179], v[222:225], v[68:71]
	s_barrier
; #define PG8_STAGE(bufoff, gbase, voff) do { _Pragma("unroll") for (int _i = 0; _i < 2; ++_i) \
;         __builtin_amdgcn_global_load_lds((const unsigned*)((const char*)(gbase) + (voff)[_i]), (PG8_LAS unsigned*)(lds + (bufoff) + ldsw + _i * 8192), 16, 0, 0); } while (0)
; #define PG8_LDA(dst, b, h) do { _Pragma("unroll") for (int m = 0; m < 4; ++m) _Pragma("unroll") for (int k = 0; k < 2; ++k) dst[m][k] = *(const PG8_LAS bf16x8*)(lds + PG8_SA(b, h) + aoff + m * 2048 + k * 1024); } while (0)
; #define PG8_LDB(dst, b, h) do { _Pragma("unroll") for (int n = 0; n < 2; ++n) _Pragma("unroll") for (int k = 0; k < 2; ++k) dst[n][k] = *(const PG8_LAS bf16x8*)(lds + PG8_SB(b, h) + boff + n * 2048 + k * 1024); } while (0)
; template <class Epi, class Sched, bool ALIGN_EPI = false, bool SP2 = false>
; __device__ __forceinline__ void gemm_phase(PG8_LAS unsigned char* lds, const Gemm g, const Sched& S, const Epi& E) {
;     ...
;         for (int t = 0; t < nt; t += 2) {
;             const bool last = (t == nt - 2);
;             const char* a1 = cA + (size_t)(t + 1) * kstA;
;             const char* a2 = last ? nA : cA + (size_t)(t + 2) * kstA; const char* b2 = last ? nB : cB + (size_t)(t + 2) * kstep;
;             const char* a3 = a2 + kstA; const char* b3 = b2 + kstep;
;             if (last && has_next) S.a_ready(nxt);
;             if constexpr (SP2) {
;             PG8_LDB(B0, 0, 0); PG8_LDB(B1, 0, 1); PG8_SCHED; PG8_LDA(At, 0, 0); PG8_STAGE(PG8_SA(1, 1), a1 + hstepA, voffA);
;             PG8_WAIT_V(8); PG8_WAIT_L(0); PG8_BAR; PG8_MMA(0, 0, At, B0); PG8_MMA(0, 1, At, B1); PG8_BAR; PG8_SCHED;
;             PG8_LDA(At, 0, 1); PG8_STAGE(PG8_SB(0, 0), b2, voffB); PG8_STAGE(PG8_SB(0, 1), b2 + hstepB, voffB); PG8_STAGE(PG8_SA(0, 0), a2, voffA);
;             PG8_WAIT_V(8); PG8_WAIT_L(0); PG8_BAR; PG8_MMA(1, 0, At, B0); PG8_MMA(1, 1, At, B1); PG8_BAR; PG8_SCHED;
;             PG8_LDB(B0, 1, 0); PG8_LDB(B1, 1, 1); PG8_SCHED; PG8_LDA(At, 1, 0); PG8_STAGE(PG8_SA(0, 1), a2 + hstepA, voffA);
;             PG8_WAIT_V(8); PG8_WAIT_L(0); PG8_BAR; PG8_MMA(0, 0, At, B0); PG8_MMA(0, 1, At, B1); PG8_BAR; PG8_SCHED;
;             PG8_LDA(At, 1, 1); PG8_STAGE(PG8_SB(1, 0), b3, voffB); PG8_STAGE(PG8_SB(1, 1), b3 + hstepB, voffB); PG8_STAGE(PG8_SA(1, 0), a3, voffA);
;             PG8_WAIT_V(8); PG8_WAIT_L(0); PG8_BAR; PG8_MMA(1, 0, At, B0); PG8_MMA(1, 1, At, B1); PG8_BAR; PG8_SCHED;
	s_setprio 0
	s_add_i32 s58, s64, s6
	v_lshl_add_u64 v[226:227], v[226:227], 0, s[20:21]
	s_mov_b32 m0, s58
	ds_read_b128 v[194:197], v154 offset:49152
	ds_read_b128 v[198:201], v154 offset:50176
	ds_read_b128 v[202:205], v154 offset:51200
	ds_read_b128 v[206:209], v154 offset:52224
	ds_read_b128 v[210:213], v154 offset:53248
	ds_read_b128 v[214:217], v154 offset:54272
	ds_read_b128 v[218:221], v154 offset:55296
	ds_read_b128 v[222:225], v154 offset:56320
	global_load_lds_dwordx4 v[226:227], off
	s_add_i32 m0, s58, 0x2000
	s_add_u32 s52, s52, 0x80080
	v_lshl_add_u64 v[226:227], v[228:229], 0, s[20:21]
	s_addc_u32 s53, s53, 0
	s_add_i32 s58, s65, s6
	global_load_lds_dwordx4 v[226:227], off
	v_lshl_add_u64 v[226:227], s[52:53], 0, v[130:131]
	s_mov_b32 m0, s58
	s_nop 0
	global_load_lds_dwordx4 v[226:227], off
	v_lshl_add_u64 v[226:227], s[52:53], 0, v[134:135]
	s_add_i32 m0, s58, 0x2000
	s_nop 0
	global_load_lds_dwordx4 v[226:227], off
	v_lshl_add_u64 v[226:227], v[230:231], 0, s[20:21]
	s_mov_b32 m0, s55
	s_nop 0
	global_load_lds_dwordx4 v[226:227], off
	v_lshl_add_u64 v[226:227], v[232:233], 0, s[20:21]
	s_mov_b32 m0, s56
	s_nop 0
	global_load_lds_dwordx4 v[226:227], off
	s_waitcnt vmcnt(8)
	s_waitcnt lgkmcnt(0)
	s_setprio 1
	s_barrier
	v_mfma_f32_16x16x32_bf16 v[60:63], v[156:159], v[194:197], v[60:63]
	v_mfma_f32_16x16x32_bf16 v[56:59], v[164:167], v[194:197], v[56:59]
	v_mfma_f32_16x16x32_bf16 v[40:43], v[164:167], v[202:205], v[40:43]
	v_mfma_f32_16x16x32_bf16 v[44:47], v[156:159], v[202:205], v[44:47]
	v_mfma_f32_16x16x32_bf16 v[28:31], v[156:159], v[210:213], v[28:31]
	v_mfma_f32_16x16x32_bf16 v[24:27], v[164:167], v[210:213], v[24:27]
	v_mfma_f32_16x16x32_bf16 v[8:11], v[164:167], v[218:221], v[8:11]
	v_mfma_f32_16x16x32_bf16 v[12:15], v[156:159], v[218:221], v[12:15]
	v_mfma_f32_16x16x32_bf16 v[60:63], v[160:163], v[198:201], v[60:63]
	v_mfma_f32_16x16x32_bf16 v[56:59], v[168:171], v[198:201], v[56:59]
	v_mfma_f32_16x16x32_bf16 v[40:43], v[168:171], v[206:209], v[40:43]
	v_mfma_f32_16x16x32_bf16 v[44:47], v[160:163], v[206:209], v[44:47]
	v_mfma_f32_16x16x32_bf16 v[28:31], v[160:163], v[214:217], v[28:31]
	v_mfma_f32_16x16x32_bf16 v[24:27], v[168:171], v[214:217], v[24:27]
	v_mfma_f32_16x16x32_bf16 v[8:11], v[168:171], v[222:225], v[8:11]
	v_mfma_f32_16x16x32_bf16 v[12:15], v[160:163], v[222:225], v[12:15]
	s_setprio 0
	s_setprio 1
	v_mfma_f32_16x16x32_bf16 v[52:55], v[172:175], v[194:197], v[52:55]
	v_mfma_f32_16x16x32_bf16 v[48:51], v[180:183], v[194:197], v[48:51]
	v_mfma_f32_16x16x32_bf16 v[32:35], v[180:183], v[202:205], v[32:35]
	v_mfma_f32_16x16x32_bf16 v[36:39], v[172:175], v[202:205], v[36:39]
	v_mfma_f32_16x16x32_bf16 v[20:23], v[172:175], v[210:213], v[20:23]
	v_mfma_f32_16x16x32_bf16 v[16:19], v[180:183], v[210:213], v[16:19]
	v_mfma_f32_16x16x32_bf16 v[0:3], v[180:183], v[218:221], v[0:3]
	v_mfma_f32_16x16x32_bf16 v[4:7], v[172:175], v[218:221], v[4:7]
	v_mfma_f32_16x16x32_bf16 v[52:55], v[176:179], v[198:201], v[52:55]
	v_mfma_f32_16x16x32_bf16 v[48:51], v[190:193], v[198:201], v[48:51]
	v_mfma_f32_16x16x32_bf16 v[32:35], v[190:193], v[206:209], v[32:35]
	v_mfma_f32_16x16x32_bf16 v[36:39], v[176:179], v[206:209], v[36:39]
	v_mfma_f32_16x16x32_bf16 v[20:23], v[176:179], v[214:217], v[20:23]
	v_mfma_f32_16x16x32_bf16 v[16:19], v[190:193], v[214:217], v[16:19]
	v_mfma_f32_16x16x32_bf16 v[0:3], v[190:193], v[222:225], v[0:3]
	v_mfma_f32_16x16x32_bf16 v[4:7], v[176:179], v[222:225], v[4:7]
	s_barrier
	s_setprio 0
	s_add_i32 s63, s63, 2
	s_add_u32 s50, s50, 0x100
	s_addc_u32 s51, s51, 0
	s_add_u32 s39, s39, 0x100
	s_addc_u32 s41, s41, 0
	s_cmp_gt_u32 s63, 29
	s_cbranch_scc1 .Lmy_peel_5_exit
.LBB0_1307:
	ds_read_b128 v[156:159], v152
	ds_read_b128 v[160:163], v152 offset:1024
	ds_read_b128 v[164:167], v152 offset:2048
	ds_read_b128 v[168:171], v152 offset:3072
	ds_read_b128 v[172:175], v153
	ds_read_b128 v[176:179], v153 offset:1024
	ds_read_b128 v[180:183], v153 offset:2048
	ds_read_b128 v[190:193], v153 offset:3072
	s_add_u32 s52, s50, 0xfff80080
	s_addc_u32 s53, s51, -1
	s_cmp_eq_u32 s63, 28
	s_cselect_b32 s59, s4, s53
	s_cselect_b32 s58, s5, s52
	s_cselect_b32 s53, s12, s41
	s_cselect_b32 s52, s13, s39
	v_lshl_add_u64 v[226:227], s[50:51], 0, v[142:143]
	s_add_i32 m0, s7, 0xc000
	ds_read_b128 v[194:197], v154
	ds_read_b128 v[198:201], v154 offset:1024
	ds_read_b128 v[202:205], v154 offset:2048
	ds_read_b128 v[206:209], v154 offset:3072
	ds_read_b128 v[210:213], v154 offset:4096
	ds_read_b128 v[214:217], v154 offset:5120
	ds_read_b128 v[218:221], v154 offset:6144
	ds_read_b128 v[222:225], v154 offset:7168
	global_load_lds_dwordx4 v[226:227], off
	v_lshl_add_u64 v[226:227], s[50:51], 0, v[144:145]
	s_add_i32 m0, s7, 0xe000
	s_nop 0
	global_load_lds_dwordx4 v[226:227], off
	s_waitcnt vmcnt(8)
	s_waitcnt lgkmcnt(0)
	s_setprio 1
	s_barrier
; #define PG8_STAGE(bufoff, gbase, voff) do { _Pragma("unroll") for (int _i = 0; _i < 2; ++_i) \
;         __builtin_amdgcn_global_load_lds((const unsigned*)((const char*)(gbase) + (voff)[_i]), (PG8_LAS unsigned*)(lds + (bufoff) + ldsw + _i * 8192), 16, 0, 0); } while (0)
; #define PG8_LDA(dst, b, h) do { _Pragma("unroll") for (int m = 0; m < 4; ++m) _Pragma("unroll") for (int k = 0; k < 2; ++k) dst[m][k] = *(const PG8_LAS bf16x8*)(lds + PG8_SA(b, h) + aoff + m * 2048 + k * 1024); } while (0)
; #define PG8_LDB(dst, b, h) do { _Pragma("unroll") for (int n = 0; n < 2; ++n) _Pragma("unroll") for (int k = 0; k < 2; ++k) dst[n][k] = *(const PG8_LAS bf16x8*)(lds + PG8_SB(b, h) + boff + n * 2048 + k * 1024); } while (0)
; #define PG8_MMA(ai, bj, At, Bt) do { __builtin_amdgcn_s_setprio(1); _Pragma("unroll") for (int m = 0; m < 4; ++m) _Pragma("unroll") for (int n = 0; n < 2; ++n) _Pragma("unroll") for (int k = 0; k < 2; ++k) \
;         acc[ai][bj][m][n] = __builtin_amdgcn_mfma_f32_16x16x32_bf16(Bt[n][k], At[m][k], acc[ai][bj][m][n], 0, 0, 0); __builtin_amdgcn_s_setprio(0); } while (0)
; #define PG8_WAIT_V(n) asm volatile("s_waitcnt vmcnt(" #n ")" ::: "memory")
; #define PG8_WAIT_L(n) asm volatile("s_waitcnt lgkmcnt(" #n ")" ::: "memory")
; #define PG8_BAR __builtin_amdgcn_s_barrier()
; #define PG8_SCHED __builtin_amdgcn_sched_barrier(0)
; template <class Epi, class Sched, bool ALIGN_EPI = false, bool SP2 = false>
; __device__ __forceinline__ void gemm_phase(PG8_LAS unsigned char* lds, const Gemm g, const Sched& S, const Epi& E) {
;     ...
;             PG8_LDB(B0, 0, 0); PG8_LDB(B1, 0, 1); PG8_SCHED; PG8_LDA(At, 0, 0); PG8_STAGE(PG8_SA(1, 1), a1 + hstepA, voffA);
;             PG8_WAIT_V(8); PG8_WAIT_L(0); PG8_BAR; PG8_MMA(0, 0, At, B0); PG8_MMA(0, 1, At, B1); PG8_BAR; PG8_SCHED;
;             PG8_LDA(At, 0, 1); PG8_STAGE(PG8_SB(0, 0), b2, voffB); PG8_STAGE(PG8_SB(0, 1), b2 + hstepB, voffB); PG8_STAGE(PG8_SA(0, 0), a2, voffA);
;             PG8_WAIT_V(8); PG8_WAIT_L(0); PG8_BAR; PG8_MMA(1, 0, At, B0); PG8_MMA(1, 1, At, B1); PG8_BAR; PG8_SCHED;
	v_mfma_f32_16x16x32_bf16 v[124:127], v[156:159], v[194:197], v[124:127]
	v_mfma_f32_16x16x32_bf16 v[120:123], v[164:167], v[194:197], v[120:123]
	v_mfma_f32_16x16x32_bf16 v[104:107], v[164:167], v[202:205], v[104:107]
	v_mfma_f32_16x16x32_bf16 v[108:111], v[156:159], v[202:205], v[108:111]
	v_mfma_f32_16x16x32_bf16 v[92:95], v[156:159], v[210:213], v[92:95]
	v_mfma_f32_16x16x32_bf16 v[88:91], v[164:167], v[210:213], v[88:91]
	v_mfma_f32_16x16x32_bf16 v[72:75], v[164:167], v[218:221], v[72:75]
	v_mfma_f32_16x16x32_bf16 v[76:79], v[156:159], v[218:221], v[76:79]
	v_mfma_f32_16x16x32_bf16 v[124:127], v[160:163], v[198:201], v[124:127]
	v_mfma_f32_16x16x32_bf16 v[120:123], v[168:171], v[198:201], v[120:123]
	v_mfma_f32_16x16x32_bf16 v[104:107], v[168:171], v[206:209], v[104:107]
	v_mfma_f32_16x16x32_bf16 v[108:111], v[160:163], v[206:209], v[108:111]
	v_mfma_f32_16x16x32_bf16 v[92:95], v[160:163], v[214:217], v[92:95]
	v_mfma_f32_16x16x32_bf16 v[88:91], v[168:171], v[214:217], v[88:91]
	v_mfma_f32_16x16x32_bf16 v[72:75], v[168:171], v[222:225], v[72:75]
	v_mfma_f32_16x16x32_bf16 v[76:79], v[160:163], v[222:225], v[76:79]
	s_setprio 0
	s_setprio 1
	v_mfma_f32_16x16x32_bf16 v[116:119], v[172:175], v[194:197], v[116:119]
	v_mfma_f32_16x16x32_bf16 v[112:115], v[180:183], v[194:197], v[112:115]
	v_mfma_f32_16x16x32_bf16 v[96:99], v[180:183], v[202:205], v[96:99]
	v_mfma_f32_16x16x32_bf16 v[100:103], v[172:175], v[202:205], v[100:103]
	v_mfma_f32_16x16x32_bf16 v[84:87], v[172:175], v[210:213], v[84:87]
	v_mfma_f32_16x16x32_bf16 v[80:83], v[180:183], v[210:213], v[80:83]
	v_mfma_f32_16x16x32_bf16 v[64:67], v[180:183], v[218:221], v[64:67]
	v_mfma_f32_16x16x32_bf16 v[68:71], v[172:175], v[218:221], v[68:71]
	v_mfma_f32_16x16x32_bf16 v[116:119], v[176:179], v[198:201], v[116:119]
	v_mfma_f32_16x16x32_bf16 v[112:115], v[190:193], v[198:201], v[112:115]
	v_mfma_f32_16x16x32_bf16 v[96:99], v[190:193], v[206:209], v[96:99]
	v_mfma_f32_16x16x32_bf16 v[100:103], v[176:179], v[206:209], v[100:103]
	v_mfma_f32_16x16x32_bf16 v[84:87], v[176:179], v[214:217], v[84:87]
	v_mfma_f32_16x16x32_bf16 v[80:83], v[190:193], v[214:217], v[80:83]
	v_mfma_f32_16x16x32_bf16 v[64:67], v[190:193], v[222:225], v[64:67]
	v_mfma_f32_16x16x32_bf16 v[68:71], v[176:179], v[222:225], v[68:71]
	s_barrier
	s_setprio 0
	s_add_i32 s64, s57, s6
	v_lshl_add_u64 v[226:227], s[52:53], 0, v[130:131]
	s_mov_b32 m0, s64
	ds_read_b128 v[194:197], v154 offset:16384
	ds_read_b128 v[198:201], v154 offset:17408
	ds_read_b128 v[202:205], v154 offset:18432
	ds_read_b128 v[206:209], v154 offset:19456
	ds_read_b128 v[210:213], v154 offset:20480
	ds_read_b128 v[214:217], v154 offset:21504
	ds_read_b128 v[218:221], v154 offset:22528
	ds_read_b128 v[222:225], v154 offset:23552
	global_load_lds_dwordx4 v[226:227], off
	s_add_i32 m0, s64, 0x2000
	s_add_u32 s64, s52, 0x80000
	v_lshl_add_u64 v[228:229], s[52:53], 0, v[134:135]
	s_addc_u32 s65, s53, 0
	s_add_i32 s66, s61, s6
	global_load_lds_dwordx4 v[228:229], off
	v_lshl_add_u64 v[230:231], s[64:65], 0, v[130:131]
	s_mov_b32 m0, s66
	v_lshl_add_u64 v[232:233], s[58:59], 0, v[132:133]
	global_load_lds_dwordx4 v[230:231], off
	v_lshl_add_u64 v[230:231], s[64:65], 0, v[134:135]
	s_add_i32 m0, s66, 0x2000
	s_nop 0
	global_load_lds_dwordx4 v[230:231], off
	v_lshl_add_u64 v[230:231], s[58:59], 0, v[128:129]
	s_mov_b32 m0, s7
	s_nop 0
	global_load_lds_dwordx4 v[230:231], off
	s_mov_b32 m0, s8
	s_nop 0
	global_load_lds_dwordx4 v[232:233], off
	s_waitcnt vmcnt(8)
	s_waitcnt lgkmcnt(0)
	s_setprio 1
	s_barrier
	v_mfma_f32_16x16x32_bf16 v[60:63], v[156:159], v[194:197], v[60:63]
	v_mfma_f32_16x16x32_bf16 v[56:59], v[164:167], v[194:197], v[56:59]
	v_mfma_f32_16x16x32_bf16 v[40:43], v[164:167], v[202:205], v[40:43]
	v_mfma_f32_16x16x32_bf16 v[44:47], v[156:159], v[202:205], v[44:47]
	v_mfma_f32_16x16x32_bf16 v[28:31], v[156:159], v[210:213], v[28:31]
	v_mfma_f32_16x16x32_bf16 v[24:27], v[164:167], v[210:213], v[24:27]
	v_mfma_f32_16x16x32_bf16 v[8:11], v[164:167], v[218:221], v[8:11]
	v_mfma_f32_16x16x32_bf16 v[12:15], v[156:159], v[218:221], v[12:15]
	v_mfma_f32_16x16x32_bf16 v[60:63], v[160:163], v[198:201], v[60:63]
	v_mfma_f32_16x16x32_bf16 v[56:59], v[168:171], v[198:201], v[56:59]
	v_mfma_f32_16x16x32_bf16 v[40:43], v[168:171], v[206:209], v[40:43]
	v_mfma_f32_16x16x32_bf16 v[44:47], v[160:163], v[206:209], v[44:47]
	v_mfma_f32_16x16x32_bf16 v[28:31], v[160:163], v[214:217], v[28:31]
	v_mfma_f32_16x16x32_bf16 v[24:27], v[168:171], v[214:217], v[24:27]
	v_mfma_f32_16x16x32_bf16 v[8:11], v[168:171], v[222:225], v[8:11]
	v_mfma_f32_16x16x32_bf16 v[12:15], v[160:163], v[222:225], v[12:15]
	s_setprio 0
	s_setprio 1
	v_mfma_f32_16x16x32_bf16 v[52:55], v[172:175], v[194:197], v[52:55]
	v_mfma_f32_16x16x32_bf16 v[48:51], v[180:183], v[194:197], v[48:51]
	v_mfma_f32_16x16x32_bf16 v[32:35], v[180:183], v[202:205], v[32:35]
	v_mfma_f32_16x16x32_bf16 v[36:39], v[172:175], v[202:205], v[36:39]
	v_mfma_f32_16x16x32_bf16 v[20:23], v[172:175], v[210:213], v[20:23]
	v_mfma_f32_16x16x32_bf16 v[16:19], v[180:183], v[210:213], v[16:19]
	v_mfma_f32_16x16x32_bf16 v[0:3], v[180:183], v[218:221], v[0:3]
	v_mfma_f32_16x16x32_bf16 v[4:7], v[172:175], v[218:221], v[4:7]
	v_mfma_f32_16x16x32_bf16 v[52:55], v[176:179], v[198:201], v[52:55]
	v_mfma_f32_16x16x32_bf16 v[48:51], v[190:193], v[198:201], v[48:51]
	v_mfma_f32_16x16x32_bf16 v[32:35], v[190:193], v[206:209], v[32:35]
	v_mfma_f32_16x16x32_bf16 v[36:39], v[176:179], v[206:209], v[36:39]
	v_mfma_f32_16x16x32_bf16 v[20:23], v[176:179], v[214:217], v[20:23]
	v_mfma_f32_16x16x32_bf16 v[16:19], v[190:193], v[214:217], v[16:19]
	v_mfma_f32_16x16x32_bf16 v[0:3], v[190:193], v[222:225], v[0:3]
	v_mfma_f32_16x16x32_bf16 v[4:7], v[176:179], v[222:225], v[4:7]
	s_barrier
; #define PG8_STAGE(bufoff, gbase, voff) do { _Pragma("unroll") for (int _i = 0; _i < 2; ++_i) \
;         __builtin_amdgcn_global_load_lds((const unsigned*)((const char*)(gbase) + (voff)[_i]), (PG8_LAS unsigned*)(lds + (bufoff) + ldsw + _i * 8192), 16, 0, 0); } while (0)
; #define PG8_LDA(dst, b, h) do { _Pragma("unroll") for (int m = 0; m < 4; ++m) _Pragma("unroll") for (int k = 0; k < 2; ++k) dst[m][k] = *(const PG8_LAS bf16x8*)(lds + PG8_SA(b, h) + aoff + m * 2048 + k * 1024); } while (0)
; #define PG8_LDB(dst, b, h) do { _Pragma("unroll") for (int n = 0; n < 2; ++n) _Pragma("unroll") for (int k = 0; k < 2; ++k) dst[n][k] = *(const PG8_LAS bf16x8*)(lds + PG8_SB(b, h) + boff + n * 2048 + k * 1024); } while (0)
; #define PG8_MMA(ai, bj, At, Bt) do { __builtin_amdgcn_s_setprio(1); _Pragma("unroll") for (int m = 0; m < 4; ++m) _Pragma("unroll") for (int n = 0; n < 2; ++n) _Pragma("unroll") for (int k = 0; k < 2; ++k) \
;         acc[ai][bj][m][n] = __builtin_amdgcn_mfma_f32_16x16x32_bf16(Bt[n][k], At[m][k], acc[ai][bj][m][n], 0, 0, 0); __builtin_amdgcn_s_setprio(0); } while (0)
; #define PG8_WAIT_V(n) asm volatile("s_waitcnt vmcnt(" #n ")" ::: "memory")
; #define PG8_WAIT_L(n) asm volatile("s_waitcnt lgkmcnt(" #n ")" ::: "memory")
; #define PG8_BAR __builtin_amdgcn_s_barrier()
; #define PG8_SCHED __builtin_amdgcn_sched_barrier(0)
; template <class Epi, class Sched, bool ALIGN_EPI = false, bool SP2 = false>
; __device__ __forceinline__ void gemm_phase(PG8_LAS unsigned char* lds, const Gemm g, const Sched& S, const Epi& E) {
;     ...
;             PG8_LDB(B0, 1, 0); PG8_LDB(B1, 1, 1); PG8_SCHED; PG8_LDA(At, 1, 0); PG8_STAGE(PG8_SA(0, 1), a2 + hstepA, voffA);
;             PG8_WAIT_V(8); PG8_WAIT_L(0); PG8_BAR; PG8_MMA(0, 0, At, B0); PG8_MMA(0, 1, At, B1); PG8_BAR; PG8_SCHED;
	s_setprio 0
	s_add_i32 s64, 0, 0x18000
	v_add_u32_e32 v155, s64, v150
	s_add_i32 s65, 0, 0x1c000
	ds_read_b128 v[156:159], v155
	ds_read_b128 v[160:163], v155 offset:1024
	ds_read_b128 v[164:167], v155 offset:2048
	ds_read_b128 v[168:171], v155 offset:3072
	v_add_u32_e32 v155, s65, v150
	ds_read_b128 v[172:175], v155
	ds_read_b128 v[176:179], v155 offset:1024
	ds_read_b128 v[180:183], v155 offset:2048
	ds_read_b128 v[190:193], v155 offset:3072
	s_add_u32 s58, s58, 0x80000
	s_addc_u32 s59, s59, 0
	s_mov_b32 m0, s9
	v_lshl_add_u64 v[234:235], s[58:59], 0, v[128:129]
	ds_read_b128 v[194:197], v154 offset:32768
	ds_read_b128 v[198:201], v154 offset:33792
	ds_read_b128 v[202:205], v154 offset:34816
	ds_read_b128 v[206:209], v154 offset:35840
	ds_read_b128 v[210:213], v154 offset:36864
	ds_read_b128 v[214:217], v154 offset:37888
	ds_read_b128 v[218:221], v154 offset:38912
	ds_read_b128 v[222:225], v154 offset:39936
	global_load_lds_dwordx4 v[234:235], off
	v_lshl_add_u64 v[234:235], s[58:59], 0, v[132:133]
	s_mov_b32 m0, s11
	s_nop 0
	global_load_lds_dwordx4 v[234:235], off
	s_waitcnt vmcnt(8)
	s_waitcnt lgkmcnt(0)
	s_setprio 1
	s_barrier
	v_mfma_f32_16x16x32_bf16 v[124:127], v[156:159], v[194:197], v[124:127]
	v_mfma_f32_16x16x32_bf16 v[120:123], v[164:167], v[194:197], v[120:123]
	v_mfma_f32_16x16x32_bf16 v[104:107], v[164:167], v[202:205], v[104:107]
	v_mfma_f32_16x16x32_bf16 v[108:111], v[156:159], v[202:205], v[108:111]
	v_mfma_f32_16x16x32_bf16 v[92:95], v[156:159], v[210:213], v[92:95]
	v_mfma_f32_16x16x32_bf16 v[88:91], v[164:167], v[210:213], v[88:91]
	v_mfma_f32_16x16x32_bf16 v[72:75], v[164:167], v[218:221], v[72:75]
	v_mfma_f32_16x16x32_bf16 v[76:79], v[156:159], v[218:221], v[76:79]
	v_mfma_f32_16x16x32_bf16 v[124:127], v[160:163], v[198:201], v[124:127]
	v_mfma_f32_16x16x32_bf16 v[120:123], v[168:171], v[198:201], v[120:123]
	v_mfma_f32_16x16x32_bf16 v[104:107], v[168:171], v[206:209], v[104:107]
	v_mfma_f32_16x16x32_bf16 v[108:111], v[160:163], v[206:209], v[108:111]
	v_mfma_f32_16x16x32_bf16 v[92:95], v[160:163], v[214:217], v[92:95]
	v_mfma_f32_16x16x32_bf16 v[88:91], v[168:171], v[214:217], v[88:91]
	v_mfma_f32_16x16x32_bf16 v[72:75], v[168:171], v[222:225], v[72:75]
	v_mfma_f32_16x16x32_bf16 v[76:79], v[160:163], v[222:225], v[76:79]
	s_setprio 0
	s_setprio 1
	v_mfma_f32_16x16x32_bf16 v[116:119], v[172:175], v[194:197], v[116:119]
	v_mfma_f32_16x16x32_bf16 v[112:115], v[180:183], v[194:197], v[112:115]
	v_mfma_f32_16x16x32_bf16 v[96:99], v[180:183], v[202:205], v[96:99]
	v_mfma_f32_16x16x32_bf16 v[100:103], v[172:175], v[202:205], v[100:103]
	v_mfma_f32_16x16x32_bf16 v[84:87], v[172:175], v[210:213], v[84:87]
	v_mfma_f32_16x16x32_bf16 v[80:83], v[180:183], v[210:213], v[80:83]
	v_mfma_f32_16x16x32_bf16 v[64:67], v[180:183], v[218:221], v[64:67]
	v_mfma_f32_16x16x32_bf16 v[68:71], v[172:175], v[218:221], v[68:71]
	v_mfma_f32_16x16x32_bf16 v[116:119], v[176:179], v[198:201], v[116:119]
	v_mfma_f32_16x16x32_bf16 v[112:115], v[190:193], v[198:201], v[112:115]
	v_mfma_f32_16x16x32_bf16 v[96:99], v[190:193], v[206:209], v[96:99]
	v_mfma_f32_16x16x32_bf16 v[100:103], v[176:179], v[206:209], v[100:103]
	v_mfma_f32_16x16x32_bf16 v[84:87], v[176:179], v[214:217], v[84:87]
	v_mfma_f32_16x16x32_bf16 v[80:83], v[190:193], v[214:217], v[80:83]
	v_mfma_f32_16x16x32_bf16 v[64:67], v[190:193], v[222:225], v[64:67]
	v_mfma_f32_16x16x32_bf16 v[68:71], v[176:179], v[222:225], v[68:71]
	s_barrier
; #define PG8_STAGE(bufoff, gbase, voff) do { _Pragma("unroll") for (int _i = 0; _i < 2; ++_i) \
;         __builtin_amdgcn_global_load_lds((const unsigned*)((const char*)(gbase) + (voff)[_i]), (PG8_LAS unsigned*)(lds + (bufoff) + ldsw + _i * 8192), 16, 0, 0); } while (0)
; #define PG8_LDA(dst, b, h) do { _Pragma("unroll") for (int m = 0; m < 4; ++m) _Pragma("unroll") for (int k = 0; k < 2; ++k) dst[m][k] = *(const PG8_LAS bf16x8*)(lds + PG8_SA(b, h) + aoff + m * 2048 + k * 1024); } while (0)
; #define PG8_MMA(ai, bj, At, Bt) do { __builtin_amdgcn_s_setprio(1); _Pragma("unroll") for (int m = 0; m < 4; ++m) _Pragma("unroll") for (int n = 0; n < 2; ++n) _Pragma("unroll") for (int k = 0; k < 2; ++k) \
;         acc[ai][bj][m][n] = __builtin_amdgcn_mfma_f32_16x16x32_bf16(Bt[n][k], At[m][k], acc[ai][bj][m][n], 0, 0, 0); __builtin_amdgcn_s_setprio(0); } while (0)
; #define PG8_WAIT_V(n) asm volatile("s_waitcnt vmcnt(" #n ")" ::: "memory")
; #define PG8_WAIT_L(n) asm volatile("s_waitcnt lgkmcnt(" #n ")" ::: "memory")
; #define PG8_BAR __builtin_amdgcn_s_barrier()
; #define PG8_SCHED __builtin_amdgcn_sched_barrier(0)
; template <class Epi, class Sched, bool ALIGN_EPI = false, bool SP2 = false>
; __device__ __forceinline__ void gemm_phase(PG8_LAS unsigned char* lds, const Gemm g, const Sched& S, const Epi& E) {
;     ...
;             PG8_LDA(At, 1, 1); PG8_STAGE(PG8_SB(1, 0), b3, voffB); PG8_STAGE(PG8_SB(1, 1), b3 + hstepB, voffB); PG8_STAGE(PG8_SA(1, 0), a3, voffA);
;             PG8_WAIT_V(8); PG8_WAIT_L(0); PG8_BAR; PG8_MMA(1, 0, At, B0); PG8_MMA(1, 1, At, B1); PG8_BAR; PG8_SCHED;
	s_setprio 0
	s_add_i32 s58, s64, s6
	v_lshl_add_u64 v[226:227], v[226:227], 0, s[20:21]
	s_mov_b32 m0, s58
	ds_read_b128 v[194:197], v154 offset:49152
	ds_read_b128 v[198:201], v154 offset:50176
	ds_read_b128 v[202:205], v154 offset:51200
	ds_read_b128 v[206:209], v154 offset:52224
	ds_read_b128 v[210:213], v154 offset:53248
	ds_read_b128 v[214:217], v154 offset:54272
	ds_read_b128 v[218:221], v154 offset:55296
	ds_read_b128 v[222:225], v154 offset:56320
	global_load_lds_dwordx4 v[226:227], off
	s_add_i32 m0, s58, 0x2000
	s_add_u32 s52, s52, 0x80080
	v_lshl_add_u64 v[226:227], v[228:229], 0, s[20:21]
	s_addc_u32 s53, s53, 0
	s_add_i32 s58, s65, s6
	global_load_lds_dwordx4 v[226:227], off
	v_lshl_add_u64 v[226:227], s[52:53], 0, v[130:131]
	s_mov_b32 m0, s58
	s_nop 0
	global_load_lds_dwordx4 v[226:227], off
	v_lshl_add_u64 v[226:227], s[52:53], 0, v[134:135]
	s_add_i32 m0, s58, 0x2000
	s_nop 0
	global_load_lds_dwordx4 v[226:227], off
	v_lshl_add_u64 v[226:227], v[230:231], 0, s[20:21]
	s_mov_b32 m0, s55
	s_nop 0
	global_load_lds_dwordx4 v[226:227], off
	v_lshl_add_u64 v[226:227], v[232:233], 0, s[20:21]
	s_mov_b32 m0, s56
	s_nop 0
	global_load_lds_dwordx4 v[226:227], off
	s_waitcnt vmcnt(8)
	s_waitcnt lgkmcnt(0)
	s_setprio 1
	s_barrier
	v_mfma_f32_16x16x32_bf16 v[60:63], v[156:159], v[194:197], v[60:63]
	v_mfma_f32_16x16x32_bf16 v[56:59], v[164:167], v[194:197], v[56:59]
	v_mfma_f32_16x16x32_bf16 v[40:43], v[164:167], v[202:205], v[40:43]
	v_mfma_f32_16x16x32_bf16 v[44:47], v[156:159], v[202:205], v[44:47]
	v_mfma_f32_16x16x32_bf16 v[28:31], v[156:159], v[210:213], v[28:31]
	v_mfma_f32_16x16x32_bf16 v[24:27], v[164:167], v[210:213], v[24:27]
	v_mfma_f32_16x16x32_bf16 v[8:11], v[164:167], v[218:221], v[8:11]
	v_mfma_f32_16x16x32_bf16 v[12:15], v[156:159], v[218:221], v[12:15]
	v_mfma_f32_16x16x32_bf16 v[60:63], v[160:163], v[198:201], v[60:63]
	v_mfma_f32_16x16x32_bf16 v[56:59], v[168:171], v[198:201], v[56:59]
	v_mfma_f32_16x16x32_bf16 v[40:43], v[168:171], v[206:209], v[40:43]
	v_mfma_f32_16x16x32_bf16 v[44:47], v[160:163], v[206:209], v[44:47]
	v_mfma_f32_16x16x32_bf16 v[28:31], v[160:163], v[214:217], v[28:31]
	v_mfma_f32_16x16x32_bf16 v[24:27], v[168:171], v[214:217], v[24:27]
	v_mfma_f32_16x16x32_bf16 v[8:11], v[168:171], v[222:225], v[8:11]
	v_mfma_f32_16x16x32_bf16 v[12:15], v[160:163], v[222:225], v[12:15]
	s_setprio 0
	s_setprio 1
	v_mfma_f32_16x16x32_bf16 v[52:55], v[172:175], v[194:197], v[52:55]
	v_mfma_f32_16x16x32_bf16 v[48:51], v[180:183], v[194:197], v[48:51]
	v_mfma_f32_16x16x32_bf16 v[32:35], v[180:183], v[202:205], v[32:35]
	v_mfma_f32_16x16x32_bf16 v[36:39], v[172:175], v[202:205], v[36:39]
	v_mfma_f32_16x16x32_bf16 v[20:23], v[172:175], v[210:213], v[20:23]
	v_mfma_f32_16x16x32_bf16 v[16:19], v[180:183], v[210:213], v[16:19]
	v_mfma_f32_16x16x32_bf16 v[0:3], v[180:183], v[218:221], v[0:3]
	v_mfma_f32_16x16x32_bf16 v[4:7], v[172:175], v[218:221], v[4:7]
	v_mfma_f32_16x16x32_bf16 v[52:55], v[176:179], v[198:201], v[52:55]
	v_mfma_f32_16x16x32_bf16 v[48:51], v[190:193], v[198:201], v[48:51]
	v_mfma_f32_16x16x32_bf16 v[32:35], v[190:193], v[206:209], v[32:35]
	v_mfma_f32_16x16x32_bf16 v[36:39], v[176:179], v[206:209], v[36:39]
	v_mfma_f32_16x16x32_bf16 v[20:23], v[176:179], v[214:217], v[20:23]
	v_mfma_f32_16x16x32_bf16 v[16:19], v[190:193], v[214:217], v[16:19]
	v_mfma_f32_16x16x32_bf16 v[0:3], v[190:193], v[222:225], v[0:3]
	v_mfma_f32_16x16x32_bf16 v[4:7], v[176:179], v[222:225], v[4:7]
	s_barrier
	s_setprio 0
	s_add_i32 s63, s63, 2
	s_add_u32 s50, s50, 0x100
	s_addc_u32 s51, s51, 0
	s_add_u32 s39, s39, 0x100
	s_addc_u32 s41, s41, 0
	s_cmp_gt_u32 s63, 29
	s_cbranch_scc0 .LBB0_1307

; #define PG8_STAGE(bufoff, gbase, voff) do { _Pragma("unroll") for (int _i = 0; _i < 2; ++_i) \
;         __builtin_amdgcn_global_load_lds((const unsigned*)((const char*)(gbase) + (voff)[_i]), (PG8_LAS unsigned*)(lds + (bufoff) + ldsw + _i * 8192), 16, 0, 0); } while (0)
; #define PG8_LDA(dst, b, h) do { _Pragma("unroll") for (int m = 0; m < 4; ++m) _Pragma("unroll") for (int k = 0; k < 2; ++k) dst[m][k] = *(const PG8_LAS bf16x8*)(lds + PG8_SA(b, h) + aoff + m * 2048 + k * 1024); } while (0)
; #define PG8_LDB(dst, b, h) do { _Pragma("unroll") for (int n = 0; n < 2; ++n) _Pragma("unroll") for (int k = 0; k < 2; ++k) dst[n][k] = *(const PG8_LAS bf16x8*)(lds + PG8_SB(b, h) + boff + n * 2048 + k * 1024); } while (0)
; #define PG8_MMA(ai, bj, At, Bt) do { __builtin_amdgcn_s_setprio(1); _Pragma("unroll") for (int m = 0; m < 4; ++m) _Pragma("unroll") for (int n = 0; n < 2; ++n) _Pragma("unroll") for (int k = 0; k < 2; ++k) \
;         acc[ai][bj][m][n] = __builtin_amdgcn_mfma_f32_16x16x32_bf16(Bt[n][k], At[m][k], acc[ai][bj][m][n], 0, 0, 0); __builtin_amdgcn_s_setprio(0); } while (0)
; #define PG8_WAIT_V(n) asm volatile("s_waitcnt vmcnt(" #n ")" ::: "memory")
; #define PG8_WAIT_L(n) asm volatile("s_waitcnt lgkmcnt(" #n ")" ::: "memory")
; #define PG8_BAR __builtin_amdgcn_s_barrier()
; template <class Epi, class Sched, bool ALIGN_EPI = false, bool SP2 = false>
; __device__ __forceinline__ void gemm_phase(PG8_LAS unsigned char* lds, const Gemm g, const Sched& S, const Epi& E) {
;     ...
;             const char* a1 = cA + (size_t)(t + 1) * kstA;
;             const char* a2 = last ? nA : cA + (size_t)(t + 2) * kstA; const char* b2 = last ? nB : cB + (size_t)(t + 2) * kstep;
;             const char* a3 = a2 + kstA; const char* b3 = b2 + kstep;
;             if (last && has_next) S.a_ready(nxt);
;             if constexpr (SP2) {
;             PG8_LDB(B0, 0, 0); PG8_LDB(B1, 0, 1); PG8_SCHED; PG8_LDA(At, 0, 0); PG8_STAGE(PG8_SA(1, 1), a1 + hstepA, voffA);
;             PG8_WAIT_V(8); PG8_WAIT_L(0); PG8_BAR; PG8_MMA(0, 0, At, B0); PG8_MMA(0, 1, At, B1); PG8_BAR; PG8_SCHED;
;             PG8_LDA(At, 0, 1); PG8_STAGE(PG8_SB(0, 0), b2, voffB); PG8_STAGE(PG8_SB(0, 1), b2 + hstepB, voffB); PG8_STAGE(PG8_SA(0, 0), a2, voffA);
;             PG8_WAIT_V(8); PG8_WAIT_L(0); PG8_BAR; PG8_MMA(1, 0, At, B0); PG8_MMA(1, 1, At, B1); PG8_BAR; PG8_SCHED;
.LBB0_1404:
	s_or_b32 s48, s68, 1
	s_add_i32 s68, s68, 2
	s_mov_b32 s69, s49
	s_lshl_b64 s[4:5], s[48:49], 15
	s_lshl_b64 s[6:7], s[68:69], 15
	s_add_u32 s12, s34, s6
	v_add_u32_e32 v170, s10, v177
	v_add_u32_e32 v174, s11, v177
	s_addc_u32 s13, s35, s7
	ds_read_b128 v[158:161], v170
	ds_read_b128 v[162:165], v170 offset:1024
	ds_read_b128 v[166:169], v170 offset:2048
	ds_read_b128 v[170:173], v170 offset:3072
	ds_read_b128 v[180:183], v174
	ds_read_b128 v[190:193], v174 offset:1024
	ds_read_b128 v[194:197], v174 offset:2048
	ds_read_b128 v[198:201], v174 offset:3072
	s_and_b64 s[6:7], s[50:51], exec
	s_cselect_b32 s59, s13, s61
	s_cselect_b32 s58, s12, s60
	s_lshl_b64 s[6:7], s[68:69], 7
	s_add_u32 s12, s40, s6
	s_addc_u32 s13, s41, s7
	s_and_b64 s[6:7], s[50:51], exec
	s_cselect_b32 s53, s13, s63
	s_cselect_b32 s52, s12, s62
	s_add_u32 s50, s58, 0x8000
	s_addc_u32 s51, s59, 0
	s_add_u32 s4, s21, s4
	s_addc_u32 s5, s39, s5
	v_lshl_add_u64 v[174:175], s[4:5], 0, v[128:129]
	s_add_i32 m0, s74, 0xc000
	ds_read_b128 v[202:205], v179
	ds_read_b128 v[206:209], v179 offset:1024
	ds_read_b128 v[210:213], v179 offset:2048
	ds_read_b128 v[214:217], v179 offset:3072
	ds_read_b128 v[218:221], v179 offset:4096
	ds_read_b128 v[222:225], v179 offset:5120
	ds_read_b128 v[226:229], v179 offset:6144
	ds_read_b128 v[230:233], v179 offset:7168
	global_load_lds_dwordx4 v[174:175], off
	v_lshl_add_u64 v[174:175], s[4:5], 0, v[132:133]
	s_add_i32 m0, s74, 0xe000
	s_nop 0
	global_load_lds_dwordx4 v[174:175], off
	s_waitcnt vmcnt(8)
	s_waitcnt lgkmcnt(0)
	s_setprio 1
	s_barrier
	v_mfma_f32_16x16x32_bf16 v[124:127], v[158:161], v[202:205], v[124:127]
	v_mfma_f32_16x16x32_bf16 v[120:123], v[166:169], v[202:205], v[120:123]
	v_mfma_f32_16x16x32_bf16 v[112:115], v[166:169], v[210:213], v[112:115]
	v_mfma_f32_16x16x32_bf16 v[116:119], v[158:161], v[210:213], v[116:119]
	v_mfma_f32_16x16x32_bf16 v[108:111], v[158:161], v[218:221], v[108:111]
	v_mfma_f32_16x16x32_bf16 v[104:107], v[166:169], v[218:221], v[104:107]
	v_mfma_f32_16x16x32_bf16 v[96:99], v[166:169], v[226:229], v[96:99]
	v_mfma_f32_16x16x32_bf16 v[100:103], v[158:161], v[226:229], v[100:103]
	v_mfma_f32_16x16x32_bf16 v[124:127], v[162:165], v[206:209], v[124:127]
	v_mfma_f32_16x16x32_bf16 v[120:123], v[170:173], v[206:209], v[120:123]
	v_mfma_f32_16x16x32_bf16 v[112:115], v[170:173], v[214:217], v[112:115]
	v_mfma_f32_16x16x32_bf16 v[116:119], v[162:165], v[214:217], v[116:119]
	v_mfma_f32_16x16x32_bf16 v[108:111], v[162:165], v[222:225], v[108:111]
	v_mfma_f32_16x16x32_bf16 v[104:107], v[170:173], v[222:225], v[104:107]
	v_mfma_f32_16x16x32_bf16 v[96:99], v[170:173], v[230:233], v[96:99]
	v_mfma_f32_16x16x32_bf16 v[100:103], v[162:165], v[230:233], v[100:103]
	s_setprio 0
	s_setprio 1
	v_mfma_f32_16x16x32_bf16 v[92:95], v[180:183], v[202:205], v[92:95]
	v_mfma_f32_16x16x32_bf16 v[88:91], v[194:197], v[202:205], v[88:91]
	v_mfma_f32_16x16x32_bf16 v[80:83], v[194:197], v[210:213], v[80:83]
	v_mfma_f32_16x16x32_bf16 v[84:87], v[180:183], v[210:213], v[84:87]
	v_mfma_f32_16x16x32_bf16 v[76:79], v[180:183], v[218:221], v[76:79]
	v_mfma_f32_16x16x32_bf16 v[72:75], v[194:197], v[218:221], v[72:75]
	v_mfma_f32_16x16x32_bf16 v[64:67], v[194:197], v[226:229], v[64:67]
	v_mfma_f32_16x16x32_bf16 v[68:71], v[180:183], v[226:229], v[68:71]
	v_mfma_f32_16x16x32_bf16 v[92:95], v[190:193], v[206:209], v[92:95]
	v_mfma_f32_16x16x32_bf16 v[88:91], v[198:201], v[206:209], v[88:91]
	v_mfma_f32_16x16x32_bf16 v[80:83], v[198:201], v[214:217], v[80:83]
	v_mfma_f32_16x16x32_bf16 v[84:87], v[190:193], v[214:217], v[84:87]
	v_mfma_f32_16x16x32_bf16 v[76:79], v[190:193], v[222:225], v[76:79]
	v_mfma_f32_16x16x32_bf16 v[72:75], v[198:201], v[222:225], v[72:75]
	v_mfma_f32_16x16x32_bf16 v[64:67], v[198:201], v[230:233], v[64:67]
	v_mfma_f32_16x16x32_bf16 v[68:71], v[190:193], v[230:233], v[68:71]
	s_barrier
	s_setprio 0
	s_add_i32 s4, s10, s77
	v_lshl_add_u64 v[174:175], s[52:53], 0, v[130:131]
	s_mov_b32 m0, s4
	ds_read_b128 v[202:205], v179 offset:16384
	ds_read_b128 v[206:209], v179 offset:17408
	ds_read_b128 v[210:213], v179 offset:18432
	ds_read_b128 v[214:217], v179 offset:19456
	ds_read_b128 v[218:221], v179 offset:20480
	ds_read_b128 v[222:225], v179 offset:21504
	ds_read_b128 v[226:229], v179 offset:22528
	ds_read_b128 v[230:233], v179 offset:23552
	global_load_lds_dwordx4 v[174:175], off
	s_add_i32 m0, s4, 0x2000
	s_add_u32 s4, s52, 0x160000
	v_lshl_add_u64 v[234:235], s[52:53], 0, v[134:135]
	s_addc_u32 s5, s53, 0
	s_add_i32 s6, s11, s77
	global_load_lds_dwordx4 v[234:235], off
	v_lshl_add_u64 v[236:237], s[4:5], 0, v[130:131]
	s_mov_b32 m0, s6
	s_nop 0
	global_load_lds_dwordx4 v[236:237], off
	v_lshl_add_u64 v[236:237], s[4:5], 0, v[134:135]
	s_add_i32 m0, s6, 0x2000
	s_nop 0
	global_load_lds_dwordx4 v[236:237], off
	v_lshl_add_u64 v[236:237], s[58:59], 0, v[128:129]
	s_mov_b32 m0, s74
	s_nop 0
	global_load_lds_dwordx4 v[236:237], off
	v_lshl_add_u64 v[236:237], s[58:59], 0, v[132:133]
	s_mov_b32 m0, s96
	s_nop 0
	global_load_lds_dwordx4 v[236:237], off
	s_waitcnt vmcnt(8)
	s_waitcnt lgkmcnt(0)
	s_setprio 1
	s_barrier
; #define PG8_STAGE(bufoff, gbase, voff) do { _Pragma("unroll") for (int _i = 0; _i < 2; ++_i) \
;         __builtin_amdgcn_global_load_lds((const unsigned*)((const char*)(gbase) + (voff)[_i]), (PG8_LAS unsigned*)(lds + (bufoff) + ldsw + _i * 8192), 16, 0, 0); } while (0)
; #define PG8_LDA(dst, b, h) do { _Pragma("unroll") for (int m = 0; m < 4; ++m) _Pragma("unroll") for (int k = 0; k < 2; ++k) dst[m][k] = *(const PG8_LAS bf16x8*)(lds + PG8_SA(b, h) + aoff + m * 2048 + k * 1024); } while (0)
; #define PG8_LDB(dst, b, h) do { _Pragma("unroll") for (int n = 0; n < 2; ++n) _Pragma("unroll") for (int k = 0; k < 2; ++k) dst[n][k] = *(const PG8_LAS bf16x8*)(lds + PG8_SB(b, h) + boff + n * 2048 + k * 1024); } while (0)
; #define PG8_MMA(ai, bj, At, Bt) do { __builtin_amdgcn_s_setprio(1); _Pragma("unroll") for (int m = 0; m < 4; ++m) _Pragma("unroll") for (int n = 0; n < 2; ++n) _Pragma("unroll") for (int k = 0; k < 2; ++k) \
;         acc[ai][bj][m][n] = __builtin_amdgcn_mfma_f32_16x16x32_bf16(Bt[n][k], At[m][k], acc[ai][bj][m][n], 0, 0, 0); __builtin_amdgcn_s_setprio(0); } while (0)
; #define PG8_WAIT_V(n) asm volatile("s_waitcnt vmcnt(" #n ")" ::: "memory")
; #define PG8_WAIT_L(n) asm volatile("s_waitcnt lgkmcnt(" #n ")" ::: "memory")
; #define PG8_BAR __builtin_amdgcn_s_barrier()
; #define PG8_SCHED __builtin_amdgcn_sched_barrier(0)
; template <class Epi, class Sched, bool ALIGN_EPI = false, bool SP2 = false>
; __device__ __forceinline__ void gemm_phase(PG8_LAS unsigned char* lds, const Gemm g, const Sched& S, const Epi& E) {
;     ...
;             PG8_WAIT_V(8); PG8_WAIT_L(0); PG8_BAR; PG8_MMA(1, 0, At, B0); PG8_MMA(1, 1, At, B1); PG8_BAR; PG8_SCHED;
;             PG8_LDB(B0, 1, 0); PG8_LDB(B1, 1, 1); PG8_SCHED; PG8_LDA(At, 1, 0); PG8_STAGE(PG8_SA(0, 1), a2 + hstepA, voffA);
;             PG8_WAIT_V(8); PG8_WAIT_L(0); PG8_BAR; PG8_MMA(0, 0, At, B0); PG8_MMA(0, 1, At, B1); PG8_BAR; PG8_SCHED;
	v_mfma_f32_16x16x32_bf16 v[60:63], v[158:161], v[202:205], v[60:63]
	v_mfma_f32_16x16x32_bf16 v[56:59], v[166:169], v[202:205], v[56:59]
	v_mfma_f32_16x16x32_bf16 v[48:51], v[166:169], v[210:213], v[48:51]
	v_mfma_f32_16x16x32_bf16 v[52:55], v[158:161], v[210:213], v[52:55]
	v_mfma_f32_16x16x32_bf16 v[44:47], v[158:161], v[218:221], v[44:47]
	v_mfma_f32_16x16x32_bf16 v[40:43], v[166:169], v[218:221], v[40:43]
	v_mfma_f32_16x16x32_bf16 v[32:35], v[166:169], v[226:229], v[32:35]
	v_mfma_f32_16x16x32_bf16 v[36:39], v[158:161], v[226:229], v[36:39]
	v_mfma_f32_16x16x32_bf16 v[60:63], v[162:165], v[206:209], v[60:63]
	v_mfma_f32_16x16x32_bf16 v[56:59], v[170:173], v[206:209], v[56:59]
	v_mfma_f32_16x16x32_bf16 v[48:51], v[170:173], v[214:217], v[48:51]
	v_mfma_f32_16x16x32_bf16 v[52:55], v[162:165], v[214:217], v[52:55]
	v_mfma_f32_16x16x32_bf16 v[44:47], v[162:165], v[222:225], v[44:47]
	v_mfma_f32_16x16x32_bf16 v[40:43], v[170:173], v[222:225], v[40:43]
	v_mfma_f32_16x16x32_bf16 v[32:35], v[170:173], v[230:233], v[32:35]
	v_mfma_f32_16x16x32_bf16 v[36:39], v[162:165], v[230:233], v[36:39]
	s_setprio 0
	s_setprio 1
	v_mfma_f32_16x16x32_bf16 v[28:31], v[180:183], v[202:205], v[28:31]
	v_mfma_f32_16x16x32_bf16 v[24:27], v[194:197], v[202:205], v[24:27]
	v_mfma_f32_16x16x32_bf16 v[16:19], v[194:197], v[210:213], v[16:19]
	v_mfma_f32_16x16x32_bf16 v[20:23], v[180:183], v[210:213], v[20:23]
	v_mfma_f32_16x16x32_bf16 v[12:15], v[180:183], v[218:221], v[12:15]
	v_mfma_f32_16x16x32_bf16 v[8:11], v[194:197], v[218:221], v[8:11]
	v_mfma_f32_16x16x32_bf16 v[0:3], v[194:197], v[226:229], v[0:3]
	v_mfma_f32_16x16x32_bf16 v[4:7], v[180:183], v[226:229], v[4:7]
	v_mfma_f32_16x16x32_bf16 v[28:31], v[190:193], v[206:209], v[28:31]
	v_mfma_f32_16x16x32_bf16 v[24:27], v[198:201], v[206:209], v[24:27]
	v_mfma_f32_16x16x32_bf16 v[16:19], v[198:201], v[214:217], v[16:19]
	v_mfma_f32_16x16x32_bf16 v[20:23], v[190:193], v[214:217], v[20:23]
	v_mfma_f32_16x16x32_bf16 v[12:15], v[190:193], v[222:225], v[12:15]
	v_mfma_f32_16x16x32_bf16 v[8:11], v[198:201], v[222:225], v[8:11]
	v_mfma_f32_16x16x32_bf16 v[0:3], v[198:201], v[230:233], v[0:3]
	v_mfma_f32_16x16x32_bf16 v[4:7], v[190:193], v[230:233], v[4:7]
	s_barrier
	s_setprio 0
	s_add_i32 s6, 0, 0x18000
	s_add_i32 s7, 0, 0x1c000
	v_add_u32_e32 v170, s6, v177
	v_add_u32_e32 v198, s7, v177
	ds_read_b128 v[158:161], v170
	ds_read_b128 v[162:165], v170 offset:1024
	ds_read_b128 v[166:169], v170 offset:2048
	ds_read_b128 v[170:173], v170 offset:3072
	ds_read_b128 v[180:183], v198
	ds_read_b128 v[190:193], v198 offset:1024
	ds_read_b128 v[194:197], v198 offset:2048
	ds_read_b128 v[198:201], v198 offset:3072
	s_add_u32 s4, s58, 0x4000
	s_addc_u32 s5, s59, 0
	s_mov_b32 m0, s97
	v_lshl_add_u64 v[236:237], s[4:5], 0, v[128:129]
	ds_read_b128 v[202:205], v179 offset:32768
	ds_read_b128 v[206:209], v179 offset:33792
	ds_read_b128 v[210:213], v179 offset:34816
	ds_read_b128 v[214:217], v179 offset:35840
	ds_read_b128 v[218:221], v179 offset:36864
	ds_read_b128 v[222:225], v179 offset:37888
	ds_read_b128 v[226:229], v179 offset:38912
	ds_read_b128 v[230:233], v179 offset:39936
	global_load_lds_dwordx4 v[236:237], off
	v_lshl_add_u64 v[236:237], s[4:5], 0, v[132:133]
	s_mov_b32 m0, s75
	s_nop 0
	global_load_lds_dwordx4 v[236:237], off
	s_waitcnt vmcnt(8)
	s_waitcnt lgkmcnt(0)
	s_setprio 1
	s_barrier
	v_mfma_f32_16x16x32_bf16 v[124:127], v[158:161], v[202:205], v[124:127]
	v_mfma_f32_16x16x32_bf16 v[120:123], v[166:169], v[202:205], v[120:123]
	v_mfma_f32_16x16x32_bf16 v[112:115], v[166:169], v[210:213], v[112:115]
	v_mfma_f32_16x16x32_bf16 v[116:119], v[158:161], v[210:213], v[116:119]
	v_mfma_f32_16x16x32_bf16 v[108:111], v[158:161], v[218:221], v[108:111]
	v_mfma_f32_16x16x32_bf16 v[104:107], v[166:169], v[218:221], v[104:107]
	v_mfma_f32_16x16x32_bf16 v[96:99], v[166:169], v[226:229], v[96:99]
	v_mfma_f32_16x16x32_bf16 v[100:103], v[158:161], v[226:229], v[100:103]
	v_mfma_f32_16x16x32_bf16 v[124:127], v[162:165], v[206:209], v[124:127]
	v_mfma_f32_16x16x32_bf16 v[120:123], v[170:173], v[206:209], v[120:123]
	v_mfma_f32_16x16x32_bf16 v[112:115], v[170:173], v[214:217], v[112:115]
	v_mfma_f32_16x16x32_bf16 v[116:119], v[162:165], v[214:217], v[116:119]
	v_mfma_f32_16x16x32_bf16 v[108:111], v[162:165], v[222:225], v[108:111]
	v_mfma_f32_16x16x32_bf16 v[104:107], v[170:173], v[222:225], v[104:107]
	v_mfma_f32_16x16x32_bf16 v[96:99], v[170:173], v[230:233], v[96:99]
	v_mfma_f32_16x16x32_bf16 v[100:103], v[162:165], v[230:233], v[100:103]
	s_setprio 0
	s_setprio 1
	v_mfma_f32_16x16x32_bf16 v[92:95], v[180:183], v[202:205], v[92:95]
	v_mfma_f32_16x16x32_bf16 v[88:91], v[194:197], v[202:205], v[88:91]
	v_mfma_f32_16x16x32_bf16 v[80:83], v[194:197], v[210:213], v[80:83]
	v_mfma_f32_16x16x32_bf16 v[84:87], v[180:183], v[210:213], v[84:87]
	v_mfma_f32_16x16x32_bf16 v[76:79], v[180:183], v[218:221], v[76:79]
	v_mfma_f32_16x16x32_bf16 v[72:75], v[194:197], v[218:221], v[72:75]
	v_mfma_f32_16x16x32_bf16 v[64:67], v[194:197], v[226:229], v[64:67]
	v_mfma_f32_16x16x32_bf16 v[68:71], v[180:183], v[226:229], v[68:71]
	v_mfma_f32_16x16x32_bf16 v[92:95], v[190:193], v[206:209], v[92:95]
	v_mfma_f32_16x16x32_bf16 v[88:91], v[198:201], v[206:209], v[88:91]
	v_mfma_f32_16x16x32_bf16 v[80:83], v[198:201], v[214:217], v[80:83]
	v_mfma_f32_16x16x32_bf16 v[84:87], v[190:193], v[214:217], v[84:87]
	v_mfma_f32_16x16x32_bf16 v[76:79], v[190:193], v[222:225], v[76:79]
	v_mfma_f32_16x16x32_bf16 v[72:75], v[198:201], v[222:225], v[72:75]
	v_mfma_f32_16x16x32_bf16 v[64:67], v[198:201], v[230:233], v[64:67]
	v_mfma_f32_16x16x32_bf16 v[68:71], v[190:193], v[230:233], v[68:71]
	s_barrier
; #define PG8_STAGE(bufoff, gbase, voff) do { _Pragma("unroll") for (int _i = 0; _i < 2; ++_i) \
;         __builtin_amdgcn_global_load_lds((const unsigned*)((const char*)(gbase) + (voff)[_i]), (PG8_LAS unsigned*)(lds + (bufoff) + ldsw + _i * 8192), 16, 0, 0); } while (0)
; #define PG8_LDA(dst, b, h) do { _Pragma("unroll") for (int m = 0; m < 4; ++m) _Pragma("unroll") for (int k = 0; k < 2; ++k) dst[m][k] = *(const PG8_LAS bf16x8*)(lds + PG8_SA(b, h) + aoff + m * 2048 + k * 1024); } while (0)
; #define PG8_MMA(ai, bj, At, Bt) do { __builtin_amdgcn_s_setprio(1); _Pragma("unroll") for (int m = 0; m < 4; ++m) _Pragma("unroll") for (int n = 0; n < 2; ++n) _Pragma("unroll") for (int k = 0; k < 2; ++k) \
;         acc[ai][bj][m][n] = __builtin_amdgcn_mfma_f32_16x16x32_bf16(Bt[n][k], At[m][k], acc[ai][bj][m][n], 0, 0, 0); __builtin_amdgcn_s_setprio(0); } while (0)
; #define PG8_WAIT_V(n) asm volatile("s_waitcnt vmcnt(" #n ")" ::: "memory")
; #define PG8_WAIT_L(n) asm volatile("s_waitcnt lgkmcnt(" #n ")" ::: "memory")
; #define PG8_BAR __builtin_amdgcn_s_barrier()
; #define PG8_SCHED __builtin_amdgcn_sched_barrier(0)
; template <class Epi, class Sched, bool ALIGN_EPI = false, bool SP2 = false>
; __device__ __forceinline__ void gemm_phase(PG8_LAS unsigned char* lds, const Gemm g, const Sched& S, const Epi& E) {
;     ...
;             PG8_LDA(At, 1, 1); PG8_STAGE(PG8_SB(1, 0), b3, voffB); PG8_STAGE(PG8_SB(1, 1), b3 + hstepB, voffB); PG8_STAGE(PG8_SA(1, 0), a3, voffA);
;             PG8_WAIT_V(8); PG8_WAIT_L(0); PG8_BAR; PG8_MMA(1, 0, At, B0); PG8_MMA(1, 1, At, B1); PG8_BAR; PG8_SCHED;
	s_setprio 0
	s_add_i32 s4, s6, s77
	v_lshl_add_u64 v[174:175], v[174:175], 0, s[64:65]
	s_mov_b32 m0, s4
	ds_read_b128 v[202:205], v179 offset:49152
	ds_read_b128 v[206:209], v179 offset:50176
	ds_read_b128 v[210:213], v179 offset:51200
	ds_read_b128 v[214:217], v179 offset:52224
	ds_read_b128 v[218:221], v179 offset:53248
	ds_read_b128 v[222:225], v179 offset:54272
	ds_read_b128 v[226:229], v179 offset:55296
	ds_read_b128 v[230:233], v179 offset:56320
	global_load_lds_dwordx4 v[174:175], off
	s_add_i32 m0, s4, 0x2000
	s_add_u32 s4, s52, 0x160080
	v_lshl_add_u64 v[174:175], v[234:235], 0, s[64:65]
	s_addc_u32 s5, s53, 0
	s_add_i32 s6, s7, s77
	global_load_lds_dwordx4 v[174:175], off
	v_lshl_add_u64 v[174:175], s[4:5], 0, v[130:131]
	s_mov_b32 m0, s6
	s_nop 0
	global_load_lds_dwordx4 v[174:175], off
	v_lshl_add_u64 v[174:175], s[4:5], 0, v[134:135]
	s_add_i32 m0, s6, 0x2000
	s_nop 0
	global_load_lds_dwordx4 v[174:175], off
	v_lshl_add_u64 v[174:175], s[50:51], 0, v[128:129]
	s_mov_b32 m0, s43
	s_nop 0
	global_load_lds_dwordx4 v[174:175], off
	v_lshl_add_u64 v[174:175], s[50:51], 0, v[132:133]
	s_mov_b32 m0, s56
	s_nop 0
	global_load_lds_dwordx4 v[174:175], off
	s_waitcnt vmcnt(8)
	s_waitcnt lgkmcnt(0)
	s_setprio 1
	s_barrier
	v_mfma_f32_16x16x32_bf16 v[60:63], v[158:161], v[202:205], v[60:63]
	v_mfma_f32_16x16x32_bf16 v[56:59], v[166:169], v[202:205], v[56:59]
	v_mfma_f32_16x16x32_bf16 v[48:51], v[166:169], v[210:213], v[48:51]
	v_mfma_f32_16x16x32_bf16 v[52:55], v[158:161], v[210:213], v[52:55]
	v_mfma_f32_16x16x32_bf16 v[44:47], v[158:161], v[218:221], v[44:47]
	v_mfma_f32_16x16x32_bf16 v[40:43], v[166:169], v[218:221], v[40:43]
	v_mfma_f32_16x16x32_bf16 v[32:35], v[166:169], v[226:229], v[32:35]
	v_mfma_f32_16x16x32_bf16 v[36:39], v[158:161], v[226:229], v[36:39]
	v_mfma_f32_16x16x32_bf16 v[60:63], v[162:165], v[206:209], v[60:63]
	v_mfma_f32_16x16x32_bf16 v[56:59], v[170:173], v[206:209], v[56:59]
	v_mfma_f32_16x16x32_bf16 v[48:51], v[170:173], v[214:217], v[48:51]
	v_mfma_f32_16x16x32_bf16 v[52:55], v[162:165], v[214:217], v[52:55]
	v_mfma_f32_16x16x32_bf16 v[44:47], v[162:165], v[222:225], v[44:47]
	v_mfma_f32_16x16x32_bf16 v[40:43], v[170:173], v[222:225], v[40:43]
	v_mfma_f32_16x16x32_bf16 v[32:35], v[170:173], v[230:233], v[32:35]
	v_mfma_f32_16x16x32_bf16 v[36:39], v[162:165], v[230:233], v[36:39]
	s_setprio 0
	s_setprio 1
	v_mfma_f32_16x16x32_bf16 v[28:31], v[180:183], v[202:205], v[28:31]
	v_mfma_f32_16x16x32_bf16 v[24:27], v[194:197], v[202:205], v[24:27]
	v_mfma_f32_16x16x32_bf16 v[16:19], v[194:197], v[210:213], v[16:19]
	v_mfma_f32_16x16x32_bf16 v[20:23], v[180:183], v[210:213], v[20:23]
	v_mfma_f32_16x16x32_bf16 v[12:15], v[180:183], v[218:221], v[12:15]
	v_mfma_f32_16x16x32_bf16 v[8:11], v[194:197], v[218:221], v[8:11]
	v_mfma_f32_16x16x32_bf16 v[0:3], v[194:197], v[226:229], v[0:3]
	v_mfma_f32_16x16x32_bf16 v[4:7], v[180:183], v[226:229], v[4:7]
	v_mfma_f32_16x16x32_bf16 v[28:31], v[190:193], v[206:209], v[28:31]
	v_mfma_f32_16x16x32_bf16 v[24:27], v[198:201], v[206:209], v[24:27]
	v_mfma_f32_16x16x32_bf16 v[16:19], v[198:201], v[214:217], v[16:19]
	v_mfma_f32_16x16x32_bf16 v[20:23], v[190:193], v[214:217], v[20:23]
	v_mfma_f32_16x16x32_bf16 v[12:15], v[190:193], v[222:225], v[12:15]
	v_mfma_f32_16x16x32_bf16 v[8:11], v[198:201], v[222:225], v[8:11]
	v_mfma_f32_16x16x32_bf16 v[0:3], v[198:201], v[230:233], v[0:3]
	v_mfma_f32_16x16x32_bf16 v[4:7], v[190:193], v[230:233], v[4:7]
	s_barrier
	s_setprio 0
	s_cmp_ge_i32 s68, s57
	s_cbranch_scc1 .LBB0_1416

; #define PG8_STAGE(bufoff, gbase, voff) do { _Pragma("unroll") for (int _i = 0; _i < 2; ++_i) \
;         __builtin_amdgcn_global_load_lds((const unsigned*)((const char*)(gbase) + (voff)[_i]), (PG8_LAS unsigned*)(lds + (bufoff) + ldsw + _i * 8192), 16, 0, 0); } while (0)
; #define PG8_LDA(dst, b, h) do { _Pragma("unroll") for (int m = 0; m < 4; ++m) _Pragma("unroll") for (int k = 0; k < 2; ++k) dst[m][k] = *(const PG8_LAS bf16x8*)(lds + PG8_SA(b, h) + aoff + m * 2048 + k * 1024); } while (0)
; #define PG8_LDB(dst, b, h) do { _Pragma("unroll") for (int n = 0; n < 2; ++n) _Pragma("unroll") for (int k = 0; k < 2; ++k) dst[n][k] = *(const PG8_LAS bf16x8*)(lds + PG8_SB(b, h) + boff + n * 2048 + k * 1024); } while (0)
; #define PG8_WAIT_V(n) asm volatile("s_waitcnt vmcnt(" #n ")" ::: "memory")
; #define PG8_WAIT_L(n) asm volatile("s_waitcnt lgkmcnt(" #n ")" ::: "memory")
; template <class Epi, class Sched, bool ALIGN_EPI = false, bool SP2 = false>
; __device__ __forceinline__ void gemm_phase(PG8_LAS unsigned char* lds, const Gemm g, const Sched& S, const Epi& E) {
;     ...
;         const bool has_next = S.next(ui + 1, nxt);
;         const char* nA = has_next ? (const char*)g.A + (size_t)nxt.pm * tstepA + (size_t)nxt.z * g.azs + (size_t)(nxt.k0 >> 6) * kstA : cA; const char* nB = has_next ? (const char*)g.Bt + (size_t)nxt.pn * tstepB + (size_t)nxt.z * g.bzs + (size_t)nxt.k0 * 2 : cB;
;         const int nt = cur.nt;
;         for (int t = 0; t < nt; t += 2) {
;             const bool last = (t == nt - 2);
;             const char* a1 = cA + (size_t)(t + 1) * kstA;
;             const char* a2 = last ? nA : cA + (size_t)(t + 2) * kstA; const char* b2 = last ? nB : cB + (size_t)(t + 2) * kstep;
;             const char* a3 = a2 + kstA; const char* b3 = b2 + kstep;
;             if (last && has_next) S.a_ready(nxt);
;             if constexpr (SP2) {
;             PG8_LDB(B0, 0, 0); PG8_LDB(B1, 0, 1); PG8_SCHED; PG8_LDA(At, 0, 0); PG8_STAGE(PG8_SA(1, 1), a1 + hstepA, voffA);
;             PG8_WAIT_V(8); PG8_WAIT_L(0); PG8_BAR; PG8_MMA(0, 0, At, B0); PG8_MMA(0, 1, At, B1); PG8_BAR; PG8_SCHED;
;             PG8_LDA(At, 0, 1); PG8_STAGE(PG8_SB(0, 0), b2, voffB); PG8_STAGE(PG8_SB(0, 1), b2 + hstepB, voffB); PG8_STAGE(PG8_SA(0, 0), a2, voffA);
;             PG8_WAIT_V(8); PG8_WAIT_L(0); PG8_BAR; PG8_MMA(1, 0, At, B0); PG8_MMA(1, 1, At, B1); PG8_BAR; PG8_SCHED;
.LBB0_1656:
	s_ashr_i32 s41, s40, 31
	s_lshl_b64 s[4:5], s[40:41], 20
	v_readlane_b32 s12, v254, 41
	v_readlane_b32 s13, v254, 42
	s_add_u32 s48, s12, s4
	s_addc_u32 s49, s13, s5
	s_and_b64 s[4:5], s[44:45], exec
	s_cselect_b32 s4, s49, s51
	s_cselect_b32 s5, s48, s50
	s_ashr_i32 s39, s38, 31
	s_lshl_b64 s[12:13], s[38:39], 20
	s_add_u32 s54, s3, s12
	s_addc_u32 s55, s10, s13
	s_and_b64 s[12:13], s[44:45], exec
	s_cselect_b32 s12, s55, s53
	s_cselect_b32 s13, s54, s52
	s_add_u32 s50, s50, 0x80080
	s_addc_u32 s51, s51, 0
	s_add_u32 s39, s52, 0x100
	s_addc_u32 s41, s53, 0
	s_mov_b32 s63, -2
	ds_read_b128 v[156:159], v152
	ds_read_b128 v[160:163], v152 offset:1024
	ds_read_b128 v[164:167], v152 offset:2048
	ds_read_b128 v[168:171], v152 offset:3072
	ds_read_b128 v[172:175], v153
	ds_read_b128 v[176:179], v153 offset:1024
	ds_read_b128 v[180:183], v153 offset:2048
	ds_read_b128 v[190:193], v153 offset:3072
	s_add_u32 s52, s50, 0xfff80080
	s_addc_u32 s53, s51, -1
	s_cmp_eq_u32 s63, 28
	s_cselect_b32 s59, s4, s53
	s_cselect_b32 s58, s5, s52
	s_cselect_b32 s53, s12, s41
	s_cselect_b32 s52, s13, s39
	v_lshl_add_u64 v[226:227], s[50:51], 0, v[142:143]
	s_add_i32 m0, s7, 0xc000
	ds_read_b128 v[194:197], v154
	ds_read_b128 v[198:201], v154 offset:1024
	ds_read_b128 v[202:205], v154 offset:2048
	ds_read_b128 v[206:209], v154 offset:3072
	ds_read_b128 v[210:213], v154 offset:4096
	ds_read_b128 v[214:217], v154 offset:5120
	ds_read_b128 v[218:221], v154 offset:6144
	ds_read_b128 v[222:225], v154 offset:7168
	global_load_lds_dwordx4 v[226:227], off
	v_lshl_add_u64 v[226:227], s[50:51], 0, v[144:145]
	s_add_i32 m0, s7, 0xe000
	s_nop 0
	global_load_lds_dwordx4 v[226:227], off
	s_waitcnt vmcnt(8)
	s_waitcnt lgkmcnt(0)
	s_setprio 1
	s_barrier
	v_mfma_f32_16x16x32_bf16 v[124:127], v[156:159], v[194:197], 0
	v_mfma_f32_16x16x32_bf16 v[120:123], v[164:167], v[194:197], 0
	v_mfma_f32_16x16x32_bf16 v[104:107], v[164:167], v[202:205], 0
	v_mfma_f32_16x16x32_bf16 v[108:111], v[156:159], v[202:205], 0
	v_mfma_f32_16x16x32_bf16 v[92:95], v[156:159], v[210:213], 0
	v_mfma_f32_16x16x32_bf16 v[88:91], v[164:167], v[210:213], 0
	v_mfma_f32_16x16x32_bf16 v[72:75], v[164:167], v[218:221], 0
	v_mfma_f32_16x16x32_bf16 v[76:79], v[156:159], v[218:221], 0
	v_mfma_f32_16x16x32_bf16 v[124:127], v[160:163], v[198:201], v[124:127]
	v_mfma_f32_16x16x32_bf16 v[120:123], v[168:171], v[198:201], v[120:123]
	v_mfma_f32_16x16x32_bf16 v[104:107], v[168:171], v[206:209], v[104:107]
	v_mfma_f32_16x16x32_bf16 v[108:111], v[160:163], v[206:209], v[108:111]
	v_mfma_f32_16x16x32_bf16 v[92:95], v[160:163], v[214:217], v[92:95]
	v_mfma_f32_16x16x32_bf16 v[88:91], v[168:171], v[214:217], v[88:91]
	v_mfma_f32_16x16x32_bf16 v[72:75], v[168:171], v[222:225], v[72:75]
	v_mfma_f32_16x16x32_bf16 v[76:79], v[160:163], v[222:225], v[76:79]
	s_setprio 0
	s_setprio 1
	v_mfma_f32_16x16x32_bf16 v[116:119], v[172:175], v[194:197], 0
	v_mfma_f32_16x16x32_bf16 v[112:115], v[180:183], v[194:197], 0
	v_mfma_f32_16x16x32_bf16 v[96:99], v[180:183], v[202:205], 0
	v_mfma_f32_16x16x32_bf16 v[100:103], v[172:175], v[202:205], 0
	v_mfma_f32_16x16x32_bf16 v[84:87], v[172:175], v[210:213], 0
	v_mfma_f32_16x16x32_bf16 v[80:83], v[180:183], v[210:213], 0
	v_mfma_f32_16x16x32_bf16 v[64:67], v[180:183], v[218:221], 0
	v_mfma_f32_16x16x32_bf16 v[68:71], v[172:175], v[218:221], 0
	v_mfma_f32_16x16x32_bf16 v[116:119], v[176:179], v[198:201], v[116:119]
	v_mfma_f32_16x16x32_bf16 v[112:115], v[190:193], v[198:201], v[112:115]
	v_mfma_f32_16x16x32_bf16 v[96:99], v[190:193], v[206:209], v[96:99]
	v_mfma_f32_16x16x32_bf16 v[100:103], v[176:179], v[206:209], v[100:103]
	v_mfma_f32_16x16x32_bf16 v[84:87], v[176:179], v[214:217], v[84:87]
	v_mfma_f32_16x16x32_bf16 v[80:83], v[190:193], v[214:217], v[80:83]
	v_mfma_f32_16x16x32_bf16 v[64:67], v[190:193], v[222:225], v[64:67]
	v_mfma_f32_16x16x32_bf16 v[68:71], v[176:179], v[222:225], v[68:71]
	s_barrier
	s_setprio 0
	s_add_i32 s64, s56, s6
	v_lshl_add_u64 v[226:227], s[52:53], 0, v[130:131]
	s_mov_b32 m0, s64
	ds_read_b128 v[194:197], v154 offset:16384
	ds_read_b128 v[198:201], v154 offset:17408
	ds_read_b128 v[202:205], v154 offset:18432
	ds_read_b128 v[206:209], v154 offset:19456
	ds_read_b128 v[210:213], v154 offset:20480
	ds_read_b128 v[214:217], v154 offset:21504
	ds_read_b128 v[218:221], v154 offset:22528
	ds_read_b128 v[222:225], v154 offset:23552
	global_load_lds_dwordx4 v[226:227], off
	s_add_i32 m0, s64, 0x2000
	s_add_u32 s64, s52, 0x80000
	v_lshl_add_u64 v[228:229], s[52:53], 0, v[134:135]
	s_addc_u32 s65, s53, 0
	s_add_i32 s66, s57, s6
	global_load_lds_dwordx4 v[228:229], off
	v_lshl_add_u64 v[230:231], s[64:65], 0, v[130:131]
	s_mov_b32 m0, s66
	v_lshl_add_u64 v[232:233], s[58:59], 0, v[132:133]
	global_load_lds_dwordx4 v[230:231], off
	v_lshl_add_u64 v[230:231], s[64:65], 0, v[134:135]
	s_add_i32 m0, s66, 0x2000
	s_nop 0
	global_load_lds_dwordx4 v[230:231], off
	v_lshl_add_u64 v[230:231], s[58:59], 0, v[128:129]
	s_mov_b32 m0, s7
	s_nop 0
	global_load_lds_dwordx4 v[230:231], off
	s_mov_b32 m0, s8
	s_nop 0
	global_load_lds_dwordx4 v[232:233], off
	s_waitcnt vmcnt(8)
	s_waitcnt lgkmcnt(0)
	s_setprio 1
	s_barrier
; #define PG8_STAGE(bufoff, gbase, voff) do { _Pragma("unroll") for (int _i = 0; _i < 2; ++_i) \
;         __builtin_amdgcn_global_load_lds((const unsigned*)((const char*)(gbase) + (voff)[_i]), (PG8_LAS unsigned*)(lds + (bufoff) + ldsw + _i * 8192), 16, 0, 0); } while (0)
; #define PG8_LDA(dst, b, h) do { _Pragma("unroll") for (int m = 0; m < 4; ++m) _Pragma("unroll") for (int k = 0; k < 2; ++k) dst[m][k] = *(const PG8_LAS bf16x8*)(lds + PG8_SA(b, h) + aoff + m * 2048 + k * 1024); } while (0)
; #define PG8_LDB(dst, b, h) do { _Pragma("unroll") for (int n = 0; n < 2; ++n) _Pragma("unroll") for (int k = 0; k < 2; ++k) dst[n][k] = *(const PG8_LAS bf16x8*)(lds + PG8_SB(b, h) + boff + n * 2048 + k * 1024); } while (0)
; #define PG8_MMA(ai, bj, At, Bt) do { __builtin_amdgcn_s_setprio(1); _Pragma("unroll") for (int m = 0; m < 4; ++m) _Pragma("unroll") for (int n = 0; n < 2; ++n) _Pragma("unroll") for (int k = 0; k < 2; ++k) \
;         acc[ai][bj][m][n] = __builtin_amdgcn_mfma_f32_16x16x32_bf16(Bt[n][k], At[m][k], acc[ai][bj][m][n], 0, 0, 0); __builtin_amdgcn_s_setprio(0); } while (0)
; #define PG8_WAIT_V(n) asm volatile("s_waitcnt vmcnt(" #n ")" ::: "memory")
; #define PG8_WAIT_L(n) asm volatile("s_waitcnt lgkmcnt(" #n ")" ::: "memory")
; #define PG8_BAR __builtin_amdgcn_s_barrier()
; #define PG8_SCHED __builtin_amdgcn_sched_barrier(0)
; template <class Epi, class Sched, bool ALIGN_EPI = false, bool SP2 = false>
; __device__ __forceinline__ void gemm_phase(PG8_LAS unsigned char* lds, const Gemm g, const Sched& S, const Epi& E) {
;     ...
;             PG8_WAIT_V(8); PG8_WAIT_L(0); PG8_BAR; PG8_MMA(1, 0, At, B0); PG8_MMA(1, 1, At, B1); PG8_BAR; PG8_SCHED;
;             PG8_LDB(B0, 1, 0); PG8_LDB(B1, 1, 1); PG8_SCHED; PG8_LDA(At, 1, 0); PG8_STAGE(PG8_SA(0, 1), a2 + hstepA, voffA);
;             PG8_WAIT_V(8); PG8_WAIT_L(0); PG8_BAR; PG8_MMA(0, 0, At, B0); PG8_MMA(0, 1, At, B1); PG8_BAR; PG8_SCHED;
	v_mfma_f32_16x16x32_bf16 v[60:63], v[156:159], v[194:197], 0
	v_mfma_f32_16x16x32_bf16 v[56:59], v[164:167], v[194:197], 0
	v_mfma_f32_16x16x32_bf16 v[40:43], v[164:167], v[202:205], 0
	v_mfma_f32_16x16x32_bf16 v[44:47], v[156:159], v[202:205], 0
	v_mfma_f32_16x16x32_bf16 v[28:31], v[156:159], v[210:213], 0
	v_mfma_f32_16x16x32_bf16 v[24:27], v[164:167], v[210:213], 0
	v_mfma_f32_16x16x32_bf16 v[8:11], v[164:167], v[218:221], 0
	v_mfma_f32_16x16x32_bf16 v[12:15], v[156:159], v[218:221], 0
	v_mfma_f32_16x16x32_bf16 v[60:63], v[160:163], v[198:201], v[60:63]
	v_mfma_f32_16x16x32_bf16 v[56:59], v[168:171], v[198:201], v[56:59]
	v_mfma_f32_16x16x32_bf16 v[40:43], v[168:171], v[206:209], v[40:43]
	v_mfma_f32_16x16x32_bf16 v[44:47], v[160:163], v[206:209], v[44:47]
	v_mfma_f32_16x16x32_bf16 v[28:31], v[160:163], v[214:217], v[28:31]
	v_mfma_f32_16x16x32_bf16 v[24:27], v[168:171], v[214:217], v[24:27]
	v_mfma_f32_16x16x32_bf16 v[8:11], v[168:171], v[222:225], v[8:11]
	v_mfma_f32_16x16x32_bf16 v[12:15], v[160:163], v[222:225], v[12:15]
	s_setprio 0
	s_setprio 1
	v_mfma_f32_16x16x32_bf16 v[52:55], v[172:175], v[194:197], 0
	v_mfma_f32_16x16x32_bf16 v[48:51], v[180:183], v[194:197], 0
	v_mfma_f32_16x16x32_bf16 v[32:35], v[180:183], v[202:205], 0
	v_mfma_f32_16x16x32_bf16 v[36:39], v[172:175], v[202:205], 0
	v_mfma_f32_16x16x32_bf16 v[20:23], v[172:175], v[210:213], 0
	v_mfma_f32_16x16x32_bf16 v[16:19], v[180:183], v[210:213], 0
	v_mfma_f32_16x16x32_bf16 v[0:3], v[180:183], v[218:221], 0
	v_mfma_f32_16x16x32_bf16 v[4:7], v[172:175], v[218:221], 0
	v_mfma_f32_16x16x32_bf16 v[52:55], v[176:179], v[198:201], v[52:55]
	v_mfma_f32_16x16x32_bf16 v[48:51], v[190:193], v[198:201], v[48:51]
	v_mfma_f32_16x16x32_bf16 v[32:35], v[190:193], v[206:209], v[32:35]
	v_mfma_f32_16x16x32_bf16 v[36:39], v[176:179], v[206:209], v[36:39]
	v_mfma_f32_16x16x32_bf16 v[20:23], v[176:179], v[214:217], v[20:23]
	v_mfma_f32_16x16x32_bf16 v[16:19], v[190:193], v[214:217], v[16:19]
	v_mfma_f32_16x16x32_bf16 v[0:3], v[190:193], v[222:225], v[0:3]
	v_mfma_f32_16x16x32_bf16 v[4:7], v[176:179], v[222:225], v[4:7]
	s_barrier
	s_setprio 0
	s_add_i32 s64, 0, 0x18000
	v_add_u32_e32 v155, s64, v150
	s_add_i32 s65, 0, 0x1c000
	ds_read_b128 v[156:159], v155
	ds_read_b128 v[160:163], v155 offset:1024
	ds_read_b128 v[164:167], v155 offset:2048
	ds_read_b128 v[168:171], v155 offset:3072
	v_add_u32_e32 v155, s65, v150
	ds_read_b128 v[172:175], v155
	ds_read_b128 v[176:179], v155 offset:1024
	ds_read_b128 v[180:183], v155 offset:2048
	ds_read_b128 v[190:193], v155 offset:3072
	s_add_u32 s58, s58, 0x80000
	s_addc_u32 s59, s59, 0
	s_mov_b32 m0, s9
	v_lshl_add_u64 v[234:235], s[58:59], 0, v[128:129]
	ds_read_b128 v[194:197], v154 offset:32768
	ds_read_b128 v[198:201], v154 offset:33792
	ds_read_b128 v[202:205], v154 offset:34816
	ds_read_b128 v[206:209], v154 offset:35840
	ds_read_b128 v[210:213], v154 offset:36864
	ds_read_b128 v[214:217], v154 offset:37888
	ds_read_b128 v[218:221], v154 offset:38912
	ds_read_b128 v[222:225], v154 offset:39936
	global_load_lds_dwordx4 v[234:235], off
	v_lshl_add_u64 v[234:235], s[58:59], 0, v[132:133]
	s_mov_b32 m0, s11
	s_nop 0
	global_load_lds_dwordx4 v[234:235], off
	s_waitcnt vmcnt(8)
	s_waitcnt lgkmcnt(0)
	s_setprio 1
	s_barrier
	v_mfma_f32_16x16x32_bf16 v[124:127], v[156:159], v[194:197], v[124:127]
	v_mfma_f32_16x16x32_bf16 v[120:123], v[164:167], v[194:197], v[120:123]
	v_mfma_f32_16x16x32_bf16 v[104:107], v[164:167], v[202:205], v[104:107]
	v_mfma_f32_16x16x32_bf16 v[108:111], v[156:159], v[202:205], v[108:111]
	v_mfma_f32_16x16x32_bf16 v[92:95], v[156:159], v[210:213], v[92:95]
	v_mfma_f32_16x16x32_bf16 v[88:91], v[164:167], v[210:213], v[88:91]
	v_mfma_f32_16x16x32_bf16 v[72:75], v[164:167], v[218:221], v[72:75]
	v_mfma_f32_16x16x32_bf16 v[76:79], v[156:159], v[218:221], v[76:79]
	v_mfma_f32_16x16x32_bf16 v[124:127], v[160:163], v[198:201], v[124:127]
	v_mfma_f32_16x16x32_bf16 v[120:123], v[168:171], v[198:201], v[120:123]
	v_mfma_f32_16x16x32_bf16 v[104:107], v[168:171], v[206:209], v[104:107]
	v_mfma_f32_16x16x32_bf16 v[108:111], v[160:163], v[206:209], v[108:111]
	v_mfma_f32_16x16x32_bf16 v[92:95], v[160:163], v[214:217], v[92:95]
	v_mfma_f32_16x16x32_bf16 v[88:91], v[168:171], v[214:217], v[88:91]
	v_mfma_f32_16x16x32_bf16 v[72:75], v[168:171], v[222:225], v[72:75]
	v_mfma_f32_16x16x32_bf16 v[76:79], v[160:163], v[222:225], v[76:79]
	s_setprio 0
	s_setprio 1
	v_mfma_f32_16x16x32_bf16 v[116:119], v[172:175], v[194:197], v[116:119]
	v_mfma_f32_16x16x32_bf16 v[112:115], v[180:183], v[194:197], v[112:115]
	v_mfma_f32_16x16x32_bf16 v[96:99], v[180:183], v[202:205], v[96:99]
	v_mfma_f32_16x16x32_bf16 v[100:103], v[172:175], v[202:205], v[100:103]
	v_mfma_f32_16x16x32_bf16 v[84:87], v[172:175], v[210:213], v[84:87]
	v_mfma_f32_16x16x32_bf16 v[80:83], v[180:183], v[210:213], v[80:83]
	v_mfma_f32_16x16x32_bf16 v[64:67], v[180:183], v[218:221], v[64:67]
	v_mfma_f32_16x16x32_bf16 v[68:71], v[172:175], v[218:221], v[68:71]
	v_mfma_f32_16x16x32_bf16 v[116:119], v[176:179], v[198:201], v[116:119]
	v_mfma_f32_16x16x32_bf16 v[112:115], v[190:193], v[198:201], v[112:115]
	v_mfma_f32_16x16x32_bf16 v[96:99], v[190:193], v[206:209], v[96:99]
	v_mfma_f32_16x16x32_bf16 v[100:103], v[176:179], v[206:209], v[100:103]
	v_mfma_f32_16x16x32_bf16 v[84:87], v[176:179], v[214:217], v[84:87]
	v_mfma_f32_16x16x32_bf16 v[80:83], v[190:193], v[214:217], v[80:83]
	v_mfma_f32_16x16x32_bf16 v[64:67], v[190:193], v[222:225], v[64:67]
	v_mfma_f32_16x16x32_bf16 v[68:71], v[176:179], v[222:225], v[68:71]
	s_barrier
; #define PG8_STAGE(bufoff, gbase, voff) do { _Pragma("unroll") for (int _i = 0; _i < 2; ++_i) \
;         __builtin_amdgcn_global_load_lds((const unsigned*)((const char*)(gbase) + (voff)[_i]), (PG8_LAS unsigned*)(lds + (bufoff) + ldsw + _i * 8192), 16, 0, 0); } while (0)
; #define PG8_LDA(dst, b, h) do { _Pragma("unroll") for (int m = 0; m < 4; ++m) _Pragma("unroll") for (int k = 0; k < 2; ++k) dst[m][k] = *(const PG8_LAS bf16x8*)(lds + PG8_SA(b, h) + aoff + m * 2048 + k * 1024); } while (0)
; #define PG8_LDB(dst, b, h) do { _Pragma("unroll") for (int n = 0; n < 2; ++n) _Pragma("unroll") for (int k = 0; k < 2; ++k) dst[n][k] = *(const PG8_LAS bf16x8*)(lds + PG8_SB(b, h) + boff + n * 2048 + k * 1024); } while (0)
; template <class Epi, class Sched, bool ALIGN_EPI = false, bool SP2 = false>
; __device__ __forceinline__ void gemm_phase(PG8_LAS unsigned char* lds, const Gemm g, const Sched& S, const Epi& E) {
;     ...
;         for (int t = 0; t < nt; t += 2) {
;             const bool last = (t == nt - 2);
;             const char* a1 = cA + (size_t)(t + 1) * kstA;
;             const char* a2 = last ? nA : cA + (size_t)(t + 2) * kstA; const char* b2 = last ? nB : cB + (size_t)(t + 2) * kstep;
;             const char* a3 = a2 + kstA; const char* b3 = b2 + kstep;
;             if (last && has_next) S.a_ready(nxt);
;             if constexpr (SP2) {
;             PG8_LDB(B0, 0, 0); PG8_LDB(B1, 0, 1); PG8_SCHED; PG8_LDA(At, 0, 0); PG8_STAGE(PG8_SA(1, 1), a1 + hstepA, voffA);
;             PG8_WAIT_V(8); PG8_WAIT_L(0); PG8_BAR; PG8_MMA(0, 0, At, B0); PG8_MMA(0, 1, At, B1); PG8_BAR; PG8_SCHED;
;             PG8_LDA(At, 0, 1); PG8_STAGE(PG8_SB(0, 0), b2, voffB); PG8_STAGE(PG8_SB(0, 1), b2 + hstepB, voffB); PG8_STAGE(PG8_SA(0, 0), a2, voffA);
;             PG8_WAIT_V(8); PG8_WAIT_L(0); PG8_BAR; PG8_MMA(1, 0, At, B0); PG8_MMA(1, 1, At, B1); PG8_BAR; PG8_SCHED;
;             PG8_LDB(B0, 1, 0); PG8_LDB(B1, 1, 1); PG8_SCHED; PG8_LDA(At, 1, 0); PG8_STAGE(PG8_SA(0, 1), a2 + hstepA, voffA);
;             PG8_WAIT_V(8); PG8_WAIT_L(0); PG8_BAR; PG8_MMA(0, 0, At, B0); PG8_MMA(0, 1, At, B1); PG8_BAR; PG8_SCHED;
;             PG8_LDA(At, 1, 1); PG8_STAGE(PG8_SB(1, 0), b3, voffB); PG8_STAGE(PG8_SB(1, 1), b3 + hstepB, voffB); PG8_STAGE(PG8_SA(1, 0), a3, voffA);
;             PG8_WAIT_V(8); PG8_WAIT_L(0); PG8_BAR; PG8_MMA(1, 0, At, B0); PG8_MMA(1, 1, At, B1); PG8_BAR; PG8_SCHED;
	s_setprio 0
	s_add_i32 s58, s64, s6
	v_lshl_add_u64 v[226:227], v[226:227], 0, s[20:21]
	s_mov_b32 m0, s58
	ds_read_b128 v[194:197], v154 offset:49152
	ds_read_b128 v[198:201], v154 offset:50176
	ds_read_b128 v[202:205], v154 offset:51200
	ds_read_b128 v[206:209], v154 offset:52224
	ds_read_b128 v[210:213], v154 offset:53248
	ds_read_b128 v[214:217], v154 offset:54272
	ds_read_b128 v[218:221], v154 offset:55296
	ds_read_b128 v[222:225], v154 offset:56320
	global_load_lds_dwordx4 v[226:227], off
	s_add_i32 m0, s58, 0x2000
	s_add_u32 s52, s52, 0x80080
	v_lshl_add_u64 v[226:227], v[228:229], 0, s[20:21]
	s_addc_u32 s53, s53, 0
	s_add_i32 s58, s65, s6
	global_load_lds_dwordx4 v[226:227], off
	v_lshl_add_u64 v[226:227], s[52:53], 0, v[130:131]
	s_mov_b32 m0, s58
	s_nop 0
	global_load_lds_dwordx4 v[226:227], off
	v_lshl_add_u64 v[226:227], s[52:53], 0, v[134:135]
	s_add_i32 m0, s58, 0x2000
	s_nop 0
	global_load_lds_dwordx4 v[226:227], off
	v_lshl_add_u64 v[226:227], v[230:231], 0, s[20:21]
	s_mov_b32 m0, s46
	s_nop 0
	global_load_lds_dwordx4 v[226:227], off
	v_lshl_add_u64 v[226:227], v[232:233], 0, s[20:21]
	s_mov_b32 m0, s47
	s_nop 0
	global_load_lds_dwordx4 v[226:227], off
	s_waitcnt vmcnt(8)
	s_waitcnt lgkmcnt(0)
	s_setprio 1
	s_barrier
	v_mfma_f32_16x16x32_bf16 v[60:63], v[156:159], v[194:197], v[60:63]
	v_mfma_f32_16x16x32_bf16 v[56:59], v[164:167], v[194:197], v[56:59]
	v_mfma_f32_16x16x32_bf16 v[40:43], v[164:167], v[202:205], v[40:43]
	v_mfma_f32_16x16x32_bf16 v[44:47], v[156:159], v[202:205], v[44:47]
	v_mfma_f32_16x16x32_bf16 v[28:31], v[156:159], v[210:213], v[28:31]
	v_mfma_f32_16x16x32_bf16 v[24:27], v[164:167], v[210:213], v[24:27]
	v_mfma_f32_16x16x32_bf16 v[8:11], v[164:167], v[218:221], v[8:11]
	v_mfma_f32_16x16x32_bf16 v[12:15], v[156:159], v[218:221], v[12:15]
	v_mfma_f32_16x16x32_bf16 v[60:63], v[160:163], v[198:201], v[60:63]
	v_mfma_f32_16x16x32_bf16 v[56:59], v[168:171], v[198:201], v[56:59]
	v_mfma_f32_16x16x32_bf16 v[40:43], v[168:171], v[206:209], v[40:43]
	v_mfma_f32_16x16x32_bf16 v[44:47], v[160:163], v[206:209], v[44:47]
	v_mfma_f32_16x16x32_bf16 v[28:31], v[160:163], v[214:217], v[28:31]
	v_mfma_f32_16x16x32_bf16 v[24:27], v[168:171], v[214:217], v[24:27]
	v_mfma_f32_16x16x32_bf16 v[8:11], v[168:171], v[222:225], v[8:11]
	v_mfma_f32_16x16x32_bf16 v[12:15], v[160:163], v[222:225], v[12:15]
	s_setprio 0
	s_setprio 1
	v_mfma_f32_16x16x32_bf16 v[52:55], v[172:175], v[194:197], v[52:55]
	v_mfma_f32_16x16x32_bf16 v[48:51], v[180:183], v[194:197], v[48:51]
	v_mfma_f32_16x16x32_bf16 v[32:35], v[180:183], v[202:205], v[32:35]
	v_mfma_f32_16x16x32_bf16 v[36:39], v[172:175], v[202:205], v[36:39]
	v_mfma_f32_16x16x32_bf16 v[20:23], v[172:175], v[210:213], v[20:23]
	v_mfma_f32_16x16x32_bf16 v[16:19], v[180:183], v[210:213], v[16:19]
	v_mfma_f32_16x16x32_bf16 v[0:3], v[180:183], v[218:221], v[0:3]
	v_mfma_f32_16x16x32_bf16 v[4:7], v[172:175], v[218:221], v[4:7]
	v_mfma_f32_16x16x32_bf16 v[52:55], v[176:179], v[198:201], v[52:55]
	v_mfma_f32_16x16x32_bf16 v[48:51], v[190:193], v[198:201], v[48:51]
	v_mfma_f32_16x16x32_bf16 v[32:35], v[190:193], v[206:209], v[32:35]
	v_mfma_f32_16x16x32_bf16 v[36:39], v[176:179], v[206:209], v[36:39]
	v_mfma_f32_16x16x32_bf16 v[20:23], v[176:179], v[214:217], v[20:23]
	v_mfma_f32_16x16x32_bf16 v[16:19], v[190:193], v[214:217], v[16:19]
	v_mfma_f32_16x16x32_bf16 v[0:3], v[190:193], v[222:225], v[0:3]
	v_mfma_f32_16x16x32_bf16 v[4:7], v[176:179], v[222:225], v[4:7]
	s_barrier
	s_setprio 0
	s_add_i32 s63, s63, 2
	s_add_u32 s50, s50, 0x100
	s_addc_u32 s51, s51, 0
	s_add_u32 s39, s39, 0x100
	s_addc_u32 s41, s41, 0
	s_cmp_gt_u32 s63, 29
	s_cbranch_scc1 .Lmy_peel_7_exit
.LBB0_1657:
	ds_read_b128 v[156:159], v152
	ds_read_b128 v[160:163], v152 offset:1024
	ds_read_b128 v[164:167], v152 offset:2048
	ds_read_b128 v[168:171], v152 offset:3072
	ds_read_b128 v[172:175], v153
	ds_read_b128 v[176:179], v153 offset:1024
	ds_read_b128 v[180:183], v153 offset:2048
	ds_read_b128 v[190:193], v153 offset:3072
	s_add_u32 s52, s50, 0xfff80080
	s_addc_u32 s53, s51, -1
	s_cmp_eq_u32 s63, 28
	s_cselect_b32 s59, s4, s53
	s_cselect_b32 s58, s5, s52
	s_cselect_b32 s53, s12, s41
	s_cselect_b32 s52, s13, s39
	v_lshl_add_u64 v[226:227], s[50:51], 0, v[142:143]
	s_add_i32 m0, s7, 0xc000
	ds_read_b128 v[194:197], v154
	ds_read_b128 v[198:201], v154 offset:1024
	ds_read_b128 v[202:205], v154 offset:2048
	ds_read_b128 v[206:209], v154 offset:3072
	ds_read_b128 v[210:213], v154 offset:4096
	ds_read_b128 v[214:217], v154 offset:5120
	ds_read_b128 v[218:221], v154 offset:6144
	ds_read_b128 v[222:225], v154 offset:7168
	global_load_lds_dwordx4 v[226:227], off
	v_lshl_add_u64 v[226:227], s[50:51], 0, v[144:145]
	s_add_i32 m0, s7, 0xe000
	s_nop 0
	global_load_lds_dwordx4 v[226:227], off
	s_waitcnt vmcnt(8)
	s_waitcnt lgkmcnt(0)
	s_setprio 1
	s_barrier
; #define PG8_STAGE(bufoff, gbase, voff) do { _Pragma("unroll") for (int _i = 0; _i < 2; ++_i) \
;         __builtin_amdgcn_global_load_lds((const unsigned*)((const char*)(gbase) + (voff)[_i]), (PG8_LAS unsigned*)(lds + (bufoff) + ldsw + _i * 8192), 16, 0, 0); } while (0)
; #define PG8_LDA(dst, b, h) do { _Pragma("unroll") for (int m = 0; m < 4; ++m) _Pragma("unroll") for (int k = 0; k < 2; ++k) dst[m][k] = *(const PG8_LAS bf16x8*)(lds + PG8_SA(b, h) + aoff + m * 2048 + k * 1024); } while (0)
; #define PG8_MMA(ai, bj, At, Bt) do { __builtin_amdgcn_s_setprio(1); _Pragma("unroll") for (int m = 0; m < 4; ++m) _Pragma("unroll") for (int n = 0; n < 2; ++n) _Pragma("unroll") for (int k = 0; k < 2; ++k) \
;         acc[ai][bj][m][n] = __builtin_amdgcn_mfma_f32_16x16x32_bf16(Bt[n][k], At[m][k], acc[ai][bj][m][n], 0, 0, 0); __builtin_amdgcn_s_setprio(0); } while (0)
; #define PG8_WAIT_V(n) asm volatile("s_waitcnt vmcnt(" #n ")" ::: "memory")
; #define PG8_WAIT_L(n) asm volatile("s_waitcnt lgkmcnt(" #n ")" ::: "memory")
; #define PG8_BAR __builtin_amdgcn_s_barrier()
; #define PG8_SCHED __builtin_amdgcn_sched_barrier(0)
; template <class Epi, class Sched, bool ALIGN_EPI = false, bool SP2 = false>
; __device__ __forceinline__ void gemm_phase(PG8_LAS unsigned char* lds, const Gemm g, const Sched& S, const Epi& E) {
;     ...
;             PG8_WAIT_V(8); PG8_WAIT_L(0); PG8_BAR; PG8_MMA(0, 0, At, B0); PG8_MMA(0, 1, At, B1); PG8_BAR; PG8_SCHED;
;             PG8_LDA(At, 0, 1); PG8_STAGE(PG8_SB(0, 0), b2, voffB); PG8_STAGE(PG8_SB(0, 1), b2 + hstepB, voffB); PG8_STAGE(PG8_SA(0, 0), a2, voffA);
;             PG8_WAIT_V(8); PG8_WAIT_L(0); PG8_BAR; PG8_MMA(1, 0, At, B0); PG8_MMA(1, 1, At, B1); PG8_BAR; PG8_SCHED;
	v_mfma_f32_16x16x32_bf16 v[124:127], v[156:159], v[194:197], v[124:127]
	v_mfma_f32_16x16x32_bf16 v[120:123], v[164:167], v[194:197], v[120:123]
	v_mfma_f32_16x16x32_bf16 v[104:107], v[164:167], v[202:205], v[104:107]
	v_mfma_f32_16x16x32_bf16 v[108:111], v[156:159], v[202:205], v[108:111]
	v_mfma_f32_16x16x32_bf16 v[92:95], v[156:159], v[210:213], v[92:95]
	v_mfma_f32_16x16x32_bf16 v[88:91], v[164:167], v[210:213], v[88:91]
	v_mfma_f32_16x16x32_bf16 v[72:75], v[164:167], v[218:221], v[72:75]
	v_mfma_f32_16x16x32_bf16 v[76:79], v[156:159], v[218:221], v[76:79]
	v_mfma_f32_16x16x32_bf16 v[124:127], v[160:163], v[198:201], v[124:127]
	v_mfma_f32_16x16x32_bf16 v[120:123], v[168:171], v[198:201], v[120:123]
	v_mfma_f32_16x16x32_bf16 v[104:107], v[168:171], v[206:209], v[104:107]
	v_mfma_f32_16x16x32_bf16 v[108:111], v[160:163], v[206:209], v[108:111]
	v_mfma_f32_16x16x32_bf16 v[92:95], v[160:163], v[214:217], v[92:95]
	v_mfma_f32_16x16x32_bf16 v[88:91], v[168:171], v[214:217], v[88:91]
	v_mfma_f32_16x16x32_bf16 v[72:75], v[168:171], v[222:225], v[72:75]
	v_mfma_f32_16x16x32_bf16 v[76:79], v[160:163], v[222:225], v[76:79]
	s_setprio 0
	s_setprio 1
	v_mfma_f32_16x16x32_bf16 v[116:119], v[172:175], v[194:197], v[116:119]
	v_mfma_f32_16x16x32_bf16 v[112:115], v[180:183], v[194:197], v[112:115]
	v_mfma_f32_16x16x32_bf16 v[96:99], v[180:183], v[202:205], v[96:99]
	v_mfma_f32_16x16x32_bf16 v[100:103], v[172:175], v[202:205], v[100:103]
	v_mfma_f32_16x16x32_bf16 v[84:87], v[172:175], v[210:213], v[84:87]
	v_mfma_f32_16x16x32_bf16 v[80:83], v[180:183], v[210:213], v[80:83]
	v_mfma_f32_16x16x32_bf16 v[64:67], v[180:183], v[218:221], v[64:67]
	v_mfma_f32_16x16x32_bf16 v[68:71], v[172:175], v[218:221], v[68:71]
	v_mfma_f32_16x16x32_bf16 v[116:119], v[176:179], v[198:201], v[116:119]
	v_mfma_f32_16x16x32_bf16 v[112:115], v[190:193], v[198:201], v[112:115]
	v_mfma_f32_16x16x32_bf16 v[96:99], v[190:193], v[206:209], v[96:99]
	v_mfma_f32_16x16x32_bf16 v[100:103], v[176:179], v[206:209], v[100:103]
	v_mfma_f32_16x16x32_bf16 v[84:87], v[176:179], v[214:217], v[84:87]
	v_mfma_f32_16x16x32_bf16 v[80:83], v[190:193], v[214:217], v[80:83]
	v_mfma_f32_16x16x32_bf16 v[64:67], v[190:193], v[222:225], v[64:67]
	v_mfma_f32_16x16x32_bf16 v[68:71], v[176:179], v[222:225], v[68:71]
	s_barrier
	s_setprio 0
	s_add_i32 s64, s56, s6
	v_lshl_add_u64 v[226:227], s[52:53], 0, v[130:131]
	s_mov_b32 m0, s64
	ds_read_b128 v[194:197], v154 offset:16384
	ds_read_b128 v[198:201], v154 offset:17408
	ds_read_b128 v[202:205], v154 offset:18432
	ds_read_b128 v[206:209], v154 offset:19456
	ds_read_b128 v[210:213], v154 offset:20480
	ds_read_b128 v[214:217], v154 offset:21504
	ds_read_b128 v[218:221], v154 offset:22528
	ds_read_b128 v[222:225], v154 offset:23552
	global_load_lds_dwordx4 v[226:227], off
	s_add_i32 m0, s64, 0x2000
	s_add_u32 s64, s52, 0x80000
	v_lshl_add_u64 v[228:229], s[52:53], 0, v[134:135]
	s_addc_u32 s65, s53, 0
	s_add_i32 s66, s57, s6
	global_load_lds_dwordx4 v[228:229], off
	v_lshl_add_u64 v[230:231], s[64:65], 0, v[130:131]
	s_mov_b32 m0, s66
	v_lshl_add_u64 v[232:233], s[58:59], 0, v[132:133]
	global_load_lds_dwordx4 v[230:231], off
	v_lshl_add_u64 v[230:231], s[64:65], 0, v[134:135]
	s_add_i32 m0, s66, 0x2000
	s_nop 0
	global_load_lds_dwordx4 v[230:231], off
	v_lshl_add_u64 v[230:231], s[58:59], 0, v[128:129]
	s_mov_b32 m0, s7
	s_nop 0
	global_load_lds_dwordx4 v[230:231], off
	s_mov_b32 m0, s8
	s_nop 0
	global_load_lds_dwordx4 v[232:233], off
	s_waitcnt vmcnt(8)
	s_waitcnt lgkmcnt(0)
	s_setprio 1
	s_barrier
	v_mfma_f32_16x16x32_bf16 v[60:63], v[156:159], v[194:197], v[60:63]
	v_mfma_f32_16x16x32_bf16 v[56:59], v[164:167], v[194:197], v[56:59]
	v_mfma_f32_16x16x32_bf16 v[40:43], v[164:167], v[202:205], v[40:43]
	v_mfma_f32_16x16x32_bf16 v[44:47], v[156:159], v[202:205], v[44:47]
	v_mfma_f32_16x16x32_bf16 v[28:31], v[156:159], v[210:213], v[28:31]
	v_mfma_f32_16x16x32_bf16 v[24:27], v[164:167], v[210:213], v[24:27]
	v_mfma_f32_16x16x32_bf16 v[8:11], v[164:167], v[218:221], v[8:11]
	v_mfma_f32_16x16x32_bf16 v[12:15], v[156:159], v[218:221], v[12:15]
	v_mfma_f32_16x16x32_bf16 v[60:63], v[160:163], v[198:201], v[60:63]
	v_mfma_f32_16x16x32_bf16 v[56:59], v[168:171], v[198:201], v[56:59]
	v_mfma_f32_16x16x32_bf16 v[40:43], v[168:171], v[206:209], v[40:43]
	v_mfma_f32_16x16x32_bf16 v[44:47], v[160:163], v[206:209], v[44:47]
	v_mfma_f32_16x16x32_bf16 v[28:31], v[160:163], v[214:217], v[28:31]
	v_mfma_f32_16x16x32_bf16 v[24:27], v[168:171], v[214:217], v[24:27]
	v_mfma_f32_16x16x32_bf16 v[8:11], v[168:171], v[222:225], v[8:11]
	v_mfma_f32_16x16x32_bf16 v[12:15], v[160:163], v[222:225], v[12:15]
	s_setprio 0
	s_setprio 1
	v_mfma_f32_16x16x32_bf16 v[52:55], v[172:175], v[194:197], v[52:55]
	v_mfma_f32_16x16x32_bf16 v[48:51], v[180:183], v[194:197], v[48:51]
	v_mfma_f32_16x16x32_bf16 v[32:35], v[180:183], v[202:205], v[32:35]
	v_mfma_f32_16x16x32_bf16 v[36:39], v[172:175], v[202:205], v[36:39]
	v_mfma_f32_16x16x32_bf16 v[20:23], v[172:175], v[210:213], v[20:23]
	v_mfma_f32_16x16x32_bf16 v[16:19], v[180:183], v[210:213], v[16:19]
	v_mfma_f32_16x16x32_bf16 v[0:3], v[180:183], v[218:221], v[0:3]
	v_mfma_f32_16x16x32_bf16 v[4:7], v[172:175], v[218:221], v[4:7]
	v_mfma_f32_16x16x32_bf16 v[52:55], v[176:179], v[198:201], v[52:55]
	v_mfma_f32_16x16x32_bf16 v[48:51], v[190:193], v[198:201], v[48:51]
	v_mfma_f32_16x16x32_bf16 v[32:35], v[190:193], v[206:209], v[32:35]
	v_mfma_f32_16x16x32_bf16 v[36:39], v[176:179], v[206:209], v[36:39]
	v_mfma_f32_16x16x32_bf16 v[20:23], v[176:179], v[214:217], v[20:23]
	v_mfma_f32_16x16x32_bf16 v[16:19], v[190:193], v[214:217], v[16:19]
	v_mfma_f32_16x16x32_bf16 v[0:3], v[190:193], v[222:225], v[0:3]
	v_mfma_f32_16x16x32_bf16 v[4:7], v[176:179], v[222:225], v[4:7]
	s_barrier
; #define PG8_STAGE(bufoff, gbase, voff) do { _Pragma("unroll") for (int _i = 0; _i < 2; ++_i) \
;         __builtin_amdgcn_global_load_lds((const unsigned*)((const char*)(gbase) + (voff)[_i]), (PG8_LAS unsigned*)(lds + (bufoff) + ldsw + _i * 8192), 16, 0, 0); } while (0)
; #define PG8_LDA(dst, b, h) do { _Pragma("unroll") for (int m = 0; m < 4; ++m) _Pragma("unroll") for (int k = 0; k < 2; ++k) dst[m][k] = *(const PG8_LAS bf16x8*)(lds + PG8_SA(b, h) + aoff + m * 2048 + k * 1024); } while (0)
; #define PG8_LDB(dst, b, h) do { _Pragma("unroll") for (int n = 0; n < 2; ++n) _Pragma("unroll") for (int k = 0; k < 2; ++k) dst[n][k] = *(const PG8_LAS bf16x8*)(lds + PG8_SB(b, h) + boff + n * 2048 + k * 1024); } while (0)
; #define PG8_MMA(ai, bj, At, Bt) do { __builtin_amdgcn_s_setprio(1); _Pragma("unroll") for (int m = 0; m < 4; ++m) _Pragma("unroll") for (int n = 0; n < 2; ++n) _Pragma("unroll") for (int k = 0; k < 2; ++k) \
;         acc[ai][bj][m][n] = __builtin_amdgcn_mfma_f32_16x16x32_bf16(Bt[n][k], At[m][k], acc[ai][bj][m][n], 0, 0, 0); __builtin_amdgcn_s_setprio(0); } while (0)
; #define PG8_WAIT_V(n) asm volatile("s_waitcnt vmcnt(" #n ")" ::: "memory")
; #define PG8_WAIT_L(n) asm volatile("s_waitcnt lgkmcnt(" #n ")" ::: "memory")
; #define PG8_BAR __builtin_amdgcn_s_barrier()
; #define PG8_SCHED __builtin_amdgcn_sched_barrier(0)
; template <class Epi, class Sched, bool ALIGN_EPI = false, bool SP2 = false>
; __device__ __forceinline__ void gemm_phase(PG8_LAS unsigned char* lds, const Gemm g, const Sched& S, const Epi& E) {
;     ...
;             PG8_LDB(B0, 1, 0); PG8_LDB(B1, 1, 1); PG8_SCHED; PG8_LDA(At, 1, 0); PG8_STAGE(PG8_SA(0, 1), a2 + hstepA, voffA);
;             PG8_WAIT_V(8); PG8_WAIT_L(0); PG8_BAR; PG8_MMA(0, 0, At, B0); PG8_MMA(0, 1, At, B1); PG8_BAR; PG8_SCHED;
	s_setprio 0
	s_add_i32 s64, 0, 0x18000
	v_add_u32_e32 v155, s64, v150
	s_add_i32 s65, 0, 0x1c000
	ds_read_b128 v[156:159], v155
	ds_read_b128 v[160:163], v155 offset:1024
	ds_read_b128 v[164:167], v155 offset:2048
	ds_read_b128 v[168:171], v155 offset:3072
	v_add_u32_e32 v155, s65, v150
	ds_read_b128 v[172:175], v155
	ds_read_b128 v[176:179], v155 offset:1024
	ds_read_b128 v[180:183], v155 offset:2048
	ds_read_b128 v[190:193], v155 offset:3072
	s_add_u32 s58, s58, 0x80000
	s_addc_u32 s59, s59, 0
	s_mov_b32 m0, s9
	v_lshl_add_u64 v[234:235], s[58:59], 0, v[128:129]
	ds_read_b128 v[194:197], v154 offset:32768
	ds_read_b128 v[198:201], v154 offset:33792
	ds_read_b128 v[202:205], v154 offset:34816
	ds_read_b128 v[206:209], v154 offset:35840
	ds_read_b128 v[210:213], v154 offset:36864
	ds_read_b128 v[214:217], v154 offset:37888
	ds_read_b128 v[218:221], v154 offset:38912
	ds_read_b128 v[222:225], v154 offset:39936
	global_load_lds_dwordx4 v[234:235], off
	v_lshl_add_u64 v[234:235], s[58:59], 0, v[132:133]
	s_mov_b32 m0, s11
	s_nop 0
	global_load_lds_dwordx4 v[234:235], off
	s_waitcnt vmcnt(8)
	s_waitcnt lgkmcnt(0)
	s_setprio 1
	s_barrier
	v_mfma_f32_16x16x32_bf16 v[124:127], v[156:159], v[194:197], v[124:127]
	v_mfma_f32_16x16x32_bf16 v[120:123], v[164:167], v[194:197], v[120:123]
	v_mfma_f32_16x16x32_bf16 v[104:107], v[164:167], v[202:205], v[104:107]
	v_mfma_f32_16x16x32_bf16 v[108:111], v[156:159], v[202:205], v[108:111]
	v_mfma_f32_16x16x32_bf16 v[92:95], v[156:159], v[210:213], v[92:95]
	v_mfma_f32_16x16x32_bf16 v[88:91], v[164:167], v[210:213], v[88:91]
	v_mfma_f32_16x16x32_bf16 v[72:75], v[164:167], v[218:221], v[72:75]
	v_mfma_f32_16x16x32_bf16 v[76:79], v[156:159], v[218:221], v[76:79]
	v_mfma_f32_16x16x32_bf16 v[124:127], v[160:163], v[198:201], v[124:127]
	v_mfma_f32_16x16x32_bf16 v[120:123], v[168:171], v[198:201], v[120:123]
	v_mfma_f32_16x16x32_bf16 v[104:107], v[168:171], v[206:209], v[104:107]
	v_mfma_f32_16x16x32_bf16 v[108:111], v[160:163], v[206:209], v[108:111]
	v_mfma_f32_16x16x32_bf16 v[92:95], v[160:163], v[214:217], v[92:95]
	v_mfma_f32_16x16x32_bf16 v[88:91], v[168:171], v[214:217], v[88:91]
	v_mfma_f32_16x16x32_bf16 v[72:75], v[168:171], v[222:225], v[72:75]
	v_mfma_f32_16x16x32_bf16 v[76:79], v[160:163], v[222:225], v[76:79]
	s_setprio 0
	s_setprio 1
	v_mfma_f32_16x16x32_bf16 v[116:119], v[172:175], v[194:197], v[116:119]
	v_mfma_f32_16x16x32_bf16 v[112:115], v[180:183], v[194:197], v[112:115]
	v_mfma_f32_16x16x32_bf16 v[96:99], v[180:183], v[202:205], v[96:99]
	v_mfma_f32_16x16x32_bf16 v[100:103], v[172:175], v[202:205], v[100:103]
	v_mfma_f32_16x16x32_bf16 v[84:87], v[172:175], v[210:213], v[84:87]
	v_mfma_f32_16x16x32_bf16 v[80:83], v[180:183], v[210:213], v[80:83]
	v_mfma_f32_16x16x32_bf16 v[64:67], v[180:183], v[218:221], v[64:67]
	v_mfma_f32_16x16x32_bf16 v[68:71], v[172:175], v[218:221], v[68:71]
	v_mfma_f32_16x16x32_bf16 v[116:119], v[176:179], v[198:201], v[116:119]
	v_mfma_f32_16x16x32_bf16 v[112:115], v[190:193], v[198:201], v[112:115]
	v_mfma_f32_16x16x32_bf16 v[96:99], v[190:193], v[206:209], v[96:99]
	v_mfma_f32_16x16x32_bf16 v[100:103], v[176:179], v[206:209], v[100:103]
	v_mfma_f32_16x16x32_bf16 v[84:87], v[176:179], v[214:217], v[84:87]
	v_mfma_f32_16x16x32_bf16 v[80:83], v[190:193], v[214:217], v[80:83]
	v_mfma_f32_16x16x32_bf16 v[64:67], v[190:193], v[222:225], v[64:67]
	v_mfma_f32_16x16x32_bf16 v[68:71], v[176:179], v[222:225], v[68:71]
	s_barrier
; #define PG8_STAGE(bufoff, gbase, voff) do { _Pragma("unroll") for (int _i = 0; _i < 2; ++_i) \
;         __builtin_amdgcn_global_load_lds((const unsigned*)((const char*)(gbase) + (voff)[_i]), (PG8_LAS unsigned*)(lds + (bufoff) + ldsw + _i * 8192), 16, 0, 0); } while (0)
; #define PG8_LDA(dst, b, h) do { _Pragma("unroll") for (int m = 0; m < 4; ++m) _Pragma("unroll") for (int k = 0; k < 2; ++k) dst[m][k] = *(const PG8_LAS bf16x8*)(lds + PG8_SA(b, h) + aoff + m * 2048 + k * 1024); } while (0)
; #define PG8_MMA(ai, bj, At, Bt) do { __builtin_amdgcn_s_setprio(1); _Pragma("unroll") for (int m = 0; m < 4; ++m) _Pragma("unroll") for (int n = 0; n < 2; ++n) _Pragma("unroll") for (int k = 0; k < 2; ++k) \
;         acc[ai][bj][m][n] = __builtin_amdgcn_mfma_f32_16x16x32_bf16(Bt[n][k], At[m][k], acc[ai][bj][m][n], 0, 0, 0); __builtin_amdgcn_s_setprio(0); } while (0)
; #define PG8_WAIT_V(n) asm volatile("s_waitcnt vmcnt(" #n ")" ::: "memory")
; #define PG8_WAIT_L(n) asm volatile("s_waitcnt lgkmcnt(" #n ")" ::: "memory")
; #define PG8_BAR __builtin_amdgcn_s_barrier()
; #define PG8_SCHED __builtin_amdgcn_sched_barrier(0)
; template <class Epi, class Sched, bool ALIGN_EPI = false, bool SP2 = false>
; __device__ __forceinline__ void gemm_phase(PG8_LAS unsigned char* lds, const Gemm g, const Sched& S, const Epi& E) {
;     ...
;         for (int t = 0; t < nt; t += 2) {
;     ...
;             PG8_LDA(At, 1, 1); PG8_STAGE(PG8_SB(1, 0), b3, voffB); PG8_STAGE(PG8_SB(1, 1), b3 + hstepB, voffB); PG8_STAGE(PG8_SA(1, 0), a3, voffA);
;             PG8_WAIT_V(8); PG8_WAIT_L(0); PG8_BAR; PG8_MMA(1, 0, At, B0); PG8_MMA(1, 1, At, B1); PG8_BAR; PG8_SCHED;
	s_setprio 0
	s_add_i32 s58, s64, s6
	v_lshl_add_u64 v[226:227], v[226:227], 0, s[20:21]
	s_mov_b32 m0, s58
	ds_read_b128 v[194:197], v154 offset:49152
	ds_read_b128 v[198:201], v154 offset:50176
	ds_read_b128 v[202:205], v154 offset:51200
	ds_read_b128 v[206:209], v154 offset:52224
	ds_read_b128 v[210:213], v154 offset:53248
	ds_read_b128 v[214:217], v154 offset:54272
	ds_read_b128 v[218:221], v154 offset:55296
	ds_read_b128 v[222:225], v154 offset:56320
	global_load_lds_dwordx4 v[226:227], off
	s_add_i32 m0, s58, 0x2000
	s_add_u32 s52, s52, 0x80080
	v_lshl_add_u64 v[226:227], v[228:229], 0, s[20:21]
	s_addc_u32 s53, s53, 0
	s_add_i32 s58, s65, s6
	global_load_lds_dwordx4 v[226:227], off
	v_lshl_add_u64 v[226:227], s[52:53], 0, v[130:131]
	s_mov_b32 m0, s58
	s_nop 0
	global_load_lds_dwordx4 v[226:227], off
	v_lshl_add_u64 v[226:227], s[52:53], 0, v[134:135]
	s_add_i32 m0, s58, 0x2000
	s_nop 0
	global_load_lds_dwordx4 v[226:227], off
	v_lshl_add_u64 v[226:227], v[230:231], 0, s[20:21]
	s_mov_b32 m0, s46
	s_nop 0
	global_load_lds_dwordx4 v[226:227], off
	v_lshl_add_u64 v[226:227], v[232:233], 0, s[20:21]
	s_mov_b32 m0, s47
	s_nop 0
	global_load_lds_dwordx4 v[226:227], off
	s_waitcnt vmcnt(8)
	s_waitcnt lgkmcnt(0)
	s_setprio 1
	s_barrier
	v_mfma_f32_16x16x32_bf16 v[60:63], v[156:159], v[194:197], v[60:63]
	v_mfma_f32_16x16x32_bf16 v[56:59], v[164:167], v[194:197], v[56:59]
	v_mfma_f32_16x16x32_bf16 v[40:43], v[164:167], v[202:205], v[40:43]
	v_mfma_f32_16x16x32_bf16 v[44:47], v[156:159], v[202:205], v[44:47]
	v_mfma_f32_16x16x32_bf16 v[28:31], v[156:159], v[210:213], v[28:31]
	v_mfma_f32_16x16x32_bf16 v[24:27], v[164:167], v[210:213], v[24:27]
	v_mfma_f32_16x16x32_bf16 v[8:11], v[164:167], v[218:221], v[8:11]
	v_mfma_f32_16x16x32_bf16 v[12:15], v[156:159], v[218:221], v[12:15]
	v_mfma_f32_16x16x32_bf16 v[60:63], v[160:163], v[198:201], v[60:63]
	v_mfma_f32_16x16x32_bf16 v[56:59], v[168:171], v[198:201], v[56:59]
	v_mfma_f32_16x16x32_bf16 v[40:43], v[168:171], v[206:209], v[40:43]
	v_mfma_f32_16x16x32_bf16 v[44:47], v[160:163], v[206:209], v[44:47]
	v_mfma_f32_16x16x32_bf16 v[28:31], v[160:163], v[214:217], v[28:31]
	v_mfma_f32_16x16x32_bf16 v[24:27], v[168:171], v[214:217], v[24:27]
	v_mfma_f32_16x16x32_bf16 v[8:11], v[168:171], v[222:225], v[8:11]
	v_mfma_f32_16x16x32_bf16 v[12:15], v[160:163], v[222:225], v[12:15]
	s_setprio 0
	s_setprio 1
	v_mfma_f32_16x16x32_bf16 v[52:55], v[172:175], v[194:197], v[52:55]
	v_mfma_f32_16x16x32_bf16 v[48:51], v[180:183], v[194:197], v[48:51]
	v_mfma_f32_16x16x32_bf16 v[32:35], v[180:183], v[202:205], v[32:35]
	v_mfma_f32_16x16x32_bf16 v[36:39], v[172:175], v[202:205], v[36:39]
	v_mfma_f32_16x16x32_bf16 v[20:23], v[172:175], v[210:213], v[20:23]
	v_mfma_f32_16x16x32_bf16 v[16:19], v[180:183], v[210:213], v[16:19]
	v_mfma_f32_16x16x32_bf16 v[0:3], v[180:183], v[218:221], v[0:3]
	v_mfma_f32_16x16x32_bf16 v[4:7], v[172:175], v[218:221], v[4:7]
	v_mfma_f32_16x16x32_bf16 v[52:55], v[176:179], v[198:201], v[52:55]
	v_mfma_f32_16x16x32_bf16 v[48:51], v[190:193], v[198:201], v[48:51]
	v_mfma_f32_16x16x32_bf16 v[32:35], v[190:193], v[206:209], v[32:35]
	v_mfma_f32_16x16x32_bf16 v[36:39], v[176:179], v[206:209], v[36:39]
	v_mfma_f32_16x16x32_bf16 v[20:23], v[176:179], v[214:217], v[20:23]
	v_mfma_f32_16x16x32_bf16 v[16:19], v[190:193], v[214:217], v[16:19]
	v_mfma_f32_16x16x32_bf16 v[0:3], v[190:193], v[222:225], v[0:3]
	v_mfma_f32_16x16x32_bf16 v[4:7], v[176:179], v[222:225], v[4:7]
	s_barrier
	s_setprio 0
	s_add_i32 s63, s63, 2
	s_add_u32 s50, s50, 0x100
	s_addc_u32 s51, s51, 0
	s_add_u32 s39, s39, 0x100
	s_addc_u32 s41, s41, 0
	s_cmp_gt_u32 s63, 29
	s_cbranch_scc0 .LBB0_1657

; #define PG8_STAGE(bufoff, gbase, voff) do { _Pragma("unroll") for (int _i = 0; _i < 2; ++_i) \
;         __builtin_amdgcn_global_load_lds((const unsigned*)((const char*)(gbase) + (voff)[_i]), (PG8_LAS unsigned*)(lds + (bufoff) + ldsw + _i * 8192), 16, 0, 0); } while (0)
; #define PG8_LDA(dst, b, h) do { _Pragma("unroll") for (int m = 0; m < 4; ++m) _Pragma("unroll") for (int k = 0; k < 2; ++k) dst[m][k] = *(const PG8_LAS bf16x8*)(lds + PG8_SA(b, h) + aoff + m * 2048 + k * 1024); } while (0)
; #define PG8_LDB(dst, b, h) do { _Pragma("unroll") for (int n = 0; n < 2; ++n) _Pragma("unroll") for (int k = 0; k < 2; ++k) dst[n][k] = *(const PG8_LAS bf16x8*)(lds + PG8_SB(b, h) + boff + n * 2048 + k * 1024); } while (0)
; #define PG8_MMA(ai, bj, At, Bt) do { __builtin_amdgcn_s_setprio(1); _Pragma("unroll") for (int m = 0; m < 4; ++m) _Pragma("unroll") for (int n = 0; n < 2; ++n) _Pragma("unroll") for (int k = 0; k < 2; ++k) \
;         acc[ai][bj][m][n] = __builtin_amdgcn_mfma_f32_16x16x32_bf16(Bt[n][k], At[m][k], acc[ai][bj][m][n], 0, 0, 0); __builtin_amdgcn_s_setprio(0); } while (0)
; #define PG8_WAIT_V(n) asm volatile("s_waitcnt vmcnt(" #n ")" ::: "memory")
; #define PG8_BAR __builtin_amdgcn_s_barrier()
; template <class Epi, class Sched, bool ALIGN_EPI = false, bool SP2 = false>
; __device__ __forceinline__ void gemm_phase(PG8_LAS unsigned char* lds, const Gemm g, const Sched& S, const Epi& E) {
;     ...
;         for (int t = 0; t < nt; t += 2) {
;             const bool last = (t == nt - 2);
;             const char* a1 = cA + (size_t)(t + 1) * kstA;
;             const char* a2 = last ? nA : cA + (size_t)(t + 2) * kstA; const char* b2 = last ? nB : cB + (size_t)(t + 2) * kstep;
;             const char* a3 = a2 + kstA; const char* b3 = b2 + kstep;
;             if (last && has_next) S.a_ready(nxt);
;             if constexpr (SP2) {
;             PG8_LDB(B0, 0, 0); PG8_LDB(B1, 0, 1); PG8_SCHED; PG8_LDA(At, 0, 0); PG8_STAGE(PG8_SA(1, 1), a1 + hstepA, voffA);
;             PG8_WAIT_V(8); PG8_WAIT_L(0); PG8_BAR; PG8_MMA(0, 0, At, B0); PG8_MMA(0, 1, At, B1); PG8_BAR; PG8_SCHED;
;             PG8_LDA(At, 0, 1); PG8_STAGE(PG8_SB(0, 0), b2, voffB); PG8_STAGE(PG8_SB(0, 1), b2 + hstepB, voffB); PG8_STAGE(PG8_SA(0, 0), a2, voffA);
;             PG8_WAIT_V(8); PG8_WAIT_L(0); PG8_BAR; PG8_MMA(1, 0, At, B0); PG8_MMA(1, 1, At, B1); PG8_BAR; PG8_SCHED;
.LBB0_1754:
	s_or_b32 s44, s62, 1
	s_add_i32 s62, s62, 2
	s_mov_b32 s63, s45
	s_lshl_b64 s[4:5], s[44:45], 15
	s_lshl_b64 s[6:7], s[62:63], 15
	s_add_u32 s12, s34, s6
	v_add_u32_e32 v170, s10, v177
	v_add_u32_e32 v174, s11, v177
	s_addc_u32 s13, s35, s7
	ds_read_b128 v[158:161], v170
	ds_read_b128 v[162:165], v170 offset:1024
	ds_read_b128 v[166:169], v170 offset:2048
	ds_read_b128 v[170:173], v170 offset:3072
	ds_read_b128 v[180:183], v174
	ds_read_b128 v[190:193], v174 offset:1024
	ds_read_b128 v[194:197], v174 offset:2048
	ds_read_b128 v[198:201], v174 offset:3072
	s_and_b64 s[6:7], s[50:51], exec
	s_cselect_b32 s69, s13, s59
	s_cselect_b32 s68, s12, s58
	s_lshl_b64 s[6:7], s[62:63], 7
	s_add_u32 s12, s40, s6
	s_addc_u32 s13, s41, s7
	s_and_b64 s[6:7], s[50:51], exec
	s_cselect_b32 s53, s13, s61
	s_cselect_b32 s52, s12, s60
	s_add_u32 s50, s68, 0x8000
	s_addc_u32 s51, s69, 0
	s_add_u32 s4, s21, s4
	s_addc_u32 s5, s39, s5
	v_lshl_add_u64 v[174:175], s[4:5], 0, v[128:129]
	s_add_i32 m0, s74, 0xc000
	ds_read_b128 v[202:205], v179
	ds_read_b128 v[206:209], v179 offset:1024
	ds_read_b128 v[210:213], v179 offset:2048
	ds_read_b128 v[214:217], v179 offset:3072
	ds_read_b128 v[218:221], v179 offset:4096
	ds_read_b128 v[222:225], v179 offset:5120
	ds_read_b128 v[226:229], v179 offset:6144
	ds_read_b128 v[230:233], v179 offset:7168
	global_load_lds_dwordx4 v[174:175], off
	v_lshl_add_u64 v[174:175], s[4:5], 0, v[132:133]
	s_add_i32 m0, s74, 0xe000
	s_nop 0
	global_load_lds_dwordx4 v[174:175], off
	s_waitcnt vmcnt(8)
	s_waitcnt lgkmcnt(0)
	s_setprio 1
	s_barrier
	v_mfma_f32_16x16x32_bf16 v[124:127], v[158:161], v[202:205], v[124:127]
	v_mfma_f32_16x16x32_bf16 v[120:123], v[166:169], v[202:205], v[120:123]
	v_mfma_f32_16x16x32_bf16 v[112:115], v[166:169], v[210:213], v[112:115]
	v_mfma_f32_16x16x32_bf16 v[116:119], v[158:161], v[210:213], v[116:119]
	v_mfma_f32_16x16x32_bf16 v[108:111], v[158:161], v[218:221], v[108:111]
	v_mfma_f32_16x16x32_bf16 v[104:107], v[166:169], v[218:221], v[104:107]
	v_mfma_f32_16x16x32_bf16 v[96:99], v[166:169], v[226:229], v[96:99]
	v_mfma_f32_16x16x32_bf16 v[100:103], v[158:161], v[226:229], v[100:103]
	v_mfma_f32_16x16x32_bf16 v[124:127], v[162:165], v[206:209], v[124:127]
	v_mfma_f32_16x16x32_bf16 v[120:123], v[170:173], v[206:209], v[120:123]
	v_mfma_f32_16x16x32_bf16 v[112:115], v[170:173], v[214:217], v[112:115]
	v_mfma_f32_16x16x32_bf16 v[116:119], v[162:165], v[214:217], v[116:119]
	v_mfma_f32_16x16x32_bf16 v[108:111], v[162:165], v[222:225], v[108:111]
	v_mfma_f32_16x16x32_bf16 v[104:107], v[170:173], v[222:225], v[104:107]
	v_mfma_f32_16x16x32_bf16 v[96:99], v[170:173], v[230:233], v[96:99]
	v_mfma_f32_16x16x32_bf16 v[100:103], v[162:165], v[230:233], v[100:103]
	s_setprio 0
	s_setprio 1
	v_mfma_f32_16x16x32_bf16 v[92:95], v[180:183], v[202:205], v[92:95]
	v_mfma_f32_16x16x32_bf16 v[88:91], v[194:197], v[202:205], v[88:91]
	v_mfma_f32_16x16x32_bf16 v[80:83], v[194:197], v[210:213], v[80:83]
	v_mfma_f32_16x16x32_bf16 v[84:87], v[180:183], v[210:213], v[84:87]
	v_mfma_f32_16x16x32_bf16 v[76:79], v[180:183], v[218:221], v[76:79]
	v_mfma_f32_16x16x32_bf16 v[72:75], v[194:197], v[218:221], v[72:75]
	v_mfma_f32_16x16x32_bf16 v[64:67], v[194:197], v[226:229], v[64:67]
	v_mfma_f32_16x16x32_bf16 v[68:71], v[180:183], v[226:229], v[68:71]
	v_mfma_f32_16x16x32_bf16 v[92:95], v[190:193], v[206:209], v[92:95]
	v_mfma_f32_16x16x32_bf16 v[88:91], v[198:201], v[206:209], v[88:91]
	v_mfma_f32_16x16x32_bf16 v[80:83], v[198:201], v[214:217], v[80:83]
	v_mfma_f32_16x16x32_bf16 v[84:87], v[190:193], v[214:217], v[84:87]
	v_mfma_f32_16x16x32_bf16 v[76:79], v[190:193], v[222:225], v[76:79]
	v_mfma_f32_16x16x32_bf16 v[72:75], v[198:201], v[222:225], v[72:75]
	v_mfma_f32_16x16x32_bf16 v[64:67], v[198:201], v[230:233], v[64:67]
	v_mfma_f32_16x16x32_bf16 v[68:71], v[190:193], v[230:233], v[68:71]
	s_barrier
	s_setprio 0
	s_add_i32 s4, s10, s71
	v_lshl_add_u64 v[174:175], s[52:53], 0, v[130:131]
	s_mov_b32 m0, s4
	ds_read_b128 v[202:205], v179 offset:16384
	ds_read_b128 v[206:209], v179 offset:17408
	ds_read_b128 v[210:213], v179 offset:18432
	ds_read_b128 v[214:217], v179 offset:19456
	ds_read_b128 v[218:221], v179 offset:20480
	ds_read_b128 v[222:225], v179 offset:21504
	ds_read_b128 v[226:229], v179 offset:22528
	ds_read_b128 v[230:233], v179 offset:23552
	global_load_lds_dwordx4 v[174:175], off
	s_add_i32 m0, s4, 0x2000
	s_add_u32 s4, s52, 0x160000
	v_lshl_add_u64 v[234:235], s[52:53], 0, v[134:135]
	s_addc_u32 s5, s53, 0
	s_add_i32 s6, s11, s71
	global_load_lds_dwordx4 v[234:235], off
	v_lshl_add_u64 v[236:237], s[4:5], 0, v[130:131]
	s_mov_b32 m0, s6
	s_nop 0
	global_load_lds_dwordx4 v[236:237], off
	v_lshl_add_u64 v[236:237], s[4:5], 0, v[134:135]
	s_add_i32 m0, s6, 0x2000
	s_nop 0
	global_load_lds_dwordx4 v[236:237], off
	v_lshl_add_u64 v[236:237], s[68:69], 0, v[128:129]
	s_mov_b32 m0, s74
	s_nop 0
	global_load_lds_dwordx4 v[236:237], off
	v_lshl_add_u64 v[236:237], s[68:69], 0, v[132:133]
	s_mov_b32 m0, s76
	s_nop 0
	global_load_lds_dwordx4 v[236:237], off
	s_waitcnt vmcnt(8)
	s_waitcnt lgkmcnt(0)
	s_setprio 1
	s_barrier
; #define PG8_STAGE(bufoff, gbase, voff) do { _Pragma("unroll") for (int _i = 0; _i < 2; ++_i) \
;         __builtin_amdgcn_global_load_lds((const unsigned*)((const char*)(gbase) + (voff)[_i]), (PG8_LAS unsigned*)(lds + (bufoff) + ldsw + _i * 8192), 16, 0, 0); } while (0)
; #define PG8_LDA(dst, b, h) do { _Pragma("unroll") for (int m = 0; m < 4; ++m) _Pragma("unroll") for (int k = 0; k < 2; ++k) dst[m][k] = *(const PG8_LAS bf16x8*)(lds + PG8_SA(b, h) + aoff + m * 2048 + k * 1024); } while (0)
; #define PG8_LDB(dst, b, h) do { _Pragma("unroll") for (int n = 0; n < 2; ++n) _Pragma("unroll") for (int k = 0; k < 2; ++k) dst[n][k] = *(const PG8_LAS bf16x8*)(lds + PG8_SB(b, h) + boff + n * 2048 + k * 1024); } while (0)
; #define PG8_MMA(ai, bj, At, Bt) do { __builtin_amdgcn_s_setprio(1); _Pragma("unroll") for (int m = 0; m < 4; ++m) _Pragma("unroll") for (int n = 0; n < 2; ++n) _Pragma("unroll") for (int k = 0; k < 2; ++k) \
;         acc[ai][bj][m][n] = __builtin_amdgcn_mfma_f32_16x16x32_bf16(Bt[n][k], At[m][k], acc[ai][bj][m][n], 0, 0, 0); __builtin_amdgcn_s_setprio(0); } while (0)
; #define PG8_WAIT_V(n) asm volatile("s_waitcnt vmcnt(" #n ")" ::: "memory")
; #define PG8_WAIT_L(n) asm volatile("s_waitcnt lgkmcnt(" #n ")" ::: "memory")
; #define PG8_BAR __builtin_amdgcn_s_barrier()
; #define PG8_SCHED __builtin_amdgcn_sched_barrier(0)
; template <class Epi, class Sched, bool ALIGN_EPI = false, bool SP2 = false>
; __device__ __forceinline__ void gemm_phase(PG8_LAS unsigned char* lds, const Gemm g, const Sched& S, const Epi& E) {
;     ...
;             PG8_WAIT_V(8); PG8_WAIT_L(0); PG8_BAR; PG8_MMA(1, 0, At, B0); PG8_MMA(1, 1, At, B1); PG8_BAR; PG8_SCHED;
;             PG8_LDB(B0, 1, 0); PG8_LDB(B1, 1, 1); PG8_SCHED; PG8_LDA(At, 1, 0); PG8_STAGE(PG8_SA(0, 1), a2 + hstepA, voffA);
;             PG8_WAIT_V(8); PG8_WAIT_L(0); PG8_BAR; PG8_MMA(0, 0, At, B0); PG8_MMA(0, 1, At, B1); PG8_BAR; PG8_SCHED;
	v_mfma_f32_16x16x32_bf16 v[60:63], v[158:161], v[202:205], v[60:63]
	v_mfma_f32_16x16x32_bf16 v[56:59], v[166:169], v[202:205], v[56:59]
	v_mfma_f32_16x16x32_bf16 v[48:51], v[166:169], v[210:213], v[48:51]
	v_mfma_f32_16x16x32_bf16 v[52:55], v[158:161], v[210:213], v[52:55]
	v_mfma_f32_16x16x32_bf16 v[44:47], v[158:161], v[218:221], v[44:47]
	v_mfma_f32_16x16x32_bf16 v[40:43], v[166:169], v[218:221], v[40:43]
	v_mfma_f32_16x16x32_bf16 v[32:35], v[166:169], v[226:229], v[32:35]
	v_mfma_f32_16x16x32_bf16 v[36:39], v[158:161], v[226:229], v[36:39]
	v_mfma_f32_16x16x32_bf16 v[60:63], v[162:165], v[206:209], v[60:63]
	v_mfma_f32_16x16x32_bf16 v[56:59], v[170:173], v[206:209], v[56:59]
	v_mfma_f32_16x16x32_bf16 v[48:51], v[170:173], v[214:217], v[48:51]
	v_mfma_f32_16x16x32_bf16 v[52:55], v[162:165], v[214:217], v[52:55]
	v_mfma_f32_16x16x32_bf16 v[44:47], v[162:165], v[222:225], v[44:47]
	v_mfma_f32_16x16x32_bf16 v[40:43], v[170:173], v[222:225], v[40:43]
	v_mfma_f32_16x16x32_bf16 v[32:35], v[170:173], v[230:233], v[32:35]
	v_mfma_f32_16x16x32_bf16 v[36:39], v[162:165], v[230:233], v[36:39]
	s_setprio 0
	s_setprio 1
	v_mfma_f32_16x16x32_bf16 v[28:31], v[180:183], v[202:205], v[28:31]
	v_mfma_f32_16x16x32_bf16 v[24:27], v[194:197], v[202:205], v[24:27]
	v_mfma_f32_16x16x32_bf16 v[16:19], v[194:197], v[210:213], v[16:19]
	v_mfma_f32_16x16x32_bf16 v[20:23], v[180:183], v[210:213], v[20:23]
	v_mfma_f32_16x16x32_bf16 v[12:15], v[180:183], v[218:221], v[12:15]
	v_mfma_f32_16x16x32_bf16 v[8:11], v[194:197], v[218:221], v[8:11]
	v_mfma_f32_16x16x32_bf16 v[0:3], v[194:197], v[226:229], v[0:3]
	v_mfma_f32_16x16x32_bf16 v[4:7], v[180:183], v[226:229], v[4:7]
	v_mfma_f32_16x16x32_bf16 v[28:31], v[190:193], v[206:209], v[28:31]
	v_mfma_f32_16x16x32_bf16 v[24:27], v[198:201], v[206:209], v[24:27]
	v_mfma_f32_16x16x32_bf16 v[16:19], v[198:201], v[214:217], v[16:19]
	v_mfma_f32_16x16x32_bf16 v[20:23], v[190:193], v[214:217], v[20:23]
	v_mfma_f32_16x16x32_bf16 v[12:15], v[190:193], v[222:225], v[12:15]
	v_mfma_f32_16x16x32_bf16 v[8:11], v[198:201], v[222:225], v[8:11]
	v_mfma_f32_16x16x32_bf16 v[0:3], v[198:201], v[230:233], v[0:3]
	v_mfma_f32_16x16x32_bf16 v[4:7], v[190:193], v[230:233], v[4:7]
	s_barrier
	s_setprio 0
	s_add_i32 s6, 0, 0x18000
	s_add_i32 s7, 0, 0x1c000
	v_add_u32_e32 v170, s6, v177
	v_add_u32_e32 v198, s7, v177
	ds_read_b128 v[158:161], v170
	ds_read_b128 v[162:165], v170 offset:1024
	ds_read_b128 v[166:169], v170 offset:2048
	ds_read_b128 v[170:173], v170 offset:3072
	ds_read_b128 v[180:183], v198
	ds_read_b128 v[190:193], v198 offset:1024
	ds_read_b128 v[194:197], v198 offset:2048
	ds_read_b128 v[198:201], v198 offset:3072
	s_add_u32 s4, s68, 0x4000
	s_addc_u32 s5, s69, 0
	s_mov_b32 m0, s77
	v_lshl_add_u64 v[236:237], s[4:5], 0, v[128:129]
	ds_read_b128 v[202:205], v179 offset:32768
	ds_read_b128 v[206:209], v179 offset:33792
	ds_read_b128 v[210:213], v179 offset:34816
	ds_read_b128 v[214:217], v179 offset:35840
	ds_read_b128 v[218:221], v179 offset:36864
	ds_read_b128 v[222:225], v179 offset:37888
	ds_read_b128 v[226:229], v179 offset:38912
	ds_read_b128 v[230:233], v179 offset:39936
	global_load_lds_dwordx4 v[236:237], off
	v_lshl_add_u64 v[236:237], s[4:5], 0, v[132:133]
	s_mov_b32 m0, s75
	s_nop 0
	global_load_lds_dwordx4 v[236:237], off
	s_waitcnt vmcnt(8)
	s_waitcnt lgkmcnt(0)
	s_setprio 1
	s_barrier
	v_mfma_f32_16x16x32_bf16 v[124:127], v[158:161], v[202:205], v[124:127]
	v_mfma_f32_16x16x32_bf16 v[120:123], v[166:169], v[202:205], v[120:123]
	v_mfma_f32_16x16x32_bf16 v[112:115], v[166:169], v[210:213], v[112:115]
	v_mfma_f32_16x16x32_bf16 v[116:119], v[158:161], v[210:213], v[116:119]
	v_mfma_f32_16x16x32_bf16 v[108:111], v[158:161], v[218:221], v[108:111]
	v_mfma_f32_16x16x32_bf16 v[104:107], v[166:169], v[218:221], v[104:107]
	v_mfma_f32_16x16x32_bf16 v[96:99], v[166:169], v[226:229], v[96:99]
	v_mfma_f32_16x16x32_bf16 v[100:103], v[158:161], v[226:229], v[100:103]
	v_mfma_f32_16x16x32_bf16 v[124:127], v[162:165], v[206:209], v[124:127]
	v_mfma_f32_16x16x32_bf16 v[120:123], v[170:173], v[206:209], v[120:123]
	v_mfma_f32_16x16x32_bf16 v[112:115], v[170:173], v[214:217], v[112:115]
	v_mfma_f32_16x16x32_bf16 v[116:119], v[162:165], v[214:217], v[116:119]
	v_mfma_f32_16x16x32_bf16 v[108:111], v[162:165], v[222:225], v[108:111]
	v_mfma_f32_16x16x32_bf16 v[104:107], v[170:173], v[222:225], v[104:107]
	v_mfma_f32_16x16x32_bf16 v[96:99], v[170:173], v[230:233], v[96:99]
	v_mfma_f32_16x16x32_bf16 v[100:103], v[162:165], v[230:233], v[100:103]
	s_setprio 0
	s_setprio 1
	v_mfma_f32_16x16x32_bf16 v[92:95], v[180:183], v[202:205], v[92:95]
	v_mfma_f32_16x16x32_bf16 v[88:91], v[194:197], v[202:205], v[88:91]
	v_mfma_f32_16x16x32_bf16 v[80:83], v[194:197], v[210:213], v[80:83]
	v_mfma_f32_16x16x32_bf16 v[84:87], v[180:183], v[210:213], v[84:87]
	v_mfma_f32_16x16x32_bf16 v[76:79], v[180:183], v[218:221], v[76:79]
	v_mfma_f32_16x16x32_bf16 v[72:75], v[194:197], v[218:221], v[72:75]
	v_mfma_f32_16x16x32_bf16 v[64:67], v[194:197], v[226:229], v[64:67]
	v_mfma_f32_16x16x32_bf16 v[68:71], v[180:183], v[226:229], v[68:71]
	v_mfma_f32_16x16x32_bf16 v[92:95], v[190:193], v[206:209], v[92:95]
	v_mfma_f32_16x16x32_bf16 v[88:91], v[198:201], v[206:209], v[88:91]
	v_mfma_f32_16x16x32_bf16 v[80:83], v[198:201], v[214:217], v[80:83]
	v_mfma_f32_16x16x32_bf16 v[84:87], v[190:193], v[214:217], v[84:87]
	v_mfma_f32_16x16x32_bf16 v[76:79], v[190:193], v[222:225], v[76:79]
	v_mfma_f32_16x16x32_bf16 v[72:75], v[198:201], v[222:225], v[72:75]
	v_mfma_f32_16x16x32_bf16 v[64:67], v[198:201], v[230:233], v[64:67]
	v_mfma_f32_16x16x32_bf16 v[68:71], v[190:193], v[230:233], v[68:71]
	s_barrier
; #define PG8_STAGE(bufoff, gbase, voff) do { _Pragma("unroll") for (int _i = 0; _i < 2; ++_i) \
;         __builtin_amdgcn_global_load_lds((const unsigned*)((const char*)(gbase) + (voff)[_i]), (PG8_LAS unsigned*)(lds + (bufoff) + ldsw + _i * 8192), 16, 0, 0); } while (0)
; #define PG8_LDA(dst, b, h) do { _Pragma("unroll") for (int m = 0; m < 4; ++m) _Pragma("unroll") for (int k = 0; k < 2; ++k) dst[m][k] = *(const PG8_LAS bf16x8*)(lds + PG8_SA(b, h) + aoff + m * 2048 + k * 1024); } while (0)
; #define PG8_MMA(ai, bj, At, Bt) do { __builtin_amdgcn_s_setprio(1); _Pragma("unroll") for (int m = 0; m < 4; ++m) _Pragma("unroll") for (int n = 0; n < 2; ++n) _Pragma("unroll") for (int k = 0; k < 2; ++k) \
;         acc[ai][bj][m][n] = __builtin_amdgcn_mfma_f32_16x16x32_bf16(Bt[n][k], At[m][k], acc[ai][bj][m][n], 0, 0, 0); __builtin_amdgcn_s_setprio(0); } while (0)
; #define PG8_WAIT_V(n) asm volatile("s_waitcnt vmcnt(" #n ")" ::: "memory")
; #define PG8_WAIT_L(n) asm volatile("s_waitcnt lgkmcnt(" #n ")" ::: "memory")
; #define PG8_BAR __builtin_amdgcn_s_barrier()
; #define PG8_SCHED __builtin_amdgcn_sched_barrier(0)
; template <class Epi, class Sched, bool ALIGN_EPI = false, bool SP2 = false>
; __device__ __forceinline__ void gemm_phase(PG8_LAS unsigned char* lds, const Gemm g, const Sched& S, const Epi& E) {
;     ...
;             PG8_LDA(At, 1, 1); PG8_STAGE(PG8_SB(1, 0), b3, voffB); PG8_STAGE(PG8_SB(1, 1), b3 + hstepB, voffB); PG8_STAGE(PG8_SA(1, 0), a3, voffA);
;             PG8_WAIT_V(8); PG8_WAIT_L(0); PG8_BAR; PG8_MMA(1, 0, At, B0); PG8_MMA(1, 1, At, B1); PG8_BAR; PG8_SCHED;
	s_setprio 0
	s_add_i32 s4, s6, s71
	v_lshl_add_u64 v[174:175], v[174:175], 0, s[54:55]
	s_mov_b32 m0, s4
	ds_read_b128 v[202:205], v179 offset:49152
	ds_read_b128 v[206:209], v179 offset:50176
	ds_read_b128 v[210:213], v179 offset:51200
	ds_read_b128 v[214:217], v179 offset:52224
	ds_read_b128 v[218:221], v179 offset:53248
	ds_read_b128 v[222:225], v179 offset:54272
	ds_read_b128 v[226:229], v179 offset:55296
	ds_read_b128 v[230:233], v179 offset:56320
	global_load_lds_dwordx4 v[174:175], off
	s_add_i32 m0, s4, 0x2000
	s_add_u32 s4, s52, 0x160080
	v_lshl_add_u64 v[174:175], v[234:235], 0, s[54:55]
	s_addc_u32 s5, s53, 0
	s_add_i32 s6, s7, s71
	global_load_lds_dwordx4 v[174:175], off
	v_lshl_add_u64 v[174:175], s[4:5], 0, v[130:131]
	s_mov_b32 m0, s6
	s_nop 0
	global_load_lds_dwordx4 v[174:175], off
	v_lshl_add_u64 v[174:175], s[4:5], 0, v[134:135]
	s_add_i32 m0, s6, 0x2000
	s_nop 0
	global_load_lds_dwordx4 v[174:175], off
	v_lshl_add_u64 v[174:175], s[50:51], 0, v[128:129]
	s_mov_b32 m0, s95
	s_nop 0
	global_load_lds_dwordx4 v[174:175], off
	v_lshl_add_u64 v[174:175], s[50:51], 0, v[132:133]
	s_mov_b32 m0, s96
	s_nop 0
	global_load_lds_dwordx4 v[174:175], off
	s_waitcnt vmcnt(8)
	s_waitcnt lgkmcnt(0)
	s_setprio 1
	s_barrier
	v_mfma_f32_16x16x32_bf16 v[60:63], v[158:161], v[202:205], v[60:63]
	v_mfma_f32_16x16x32_bf16 v[56:59], v[166:169], v[202:205], v[56:59]
	v_mfma_f32_16x16x32_bf16 v[48:51], v[166:169], v[210:213], v[48:51]
	v_mfma_f32_16x16x32_bf16 v[52:55], v[158:161], v[210:213], v[52:55]
	v_mfma_f32_16x16x32_bf16 v[44:47], v[158:161], v[218:221], v[44:47]
	v_mfma_f32_16x16x32_bf16 v[40:43], v[166:169], v[218:221], v[40:43]
	v_mfma_f32_16x16x32_bf16 v[32:35], v[166:169], v[226:229], v[32:35]
	v_mfma_f32_16x16x32_bf16 v[36:39], v[158:161], v[226:229], v[36:39]
	v_mfma_f32_16x16x32_bf16 v[60:63], v[162:165], v[206:209], v[60:63]
	v_mfma_f32_16x16x32_bf16 v[56:59], v[170:173], v[206:209], v[56:59]
	v_mfma_f32_16x16x32_bf16 v[48:51], v[170:173], v[214:217], v[48:51]
	v_mfma_f32_16x16x32_bf16 v[52:55], v[162:165], v[214:217], v[52:55]
	v_mfma_f32_16x16x32_bf16 v[44:47], v[162:165], v[222:225], v[44:47]
	v_mfma_f32_16x16x32_bf16 v[40:43], v[170:173], v[222:225], v[40:43]
	v_mfma_f32_16x16x32_bf16 v[32:35], v[170:173], v[230:233], v[32:35]
	v_mfma_f32_16x16x32_bf16 v[36:39], v[162:165], v[230:233], v[36:39]
	s_setprio 0
	s_setprio 1
	v_mfma_f32_16x16x32_bf16 v[28:31], v[180:183], v[202:205], v[28:31]
	v_mfma_f32_16x16x32_bf16 v[24:27], v[194:197], v[202:205], v[24:27]
	v_mfma_f32_16x16x32_bf16 v[16:19], v[194:197], v[210:213], v[16:19]
	v_mfma_f32_16x16x32_bf16 v[20:23], v[180:183], v[210:213], v[20:23]
	v_mfma_f32_16x16x32_bf16 v[12:15], v[180:183], v[218:221], v[12:15]
	v_mfma_f32_16x16x32_bf16 v[8:11], v[194:197], v[218:221], v[8:11]
	v_mfma_f32_16x16x32_bf16 v[0:3], v[194:197], v[226:229], v[0:3]
	v_mfma_f32_16x16x32_bf16 v[4:7], v[180:183], v[226:229], v[4:7]
	v_mfma_f32_16x16x32_bf16 v[28:31], v[190:193], v[206:209], v[28:31]
	v_mfma_f32_16x16x32_bf16 v[24:27], v[198:201], v[206:209], v[24:27]
	v_mfma_f32_16x16x32_bf16 v[16:19], v[198:201], v[214:217], v[16:19]
	v_mfma_f32_16x16x32_bf16 v[20:23], v[190:193], v[214:217], v[20:23]
	v_mfma_f32_16x16x32_bf16 v[12:15], v[190:193], v[222:225], v[12:15]
	v_mfma_f32_16x16x32_bf16 v[8:11], v[198:201], v[222:225], v[8:11]
	v_mfma_f32_16x16x32_bf16 v[0:3], v[198:201], v[230:233], v[0:3]
	v_mfma_f32_16x16x32_bf16 v[4:7], v[190:193], v[230:233], v[4:7]
	s_barrier
	s_setprio 0
	s_cmp_ge_i32 s62, s97
	s_cbranch_scc1 .LBB0_1766

; #define PG8_STAGE(bufoff, gbase, voff) do { _Pragma("unroll") for (int _i = 0; _i < 2; ++_i) \
;         __builtin_amdgcn_global_load_lds((const unsigned*)((const char*)(gbase) + (voff)[_i]), (PG8_LAS unsigned*)(lds + (bufoff) + ldsw + _i * 8192), 16, 0, 0); } while (0)
; #define PG8_LDA(dst, b, h) do { _Pragma("unroll") for (int m = 0; m < 4; ++m) _Pragma("unroll") for (int k = 0; k < 2; ++k) dst[m][k] = *(const PG8_LAS bf16x8*)(lds + PG8_SA(b, h) + aoff + m * 2048 + k * 1024); } while (0)
; #define PG8_LDB(dst, b, h) do { _Pragma("unroll") for (int n = 0; n < 2; ++n) _Pragma("unroll") for (int k = 0; k < 2; ++k) dst[n][k] = *(const PG8_LAS bf16x8*)(lds + PG8_SB(b, h) + boff + n * 2048 + k * 1024); } while (0)
; #define PG8_WAIT_V(n) asm volatile("s_waitcnt vmcnt(" #n ")" ::: "memory")
; #define PG8_WAIT_L(n) asm volatile("s_waitcnt lgkmcnt(" #n ")" ::: "memory")
; template <class Epi, class Sched, bool ALIGN_EPI = false, bool SP2 = false>
; __device__ __forceinline__ void gemm_phase(PG8_LAS unsigned char* lds, const Gemm g, const Sched& S, const Epi& E) {
;     ...
;     for (;;) {
;         const bool has_next = S.next(ui + 1, nxt);
;         const char* nA = has_next ? (const char*)g.A + (size_t)nxt.pm * tstepA + (size_t)nxt.z * g.azs + (size_t)(nxt.k0 >> 6) * kstA : cA; const char* nB = has_next ? (const char*)g.Bt + (size_t)nxt.pn * tstepB + (size_t)nxt.z * g.bzs + (size_t)nxt.k0 * 2 : cB;
;         const int nt = cur.nt;
;         for (int t = 0; t < nt; t += 2) {
;             const bool last = (t == nt - 2);
;             const char* a1 = cA + (size_t)(t + 1) * kstA;
;             const char* a2 = last ? nA : cA + (size_t)(t + 2) * kstA; const char* b2 = last ? nB : cB + (size_t)(t + 2) * kstep;
;             const char* a3 = a2 + kstA; const char* b3 = b2 + kstep;
;             if (last && has_next) S.a_ready(nxt);
;             if constexpr (SP2) {
;             PG8_LDB(B0, 0, 0); PG8_LDB(B1, 0, 1); PG8_SCHED; PG8_LDA(At, 0, 0); PG8_STAGE(PG8_SA(1, 1), a1 + hstepA, voffA);
;             PG8_WAIT_V(8); PG8_WAIT_L(0); PG8_BAR; PG8_MMA(0, 0, At, B0); PG8_MMA(0, 1, At, B1); PG8_BAR; PG8_SCHED;
;             PG8_LDA(At, 0, 1); PG8_STAGE(PG8_SB(0, 0), b2, voffB); PG8_STAGE(PG8_SB(0, 1), b2 + hstepB, voffB); PG8_STAGE(PG8_SA(0, 0), a2, voffA);
;             PG8_WAIT_V(8); PG8_WAIT_L(0); PG8_BAR; PG8_MMA(1, 0, At, B0); PG8_MMA(1, 1, At, B1); PG8_BAR; PG8_SCHED;
.LBB0_2049:
	s_ashr_i32 s61, s60, 31
	s_lshl_b64 s[4:5], s[60:61], 20
	v_readlane_b32 s10, v254, 41
	v_readlane_b32 s11, v254, 42
	s_add_u32 s62, s10, s4
	s_addc_u32 s63, s11, s5
	s_and_b64 s[4:5], s[42:43], exec
	s_cselect_b32 s1, s63, s21
	s_cselect_b32 s3, s62, s20
	s_ashr_i32 s59, s58, 31
	s_lshl_b64 s[4:5], s[58:59], 20
	s_add_u32 s64, s72, s4
	s_addc_u32 s65, s73, s5
	s_and_b64 s[4:5], s[42:43], exec
	s_cselect_b32 s4, s65, s39
	s_cselect_b32 s5, s64, s38
	s_add_u32 s20, s20, 0x80080
	s_addc_u32 s21, s21, 0
	s_add_u32 s10, s38, 0x100
	s_addc_u32 s11, s39, 0
	s_mov_b32 s12, -2
	ds_read_b128 v[128:131], v159
	ds_read_b128 v[132:135], v159 offset:1024
	ds_read_b128 v[164:167], v159 offset:2048
	ds_read_b128 v[168:171], v159 offset:3072
	ds_read_b128 v[172:175], v160
	ds_read_b128 v[176:179], v160 offset:1024
	ds_read_b128 v[180:183], v160 offset:2048
	ds_read_b128 v[190:193], v160 offset:3072
	s_add_u32 s13, s20, 0xfff80080
	s_addc_u32 s33, s21, -1
	s_cmp_eq_u32 s12, 28
	s_cselect_b32 s41, s1, s33
	s_cselect_b32 s40, s3, s13
	s_cselect_b32 s39, s4, s11
	s_cselect_b32 s38, s5, s10
	v_lshl_add_u64 v[226:227], s[20:21], 0, v[148:149]
	s_add_i32 m0, s7, 0xc000
	ds_read_b128 v[194:197], v161
	ds_read_b128 v[198:201], v161 offset:1024
	ds_read_b128 v[202:205], v161 offset:2048
	ds_read_b128 v[206:209], v161 offset:3072
	ds_read_b128 v[210:213], v161 offset:4096
	ds_read_b128 v[214:217], v161 offset:5120
	ds_read_b128 v[218:221], v161 offset:6144
	ds_read_b128 v[222:225], v161 offset:7168
	global_load_lds_dwordx4 v[226:227], off
	v_lshl_add_u64 v[226:227], s[20:21], 0, v[150:151]
	s_add_i32 m0, s7, 0xe000
	s_nop 0
	global_load_lds_dwordx4 v[226:227], off
	s_waitcnt vmcnt(8)
	s_waitcnt lgkmcnt(0)
	s_setprio 1
	s_barrier
	v_mfma_f32_16x16x32_bf16 v[124:127], v[128:131], v[194:197], 0
	v_mfma_f32_16x16x32_bf16 v[120:123], v[164:167], v[194:197], 0
	v_mfma_f32_16x16x32_bf16 v[104:107], v[164:167], v[202:205], 0
	v_mfma_f32_16x16x32_bf16 v[108:111], v[128:131], v[202:205], 0
	v_mfma_f32_16x16x32_bf16 v[92:95], v[128:131], v[210:213], 0
	v_mfma_f32_16x16x32_bf16 v[88:91], v[164:167], v[210:213], 0
	v_mfma_f32_16x16x32_bf16 v[72:75], v[164:167], v[218:221], 0
	v_mfma_f32_16x16x32_bf16 v[76:79], v[128:131], v[218:221], 0
	v_mfma_f32_16x16x32_bf16 v[124:127], v[132:135], v[198:201], v[124:127]
	v_mfma_f32_16x16x32_bf16 v[120:123], v[168:171], v[198:201], v[120:123]
	v_mfma_f32_16x16x32_bf16 v[104:107], v[168:171], v[206:209], v[104:107]
	v_mfma_f32_16x16x32_bf16 v[108:111], v[132:135], v[206:209], v[108:111]
	v_mfma_f32_16x16x32_bf16 v[92:95], v[132:135], v[214:217], v[92:95]
	v_mfma_f32_16x16x32_bf16 v[88:91], v[168:171], v[214:217], v[88:91]
	v_mfma_f32_16x16x32_bf16 v[72:75], v[168:171], v[222:225], v[72:75]
	v_mfma_f32_16x16x32_bf16 v[76:79], v[132:135], v[222:225], v[76:79]
	s_setprio 0
	s_setprio 1
	v_mfma_f32_16x16x32_bf16 v[116:119], v[172:175], v[194:197], 0
	v_mfma_f32_16x16x32_bf16 v[112:115], v[180:183], v[194:197], 0
	v_mfma_f32_16x16x32_bf16 v[96:99], v[180:183], v[202:205], 0
	v_mfma_f32_16x16x32_bf16 v[100:103], v[172:175], v[202:205], 0
	v_mfma_f32_16x16x32_bf16 v[84:87], v[172:175], v[210:213], 0
	v_mfma_f32_16x16x32_bf16 v[80:83], v[180:183], v[210:213], 0
	v_mfma_f32_16x16x32_bf16 v[64:67], v[180:183], v[218:221], 0
	v_mfma_f32_16x16x32_bf16 v[68:71], v[172:175], v[218:221], 0
	v_mfma_f32_16x16x32_bf16 v[116:119], v[176:179], v[198:201], v[116:119]
	v_mfma_f32_16x16x32_bf16 v[112:115], v[190:193], v[198:201], v[112:115]
	v_mfma_f32_16x16x32_bf16 v[96:99], v[190:193], v[206:209], v[96:99]
	v_mfma_f32_16x16x32_bf16 v[100:103], v[176:179], v[206:209], v[100:103]
	v_mfma_f32_16x16x32_bf16 v[84:87], v[176:179], v[214:217], v[84:87]
	v_mfma_f32_16x16x32_bf16 v[80:83], v[190:193], v[214:217], v[80:83]
	v_mfma_f32_16x16x32_bf16 v[64:67], v[190:193], v[222:225], v[64:67]
	v_mfma_f32_16x16x32_bf16 v[68:71], v[176:179], v[222:225], v[68:71]
	s_barrier
	s_setprio 0
	s_add_i32 s13, s69, s6
	v_lshl_add_u64 v[226:227], s[38:39], 0, v[138:139]
	s_mov_b32 m0, s13
	ds_read_b128 v[194:197], v161 offset:16384
	ds_read_b128 v[198:201], v161 offset:17408
	ds_read_b128 v[202:205], v161 offset:18432
	ds_read_b128 v[206:209], v161 offset:19456
	ds_read_b128 v[210:213], v161 offset:20480
	ds_read_b128 v[214:217], v161 offset:21504
	ds_read_b128 v[218:221], v161 offset:22528
	ds_read_b128 v[222:225], v161 offset:23552
	global_load_lds_dwordx4 v[226:227], off
	s_add_i32 m0, s13, 0x2000
	s_add_u32 s44, s38, 0x80000
	v_lshl_add_u64 v[228:229], s[38:39], 0, v[142:143]
	s_addc_u32 s45, s39, 0
	s_add_i32 s13, s70, s6
	global_load_lds_dwordx4 v[228:229], off
	v_lshl_add_u64 v[230:231], s[44:45], 0, v[138:139]
	s_mov_b32 m0, s13
	v_lshl_add_u64 v[232:233], s[40:41], 0, v[140:141]
	global_load_lds_dwordx4 v[230:231], off
	v_lshl_add_u64 v[230:231], s[44:45], 0, v[142:143]
	s_add_i32 m0, s13, 0x2000
	s_nop 0
	global_load_lds_dwordx4 v[230:231], off
	v_lshl_add_u64 v[230:231], s[40:41], 0, v[136:137]
	s_mov_b32 m0, s7
	s_nop 0
	global_load_lds_dwordx4 v[230:231], off
	s_mov_b32 m0, s8
	s_nop 0
	global_load_lds_dwordx4 v[232:233], off
	s_waitcnt vmcnt(8)
	s_waitcnt lgkmcnt(0)
	s_setprio 1
	s_barrier
; #define PG8_STAGE(bufoff, gbase, voff) do { _Pragma("unroll") for (int _i = 0; _i < 2; ++_i) \
;         __builtin_amdgcn_global_load_lds((const unsigned*)((const char*)(gbase) + (voff)[_i]), (PG8_LAS unsigned*)(lds + (bufoff) + ldsw + _i * 8192), 16, 0, 0); } while (0)
; #define PG8_LDA(dst, b, h) do { _Pragma("unroll") for (int m = 0; m < 4; ++m) _Pragma("unroll") for (int k = 0; k < 2; ++k) dst[m][k] = *(const PG8_LAS bf16x8*)(lds + PG8_SA(b, h) + aoff + m * 2048 + k * 1024); } while (0)
; #define PG8_LDB(dst, b, h) do { _Pragma("unroll") for (int n = 0; n < 2; ++n) _Pragma("unroll") for (int k = 0; k < 2; ++k) dst[n][k] = *(const PG8_LAS bf16x8*)(lds + PG8_SB(b, h) + boff + n * 2048 + k * 1024); } while (0)
; #define PG8_MMA(ai, bj, At, Bt) do { __builtin_amdgcn_s_setprio(1); _Pragma("unroll") for (int m = 0; m < 4; ++m) _Pragma("unroll") for (int n = 0; n < 2; ++n) _Pragma("unroll") for (int k = 0; k < 2; ++k) \
;         acc[ai][bj][m][n] = __builtin_amdgcn_mfma_f32_16x16x32_bf16(Bt[n][k], At[m][k], acc[ai][bj][m][n], 0, 0, 0); __builtin_amdgcn_s_setprio(0); } while (0)
; #define PG8_WAIT_V(n) asm volatile("s_waitcnt vmcnt(" #n ")" ::: "memory")
; #define PG8_WAIT_L(n) asm volatile("s_waitcnt lgkmcnt(" #n ")" ::: "memory")
; #define PG8_BAR __builtin_amdgcn_s_barrier()
; #define PG8_SCHED __builtin_amdgcn_sched_barrier(0)
; template <class Epi, class Sched, bool ALIGN_EPI = false, bool SP2 = false>
; __device__ __forceinline__ void gemm_phase(PG8_LAS unsigned char* lds, const Gemm g, const Sched& S, const Epi& E) {
;     ...
;             PG8_WAIT_V(8); PG8_WAIT_L(0); PG8_BAR; PG8_MMA(1, 0, At, B0); PG8_MMA(1, 1, At, B1); PG8_BAR; PG8_SCHED;
;             PG8_LDB(B0, 1, 0); PG8_LDB(B1, 1, 1); PG8_SCHED; PG8_LDA(At, 1, 0); PG8_STAGE(PG8_SA(0, 1), a2 + hstepA, voffA);
;             PG8_WAIT_V(8); PG8_WAIT_L(0); PG8_BAR; PG8_MMA(0, 0, At, B0); PG8_MMA(0, 1, At, B1); PG8_BAR; PG8_SCHED;
	v_mfma_f32_16x16x32_bf16 v[60:63], v[128:131], v[194:197], 0
	v_mfma_f32_16x16x32_bf16 v[56:59], v[164:167], v[194:197], 0
	v_mfma_f32_16x16x32_bf16 v[40:43], v[164:167], v[202:205], 0
	v_mfma_f32_16x16x32_bf16 v[44:47], v[128:131], v[202:205], 0
	v_mfma_f32_16x16x32_bf16 v[28:31], v[128:131], v[210:213], 0
	v_mfma_f32_16x16x32_bf16 v[24:27], v[164:167], v[210:213], 0
	v_mfma_f32_16x16x32_bf16 v[8:11], v[164:167], v[218:221], 0
	v_mfma_f32_16x16x32_bf16 v[12:15], v[128:131], v[218:221], 0
	v_mfma_f32_16x16x32_bf16 v[60:63], v[132:135], v[198:201], v[60:63]
	v_mfma_f32_16x16x32_bf16 v[56:59], v[168:171], v[198:201], v[56:59]
	v_mfma_f32_16x16x32_bf16 v[40:43], v[168:171], v[206:209], v[40:43]
	v_mfma_f32_16x16x32_bf16 v[44:47], v[132:135], v[206:209], v[44:47]
	v_mfma_f32_16x16x32_bf16 v[28:31], v[132:135], v[214:217], v[28:31]
	v_mfma_f32_16x16x32_bf16 v[24:27], v[168:171], v[214:217], v[24:27]
	v_mfma_f32_16x16x32_bf16 v[8:11], v[168:171], v[222:225], v[8:11]
	v_mfma_f32_16x16x32_bf16 v[12:15], v[132:135], v[222:225], v[12:15]
	s_setprio 0
	s_setprio 1
	v_mfma_f32_16x16x32_bf16 v[52:55], v[172:175], v[194:197], 0
	v_mfma_f32_16x16x32_bf16 v[48:51], v[180:183], v[194:197], 0
	v_mfma_f32_16x16x32_bf16 v[32:35], v[180:183], v[202:205], 0
	v_mfma_f32_16x16x32_bf16 v[36:39], v[172:175], v[202:205], 0
	v_mfma_f32_16x16x32_bf16 v[20:23], v[172:175], v[210:213], 0
	v_mfma_f32_16x16x32_bf16 v[16:19], v[180:183], v[210:213], 0
	v_mfma_f32_16x16x32_bf16 v[0:3], v[180:183], v[218:221], 0
	v_mfma_f32_16x16x32_bf16 v[4:7], v[172:175], v[218:221], 0
	v_mfma_f32_16x16x32_bf16 v[52:55], v[176:179], v[198:201], v[52:55]
	v_mfma_f32_16x16x32_bf16 v[48:51], v[190:193], v[198:201], v[48:51]
	v_mfma_f32_16x16x32_bf16 v[32:35], v[190:193], v[206:209], v[32:35]
	v_mfma_f32_16x16x32_bf16 v[36:39], v[176:179], v[206:209], v[36:39]
	v_mfma_f32_16x16x32_bf16 v[20:23], v[176:179], v[214:217], v[20:23]
	v_mfma_f32_16x16x32_bf16 v[16:19], v[190:193], v[214:217], v[16:19]
	v_mfma_f32_16x16x32_bf16 v[0:3], v[190:193], v[222:225], v[0:3]
	v_mfma_f32_16x16x32_bf16 v[4:7], v[176:179], v[222:225], v[4:7]
	s_barrier
	s_setprio 0
	s_add_i32 s13, 0, 0x18000
	v_add_u32_e32 v144, s13, v157
	s_add_i32 s33, 0, 0x1c000
	ds_read_b128 v[128:131], v144
	ds_read_b128 v[132:135], v144 offset:1024
	ds_read_b128 v[164:167], v144 offset:2048
	ds_read_b128 v[168:171], v144 offset:3072
	v_add_u32_e32 v144, s33, v157
	ds_read_b128 v[172:175], v144
	ds_read_b128 v[176:179], v144 offset:1024
	ds_read_b128 v[180:183], v144 offset:2048
	ds_read_b128 v[190:193], v144 offset:3072
	s_add_u32 s40, s40, 0x80000
	s_addc_u32 s41, s41, 0
	s_mov_b32 m0, s9
	v_lshl_add_u64 v[234:235], s[40:41], 0, v[136:137]
	ds_read_b128 v[194:197], v161 offset:32768
	ds_read_b128 v[198:201], v161 offset:33792
	ds_read_b128 v[202:205], v161 offset:34816
	ds_read_b128 v[206:209], v161 offset:35840
	ds_read_b128 v[210:213], v161 offset:36864
	ds_read_b128 v[214:217], v161 offset:37888
	ds_read_b128 v[218:221], v161 offset:38912
	ds_read_b128 v[222:225], v161 offset:39936
	global_load_lds_dwordx4 v[234:235], off
	v_lshl_add_u64 v[234:235], s[40:41], 0, v[140:141]
	s_mov_b32 m0, s35
	s_nop 0
	global_load_lds_dwordx4 v[234:235], off
	s_waitcnt vmcnt(8)
	s_waitcnt lgkmcnt(0)
	s_setprio 1
	s_barrier
	v_mfma_f32_16x16x32_bf16 v[124:127], v[128:131], v[194:197], v[124:127]
	v_mfma_f32_16x16x32_bf16 v[120:123], v[164:167], v[194:197], v[120:123]
	v_mfma_f32_16x16x32_bf16 v[104:107], v[164:167], v[202:205], v[104:107]
	v_mfma_f32_16x16x32_bf16 v[108:111], v[128:131], v[202:205], v[108:111]
	v_mfma_f32_16x16x32_bf16 v[92:95], v[128:131], v[210:213], v[92:95]
	v_mfma_f32_16x16x32_bf16 v[88:91], v[164:167], v[210:213], v[88:91]
	v_mfma_f32_16x16x32_bf16 v[72:75], v[164:167], v[218:221], v[72:75]
	v_mfma_f32_16x16x32_bf16 v[76:79], v[128:131], v[218:221], v[76:79]
	v_mfma_f32_16x16x32_bf16 v[124:127], v[132:135], v[198:201], v[124:127]
	v_mfma_f32_16x16x32_bf16 v[120:123], v[168:171], v[198:201], v[120:123]
	v_mfma_f32_16x16x32_bf16 v[104:107], v[168:171], v[206:209], v[104:107]
	v_mfma_f32_16x16x32_bf16 v[108:111], v[132:135], v[206:209], v[108:111]
	v_mfma_f32_16x16x32_bf16 v[92:95], v[132:135], v[214:217], v[92:95]
	v_mfma_f32_16x16x32_bf16 v[88:91], v[168:171], v[214:217], v[88:91]
	v_mfma_f32_16x16x32_bf16 v[72:75], v[168:171], v[222:225], v[72:75]
	v_mfma_f32_16x16x32_bf16 v[76:79], v[132:135], v[222:225], v[76:79]
	s_setprio 0
	s_setprio 1
	v_mfma_f32_16x16x32_bf16 v[116:119], v[172:175], v[194:197], v[116:119]
	v_mfma_f32_16x16x32_bf16 v[112:115], v[180:183], v[194:197], v[112:115]
	v_mfma_f32_16x16x32_bf16 v[96:99], v[180:183], v[202:205], v[96:99]
	v_mfma_f32_16x16x32_bf16 v[100:103], v[172:175], v[202:205], v[100:103]
	v_mfma_f32_16x16x32_bf16 v[84:87], v[172:175], v[210:213], v[84:87]
	v_mfma_f32_16x16x32_bf16 v[80:83], v[180:183], v[210:213], v[80:83]
	v_mfma_f32_16x16x32_bf16 v[64:67], v[180:183], v[218:221], v[64:67]
	v_mfma_f32_16x16x32_bf16 v[68:71], v[172:175], v[218:221], v[68:71]
	v_mfma_f32_16x16x32_bf16 v[116:119], v[176:179], v[198:201], v[116:119]
	v_mfma_f32_16x16x32_bf16 v[112:115], v[190:193], v[198:201], v[112:115]
	v_mfma_f32_16x16x32_bf16 v[96:99], v[190:193], v[206:209], v[96:99]
	v_mfma_f32_16x16x32_bf16 v[100:103], v[176:179], v[206:209], v[100:103]
	v_mfma_f32_16x16x32_bf16 v[84:87], v[176:179], v[214:217], v[84:87]
	v_mfma_f32_16x16x32_bf16 v[80:83], v[190:193], v[214:217], v[80:83]
	v_mfma_f32_16x16x32_bf16 v[64:67], v[190:193], v[222:225], v[64:67]
	v_mfma_f32_16x16x32_bf16 v[68:71], v[176:179], v[222:225], v[68:71]
	s_barrier
; #define PG8_STAGE(bufoff, gbase, voff) do { _Pragma("unroll") for (int _i = 0; _i < 2; ++_i) \
;         __builtin_amdgcn_global_load_lds((const unsigned*)((const char*)(gbase) + (voff)[_i]), (PG8_LAS unsigned*)(lds + (bufoff) + ldsw + _i * 8192), 16, 0, 0); } while (0)
; #define PG8_LDA(dst, b, h) do { _Pragma("unroll") for (int m = 0; m < 4; ++m) _Pragma("unroll") for (int k = 0; k < 2; ++k) dst[m][k] = *(const PG8_LAS bf16x8*)(lds + PG8_SA(b, h) + aoff + m * 2048 + k * 1024); } while (0)
; #define PG8_LDB(dst, b, h) do { _Pragma("unroll") for (int n = 0; n < 2; ++n) _Pragma("unroll") for (int k = 0; k < 2; ++k) dst[n][k] = *(const PG8_LAS bf16x8*)(lds + PG8_SB(b, h) + boff + n * 2048 + k * 1024); } while (0)
; template <class Epi, class Sched, bool ALIGN_EPI = false, bool SP2 = false>
; __device__ __forceinline__ void gemm_phase(PG8_LAS unsigned char* lds, const Gemm g, const Sched& S, const Epi& E) {
;     ...
;         for (int t = 0; t < nt; t += 2) {
;             const bool last = (t == nt - 2);
;             const char* a1 = cA + (size_t)(t + 1) * kstA;
;             const char* a2 = last ? nA : cA + (size_t)(t + 2) * kstA; const char* b2 = last ? nB : cB + (size_t)(t + 2) * kstep;
;             const char* a3 = a2 + kstA; const char* b3 = b2 + kstep;
;             if (last && has_next) S.a_ready(nxt);
;             if constexpr (SP2) {
;             PG8_LDB(B0, 0, 0); PG8_LDB(B1, 0, 1); PG8_SCHED; PG8_LDA(At, 0, 0); PG8_STAGE(PG8_SA(1, 1), a1 + hstepA, voffA);
;             PG8_WAIT_V(8); PG8_WAIT_L(0); PG8_BAR; PG8_MMA(0, 0, At, B0); PG8_MMA(0, 1, At, B1); PG8_BAR; PG8_SCHED;
;             PG8_LDA(At, 0, 1); PG8_STAGE(PG8_SB(0, 0), b2, voffB); PG8_STAGE(PG8_SB(0, 1), b2 + hstepB, voffB); PG8_STAGE(PG8_SA(0, 0), a2, voffA);
;             PG8_WAIT_V(8); PG8_WAIT_L(0); PG8_BAR; PG8_MMA(1, 0, At, B0); PG8_MMA(1, 1, At, B1); PG8_BAR; PG8_SCHED;
;             PG8_LDB(B0, 1, 0); PG8_LDB(B1, 1, 1); PG8_SCHED; PG8_LDA(At, 1, 0); PG8_STAGE(PG8_SA(0, 1), a2 + hstepA, voffA);
;             PG8_WAIT_V(8); PG8_WAIT_L(0); PG8_BAR; PG8_MMA(0, 0, At, B0); PG8_MMA(0, 1, At, B1); PG8_BAR; PG8_SCHED;
;             PG8_LDA(At, 1, 1); PG8_STAGE(PG8_SB(1, 0), b3, voffB); PG8_STAGE(PG8_SB(1, 1), b3 + hstepB, voffB); PG8_STAGE(PG8_SA(1, 0), a3, voffA);
;             PG8_WAIT_V(8); PG8_WAIT_L(0); PG8_BAR; PG8_MMA(1, 0, At, B0); PG8_MMA(1, 1, At, B1); PG8_BAR; PG8_SCHED;
	s_setprio 0
	s_add_i32 s13, s13, s6
	v_lshl_add_u64 v[226:227], v[226:227], 0, s[54:55]
	s_mov_b32 m0, s13
	ds_read_b128 v[194:197], v161 offset:49152
	ds_read_b128 v[198:201], v161 offset:50176
	ds_read_b128 v[202:205], v161 offset:51200
	ds_read_b128 v[206:209], v161 offset:52224
	ds_read_b128 v[210:213], v161 offset:53248
	ds_read_b128 v[214:217], v161 offset:54272
	ds_read_b128 v[218:221], v161 offset:55296
	ds_read_b128 v[222:225], v161 offset:56320
	global_load_lds_dwordx4 v[226:227], off
	s_add_i32 m0, s13, 0x2000
	s_add_u32 s38, s38, 0x80080
	v_lshl_add_u64 v[226:227], v[228:229], 0, s[54:55]
	s_addc_u32 s39, s39, 0
	s_add_i32 s13, s33, s6
	global_load_lds_dwordx4 v[226:227], off
	v_lshl_add_u64 v[226:227], s[38:39], 0, v[138:139]
	s_mov_b32 m0, s13
	s_nop 0
	global_load_lds_dwordx4 v[226:227], off
	v_lshl_add_u64 v[226:227], s[38:39], 0, v[142:143]
	s_add_i32 m0, s13, 0x2000
	s_nop 0
	global_load_lds_dwordx4 v[226:227], off
	v_lshl_add_u64 v[226:227], v[230:231], 0, s[54:55]
	s_mov_b32 m0, s51
	s_nop 0
	global_load_lds_dwordx4 v[226:227], off
	v_lshl_add_u64 v[226:227], v[232:233], 0, s[54:55]
	s_mov_b32 m0, s68
	s_nop 0
	global_load_lds_dwordx4 v[226:227], off
	s_waitcnt vmcnt(8)
	s_waitcnt lgkmcnt(0)
	s_setprio 1
	s_barrier
	v_mfma_f32_16x16x32_bf16 v[60:63], v[128:131], v[194:197], v[60:63]
	v_mfma_f32_16x16x32_bf16 v[56:59], v[164:167], v[194:197], v[56:59]
	v_mfma_f32_16x16x32_bf16 v[40:43], v[164:167], v[202:205], v[40:43]
	v_mfma_f32_16x16x32_bf16 v[44:47], v[128:131], v[202:205], v[44:47]
	v_mfma_f32_16x16x32_bf16 v[28:31], v[128:131], v[210:213], v[28:31]
	v_mfma_f32_16x16x32_bf16 v[24:27], v[164:167], v[210:213], v[24:27]
	v_mfma_f32_16x16x32_bf16 v[8:11], v[164:167], v[218:221], v[8:11]
	v_mfma_f32_16x16x32_bf16 v[12:15], v[128:131], v[218:221], v[12:15]
	v_mfma_f32_16x16x32_bf16 v[60:63], v[132:135], v[198:201], v[60:63]
	v_mfma_f32_16x16x32_bf16 v[56:59], v[168:171], v[198:201], v[56:59]
	v_mfma_f32_16x16x32_bf16 v[40:43], v[168:171], v[206:209], v[40:43]
	v_mfma_f32_16x16x32_bf16 v[44:47], v[132:135], v[206:209], v[44:47]
	v_mfma_f32_16x16x32_bf16 v[28:31], v[132:135], v[214:217], v[28:31]
	v_mfma_f32_16x16x32_bf16 v[24:27], v[168:171], v[214:217], v[24:27]
	v_mfma_f32_16x16x32_bf16 v[8:11], v[168:171], v[222:225], v[8:11]
	v_mfma_f32_16x16x32_bf16 v[12:15], v[132:135], v[222:225], v[12:15]
	s_setprio 0
	s_setprio 1
	v_mfma_f32_16x16x32_bf16 v[52:55], v[172:175], v[194:197], v[52:55]
	v_mfma_f32_16x16x32_bf16 v[48:51], v[180:183], v[194:197], v[48:51]
	v_mfma_f32_16x16x32_bf16 v[32:35], v[180:183], v[202:205], v[32:35]
	v_mfma_f32_16x16x32_bf16 v[36:39], v[172:175], v[202:205], v[36:39]
	v_mfma_f32_16x16x32_bf16 v[20:23], v[172:175], v[210:213], v[20:23]
	v_mfma_f32_16x16x32_bf16 v[16:19], v[180:183], v[210:213], v[16:19]
	v_mfma_f32_16x16x32_bf16 v[0:3], v[180:183], v[218:221], v[0:3]
	v_mfma_f32_16x16x32_bf16 v[4:7], v[172:175], v[218:221], v[4:7]
	v_mfma_f32_16x16x32_bf16 v[52:55], v[176:179], v[198:201], v[52:55]
	v_mfma_f32_16x16x32_bf16 v[48:51], v[190:193], v[198:201], v[48:51]
	v_mfma_f32_16x16x32_bf16 v[32:35], v[190:193], v[206:209], v[32:35]
	v_mfma_f32_16x16x32_bf16 v[36:39], v[176:179], v[206:209], v[36:39]
	v_mfma_f32_16x16x32_bf16 v[20:23], v[176:179], v[214:217], v[20:23]
	v_mfma_f32_16x16x32_bf16 v[16:19], v[190:193], v[214:217], v[16:19]
	v_mfma_f32_16x16x32_bf16 v[0:3], v[190:193], v[222:225], v[0:3]
	v_mfma_f32_16x16x32_bf16 v[4:7], v[176:179], v[222:225], v[4:7]
	s_barrier
	s_setprio 0
	s_add_i32 s12, s12, 2
	s_add_u32 s20, s20, 0x100
	s_addc_u32 s21, s21, 0
	s_add_u32 s10, s10, 0x100
	s_addc_u32 s11, s11, 0
	s_cmp_gt_u32 s12, 29
	s_cbranch_scc1 .Lmy_peel_9_exit
.LBB0_2050:
	ds_read_b128 v[128:131], v159
	ds_read_b128 v[132:135], v159 offset:1024
	ds_read_b128 v[164:167], v159 offset:2048
	ds_read_b128 v[168:171], v159 offset:3072
	ds_read_b128 v[172:175], v160
	ds_read_b128 v[176:179], v160 offset:1024
	ds_read_b128 v[180:183], v160 offset:2048
	ds_read_b128 v[190:193], v160 offset:3072
	s_add_u32 s13, s20, 0xfff80080
	s_addc_u32 s33, s21, -1
	s_cmp_eq_u32 s12, 28
	s_cselect_b32 s41, s1, s33
	s_cselect_b32 s40, s3, s13
	s_cselect_b32 s39, s4, s11
	s_cselect_b32 s38, s5, s10
	v_lshl_add_u64 v[226:227], s[20:21], 0, v[148:149]
	s_add_i32 m0, s7, 0xc000
	ds_read_b128 v[194:197], v161
	ds_read_b128 v[198:201], v161 offset:1024
	ds_read_b128 v[202:205], v161 offset:2048
	ds_read_b128 v[206:209], v161 offset:3072
	ds_read_b128 v[210:213], v161 offset:4096
	ds_read_b128 v[214:217], v161 offset:5120
	ds_read_b128 v[218:221], v161 offset:6144
	ds_read_b128 v[222:225], v161 offset:7168
	global_load_lds_dwordx4 v[226:227], off
	v_lshl_add_u64 v[226:227], s[20:21], 0, v[150:151]
	s_add_i32 m0, s7, 0xe000
	s_nop 0
	global_load_lds_dwordx4 v[226:227], off
	s_waitcnt vmcnt(8)
	s_waitcnt lgkmcnt(0)
	s_setprio 1
	s_barrier
; #define PG8_STAGE(bufoff, gbase, voff) do { _Pragma("unroll") for (int _i = 0; _i < 2; ++_i) \
;         __builtin_amdgcn_global_load_lds((const unsigned*)((const char*)(gbase) + (voff)[_i]), (PG8_LAS unsigned*)(lds + (bufoff) + ldsw + _i * 8192), 16, 0, 0); } while (0)
; #define PG8_LDA(dst, b, h) do { _Pragma("unroll") for (int m = 0; m < 4; ++m) _Pragma("unroll") for (int k = 0; k < 2; ++k) dst[m][k] = *(const PG8_LAS bf16x8*)(lds + PG8_SA(b, h) + aoff + m * 2048 + k * 1024); } while (0)
; #define PG8_MMA(ai, bj, At, Bt) do { __builtin_amdgcn_s_setprio(1); _Pragma("unroll") for (int m = 0; m < 4; ++m) _Pragma("unroll") for (int n = 0; n < 2; ++n) _Pragma("unroll") for (int k = 0; k < 2; ++k) \
;         acc[ai][bj][m][n] = __builtin_amdgcn_mfma_f32_16x16x32_bf16(Bt[n][k], At[m][k], acc[ai][bj][m][n], 0, 0, 0); __builtin_amdgcn_s_setprio(0); } while (0)
; #define PG8_WAIT_V(n) asm volatile("s_waitcnt vmcnt(" #n ")" ::: "memory")
; #define PG8_WAIT_L(n) asm volatile("s_waitcnt lgkmcnt(" #n ")" ::: "memory")
; #define PG8_BAR __builtin_amdgcn_s_barrier()
; #define PG8_SCHED __builtin_amdgcn_sched_barrier(0)
; template <class Epi, class Sched, bool ALIGN_EPI = false, bool SP2 = false>
; __device__ __forceinline__ void gemm_phase(PG8_LAS unsigned char* lds, const Gemm g, const Sched& S, const Epi& E) {
;     ...
;             PG8_WAIT_V(8); PG8_WAIT_L(0); PG8_BAR; PG8_MMA(0, 0, At, B0); PG8_MMA(0, 1, At, B1); PG8_BAR; PG8_SCHED;
;             PG8_LDA(At, 0, 1); PG8_STAGE(PG8_SB(0, 0), b2, voffB); PG8_STAGE(PG8_SB(0, 1), b2 + hstepB, voffB); PG8_STAGE(PG8_SA(0, 0), a2, voffA);
;             PG8_WAIT_V(8); PG8_WAIT_L(0); PG8_BAR; PG8_MMA(1, 0, At, B0); PG8_MMA(1, 1, At, B1); PG8_BAR; PG8_SCHED;
	v_mfma_f32_16x16x32_bf16 v[124:127], v[128:131], v[194:197], v[124:127]
	v_mfma_f32_16x16x32_bf16 v[120:123], v[164:167], v[194:197], v[120:123]
	v_mfma_f32_16x16x32_bf16 v[104:107], v[164:167], v[202:205], v[104:107]
	v_mfma_f32_16x16x32_bf16 v[108:111], v[128:131], v[202:205], v[108:111]
	v_mfma_f32_16x16x32_bf16 v[92:95], v[128:131], v[210:213], v[92:95]
	v_mfma_f32_16x16x32_bf16 v[88:91], v[164:167], v[210:213], v[88:91]
	v_mfma_f32_16x16x32_bf16 v[72:75], v[164:167], v[218:221], v[72:75]
	v_mfma_f32_16x16x32_bf16 v[76:79], v[128:131], v[218:221], v[76:79]
	v_mfma_f32_16x16x32_bf16 v[124:127], v[132:135], v[198:201], v[124:127]
	v_mfma_f32_16x16x32_bf16 v[120:123], v[168:171], v[198:201], v[120:123]
	v_mfma_f32_16x16x32_bf16 v[104:107], v[168:171], v[206:209], v[104:107]
	v_mfma_f32_16x16x32_bf16 v[108:111], v[132:135], v[206:209], v[108:111]
	v_mfma_f32_16x16x32_bf16 v[92:95], v[132:135], v[214:217], v[92:95]
	v_mfma_f32_16x16x32_bf16 v[88:91], v[168:171], v[214:217], v[88:91]
	v_mfma_f32_16x16x32_bf16 v[72:75], v[168:171], v[222:225], v[72:75]
	v_mfma_f32_16x16x32_bf16 v[76:79], v[132:135], v[222:225], v[76:79]
	s_setprio 0
	s_setprio 1
	v_mfma_f32_16x16x32_bf16 v[116:119], v[172:175], v[194:197], v[116:119]
	v_mfma_f32_16x16x32_bf16 v[112:115], v[180:183], v[194:197], v[112:115]
	v_mfma_f32_16x16x32_bf16 v[96:99], v[180:183], v[202:205], v[96:99]
	v_mfma_f32_16x16x32_bf16 v[100:103], v[172:175], v[202:205], v[100:103]
	v_mfma_f32_16x16x32_bf16 v[84:87], v[172:175], v[210:213], v[84:87]
	v_mfma_f32_16x16x32_bf16 v[80:83], v[180:183], v[210:213], v[80:83]
	v_mfma_f32_16x16x32_bf16 v[64:67], v[180:183], v[218:221], v[64:67]
	v_mfma_f32_16x16x32_bf16 v[68:71], v[172:175], v[218:221], v[68:71]
	v_mfma_f32_16x16x32_bf16 v[116:119], v[176:179], v[198:201], v[116:119]
	v_mfma_f32_16x16x32_bf16 v[112:115], v[190:193], v[198:201], v[112:115]
	v_mfma_f32_16x16x32_bf16 v[96:99], v[190:193], v[206:209], v[96:99]
	v_mfma_f32_16x16x32_bf16 v[100:103], v[176:179], v[206:209], v[100:103]
	v_mfma_f32_16x16x32_bf16 v[84:87], v[176:179], v[214:217], v[84:87]
	v_mfma_f32_16x16x32_bf16 v[80:83], v[190:193], v[214:217], v[80:83]
	v_mfma_f32_16x16x32_bf16 v[64:67], v[190:193], v[222:225], v[64:67]
	v_mfma_f32_16x16x32_bf16 v[68:71], v[176:179], v[222:225], v[68:71]
	s_barrier
	s_setprio 0
	s_add_i32 s13, s69, s6
	v_lshl_add_u64 v[226:227], s[38:39], 0, v[138:139]
	s_mov_b32 m0, s13
	ds_read_b128 v[194:197], v161 offset:16384
	ds_read_b128 v[198:201], v161 offset:17408
	ds_read_b128 v[202:205], v161 offset:18432
	ds_read_b128 v[206:209], v161 offset:19456
	ds_read_b128 v[210:213], v161 offset:20480
	ds_read_b128 v[214:217], v161 offset:21504
	ds_read_b128 v[218:221], v161 offset:22528
	ds_read_b128 v[222:225], v161 offset:23552
	global_load_lds_dwordx4 v[226:227], off
	s_add_i32 m0, s13, 0x2000
	s_add_u32 s44, s38, 0x80000
	v_lshl_add_u64 v[228:229], s[38:39], 0, v[142:143]
	s_addc_u32 s45, s39, 0
	s_add_i32 s13, s70, s6
	global_load_lds_dwordx4 v[228:229], off
	v_lshl_add_u64 v[230:231], s[44:45], 0, v[138:139]
	s_mov_b32 m0, s13
	v_lshl_add_u64 v[232:233], s[40:41], 0, v[140:141]
	global_load_lds_dwordx4 v[230:231], off
	v_lshl_add_u64 v[230:231], s[44:45], 0, v[142:143]
	s_add_i32 m0, s13, 0x2000
	s_nop 0
	global_load_lds_dwordx4 v[230:231], off
	v_lshl_add_u64 v[230:231], s[40:41], 0, v[136:137]
	s_mov_b32 m0, s7
	s_nop 0
	global_load_lds_dwordx4 v[230:231], off
	s_mov_b32 m0, s8
	s_nop 0
	global_load_lds_dwordx4 v[232:233], off
	s_waitcnt vmcnt(8)
	s_waitcnt lgkmcnt(0)
	s_setprio 1
	s_barrier
	v_mfma_f32_16x16x32_bf16 v[60:63], v[128:131], v[194:197], v[60:63]
	v_mfma_f32_16x16x32_bf16 v[56:59], v[164:167], v[194:197], v[56:59]
	v_mfma_f32_16x16x32_bf16 v[40:43], v[164:167], v[202:205], v[40:43]
	v_mfma_f32_16x16x32_bf16 v[44:47], v[128:131], v[202:205], v[44:47]
	v_mfma_f32_16x16x32_bf16 v[28:31], v[128:131], v[210:213], v[28:31]
	v_mfma_f32_16x16x32_bf16 v[24:27], v[164:167], v[210:213], v[24:27]
	v_mfma_f32_16x16x32_bf16 v[8:11], v[164:167], v[218:221], v[8:11]
	v_mfma_f32_16x16x32_bf16 v[12:15], v[128:131], v[218:221], v[12:15]
	v_mfma_f32_16x16x32_bf16 v[60:63], v[132:135], v[198:201], v[60:63]
	v_mfma_f32_16x16x32_bf16 v[56:59], v[168:171], v[198:201], v[56:59]
	v_mfma_f32_16x16x32_bf16 v[40:43], v[168:171], v[206:209], v[40:43]
	v_mfma_f32_16x16x32_bf16 v[44:47], v[132:135], v[206:209], v[44:47]
	v_mfma_f32_16x16x32_bf16 v[28:31], v[132:135], v[214:217], v[28:31]
	v_mfma_f32_16x16x32_bf16 v[24:27], v[168:171], v[214:217], v[24:27]
	v_mfma_f32_16x16x32_bf16 v[8:11], v[168:171], v[222:225], v[8:11]
	v_mfma_f32_16x16x32_bf16 v[12:15], v[132:135], v[222:225], v[12:15]
	s_setprio 0
	s_setprio 1
	v_mfma_f32_16x16x32_bf16 v[52:55], v[172:175], v[194:197], v[52:55]
	v_mfma_f32_16x16x32_bf16 v[48:51], v[180:183], v[194:197], v[48:51]
	v_mfma_f32_16x16x32_bf16 v[32:35], v[180:183], v[202:205], v[32:35]
	v_mfma_f32_16x16x32_bf16 v[36:39], v[172:175], v[202:205], v[36:39]
	v_mfma_f32_16x16x32_bf16 v[20:23], v[172:175], v[210:213], v[20:23]
	v_mfma_f32_16x16x32_bf16 v[16:19], v[180:183], v[210:213], v[16:19]
	v_mfma_f32_16x16x32_bf16 v[0:3], v[180:183], v[218:221], v[0:3]
	v_mfma_f32_16x16x32_bf16 v[4:7], v[172:175], v[218:221], v[4:7]
	v_mfma_f32_16x16x32_bf16 v[52:55], v[176:179], v[198:201], v[52:55]
	v_mfma_f32_16x16x32_bf16 v[48:51], v[190:193], v[198:201], v[48:51]
	v_mfma_f32_16x16x32_bf16 v[32:35], v[190:193], v[206:209], v[32:35]
	v_mfma_f32_16x16x32_bf16 v[36:39], v[176:179], v[206:209], v[36:39]
	v_mfma_f32_16x16x32_bf16 v[20:23], v[176:179], v[214:217], v[20:23]
	v_mfma_f32_16x16x32_bf16 v[16:19], v[190:193], v[214:217], v[16:19]
	v_mfma_f32_16x16x32_bf16 v[0:3], v[190:193], v[222:225], v[0:3]
	v_mfma_f32_16x16x32_bf16 v[4:7], v[176:179], v[222:225], v[4:7]
	s_barrier
; #define PG8_STAGE(bufoff, gbase, voff) do { _Pragma("unroll") for (int _i = 0; _i < 2; ++_i) \
;         __builtin_amdgcn_global_load_lds((const unsigned*)((const char*)(gbase) + (voff)[_i]), (PG8_LAS unsigned*)(lds + (bufoff) + ldsw + _i * 8192), 16, 0, 0); } while (0)
; #define PG8_LDA(dst, b, h) do { _Pragma("unroll") for (int m = 0; m < 4; ++m) _Pragma("unroll") for (int k = 0; k < 2; ++k) dst[m][k] = *(const PG8_LAS bf16x8*)(lds + PG8_SA(b, h) + aoff + m * 2048 + k * 1024); } while (0)
; #define PG8_LDB(dst, b, h) do { _Pragma("unroll") for (int n = 0; n < 2; ++n) _Pragma("unroll") for (int k = 0; k < 2; ++k) dst[n][k] = *(const PG8_LAS bf16x8*)(lds + PG8_SB(b, h) + boff + n * 2048 + k * 1024); } while (0)
; #define PG8_MMA(ai, bj, At, Bt) do { __builtin_amdgcn_s_setprio(1); _Pragma("unroll") for (int m = 0; m < 4; ++m) _Pragma("unroll") for (int n = 0; n < 2; ++n) _Pragma("unroll") for (int k = 0; k < 2; ++k) \
;         acc[ai][bj][m][n] = __builtin_amdgcn_mfma_f32_16x16x32_bf16(Bt[n][k], At[m][k], acc[ai][bj][m][n], 0, 0, 0); __builtin_amdgcn_s_setprio(0); } while (0)
; #define PG8_WAIT_V(n) asm volatile("s_waitcnt vmcnt(" #n ")" ::: "memory")
; #define PG8_WAIT_L(n) asm volatile("s_waitcnt lgkmcnt(" #n ")" ::: "memory")
; #define PG8_BAR __builtin_amdgcn_s_barrier()
; #define PG8_SCHED __builtin_amdgcn_sched_barrier(0)
; template <class Epi, class Sched, bool ALIGN_EPI = false, bool SP2 = false>
; __device__ __forceinline__ void gemm_phase(PG8_LAS unsigned char* lds, const Gemm g, const Sched& S, const Epi& E) {
;     ...
;             PG8_LDB(B0, 1, 0); PG8_LDB(B1, 1, 1); PG8_SCHED; PG8_LDA(At, 1, 0); PG8_STAGE(PG8_SA(0, 1), a2 + hstepA, voffA);
;             PG8_WAIT_V(8); PG8_WAIT_L(0); PG8_BAR; PG8_MMA(0, 0, At, B0); PG8_MMA(0, 1, At, B1); PG8_BAR; PG8_SCHED;
	s_setprio 0
	s_add_i32 s13, 0, 0x18000
	v_add_u32_e32 v144, s13, v157
	s_add_i32 s33, 0, 0x1c000
	ds_read_b128 v[128:131], v144
	ds_read_b128 v[132:135], v144 offset:1024
	ds_read_b128 v[164:167], v144 offset:2048
	ds_read_b128 v[168:171], v144 offset:3072
	v_add_u32_e32 v144, s33, v157
	ds_read_b128 v[172:175], v144
	ds_read_b128 v[176:179], v144 offset:1024
	ds_read_b128 v[180:183], v144 offset:2048
	ds_read_b128 v[190:193], v144 offset:3072
	s_add_u32 s40, s40, 0x80000
	s_addc_u32 s41, s41, 0
	s_mov_b32 m0, s9
	v_lshl_add_u64 v[234:235], s[40:41], 0, v[136:137]
	ds_read_b128 v[194:197], v161 offset:32768
	ds_read_b128 v[198:201], v161 offset:33792
	ds_read_b128 v[202:205], v161 offset:34816
	ds_read_b128 v[206:209], v161 offset:35840
	ds_read_b128 v[210:213], v161 offset:36864
	ds_read_b128 v[214:217], v161 offset:37888
	ds_read_b128 v[218:221], v161 offset:38912
	ds_read_b128 v[222:225], v161 offset:39936
	global_load_lds_dwordx4 v[234:235], off
	v_lshl_add_u64 v[234:235], s[40:41], 0, v[140:141]
	s_mov_b32 m0, s35
	s_nop 0
	global_load_lds_dwordx4 v[234:235], off
	s_waitcnt vmcnt(8)
	s_waitcnt lgkmcnt(0)
	s_setprio 1
	s_barrier
	v_mfma_f32_16x16x32_bf16 v[124:127], v[128:131], v[194:197], v[124:127]
	v_mfma_f32_16x16x32_bf16 v[120:123], v[164:167], v[194:197], v[120:123]
	v_mfma_f32_16x16x32_bf16 v[104:107], v[164:167], v[202:205], v[104:107]
	v_mfma_f32_16x16x32_bf16 v[108:111], v[128:131], v[202:205], v[108:111]
	v_mfma_f32_16x16x32_bf16 v[92:95], v[128:131], v[210:213], v[92:95]
	v_mfma_f32_16x16x32_bf16 v[88:91], v[164:167], v[210:213], v[88:91]
	v_mfma_f32_16x16x32_bf16 v[72:75], v[164:167], v[218:221], v[72:75]
	v_mfma_f32_16x16x32_bf16 v[76:79], v[128:131], v[218:221], v[76:79]
	v_mfma_f32_16x16x32_bf16 v[124:127], v[132:135], v[198:201], v[124:127]
	v_mfma_f32_16x16x32_bf16 v[120:123], v[168:171], v[198:201], v[120:123]
	v_mfma_f32_16x16x32_bf16 v[104:107], v[168:171], v[206:209], v[104:107]
	v_mfma_f32_16x16x32_bf16 v[108:111], v[132:135], v[206:209], v[108:111]
	v_mfma_f32_16x16x32_bf16 v[92:95], v[132:135], v[214:217], v[92:95]
	v_mfma_f32_16x16x32_bf16 v[88:91], v[168:171], v[214:217], v[88:91]
	v_mfma_f32_16x16x32_bf16 v[72:75], v[168:171], v[222:225], v[72:75]
	v_mfma_f32_16x16x32_bf16 v[76:79], v[132:135], v[222:225], v[76:79]
	s_setprio 0
	s_setprio 1
	v_mfma_f32_16x16x32_bf16 v[116:119], v[172:175], v[194:197], v[116:119]
	v_mfma_f32_16x16x32_bf16 v[112:115], v[180:183], v[194:197], v[112:115]
	v_mfma_f32_16x16x32_bf16 v[96:99], v[180:183], v[202:205], v[96:99]
	v_mfma_f32_16x16x32_bf16 v[100:103], v[172:175], v[202:205], v[100:103]
	v_mfma_f32_16x16x32_bf16 v[84:87], v[172:175], v[210:213], v[84:87]
	v_mfma_f32_16x16x32_bf16 v[80:83], v[180:183], v[210:213], v[80:83]
	v_mfma_f32_16x16x32_bf16 v[64:67], v[180:183], v[218:221], v[64:67]
	v_mfma_f32_16x16x32_bf16 v[68:71], v[172:175], v[218:221], v[68:71]
	v_mfma_f32_16x16x32_bf16 v[116:119], v[176:179], v[198:201], v[116:119]
	v_mfma_f32_16x16x32_bf16 v[112:115], v[190:193], v[198:201], v[112:115]
	v_mfma_f32_16x16x32_bf16 v[96:99], v[190:193], v[206:209], v[96:99]
	v_mfma_f32_16x16x32_bf16 v[100:103], v[176:179], v[206:209], v[100:103]
	v_mfma_f32_16x16x32_bf16 v[84:87], v[176:179], v[214:217], v[84:87]
	v_mfma_f32_16x16x32_bf16 v[80:83], v[190:193], v[214:217], v[80:83]
	v_mfma_f32_16x16x32_bf16 v[64:67], v[190:193], v[222:225], v[64:67]
	v_mfma_f32_16x16x32_bf16 v[68:71], v[176:179], v[222:225], v[68:71]
	s_barrier
; #define PG8_STAGE(bufoff, gbase, voff) do { _Pragma("unroll") for (int _i = 0; _i < 2; ++_i) \
;         __builtin_amdgcn_global_load_lds((const unsigned*)((const char*)(gbase) + (voff)[_i]), (PG8_LAS unsigned*)(lds + (bufoff) + ldsw + _i * 8192), 16, 0, 0); } while (0)
; #define PG8_LDA(dst, b, h) do { _Pragma("unroll") for (int m = 0; m < 4; ++m) _Pragma("unroll") for (int k = 0; k < 2; ++k) dst[m][k] = *(const PG8_LAS bf16x8*)(lds + PG8_SA(b, h) + aoff + m * 2048 + k * 1024); } while (0)
; #define PG8_MMA(ai, bj, At, Bt) do { __builtin_amdgcn_s_setprio(1); _Pragma("unroll") for (int m = 0; m < 4; ++m) _Pragma("unroll") for (int n = 0; n < 2; ++n) _Pragma("unroll") for (int k = 0; k < 2; ++k) \
;         acc[ai][bj][m][n] = __builtin_amdgcn_mfma_f32_16x16x32_bf16(Bt[n][k], At[m][k], acc[ai][bj][m][n], 0, 0, 0); __builtin_amdgcn_s_setprio(0); } while (0)
; #define PG8_WAIT_V(n) asm volatile("s_waitcnt vmcnt(" #n ")" ::: "memory")
; #define PG8_WAIT_L(n) asm volatile("s_waitcnt lgkmcnt(" #n ")" ::: "memory")
; #define PG8_BAR __builtin_amdgcn_s_barrier()
; #define PG8_SCHED __builtin_amdgcn_sched_barrier(0)
; template <class Epi, class Sched, bool ALIGN_EPI = false, bool SP2 = false>
; __device__ __forceinline__ void gemm_phase(PG8_LAS unsigned char* lds, const Gemm g, const Sched& S, const Epi& E) {
;     ...
;         for (int t = 0; t < nt; t += 2) {
;     ...
;             PG8_LDA(At, 1, 1); PG8_STAGE(PG8_SB(1, 0), b3, voffB); PG8_STAGE(PG8_SB(1, 1), b3 + hstepB, voffB); PG8_STAGE(PG8_SA(1, 0), a3, voffA);
;             PG8_WAIT_V(8); PG8_WAIT_L(0); PG8_BAR; PG8_MMA(1, 0, At, B0); PG8_MMA(1, 1, At, B1); PG8_BAR; PG8_SCHED;
	s_setprio 0
	s_add_i32 s13, s13, s6
	v_lshl_add_u64 v[226:227], v[226:227], 0, s[54:55]
	s_mov_b32 m0, s13
	ds_read_b128 v[194:197], v161 offset:49152
	ds_read_b128 v[198:201], v161 offset:50176
	ds_read_b128 v[202:205], v161 offset:51200
	ds_read_b128 v[206:209], v161 offset:52224
	ds_read_b128 v[210:213], v161 offset:53248
	ds_read_b128 v[214:217], v161 offset:54272
	ds_read_b128 v[218:221], v161 offset:55296
	ds_read_b128 v[222:225], v161 offset:56320
	global_load_lds_dwordx4 v[226:227], off
	s_add_i32 m0, s13, 0x2000
	s_add_u32 s38, s38, 0x80080
	v_lshl_add_u64 v[226:227], v[228:229], 0, s[54:55]
	s_addc_u32 s39, s39, 0
	s_add_i32 s13, s33, s6
	global_load_lds_dwordx4 v[226:227], off
	v_lshl_add_u64 v[226:227], s[38:39], 0, v[138:139]
	s_mov_b32 m0, s13
	s_nop 0
	global_load_lds_dwordx4 v[226:227], off
	v_lshl_add_u64 v[226:227], s[38:39], 0, v[142:143]
	s_add_i32 m0, s13, 0x2000
	s_nop 0
	global_load_lds_dwordx4 v[226:227], off
	v_lshl_add_u64 v[226:227], v[230:231], 0, s[54:55]
	s_mov_b32 m0, s51
	s_nop 0
	global_load_lds_dwordx4 v[226:227], off
	v_lshl_add_u64 v[226:227], v[232:233], 0, s[54:55]
	s_mov_b32 m0, s68
	s_nop 0
	global_load_lds_dwordx4 v[226:227], off
	s_waitcnt vmcnt(8)
	s_waitcnt lgkmcnt(0)
	s_setprio 1
	s_barrier
	v_mfma_f32_16x16x32_bf16 v[60:63], v[128:131], v[194:197], v[60:63]
	v_mfma_f32_16x16x32_bf16 v[56:59], v[164:167], v[194:197], v[56:59]
	v_mfma_f32_16x16x32_bf16 v[40:43], v[164:167], v[202:205], v[40:43]
	v_mfma_f32_16x16x32_bf16 v[44:47], v[128:131], v[202:205], v[44:47]
	v_mfma_f32_16x16x32_bf16 v[28:31], v[128:131], v[210:213], v[28:31]
	v_mfma_f32_16x16x32_bf16 v[24:27], v[164:167], v[210:213], v[24:27]
	v_mfma_f32_16x16x32_bf16 v[8:11], v[164:167], v[218:221], v[8:11]
	v_mfma_f32_16x16x32_bf16 v[12:15], v[128:131], v[218:221], v[12:15]
	v_mfma_f32_16x16x32_bf16 v[60:63], v[132:135], v[198:201], v[60:63]
	v_mfma_f32_16x16x32_bf16 v[56:59], v[168:171], v[198:201], v[56:59]
	v_mfma_f32_16x16x32_bf16 v[40:43], v[168:171], v[206:209], v[40:43]
	v_mfma_f32_16x16x32_bf16 v[44:47], v[132:135], v[206:209], v[44:47]
	v_mfma_f32_16x16x32_bf16 v[28:31], v[132:135], v[214:217], v[28:31]
	v_mfma_f32_16x16x32_bf16 v[24:27], v[168:171], v[214:217], v[24:27]
	v_mfma_f32_16x16x32_bf16 v[8:11], v[168:171], v[222:225], v[8:11]
	v_mfma_f32_16x16x32_bf16 v[12:15], v[132:135], v[222:225], v[12:15]
	s_setprio 0
	s_setprio 1
	v_mfma_f32_16x16x32_bf16 v[52:55], v[172:175], v[194:197], v[52:55]
	v_mfma_f32_16x16x32_bf16 v[48:51], v[180:183], v[194:197], v[48:51]
	v_mfma_f32_16x16x32_bf16 v[32:35], v[180:183], v[202:205], v[32:35]
	v_mfma_f32_16x16x32_bf16 v[36:39], v[172:175], v[202:205], v[36:39]
	v_mfma_f32_16x16x32_bf16 v[20:23], v[172:175], v[210:213], v[20:23]
	v_mfma_f32_16x16x32_bf16 v[16:19], v[180:183], v[210:213], v[16:19]
	v_mfma_f32_16x16x32_bf16 v[0:3], v[180:183], v[218:221], v[0:3]
	v_mfma_f32_16x16x32_bf16 v[4:7], v[172:175], v[218:221], v[4:7]
	v_mfma_f32_16x16x32_bf16 v[52:55], v[176:179], v[198:201], v[52:55]
	v_mfma_f32_16x16x32_bf16 v[48:51], v[190:193], v[198:201], v[48:51]
	v_mfma_f32_16x16x32_bf16 v[32:35], v[190:193], v[206:209], v[32:35]
	v_mfma_f32_16x16x32_bf16 v[36:39], v[176:179], v[206:209], v[36:39]
	v_mfma_f32_16x16x32_bf16 v[20:23], v[176:179], v[214:217], v[20:23]
	v_mfma_f32_16x16x32_bf16 v[16:19], v[190:193], v[214:217], v[16:19]
	v_mfma_f32_16x16x32_bf16 v[0:3], v[190:193], v[222:225], v[0:3]
	v_mfma_f32_16x16x32_bf16 v[4:7], v[176:179], v[222:225], v[4:7]
	s_barrier
	s_setprio 0
	s_add_i32 s12, s12, 2
	s_add_u32 s20, s20, 0x100
	s_addc_u32 s21, s21, 0
	s_add_u32 s10, s10, 0x100
	s_addc_u32 s11, s11, 0
	s_cmp_gt_u32 s12, 29
	s_cbranch_scc0 .LBB0_2050

; #define PG8_STAGE(bufoff, gbase, voff) do { _Pragma("unroll") for (int _i = 0; _i < 2; ++_i) \
;         __builtin_amdgcn_global_load_lds((const unsigned*)((const char*)(gbase) + (voff)[_i]), (PG8_LAS unsigned*)(lds + (bufoff) + ldsw + _i * 8192), 16, 0, 0); } while (0)
; #define PG8_LDA(dst, b, h) do { _Pragma("unroll") for (int m = 0; m < 4; ++m) _Pragma("unroll") for (int k = 0; k < 2; ++k) dst[m][k] = *(const PG8_LAS bf16x8*)(lds + PG8_SA(b, h) + aoff + m * 2048 + k * 1024); } while (0)
; #define PG8_LDB(dst, b, h) do { _Pragma("unroll") for (int n = 0; n < 2; ++n) _Pragma("unroll") for (int k = 0; k < 2; ++k) dst[n][k] = *(const PG8_LAS bf16x8*)(lds + PG8_SB(b, h) + boff + n * 2048 + k * 1024); } while (0)
; #define PG8_MMA(ai, bj, At, Bt) do { __builtin_amdgcn_s_setprio(1); _Pragma("unroll") for (int m = 0; m < 4; ++m) _Pragma("unroll") for (int n = 0; n < 2; ++n) _Pragma("unroll") for (int k = 0; k < 2; ++k) \
;         acc[ai][bj][m][n] = __builtin_amdgcn_mfma_f32_16x16x32_bf16(Bt[n][k], At[m][k], acc[ai][bj][m][n], 0, 0, 0); __builtin_amdgcn_s_setprio(0); } while (0)
; #define PG8_WAIT_V(n) asm volatile("s_waitcnt vmcnt(" #n ")" ::: "memory")
; #define PG8_WAIT_L(n) asm volatile("s_waitcnt lgkmcnt(" #n ")" ::: "memory")
; #define PG8_BAR __builtin_amdgcn_s_barrier()
; #define PG8_SCHED __builtin_amdgcn_sched_barrier(0)
; template <class Epi, class Sched, bool ALIGN_EPI = false, bool SP2 = false>
; __device__ __forceinline__ void gemm_phase(PG8_LAS unsigned char* lds, const Gemm g, const Sched& S, const Epi& E) {
;     ...
;         for (int t = 0; t < nt; t += 2) {
;             const bool last = (t == nt - 2);
;             const char* a1 = cA + (size_t)(t + 1) * kstA;
;             const char* a2 = last ? nA : cA + (size_t)(t + 2) * kstA; const char* b2 = last ? nB : cB + (size_t)(t + 2) * kstep;
;             const char* a3 = a2 + kstA; const char* b3 = b2 + kstep;
;             if (last && has_next) S.a_ready(nxt);
;             if constexpr (SP2) {
;             PG8_LDB(B0, 0, 0); PG8_LDB(B1, 0, 1); PG8_SCHED; PG8_LDA(At, 0, 0); PG8_STAGE(PG8_SA(1, 1), a1 + hstepA, voffA);
;             PG8_WAIT_V(8); PG8_WAIT_L(0); PG8_BAR; PG8_MMA(0, 0, At, B0); PG8_MMA(0, 1, At, B1); PG8_BAR; PG8_SCHED;
;             PG8_LDA(At, 0, 1); PG8_STAGE(PG8_SB(0, 0), b2, voffB); PG8_STAGE(PG8_SB(0, 1), b2 + hstepB, voffB); PG8_STAGE(PG8_SA(0, 0), a2, voffA);
.LBB0_2749:
	v_add_u32_e32 v176, s77, v180
	v_add_u32_e32 v183, s84, v180
	ds_read_b128 v[132:135], v176
	ds_read_b128 v[136:139], v176 offset:1024
	ds_read_b128 v[140:143], v176 offset:2048
	ds_read_b128 v[176:179], v176 offset:3072
	ds_read_b128 v[190:193], v183
	ds_read_b128 v[194:197], v183 offset:1024
	ds_read_b128 v[198:201], v183 offset:2048
	ds_read_b128 v[202:205], v183 offset:3072
	s_add_u32 s4, s46, s62
	s_addc_u32 s5, s47, s63
	s_add_u32 s12, s48, s62
	s_addc_u32 s13, s49, s63
	s_cmp_eq_u32 s7, s1
	s_cselect_b32 s67, s59, s5
	s_cselect_b32 s66, s58, s4
	s_cselect_b32 s65, s61, s13
	s_cselect_b32 s64, s60, s12
	v_lshl_add_u64 v[238:239], s[46:47], 0, v[130:131]
	s_add_i32 m0, s9, 0xc000
	ds_read_b128 v[206:209], v182
	ds_read_b128 v[210:213], v182 offset:1024
	ds_read_b128 v[214:217], v182 offset:2048
	ds_read_b128 v[218:221], v182 offset:3072
	ds_read_b128 v[222:225], v182 offset:4096
	ds_read_b128 v[226:229], v182 offset:5120
	ds_read_b128 v[230:233], v182 offset:6144
	ds_read_b128 v[234:237], v182 offset:7168
	global_load_lds_dwordx4 v[238:239], off
	v_lshl_add_u64 v[238:239], s[46:47], 0, v[128:129]
	s_add_i32 m0, s9, 0xe000
	s_nop 0
	global_load_lds_dwordx4 v[238:239], off
	s_waitcnt vmcnt(8)
	s_waitcnt lgkmcnt(0)
	s_setprio 1
	s_barrier
	v_mfma_f32_16x16x32_bf16 v[124:127], v[132:135], v[206:209], v[124:127]
	v_mfma_f32_16x16x32_bf16 v[120:123], v[140:143], v[206:209], v[120:123]
	v_mfma_f32_16x16x32_bf16 v[112:115], v[140:143], v[214:217], v[112:115]
	v_mfma_f32_16x16x32_bf16 v[116:119], v[132:135], v[214:217], v[116:119]
	v_mfma_f32_16x16x32_bf16 v[108:111], v[132:135], v[222:225], v[108:111]
	v_mfma_f32_16x16x32_bf16 v[104:107], v[140:143], v[222:225], v[104:107]
	v_mfma_f32_16x16x32_bf16 v[96:99], v[140:143], v[230:233], v[96:99]
	v_mfma_f32_16x16x32_bf16 v[100:103], v[132:135], v[230:233], v[100:103]
	v_mfma_f32_16x16x32_bf16 v[124:127], v[136:139], v[210:213], v[124:127]
	v_mfma_f32_16x16x32_bf16 v[120:123], v[176:179], v[210:213], v[120:123]
	v_mfma_f32_16x16x32_bf16 v[112:115], v[176:179], v[218:221], v[112:115]
	v_mfma_f32_16x16x32_bf16 v[116:119], v[136:139], v[218:221], v[116:119]
	v_mfma_f32_16x16x32_bf16 v[108:111], v[136:139], v[226:229], v[108:111]
	v_mfma_f32_16x16x32_bf16 v[104:107], v[176:179], v[226:229], v[104:107]
	v_mfma_f32_16x16x32_bf16 v[96:99], v[176:179], v[234:237], v[96:99]
	v_mfma_f32_16x16x32_bf16 v[100:103], v[136:139], v[234:237], v[100:103]
	s_setprio 0
	s_setprio 1
	v_mfma_f32_16x16x32_bf16 v[92:95], v[190:193], v[206:209], v[92:95]
	v_mfma_f32_16x16x32_bf16 v[88:91], v[198:201], v[206:209], v[88:91]
	v_mfma_f32_16x16x32_bf16 v[80:83], v[198:201], v[214:217], v[80:83]
	v_mfma_f32_16x16x32_bf16 v[84:87], v[190:193], v[214:217], v[84:87]
	v_mfma_f32_16x16x32_bf16 v[76:79], v[190:193], v[222:225], v[76:79]
	v_mfma_f32_16x16x32_bf16 v[72:75], v[198:201], v[222:225], v[72:75]
	v_mfma_f32_16x16x32_bf16 v[64:67], v[198:201], v[230:233], v[64:67]
	v_mfma_f32_16x16x32_bf16 v[68:71], v[190:193], v[230:233], v[68:71]
	v_mfma_f32_16x16x32_bf16 v[92:95], v[194:197], v[210:213], v[92:95]
	v_mfma_f32_16x16x32_bf16 v[88:91], v[202:205], v[210:213], v[88:91]
	v_mfma_f32_16x16x32_bf16 v[80:83], v[202:205], v[218:221], v[80:83]
	v_mfma_f32_16x16x32_bf16 v[84:87], v[194:197], v[218:221], v[84:87]
	v_mfma_f32_16x16x32_bf16 v[76:79], v[194:197], v[226:229], v[76:79]
	v_mfma_f32_16x16x32_bf16 v[72:75], v[202:205], v[226:229], v[72:75]
	v_mfma_f32_16x16x32_bf16 v[64:67], v[202:205], v[234:237], v[64:67]
	v_mfma_f32_16x16x32_bf16 v[68:71], v[194:197], v[234:237], v[68:71]
	s_barrier
	s_setprio 0
	s_add_i32 s4, s77, s8
	v_lshl_add_u64 v[238:239], s[64:65], 0, v[146:147]
	s_mov_b32 m0, s4
	ds_read_b128 v[206:209], v182 offset:16384
	ds_read_b128 v[210:213], v182 offset:17408
	ds_read_b128 v[214:217], v182 offset:18432
	ds_read_b128 v[218:221], v182 offset:19456
	ds_read_b128 v[222:225], v182 offset:20480
	ds_read_b128 v[226:229], v182 offset:21504
	ds_read_b128 v[230:233], v182 offset:22528
	ds_read_b128 v[234:237], v182 offset:23552
	global_load_lds_dwordx4 v[238:239], off
	s_add_i32 m0, s4, 0x2000
	s_add_u32 s4, s64, 0x80000
	v_lshl_add_u64 v[240:241], s[64:65], 0, v[150:151]
	s_addc_u32 s5, s65, 0
	s_add_i32 s12, s84, s8
	global_load_lds_dwordx4 v[240:241], off
	v_lshl_add_u64 v[242:243], s[4:5], 0, v[146:147]
	s_mov_b32 m0, s12
	v_lshl_add_u64 v[244:245], s[66:67], 0, v[148:149]
	global_load_lds_dwordx4 v[242:243], off
	v_lshl_add_u64 v[242:243], s[4:5], 0, v[150:151]
	s_add_i32 m0, s12, 0x2000
	s_nop 0
	global_load_lds_dwordx4 v[242:243], off
	v_lshl_add_u64 v[242:243], s[66:67], 0, v[144:145]
	s_mov_b32 m0, s9
	s_nop 0
	global_load_lds_dwordx4 v[242:243], off
	s_mov_b32 m0, s37
	s_nop 0
	global_load_lds_dwordx4 v[244:245], off
	s_waitcnt vmcnt(8)
	s_waitcnt lgkmcnt(0)
	s_setprio 1
	s_barrier
; #define PG8_STAGE(bufoff, gbase, voff) do { _Pragma("unroll") for (int _i = 0; _i < 2; ++_i) \
;         __builtin_amdgcn_global_load_lds((const unsigned*)((const char*)(gbase) + (voff)[_i]), (PG8_LAS unsigned*)(lds + (bufoff) + ldsw + _i * 8192), 16, 0, 0); } while (0)
; #define PG8_LDA(dst, b, h) do { _Pragma("unroll") for (int m = 0; m < 4; ++m) _Pragma("unroll") for (int k = 0; k < 2; ++k) dst[m][k] = *(const PG8_LAS bf16x8*)(lds + PG8_SA(b, h) + aoff + m * 2048 + k * 1024); } while (0)
; #define PG8_LDB(dst, b, h) do { _Pragma("unroll") for (int n = 0; n < 2; ++n) _Pragma("unroll") for (int k = 0; k < 2; ++k) dst[n][k] = *(const PG8_LAS bf16x8*)(lds + PG8_SB(b, h) + boff + n * 2048 + k * 1024); } while (0)
; #define PG8_MMA(ai, bj, At, Bt) do { __builtin_amdgcn_s_setprio(1); _Pragma("unroll") for (int m = 0; m < 4; ++m) _Pragma("unroll") for (int n = 0; n < 2; ++n) _Pragma("unroll") for (int k = 0; k < 2; ++k) \
;         acc[ai][bj][m][n] = __builtin_amdgcn_mfma_f32_16x16x32_bf16(Bt[n][k], At[m][k], acc[ai][bj][m][n], 0, 0, 0); __builtin_amdgcn_s_setprio(0); } while (0)
; #define PG8_WAIT_V(n) asm volatile("s_waitcnt vmcnt(" #n ")" ::: "memory")
; #define PG8_WAIT_L(n) asm volatile("s_waitcnt lgkmcnt(" #n ")" ::: "memory")
; #define PG8_BAR __builtin_amdgcn_s_barrier()
; #define PG8_SCHED __builtin_amdgcn_sched_barrier(0)
; template <class Epi, class Sched, bool ALIGN_EPI = false, bool SP2 = false>
; __device__ __forceinline__ void gemm_phase(PG8_LAS unsigned char* lds, const Gemm g, const Sched& S, const Epi& E) {
;     ...
;             PG8_WAIT_V(8); PG8_WAIT_L(0); PG8_BAR; PG8_MMA(1, 0, At, B0); PG8_MMA(1, 1, At, B1); PG8_BAR; PG8_SCHED;
;             PG8_LDB(B0, 1, 0); PG8_LDB(B1, 1, 1); PG8_SCHED; PG8_LDA(At, 1, 0); PG8_STAGE(PG8_SA(0, 1), a2 + hstepA, voffA);
;             PG8_WAIT_V(8); PG8_WAIT_L(0); PG8_BAR; PG8_MMA(0, 0, At, B0); PG8_MMA(0, 1, At, B1); PG8_BAR; PG8_SCHED;
	v_mfma_f32_16x16x32_bf16 v[60:63], v[132:135], v[206:209], v[60:63]
	v_mfma_f32_16x16x32_bf16 v[56:59], v[140:143], v[206:209], v[56:59]
	v_mfma_f32_16x16x32_bf16 v[48:51], v[140:143], v[214:217], v[48:51]
	v_mfma_f32_16x16x32_bf16 v[52:55], v[132:135], v[214:217], v[52:55]
	v_mfma_f32_16x16x32_bf16 v[44:47], v[132:135], v[222:225], v[44:47]
	v_mfma_f32_16x16x32_bf16 v[40:43], v[140:143], v[222:225], v[40:43]
	v_mfma_f32_16x16x32_bf16 v[32:35], v[140:143], v[230:233], v[32:35]
	v_mfma_f32_16x16x32_bf16 v[36:39], v[132:135], v[230:233], v[36:39]
	v_mfma_f32_16x16x32_bf16 v[60:63], v[136:139], v[210:213], v[60:63]
	v_mfma_f32_16x16x32_bf16 v[56:59], v[176:179], v[210:213], v[56:59]
	v_mfma_f32_16x16x32_bf16 v[48:51], v[176:179], v[218:221], v[48:51]
	v_mfma_f32_16x16x32_bf16 v[52:55], v[136:139], v[218:221], v[52:55]
	v_mfma_f32_16x16x32_bf16 v[44:47], v[136:139], v[226:229], v[44:47]
	v_mfma_f32_16x16x32_bf16 v[40:43], v[176:179], v[226:229], v[40:43]
	v_mfma_f32_16x16x32_bf16 v[32:35], v[176:179], v[234:237], v[32:35]
	v_mfma_f32_16x16x32_bf16 v[36:39], v[136:139], v[234:237], v[36:39]
	s_setprio 0
	s_setprio 1
	v_mfma_f32_16x16x32_bf16 v[28:31], v[190:193], v[206:209], v[28:31]
	v_mfma_f32_16x16x32_bf16 v[24:27], v[198:201], v[206:209], v[24:27]
	v_mfma_f32_16x16x32_bf16 v[16:19], v[198:201], v[214:217], v[16:19]
	v_mfma_f32_16x16x32_bf16 v[20:23], v[190:193], v[214:217], v[20:23]
	v_mfma_f32_16x16x32_bf16 v[12:15], v[190:193], v[222:225], v[12:15]
	v_mfma_f32_16x16x32_bf16 v[8:11], v[198:201], v[222:225], v[8:11]
	v_mfma_f32_16x16x32_bf16 v[0:3], v[198:201], v[230:233], v[0:3]
	v_mfma_f32_16x16x32_bf16 v[4:7], v[190:193], v[230:233], v[4:7]
	v_mfma_f32_16x16x32_bf16 v[28:31], v[194:197], v[210:213], v[28:31]
	v_mfma_f32_16x16x32_bf16 v[24:27], v[202:205], v[210:213], v[24:27]
	v_mfma_f32_16x16x32_bf16 v[16:19], v[202:205], v[218:221], v[16:19]
	v_mfma_f32_16x16x32_bf16 v[20:23], v[194:197], v[218:221], v[20:23]
	v_mfma_f32_16x16x32_bf16 v[12:15], v[194:197], v[226:229], v[12:15]
	v_mfma_f32_16x16x32_bf16 v[8:11], v[202:205], v[226:229], v[8:11]
	v_mfma_f32_16x16x32_bf16 v[0:3], v[202:205], v[234:237], v[0:3]
	v_mfma_f32_16x16x32_bf16 v[4:7], v[194:197], v[234:237], v[4:7]
	s_barrier
	s_setprio 0
	s_add_i32 s12, 0, 0x18000
	s_add_i32 s13, 0, 0x1c000
	v_add_u32_e32 v176, s12, v180
	v_add_u32_e32 v183, s13, v180
	ds_read_b128 v[132:135], v176
	ds_read_b128 v[136:139], v176 offset:1024
	ds_read_b128 v[140:143], v176 offset:2048
	ds_read_b128 v[176:179], v176 offset:3072
	ds_read_b128 v[190:193], v183
	ds_read_b128 v[194:197], v183 offset:1024
	ds_read_b128 v[198:201], v183 offset:2048
	ds_read_b128 v[202:205], v183 offset:3072
	s_add_u32 s4, s66, 0x80000
	s_addc_u32 s5, s67, 0
	s_mov_b32 m0, s70
	v_lshl_add_u64 v[246:247], s[4:5], 0, v[144:145]
	ds_read_b128 v[206:209], v182 offset:32768
	ds_read_b128 v[210:213], v182 offset:33792
	ds_read_b128 v[214:217], v182 offset:34816
	ds_read_b128 v[218:221], v182 offset:35840
	ds_read_b128 v[222:225], v182 offset:36864
	ds_read_b128 v[226:229], v182 offset:37888
	ds_read_b128 v[230:233], v182 offset:38912
	ds_read_b128 v[234:237], v182 offset:39936
	global_load_lds_dwordx4 v[246:247], off
	v_lshl_add_u64 v[246:247], s[4:5], 0, v[148:149]
	s_mov_b32 m0, s71
	s_nop 0
	global_load_lds_dwordx4 v[246:247], off
	s_waitcnt vmcnt(8)
	s_waitcnt lgkmcnt(0)
	s_setprio 1
	s_barrier
	v_mfma_f32_16x16x32_bf16 v[124:127], v[132:135], v[206:209], v[124:127]
	v_mfma_f32_16x16x32_bf16 v[120:123], v[140:143], v[206:209], v[120:123]
	v_mfma_f32_16x16x32_bf16 v[112:115], v[140:143], v[214:217], v[112:115]
	v_mfma_f32_16x16x32_bf16 v[116:119], v[132:135], v[214:217], v[116:119]
	v_mfma_f32_16x16x32_bf16 v[108:111], v[132:135], v[222:225], v[108:111]
	v_mfma_f32_16x16x32_bf16 v[104:107], v[140:143], v[222:225], v[104:107]
	v_mfma_f32_16x16x32_bf16 v[96:99], v[140:143], v[230:233], v[96:99]
	v_mfma_f32_16x16x32_bf16 v[100:103], v[132:135], v[230:233], v[100:103]
	v_mfma_f32_16x16x32_bf16 v[124:127], v[136:139], v[210:213], v[124:127]
	v_mfma_f32_16x16x32_bf16 v[120:123], v[176:179], v[210:213], v[120:123]
	v_mfma_f32_16x16x32_bf16 v[112:115], v[176:179], v[218:221], v[112:115]
	v_mfma_f32_16x16x32_bf16 v[116:119], v[136:139], v[218:221], v[116:119]
	v_mfma_f32_16x16x32_bf16 v[108:111], v[136:139], v[226:229], v[108:111]
	v_mfma_f32_16x16x32_bf16 v[104:107], v[176:179], v[226:229], v[104:107]
	v_mfma_f32_16x16x32_bf16 v[96:99], v[176:179], v[234:237], v[96:99]
	v_mfma_f32_16x16x32_bf16 v[100:103], v[136:139], v[234:237], v[100:103]
	s_setprio 0
	s_setprio 1
	v_mfma_f32_16x16x32_bf16 v[92:95], v[190:193], v[206:209], v[92:95]
	v_mfma_f32_16x16x32_bf16 v[88:91], v[198:201], v[206:209], v[88:91]
	v_mfma_f32_16x16x32_bf16 v[80:83], v[198:201], v[214:217], v[80:83]
	v_mfma_f32_16x16x32_bf16 v[84:87], v[190:193], v[214:217], v[84:87]
	v_mfma_f32_16x16x32_bf16 v[76:79], v[190:193], v[222:225], v[76:79]
	v_mfma_f32_16x16x32_bf16 v[72:75], v[198:201], v[222:225], v[72:75]
	v_mfma_f32_16x16x32_bf16 v[64:67], v[198:201], v[230:233], v[64:67]
	v_mfma_f32_16x16x32_bf16 v[68:71], v[190:193], v[230:233], v[68:71]
	v_mfma_f32_16x16x32_bf16 v[92:95], v[194:197], v[210:213], v[92:95]
	v_mfma_f32_16x16x32_bf16 v[88:91], v[202:205], v[210:213], v[88:91]
	v_mfma_f32_16x16x32_bf16 v[80:83], v[202:205], v[218:221], v[80:83]
	v_mfma_f32_16x16x32_bf16 v[84:87], v[194:197], v[218:221], v[84:87]
	v_mfma_f32_16x16x32_bf16 v[76:79], v[194:197], v[226:229], v[76:79]
	v_mfma_f32_16x16x32_bf16 v[72:75], v[202:205], v[226:229], v[72:75]
	v_mfma_f32_16x16x32_bf16 v[64:67], v[202:205], v[234:237], v[64:67]
	v_mfma_f32_16x16x32_bf16 v[68:71], v[194:197], v[234:237], v[68:71]
	s_barrier
; #define PG8_STAGE(bufoff, gbase, voff) do { _Pragma("unroll") for (int _i = 0; _i < 2; ++_i) \
;         __builtin_amdgcn_global_load_lds((const unsigned*)((const char*)(gbase) + (voff)[_i]), (PG8_LAS unsigned*)(lds + (bufoff) + ldsw + _i * 8192), 16, 0, 0); } while (0)
; #define PG8_LDA(dst, b, h) do { _Pragma("unroll") for (int m = 0; m < 4; ++m) _Pragma("unroll") for (int k = 0; k < 2; ++k) dst[m][k] = *(const PG8_LAS bf16x8*)(lds + PG8_SA(b, h) + aoff + m * 2048 + k * 1024); } while (0)
; #define PG8_MMA(ai, bj, At, Bt) do { __builtin_amdgcn_s_setprio(1); _Pragma("unroll") for (int m = 0; m < 4; ++m) _Pragma("unroll") for (int n = 0; n < 2; ++n) _Pragma("unroll") for (int k = 0; k < 2; ++k) \
;         acc[ai][bj][m][n] = __builtin_amdgcn_mfma_f32_16x16x32_bf16(Bt[n][k], At[m][k], acc[ai][bj][m][n], 0, 0, 0); __builtin_amdgcn_s_setprio(0); } while (0)
; #define PG8_WAIT_V(n) asm volatile("s_waitcnt vmcnt(" #n ")" ::: "memory")
; #define PG8_WAIT_L(n) asm volatile("s_waitcnt lgkmcnt(" #n ")" ::: "memory")
; #define PG8_BAR __builtin_amdgcn_s_barrier()
; #define PG8_SCHED __builtin_amdgcn_sched_barrier(0)
; template <class Epi, class Sched, bool ALIGN_EPI = false, bool SP2 = false>
; __device__ __forceinline__ void gemm_phase(PG8_LAS unsigned char* lds, const Gemm g, const Sched& S, const Epi& E) {
;     ...
;             PG8_LDA(At, 1, 1); PG8_STAGE(PG8_SB(1, 0), b3, voffB); PG8_STAGE(PG8_SB(1, 1), b3 + hstepB, voffB); PG8_STAGE(PG8_SA(1, 0), a3, voffA);
;             PG8_WAIT_V(8); PG8_WAIT_L(0); PG8_BAR; PG8_MMA(1, 0, At, B0); PG8_MMA(1, 1, At, B1); PG8_BAR; PG8_SCHED;
;     ...
;         if constexpr (ALIGN_EPI) { if (wr == 0) PG8_BAR; }
	s_setprio 0
	s_add_i32 s4, s12, s8
	v_lshl_add_u64 v[238:239], v[238:239], 0, s[52:53]
	s_mov_b32 m0, s4
	ds_read_b128 v[206:209], v182 offset:49152
	ds_read_b128 v[210:213], v182 offset:50176
	ds_read_b128 v[214:217], v182 offset:51200
	ds_read_b128 v[218:221], v182 offset:52224
	ds_read_b128 v[222:225], v182 offset:53248
	ds_read_b128 v[226:229], v182 offset:54272
	ds_read_b128 v[230:233], v182 offset:55296
	ds_read_b128 v[234:237], v182 offset:56320
	global_load_lds_dwordx4 v[238:239], off
	s_add_i32 m0, s4, 0x2000
	s_add_u32 s4, s64, 0x80080
	v_lshl_add_u64 v[238:239], v[240:241], 0, s[52:53]
	s_addc_u32 s5, s65, 0
	s_add_i32 s12, s13, s8
	global_load_lds_dwordx4 v[238:239], off
	v_lshl_add_u64 v[238:239], s[4:5], 0, v[146:147]
	s_mov_b32 m0, s12
	s_nop 0
	global_load_lds_dwordx4 v[238:239], off
	v_lshl_add_u64 v[238:239], s[4:5], 0, v[150:151]
	s_add_i32 m0, s12, 0x2000
	s_nop 0
	global_load_lds_dwordx4 v[238:239], off
	v_lshl_add_u64 v[238:239], v[242:243], 0, s[52:53]
	s_mov_b32 m0, s74
	s_nop 0
	global_load_lds_dwordx4 v[238:239], off
	v_lshl_add_u64 v[238:239], v[244:245], 0, s[52:53]
	s_mov_b32 m0, s75
	s_nop 0
	global_load_lds_dwordx4 v[238:239], off
	s_waitcnt vmcnt(8)
	s_waitcnt lgkmcnt(0)
	s_setprio 1
	s_barrier
	v_mfma_f32_16x16x32_bf16 v[60:63], v[132:135], v[206:209], v[60:63]
	v_mfma_f32_16x16x32_bf16 v[56:59], v[140:143], v[206:209], v[56:59]
	v_mfma_f32_16x16x32_bf16 v[48:51], v[140:143], v[214:217], v[48:51]
	v_mfma_f32_16x16x32_bf16 v[52:55], v[132:135], v[214:217], v[52:55]
	v_mfma_f32_16x16x32_bf16 v[44:47], v[132:135], v[222:225], v[44:47]
	v_mfma_f32_16x16x32_bf16 v[40:43], v[140:143], v[222:225], v[40:43]
	v_mfma_f32_16x16x32_bf16 v[32:35], v[140:143], v[230:233], v[32:35]
	v_mfma_f32_16x16x32_bf16 v[36:39], v[132:135], v[230:233], v[36:39]
	v_mfma_f32_16x16x32_bf16 v[60:63], v[136:139], v[210:213], v[60:63]
	v_mfma_f32_16x16x32_bf16 v[56:59], v[176:179], v[210:213], v[56:59]
	v_mfma_f32_16x16x32_bf16 v[48:51], v[176:179], v[218:221], v[48:51]
	v_mfma_f32_16x16x32_bf16 v[52:55], v[136:139], v[218:221], v[52:55]
	v_mfma_f32_16x16x32_bf16 v[44:47], v[136:139], v[226:229], v[44:47]
	v_mfma_f32_16x16x32_bf16 v[40:43], v[176:179], v[226:229], v[40:43]
	v_mfma_f32_16x16x32_bf16 v[32:35], v[176:179], v[234:237], v[32:35]
	v_mfma_f32_16x16x32_bf16 v[36:39], v[136:139], v[234:237], v[36:39]
	s_setprio 0
	s_setprio 1
	v_mfma_f32_16x16x32_bf16 v[28:31], v[190:193], v[206:209], v[28:31]
	v_mfma_f32_16x16x32_bf16 v[24:27], v[198:201], v[206:209], v[24:27]
	v_mfma_f32_16x16x32_bf16 v[16:19], v[198:201], v[214:217], v[16:19]
	v_mfma_f32_16x16x32_bf16 v[20:23], v[190:193], v[214:217], v[20:23]
	v_mfma_f32_16x16x32_bf16 v[12:15], v[190:193], v[222:225], v[12:15]
	v_mfma_f32_16x16x32_bf16 v[8:11], v[198:201], v[222:225], v[8:11]
	v_mfma_f32_16x16x32_bf16 v[0:3], v[198:201], v[230:233], v[0:3]
	v_mfma_f32_16x16x32_bf16 v[4:7], v[190:193], v[230:233], v[4:7]
	v_mfma_f32_16x16x32_bf16 v[28:31], v[194:197], v[210:213], v[28:31]
	v_mfma_f32_16x16x32_bf16 v[24:27], v[202:205], v[210:213], v[24:27]
	v_mfma_f32_16x16x32_bf16 v[16:19], v[202:205], v[218:221], v[16:19]
	v_mfma_f32_16x16x32_bf16 v[20:23], v[194:197], v[218:221], v[20:23]
	v_mfma_f32_16x16x32_bf16 v[12:15], v[194:197], v[226:229], v[12:15]
	v_mfma_f32_16x16x32_bf16 v[8:11], v[202:205], v[226:229], v[8:11]
	v_mfma_f32_16x16x32_bf16 v[0:3], v[202:205], v[234:237], v[0:3]
	v_mfma_f32_16x16x32_bf16 v[4:7], v[194:197], v[234:237], v[4:7]
	s_barrier
	s_setprio 0
	s_add_i32 s4, s1, 2
	s_add_u32 s62, s62, 0x100
	s_addc_u32 s63, s63, 0
	v_lshl_add_u64 v[130:131], v[130:131], 0, s[34:35]
	v_lshl_add_u64 v[128:129], v[128:129], 0, s[34:35]
	s_cmp_ge_i32 s1, s7
	s_mov_b32 s1, s4
	s_cbranch_scc0 .LBB0_2749
	s_and_b64 vcc, exec, s[54:55]
	s_cbranch_vccz .LBB0_2752
	s_barrier

; #define PG8_STAGE(bufoff, gbase, voff) do { _Pragma("unroll") for (int _i = 0; _i < 2; ++_i) \
;         __builtin_amdgcn_global_load_lds((const unsigned*)((const char*)(gbase) + (voff)[_i]), (PG8_LAS unsigned*)(lds + (bufoff) + ldsw + _i * 8192), 16, 0, 0); } while (0)
; #define PG8_LDA(dst, b, h) do { _Pragma("unroll") for (int m = 0; m < 4; ++m) _Pragma("unroll") for (int k = 0; k < 2; ++k) dst[m][k] = *(const PG8_LAS bf16x8*)(lds + PG8_SA(b, h) + aoff + m * 2048 + k * 1024); } while (0)
; #define PG8_LDB(dst, b, h) do { _Pragma("unroll") for (int n = 0; n < 2; ++n) _Pragma("unroll") for (int k = 0; k < 2; ++k) dst[n][k] = *(const PG8_LAS bf16x8*)(lds + PG8_SB(b, h) + boff + n * 2048 + k * 1024); } while (0)
; #define PG8_WAIT_V(n) asm volatile("s_waitcnt vmcnt(" #n ")" ::: "memory")
; #define PG8_WAIT_L(n) asm volatile("s_waitcnt lgkmcnt(" #n ")" ::: "memory")
; template <class Epi, class Sched, bool ALIGN_EPI = false, bool SP2 = false>
; __device__ __forceinline__ void gemm_phase(PG8_LAS unsigned char* lds, const Gemm g, const Sched& S, const Epi& E) {
;     ...
;     for (;;) {
;         const bool has_next = S.next(ui + 1, nxt);
;         const char* nA = has_next ? (const char*)g.A + (size_t)nxt.pm * tstepA + (size_t)nxt.z * g.azs + (size_t)(nxt.k0 >> 6) * kstA : cA; const char* nB = has_next ? (const char*)g.Bt + (size_t)nxt.pn * tstepB + (size_t)nxt.z * g.bzs + (size_t)nxt.k0 * 2 : cB;
;         const int nt = cur.nt;
;         for (int t = 0; t < nt; t += 2) {
;             const bool last = (t == nt - 2);
;             const char* a1 = cA + (size_t)(t + 1) * kstA;
;             const char* a2 = last ? nA : cA + (size_t)(t + 2) * kstA; const char* b2 = last ? nB : cB + (size_t)(t + 2) * kstep;
;             const char* a3 = a2 + kstA; const char* b3 = b2 + kstep;
;             if (last && has_next) S.a_ready(nxt);
;             if constexpr (SP2) {
;             PG8_LDB(B0, 0, 0); PG8_LDB(B1, 0, 1); PG8_SCHED; PG8_LDA(At, 0, 0); PG8_STAGE(PG8_SA(1, 1), a1 + hstepA, voffA);
;             PG8_WAIT_V(8); PG8_WAIT_L(0); PG8_BAR; PG8_MMA(0, 0, At, B0); PG8_MMA(0, 1, At, B1); PG8_BAR; PG8_SCHED;
;             PG8_LDA(At, 0, 1); PG8_STAGE(PG8_SB(0, 0), b2, voffB); PG8_STAGE(PG8_SB(0, 1), b2 + hstepB, voffB); PG8_STAGE(PG8_SA(0, 0), a2, voffA);
;             PG8_WAIT_V(8); PG8_WAIT_L(0); PG8_BAR; PG8_MMA(1, 0, At, B0); PG8_MMA(1, 1, At, B1); PG8_BAR; PG8_SCHED;
.LBB0_3057:
	s_ashr_i32 s23, s22, 31
	s_lshl_b64 s[4:5], s[22:23], 20
	v_readlane_b32 s12, v254, 41
	v_readlane_b32 s13, v254, 42
	s_add_u32 s24, s12, s4
	s_addc_u32 s25, s13, s5
	s_and_b64 s[4:5], s[36:37], exec
	s_cselect_b32 s4, s25, s41
	s_cselect_b32 s5, s24, s40
	s_ashr_i32 s21, s20, 31
	s_lshl_b64 s[12:13], s[20:21], 20
	s_add_u32 s30, s3, s12
	s_addc_u32 s31, s6, s13
	s_and_b64 s[12:13], s[36:37], exec
	s_cselect_b32 s12, s31, s43
	s_cselect_b32 s13, s30, s42
	s_add_u32 s40, s40, 0x80080
	s_addc_u32 s41, s41, 0
	s_add_u32 s21, s42, 0x100
	s_addc_u32 s23, s43, 0
	s_mov_b32 s35, -2
	ds_read_b128 v[156:159], v152
	ds_read_b128 v[160:163], v152 offset:1024
	ds_read_b128 v[164:167], v152 offset:2048
	ds_read_b128 v[168:171], v152 offset:3072
	ds_read_b128 v[172:175], v153
	ds_read_b128 v[176:179], v153 offset:1024
	ds_read_b128 v[180:183], v153 offset:2048
	ds_read_b128 v[190:193], v153 offset:3072
	s_add_u32 s42, s40, 0xfff80080
	s_addc_u32 s43, s41, -1
	s_cmp_eq_u32 s35, 28
	s_cselect_b32 s45, s4, s43
	s_cselect_b32 s44, s5, s42
	s_cselect_b32 s43, s12, s23
	s_cselect_b32 s42, s13, s21
	v_lshl_add_u64 v[226:227], s[40:41], 0, v[142:143]
	s_add_i32 m0, s8, 0xc000
	ds_read_b128 v[194:197], v154
	ds_read_b128 v[198:201], v154 offset:1024
	ds_read_b128 v[202:205], v154 offset:2048
	ds_read_b128 v[206:209], v154 offset:3072
	ds_read_b128 v[210:213], v154 offset:4096
	ds_read_b128 v[214:217], v154 offset:5120
	ds_read_b128 v[218:221], v154 offset:6144
	ds_read_b128 v[222:225], v154 offset:7168
	global_load_lds_dwordx4 v[226:227], off
	v_lshl_add_u64 v[226:227], s[40:41], 0, v[144:145]
	s_add_i32 m0, s8, 0xe000
	s_nop 0
	global_load_lds_dwordx4 v[226:227], off
	s_waitcnt vmcnt(8)
	s_waitcnt lgkmcnt(0)
	s_setprio 1
	s_barrier
	v_mfma_f32_16x16x32_bf16 v[124:127], v[156:159], v[194:197], 0
	v_mfma_f32_16x16x32_bf16 v[120:123], v[164:167], v[194:197], 0
	v_mfma_f32_16x16x32_bf16 v[104:107], v[164:167], v[202:205], 0
	v_mfma_f32_16x16x32_bf16 v[108:111], v[156:159], v[202:205], 0
	v_mfma_f32_16x16x32_bf16 v[92:95], v[156:159], v[210:213], 0
	v_mfma_f32_16x16x32_bf16 v[88:91], v[164:167], v[210:213], 0
	v_mfma_f32_16x16x32_bf16 v[72:75], v[164:167], v[218:221], 0
	v_mfma_f32_16x16x32_bf16 v[76:79], v[156:159], v[218:221], 0
	v_mfma_f32_16x16x32_bf16 v[124:127], v[160:163], v[198:201], v[124:127]
	v_mfma_f32_16x16x32_bf16 v[120:123], v[168:171], v[198:201], v[120:123]
	v_mfma_f32_16x16x32_bf16 v[104:107], v[168:171], v[206:209], v[104:107]
	v_mfma_f32_16x16x32_bf16 v[108:111], v[160:163], v[206:209], v[108:111]
	v_mfma_f32_16x16x32_bf16 v[92:95], v[160:163], v[214:217], v[92:95]
	v_mfma_f32_16x16x32_bf16 v[88:91], v[168:171], v[214:217], v[88:91]
	v_mfma_f32_16x16x32_bf16 v[72:75], v[168:171], v[222:225], v[72:75]
	v_mfma_f32_16x16x32_bf16 v[76:79], v[160:163], v[222:225], v[76:79]
	s_setprio 0
	s_setprio 1
	v_mfma_f32_16x16x32_bf16 v[116:119], v[172:175], v[194:197], 0
	v_mfma_f32_16x16x32_bf16 v[112:115], v[180:183], v[194:197], 0
	v_mfma_f32_16x16x32_bf16 v[96:99], v[180:183], v[202:205], 0
	v_mfma_f32_16x16x32_bf16 v[100:103], v[172:175], v[202:205], 0
	v_mfma_f32_16x16x32_bf16 v[84:87], v[172:175], v[210:213], 0
	v_mfma_f32_16x16x32_bf16 v[80:83], v[180:183], v[210:213], 0
	v_mfma_f32_16x16x32_bf16 v[64:67], v[180:183], v[218:221], 0
	v_mfma_f32_16x16x32_bf16 v[68:71], v[172:175], v[218:221], 0
	v_mfma_f32_16x16x32_bf16 v[116:119], v[176:179], v[198:201], v[116:119]
	v_mfma_f32_16x16x32_bf16 v[112:115], v[190:193], v[198:201], v[112:115]
	v_mfma_f32_16x16x32_bf16 v[96:99], v[190:193], v[206:209], v[96:99]
	v_mfma_f32_16x16x32_bf16 v[100:103], v[176:179], v[206:209], v[100:103]
	v_mfma_f32_16x16x32_bf16 v[84:87], v[176:179], v[214:217], v[84:87]
	v_mfma_f32_16x16x32_bf16 v[80:83], v[190:193], v[214:217], v[80:83]
	v_mfma_f32_16x16x32_bf16 v[64:67], v[190:193], v[222:225], v[64:67]
	v_mfma_f32_16x16x32_bf16 v[68:71], v[176:179], v[222:225], v[68:71]
	s_barrier
	s_setprio 0
	s_add_i32 s53, s50, s7
	v_lshl_add_u64 v[226:227], s[42:43], 0, v[130:131]
	s_mov_b32 m0, s53
	ds_read_b128 v[194:197], v154 offset:16384
	ds_read_b128 v[198:201], v154 offset:17408
	ds_read_b128 v[202:205], v154 offset:18432
	ds_read_b128 v[206:209], v154 offset:19456
	ds_read_b128 v[210:213], v154 offset:20480
	ds_read_b128 v[214:217], v154 offset:21504
	ds_read_b128 v[218:221], v154 offset:22528
	ds_read_b128 v[222:225], v154 offset:23552
	global_load_lds_dwordx4 v[226:227], off
	s_add_i32 m0, s53, 0x2000
	s_add_u32 s54, s42, 0x80000
	v_lshl_add_u64 v[228:229], s[42:43], 0, v[134:135]
	s_addc_u32 s55, s43, 0
	s_add_i32 s53, s51, s7
	global_load_lds_dwordx4 v[228:229], off
	v_lshl_add_u64 v[230:231], s[54:55], 0, v[130:131]
	s_mov_b32 m0, s53
	v_lshl_add_u64 v[232:233], s[44:45], 0, v[132:133]
	global_load_lds_dwordx4 v[230:231], off
	v_lshl_add_u64 v[230:231], s[54:55], 0, v[134:135]
	s_add_i32 m0, s53, 0x2000
	s_nop 0
	global_load_lds_dwordx4 v[230:231], off
	v_lshl_add_u64 v[230:231], s[44:45], 0, v[128:129]
	s_mov_b32 m0, s8
	s_nop 0
	global_load_lds_dwordx4 v[230:231], off
	s_mov_b32 m0, s9
	s_nop 0
	global_load_lds_dwordx4 v[232:233], off
	s_waitcnt vmcnt(8)
	s_waitcnt lgkmcnt(0)
	s_setprio 1
	s_barrier
; #define PG8_STAGE(bufoff, gbase, voff) do { _Pragma("unroll") for (int _i = 0; _i < 2; ++_i) \
;         __builtin_amdgcn_global_load_lds((const unsigned*)((const char*)(gbase) + (voff)[_i]), (PG8_LAS unsigned*)(lds + (bufoff) + ldsw + _i * 8192), 16, 0, 0); } while (0)
; #define PG8_LDA(dst, b, h) do { _Pragma("unroll") for (int m = 0; m < 4; ++m) _Pragma("unroll") for (int k = 0; k < 2; ++k) dst[m][k] = *(const PG8_LAS bf16x8*)(lds + PG8_SA(b, h) + aoff + m * 2048 + k * 1024); } while (0)
; #define PG8_LDB(dst, b, h) do { _Pragma("unroll") for (int n = 0; n < 2; ++n) _Pragma("unroll") for (int k = 0; k < 2; ++k) dst[n][k] = *(const PG8_LAS bf16x8*)(lds + PG8_SB(b, h) + boff + n * 2048 + k * 1024); } while (0)
; #define PG8_MMA(ai, bj, At, Bt) do { __builtin_amdgcn_s_setprio(1); _Pragma("unroll") for (int m = 0; m < 4; ++m) _Pragma("unroll") for (int n = 0; n < 2; ++n) _Pragma("unroll") for (int k = 0; k < 2; ++k) \
;         acc[ai][bj][m][n] = __builtin_amdgcn_mfma_f32_16x16x32_bf16(Bt[n][k], At[m][k], acc[ai][bj][m][n], 0, 0, 0); __builtin_amdgcn_s_setprio(0); } while (0)
; #define PG8_WAIT_V(n) asm volatile("s_waitcnt vmcnt(" #n ")" ::: "memory")
; #define PG8_WAIT_L(n) asm volatile("s_waitcnt lgkmcnt(" #n ")" ::: "memory")
; #define PG8_BAR __builtin_amdgcn_s_barrier()
; #define PG8_SCHED __builtin_amdgcn_sched_barrier(0)
; template <class Epi, class Sched, bool ALIGN_EPI = false, bool SP2 = false>
; __device__ __forceinline__ void gemm_phase(PG8_LAS unsigned char* lds, const Gemm g, const Sched& S, const Epi& E) {
;     ...
;             PG8_WAIT_V(8); PG8_WAIT_L(0); PG8_BAR; PG8_MMA(1, 0, At, B0); PG8_MMA(1, 1, At, B1); PG8_BAR; PG8_SCHED;
;             PG8_LDB(B0, 1, 0); PG8_LDB(B1, 1, 1); PG8_SCHED; PG8_LDA(At, 1, 0); PG8_STAGE(PG8_SA(0, 1), a2 + hstepA, voffA);
;             PG8_WAIT_V(8); PG8_WAIT_L(0); PG8_BAR; PG8_MMA(0, 0, At, B0); PG8_MMA(0, 1, At, B1); PG8_BAR; PG8_SCHED;
	v_mfma_f32_16x16x32_bf16 v[60:63], v[156:159], v[194:197], 0
	v_mfma_f32_16x16x32_bf16 v[56:59], v[164:167], v[194:197], 0
	v_mfma_f32_16x16x32_bf16 v[40:43], v[164:167], v[202:205], 0
	v_mfma_f32_16x16x32_bf16 v[44:47], v[156:159], v[202:205], 0
	v_mfma_f32_16x16x32_bf16 v[28:31], v[156:159], v[210:213], 0
	v_mfma_f32_16x16x32_bf16 v[24:27], v[164:167], v[210:213], 0
	v_mfma_f32_16x16x32_bf16 v[8:11], v[164:167], v[218:221], 0
	v_mfma_f32_16x16x32_bf16 v[12:15], v[156:159], v[218:221], 0
	v_mfma_f32_16x16x32_bf16 v[60:63], v[160:163], v[198:201], v[60:63]
	v_mfma_f32_16x16x32_bf16 v[56:59], v[168:171], v[198:201], v[56:59]
	v_mfma_f32_16x16x32_bf16 v[40:43], v[168:171], v[206:209], v[40:43]
	v_mfma_f32_16x16x32_bf16 v[44:47], v[160:163], v[206:209], v[44:47]
	v_mfma_f32_16x16x32_bf16 v[28:31], v[160:163], v[214:217], v[28:31]
	v_mfma_f32_16x16x32_bf16 v[24:27], v[168:171], v[214:217], v[24:27]
	v_mfma_f32_16x16x32_bf16 v[8:11], v[168:171], v[222:225], v[8:11]
	v_mfma_f32_16x16x32_bf16 v[12:15], v[160:163], v[222:225], v[12:15]
	s_setprio 0
	s_setprio 1
	v_mfma_f32_16x16x32_bf16 v[52:55], v[172:175], v[194:197], 0
	v_mfma_f32_16x16x32_bf16 v[48:51], v[180:183], v[194:197], 0
	v_mfma_f32_16x16x32_bf16 v[32:35], v[180:183], v[202:205], 0
	v_mfma_f32_16x16x32_bf16 v[36:39], v[172:175], v[202:205], 0
	v_mfma_f32_16x16x32_bf16 v[20:23], v[172:175], v[210:213], 0
	v_mfma_f32_16x16x32_bf16 v[16:19], v[180:183], v[210:213], 0
	v_mfma_f32_16x16x32_bf16 v[0:3], v[180:183], v[218:221], 0
	v_mfma_f32_16x16x32_bf16 v[4:7], v[172:175], v[218:221], 0
	v_mfma_f32_16x16x32_bf16 v[52:55], v[176:179], v[198:201], v[52:55]
	v_mfma_f32_16x16x32_bf16 v[48:51], v[190:193], v[198:201], v[48:51]
	v_mfma_f32_16x16x32_bf16 v[32:35], v[190:193], v[206:209], v[32:35]
	v_mfma_f32_16x16x32_bf16 v[36:39], v[176:179], v[206:209], v[36:39]
	v_mfma_f32_16x16x32_bf16 v[20:23], v[176:179], v[214:217], v[20:23]
	v_mfma_f32_16x16x32_bf16 v[16:19], v[190:193], v[214:217], v[16:19]
	v_mfma_f32_16x16x32_bf16 v[0:3], v[190:193], v[222:225], v[0:3]
	v_mfma_f32_16x16x32_bf16 v[4:7], v[176:179], v[222:225], v[4:7]
	s_barrier
	s_setprio 0
	s_add_i32 s53, 0, 0x18000
	v_add_u32_e32 v155, s53, v150
	s_add_i32 s54, 0, 0x1c000
	ds_read_b128 v[156:159], v155
	ds_read_b128 v[160:163], v155 offset:1024
	ds_read_b128 v[164:167], v155 offset:2048
	ds_read_b128 v[168:171], v155 offset:3072
	v_add_u32_e32 v155, s54, v150
	ds_read_b128 v[172:175], v155
	ds_read_b128 v[176:179], v155 offset:1024
	ds_read_b128 v[180:183], v155 offset:2048
	ds_read_b128 v[190:193], v155 offset:3072
	s_add_u32 s44, s44, 0x80000
	s_addc_u32 s45, s45, 0
	s_mov_b32 m0, s10
	v_lshl_add_u64 v[234:235], s[44:45], 0, v[128:129]
	ds_read_b128 v[194:197], v154 offset:32768
	ds_read_b128 v[198:201], v154 offset:33792
	ds_read_b128 v[202:205], v154 offset:34816
	ds_read_b128 v[206:209], v154 offset:35840
	ds_read_b128 v[210:213], v154 offset:36864
	ds_read_b128 v[214:217], v154 offset:37888
	ds_read_b128 v[218:221], v154 offset:38912
	ds_read_b128 v[222:225], v154 offset:39936
	global_load_lds_dwordx4 v[234:235], off
	v_lshl_add_u64 v[234:235], s[44:45], 0, v[132:133]
	s_mov_b32 m0, s11
	s_nop 0
	global_load_lds_dwordx4 v[234:235], off
	s_waitcnt vmcnt(8)
	s_waitcnt lgkmcnt(0)
	s_setprio 1
	s_barrier
	v_mfma_f32_16x16x32_bf16 v[124:127], v[156:159], v[194:197], v[124:127]
	v_mfma_f32_16x16x32_bf16 v[120:123], v[164:167], v[194:197], v[120:123]
	v_mfma_f32_16x16x32_bf16 v[104:107], v[164:167], v[202:205], v[104:107]
	v_mfma_f32_16x16x32_bf16 v[108:111], v[156:159], v[202:205], v[108:111]
	v_mfma_f32_16x16x32_bf16 v[92:95], v[156:159], v[210:213], v[92:95]
	v_mfma_f32_16x16x32_bf16 v[88:91], v[164:167], v[210:213], v[88:91]
	v_mfma_f32_16x16x32_bf16 v[72:75], v[164:167], v[218:221], v[72:75]
	v_mfma_f32_16x16x32_bf16 v[76:79], v[156:159], v[218:221], v[76:79]
	v_mfma_f32_16x16x32_bf16 v[124:127], v[160:163], v[198:201], v[124:127]
	v_mfma_f32_16x16x32_bf16 v[120:123], v[168:171], v[198:201], v[120:123]
	v_mfma_f32_16x16x32_bf16 v[104:107], v[168:171], v[206:209], v[104:107]
	v_mfma_f32_16x16x32_bf16 v[108:111], v[160:163], v[206:209], v[108:111]
	v_mfma_f32_16x16x32_bf16 v[92:95], v[160:163], v[214:217], v[92:95]
	v_mfma_f32_16x16x32_bf16 v[88:91], v[168:171], v[214:217], v[88:91]
	v_mfma_f32_16x16x32_bf16 v[72:75], v[168:171], v[222:225], v[72:75]
	v_mfma_f32_16x16x32_bf16 v[76:79], v[160:163], v[222:225], v[76:79]
	s_setprio 0
	s_setprio 1
	v_mfma_f32_16x16x32_bf16 v[116:119], v[172:175], v[194:197], v[116:119]
	v_mfma_f32_16x16x32_bf16 v[112:115], v[180:183], v[194:197], v[112:115]
	v_mfma_f32_16x16x32_bf16 v[96:99], v[180:183], v[202:205], v[96:99]
	v_mfma_f32_16x16x32_bf16 v[100:103], v[172:175], v[202:205], v[100:103]
	v_mfma_f32_16x16x32_bf16 v[84:87], v[172:175], v[210:213], v[84:87]
	v_mfma_f32_16x16x32_bf16 v[80:83], v[180:183], v[210:213], v[80:83]
	v_mfma_f32_16x16x32_bf16 v[64:67], v[180:183], v[218:221], v[64:67]
	v_mfma_f32_16x16x32_bf16 v[68:71], v[172:175], v[218:221], v[68:71]
	v_mfma_f32_16x16x32_bf16 v[116:119], v[176:179], v[198:201], v[116:119]
	v_mfma_f32_16x16x32_bf16 v[112:115], v[190:193], v[198:201], v[112:115]
	v_mfma_f32_16x16x32_bf16 v[96:99], v[190:193], v[206:209], v[96:99]
	v_mfma_f32_16x16x32_bf16 v[100:103], v[176:179], v[206:209], v[100:103]
	v_mfma_f32_16x16x32_bf16 v[84:87], v[176:179], v[214:217], v[84:87]
	v_mfma_f32_16x16x32_bf16 v[80:83], v[190:193], v[214:217], v[80:83]
	v_mfma_f32_16x16x32_bf16 v[64:67], v[190:193], v[222:225], v[64:67]
	v_mfma_f32_16x16x32_bf16 v[68:71], v[176:179], v[222:225], v[68:71]
	s_barrier
; #define PG8_STAGE(bufoff, gbase, voff) do { _Pragma("unroll") for (int _i = 0; _i < 2; ++_i) \
;         __builtin_amdgcn_global_load_lds((const unsigned*)((const char*)(gbase) + (voff)[_i]), (PG8_LAS unsigned*)(lds + (bufoff) + ldsw + _i * 8192), 16, 0, 0); } while (0)
; #define PG8_LDA(dst, b, h) do { _Pragma("unroll") for (int m = 0; m < 4; ++m) _Pragma("unroll") for (int k = 0; k < 2; ++k) dst[m][k] = *(const PG8_LAS bf16x8*)(lds + PG8_SA(b, h) + aoff + m * 2048 + k * 1024); } while (0)
; #define PG8_LDB(dst, b, h) do { _Pragma("unroll") for (int n = 0; n < 2; ++n) _Pragma("unroll") for (int k = 0; k < 2; ++k) dst[n][k] = *(const PG8_LAS bf16x8*)(lds + PG8_SB(b, h) + boff + n * 2048 + k * 1024); } while (0)
; template <class Epi, class Sched, bool ALIGN_EPI = false, bool SP2 = false>
; __device__ __forceinline__ void gemm_phase(PG8_LAS unsigned char* lds, const Gemm g, const Sched& S, const Epi& E) {
;     ...
;         for (int t = 0; t < nt; t += 2) {
;             const bool last = (t == nt - 2);
;             const char* a1 = cA + (size_t)(t + 1) * kstA;
;             const char* a2 = last ? nA : cA + (size_t)(t + 2) * kstA; const char* b2 = last ? nB : cB + (size_t)(t + 2) * kstep;
;             const char* a3 = a2 + kstA; const char* b3 = b2 + kstep;
;             if (last && has_next) S.a_ready(nxt);
;             if constexpr (SP2) {
;             PG8_LDB(B0, 0, 0); PG8_LDB(B1, 0, 1); PG8_SCHED; PG8_LDA(At, 0, 0); PG8_STAGE(PG8_SA(1, 1), a1 + hstepA, voffA);
;             PG8_WAIT_V(8); PG8_WAIT_L(0); PG8_BAR; PG8_MMA(0, 0, At, B0); PG8_MMA(0, 1, At, B1); PG8_BAR; PG8_SCHED;
;             PG8_LDA(At, 0, 1); PG8_STAGE(PG8_SB(0, 0), b2, voffB); PG8_STAGE(PG8_SB(0, 1), b2 + hstepB, voffB); PG8_STAGE(PG8_SA(0, 0), a2, voffA);
;             PG8_WAIT_V(8); PG8_WAIT_L(0); PG8_BAR; PG8_MMA(1, 0, At, B0); PG8_MMA(1, 1, At, B1); PG8_BAR; PG8_SCHED;
;             PG8_LDB(B0, 1, 0); PG8_LDB(B1, 1, 1); PG8_SCHED; PG8_LDA(At, 1, 0); PG8_STAGE(PG8_SA(0, 1), a2 + hstepA, voffA);
;             PG8_WAIT_V(8); PG8_WAIT_L(0); PG8_BAR; PG8_MMA(0, 0, At, B0); PG8_MMA(0, 1, At, B1); PG8_BAR; PG8_SCHED;
;             PG8_LDA(At, 1, 1); PG8_STAGE(PG8_SB(1, 0), b3, voffB); PG8_STAGE(PG8_SB(1, 1), b3 + hstepB, voffB); PG8_STAGE(PG8_SA(1, 0), a3, voffA);
;             PG8_WAIT_V(8); PG8_WAIT_L(0); PG8_BAR; PG8_MMA(1, 0, At, B0); PG8_MMA(1, 1, At, B1); PG8_BAR; PG8_SCHED;
	s_setprio 0
	s_add_i32 s44, s53, s7
	v_lshl_add_u64 v[226:227], v[226:227], 0, s[16:17]
	s_mov_b32 m0, s44
	ds_read_b128 v[194:197], v154 offset:49152
	ds_read_b128 v[198:201], v154 offset:50176
	ds_read_b128 v[202:205], v154 offset:51200
	ds_read_b128 v[206:209], v154 offset:52224
	ds_read_b128 v[210:213], v154 offset:53248
	ds_read_b128 v[214:217], v154 offset:54272
	ds_read_b128 v[218:221], v154 offset:55296
	ds_read_b128 v[222:225], v154 offset:56320
	global_load_lds_dwordx4 v[226:227], off
	s_add_i32 m0, s44, 0x2000
	s_add_u32 s42, s42, 0x80080
	v_lshl_add_u64 v[226:227], v[228:229], 0, s[16:17]
	s_addc_u32 s43, s43, 0
	s_add_i32 s44, s54, s7
	global_load_lds_dwordx4 v[226:227], off
	v_lshl_add_u64 v[226:227], s[42:43], 0, v[130:131]
	s_mov_b32 m0, s44
	s_nop 0
	global_load_lds_dwordx4 v[226:227], off
	v_lshl_add_u64 v[226:227], s[42:43], 0, v[134:135]
	s_add_i32 m0, s44, 0x2000
	s_nop 0
	global_load_lds_dwordx4 v[226:227], off
	v_lshl_add_u64 v[226:227], v[230:231], 0, s[16:17]
	s_mov_b32 m0, s48
	s_nop 0
	global_load_lds_dwordx4 v[226:227], off
	v_lshl_add_u64 v[226:227], v[232:233], 0, s[16:17]
	s_mov_b32 m0, s49
	s_nop 0
	global_load_lds_dwordx4 v[226:227], off
	s_waitcnt vmcnt(8)
	s_waitcnt lgkmcnt(0)
	s_setprio 1
	s_barrier
	v_mfma_f32_16x16x32_bf16 v[60:63], v[156:159], v[194:197], v[60:63]
	v_mfma_f32_16x16x32_bf16 v[56:59], v[164:167], v[194:197], v[56:59]
	v_mfma_f32_16x16x32_bf16 v[40:43], v[164:167], v[202:205], v[40:43]
	v_mfma_f32_16x16x32_bf16 v[44:47], v[156:159], v[202:205], v[44:47]
	v_mfma_f32_16x16x32_bf16 v[28:31], v[156:159], v[210:213], v[28:31]
	v_mfma_f32_16x16x32_bf16 v[24:27], v[164:167], v[210:213], v[24:27]
	v_mfma_f32_16x16x32_bf16 v[8:11], v[164:167], v[218:221], v[8:11]
	v_mfma_f32_16x16x32_bf16 v[12:15], v[156:159], v[218:221], v[12:15]
	v_mfma_f32_16x16x32_bf16 v[60:63], v[160:163], v[198:201], v[60:63]
	v_mfma_f32_16x16x32_bf16 v[56:59], v[168:171], v[198:201], v[56:59]
	v_mfma_f32_16x16x32_bf16 v[40:43], v[168:171], v[206:209], v[40:43]
	v_mfma_f32_16x16x32_bf16 v[44:47], v[160:163], v[206:209], v[44:47]
	v_mfma_f32_16x16x32_bf16 v[28:31], v[160:163], v[214:217], v[28:31]
	v_mfma_f32_16x16x32_bf16 v[24:27], v[168:171], v[214:217], v[24:27]
	v_mfma_f32_16x16x32_bf16 v[8:11], v[168:171], v[222:225], v[8:11]
	v_mfma_f32_16x16x32_bf16 v[12:15], v[160:163], v[222:225], v[12:15]
	s_setprio 0
	s_setprio 1
	v_mfma_f32_16x16x32_bf16 v[52:55], v[172:175], v[194:197], v[52:55]
	v_mfma_f32_16x16x32_bf16 v[48:51], v[180:183], v[194:197], v[48:51]
	v_mfma_f32_16x16x32_bf16 v[32:35], v[180:183], v[202:205], v[32:35]
	v_mfma_f32_16x16x32_bf16 v[36:39], v[172:175], v[202:205], v[36:39]
	v_mfma_f32_16x16x32_bf16 v[20:23], v[172:175], v[210:213], v[20:23]
	v_mfma_f32_16x16x32_bf16 v[16:19], v[180:183], v[210:213], v[16:19]
	v_mfma_f32_16x16x32_bf16 v[0:3], v[180:183], v[218:221], v[0:3]
	v_mfma_f32_16x16x32_bf16 v[4:7], v[172:175], v[218:221], v[4:7]
	v_mfma_f32_16x16x32_bf16 v[52:55], v[176:179], v[198:201], v[52:55]
	v_mfma_f32_16x16x32_bf16 v[48:51], v[190:193], v[198:201], v[48:51]
	v_mfma_f32_16x16x32_bf16 v[32:35], v[190:193], v[206:209], v[32:35]
	v_mfma_f32_16x16x32_bf16 v[36:39], v[176:179], v[206:209], v[36:39]
	v_mfma_f32_16x16x32_bf16 v[20:23], v[176:179], v[214:217], v[20:23]
	v_mfma_f32_16x16x32_bf16 v[16:19], v[190:193], v[214:217], v[16:19]
	v_mfma_f32_16x16x32_bf16 v[0:3], v[190:193], v[222:225], v[0:3]
	v_mfma_f32_16x16x32_bf16 v[4:7], v[176:179], v[222:225], v[4:7]
	s_barrier
	s_setprio 0
	s_add_i32 s35, s35, 2
	s_add_u32 s40, s40, 0x100
	s_addc_u32 s41, s41, 0
	s_add_u32 s21, s21, 0x100
	s_addc_u32 s23, s23, 0
	s_cmp_gt_u32 s35, 29
	s_cbranch_scc1 .Lmy_peel_11_exit
.LBB0_3058:
	ds_read_b128 v[156:159], v152
	ds_read_b128 v[160:163], v152 offset:1024
	ds_read_b128 v[164:167], v152 offset:2048
	ds_read_b128 v[168:171], v152 offset:3072
	ds_read_b128 v[172:175], v153
	ds_read_b128 v[176:179], v153 offset:1024
	ds_read_b128 v[180:183], v153 offset:2048
	ds_read_b128 v[190:193], v153 offset:3072
	s_add_u32 s42, s40, 0xfff80080
	s_addc_u32 s43, s41, -1
	s_cmp_eq_u32 s35, 28
	s_cselect_b32 s45, s4, s43
	s_cselect_b32 s44, s5, s42
	s_cselect_b32 s43, s12, s23
	s_cselect_b32 s42, s13, s21
	v_lshl_add_u64 v[226:227], s[40:41], 0, v[142:143]
	s_add_i32 m0, s8, 0xc000
	ds_read_b128 v[194:197], v154
	ds_read_b128 v[198:201], v154 offset:1024
	ds_read_b128 v[202:205], v154 offset:2048
	ds_read_b128 v[206:209], v154 offset:3072
	ds_read_b128 v[210:213], v154 offset:4096
	ds_read_b128 v[214:217], v154 offset:5120
	ds_read_b128 v[218:221], v154 offset:6144
	ds_read_b128 v[222:225], v154 offset:7168
	global_load_lds_dwordx4 v[226:227], off
	v_lshl_add_u64 v[226:227], s[40:41], 0, v[144:145]
	s_add_i32 m0, s8, 0xe000
	s_nop 0
	global_load_lds_dwordx4 v[226:227], off
	s_waitcnt vmcnt(8)
	s_waitcnt lgkmcnt(0)
	s_setprio 1
	s_barrier
; #define PG8_STAGE(bufoff, gbase, voff) do { _Pragma("unroll") for (int _i = 0; _i < 2; ++_i) \
;         __builtin_amdgcn_global_load_lds((const unsigned*)((const char*)(gbase) + (voff)[_i]), (PG8_LAS unsigned*)(lds + (bufoff) + ldsw + _i * 8192), 16, 0, 0); } while (0)
; #define PG8_LDA(dst, b, h) do { _Pragma("unroll") for (int m = 0; m < 4; ++m) _Pragma("unroll") for (int k = 0; k < 2; ++k) dst[m][k] = *(const PG8_LAS bf16x8*)(lds + PG8_SA(b, h) + aoff + m * 2048 + k * 1024); } while (0)
; #define PG8_MMA(ai, bj, At, Bt) do { __builtin_amdgcn_s_setprio(1); _Pragma("unroll") for (int m = 0; m < 4; ++m) _Pragma("unroll") for (int n = 0; n < 2; ++n) _Pragma("unroll") for (int k = 0; k < 2; ++k) \
;         acc[ai][bj][m][n] = __builtin_amdgcn_mfma_f32_16x16x32_bf16(Bt[n][k], At[m][k], acc[ai][bj][m][n], 0, 0, 0); __builtin_amdgcn_s_setprio(0); } while (0)
; #define PG8_WAIT_V(n) asm volatile("s_waitcnt vmcnt(" #n ")" ::: "memory")
; #define PG8_WAIT_L(n) asm volatile("s_waitcnt lgkmcnt(" #n ")" ::: "memory")
; #define PG8_BAR __builtin_amdgcn_s_barrier()
; #define PG8_SCHED __builtin_amdgcn_sched_barrier(0)
; template <class Epi, class Sched, bool ALIGN_EPI = false, bool SP2 = false>
; __device__ __forceinline__ void gemm_phase(PG8_LAS unsigned char* lds, const Gemm g, const Sched& S, const Epi& E) {
;     ...
;             PG8_WAIT_V(8); PG8_WAIT_L(0); PG8_BAR; PG8_MMA(0, 0, At, B0); PG8_MMA(0, 1, At, B1); PG8_BAR; PG8_SCHED;
;             PG8_LDA(At, 0, 1); PG8_STAGE(PG8_SB(0, 0), b2, voffB); PG8_STAGE(PG8_SB(0, 1), b2 + hstepB, voffB); PG8_STAGE(PG8_SA(0, 0), a2, voffA);
;             PG8_WAIT_V(8); PG8_WAIT_L(0); PG8_BAR; PG8_MMA(1, 0, At, B0); PG8_MMA(1, 1, At, B1); PG8_BAR; PG8_SCHED;
	v_mfma_f32_16x16x32_bf16 v[124:127], v[156:159], v[194:197], v[124:127]
	v_mfma_f32_16x16x32_bf16 v[120:123], v[164:167], v[194:197], v[120:123]
	v_mfma_f32_16x16x32_bf16 v[104:107], v[164:167], v[202:205], v[104:107]
	v_mfma_f32_16x16x32_bf16 v[108:111], v[156:159], v[202:205], v[108:111]
	v_mfma_f32_16x16x32_bf16 v[92:95], v[156:159], v[210:213], v[92:95]
	v_mfma_f32_16x16x32_bf16 v[88:91], v[164:167], v[210:213], v[88:91]
	v_mfma_f32_16x16x32_bf16 v[72:75], v[164:167], v[218:221], v[72:75]
	v_mfma_f32_16x16x32_bf16 v[76:79], v[156:159], v[218:221], v[76:79]
	v_mfma_f32_16x16x32_bf16 v[124:127], v[160:163], v[198:201], v[124:127]
	v_mfma_f32_16x16x32_bf16 v[120:123], v[168:171], v[198:201], v[120:123]
	v_mfma_f32_16x16x32_bf16 v[104:107], v[168:171], v[206:209], v[104:107]
	v_mfma_f32_16x16x32_bf16 v[108:111], v[160:163], v[206:209], v[108:111]
	v_mfma_f32_16x16x32_bf16 v[92:95], v[160:163], v[214:217], v[92:95]
	v_mfma_f32_16x16x32_bf16 v[88:91], v[168:171], v[214:217], v[88:91]
	v_mfma_f32_16x16x32_bf16 v[72:75], v[168:171], v[222:225], v[72:75]
	v_mfma_f32_16x16x32_bf16 v[76:79], v[160:163], v[222:225], v[76:79]
	s_setprio 0
	s_setprio 1
	v_mfma_f32_16x16x32_bf16 v[116:119], v[172:175], v[194:197], v[116:119]
	v_mfma_f32_16x16x32_bf16 v[112:115], v[180:183], v[194:197], v[112:115]
	v_mfma_f32_16x16x32_bf16 v[96:99], v[180:183], v[202:205], v[96:99]
	v_mfma_f32_16x16x32_bf16 v[100:103], v[172:175], v[202:205], v[100:103]
	v_mfma_f32_16x16x32_bf16 v[84:87], v[172:175], v[210:213], v[84:87]
	v_mfma_f32_16x16x32_bf16 v[80:83], v[180:183], v[210:213], v[80:83]
	v_mfma_f32_16x16x32_bf16 v[64:67], v[180:183], v[218:221], v[64:67]
	v_mfma_f32_16x16x32_bf16 v[68:71], v[172:175], v[218:221], v[68:71]
	v_mfma_f32_16x16x32_bf16 v[116:119], v[176:179], v[198:201], v[116:119]
	v_mfma_f32_16x16x32_bf16 v[112:115], v[190:193], v[198:201], v[112:115]
	v_mfma_f32_16x16x32_bf16 v[96:99], v[190:193], v[206:209], v[96:99]
	v_mfma_f32_16x16x32_bf16 v[100:103], v[176:179], v[206:209], v[100:103]
	v_mfma_f32_16x16x32_bf16 v[84:87], v[176:179], v[214:217], v[84:87]
	v_mfma_f32_16x16x32_bf16 v[80:83], v[190:193], v[214:217], v[80:83]
	v_mfma_f32_16x16x32_bf16 v[64:67], v[190:193], v[222:225], v[64:67]
	v_mfma_f32_16x16x32_bf16 v[68:71], v[176:179], v[222:225], v[68:71]
	s_barrier
	s_setprio 0
	s_add_i32 s53, s50, s7
	v_lshl_add_u64 v[226:227], s[42:43], 0, v[130:131]
	s_mov_b32 m0, s53
	ds_read_b128 v[194:197], v154 offset:16384
	ds_read_b128 v[198:201], v154 offset:17408
	ds_read_b128 v[202:205], v154 offset:18432
	ds_read_b128 v[206:209], v154 offset:19456
	ds_read_b128 v[210:213], v154 offset:20480
	ds_read_b128 v[214:217], v154 offset:21504
	ds_read_b128 v[218:221], v154 offset:22528
	ds_read_b128 v[222:225], v154 offset:23552
	global_load_lds_dwordx4 v[226:227], off
	s_add_i32 m0, s53, 0x2000
	s_add_u32 s54, s42, 0x80000
	v_lshl_add_u64 v[228:229], s[42:43], 0, v[134:135]
	s_addc_u32 s55, s43, 0
	s_add_i32 s53, s51, s7
	global_load_lds_dwordx4 v[228:229], off
	v_lshl_add_u64 v[230:231], s[54:55], 0, v[130:131]
	s_mov_b32 m0, s53
	v_lshl_add_u64 v[232:233], s[44:45], 0, v[132:133]
	global_load_lds_dwordx4 v[230:231], off
	v_lshl_add_u64 v[230:231], s[54:55], 0, v[134:135]
	s_add_i32 m0, s53, 0x2000
	s_nop 0
	global_load_lds_dwordx4 v[230:231], off
	v_lshl_add_u64 v[230:231], s[44:45], 0, v[128:129]
	s_mov_b32 m0, s8
	s_nop 0
	global_load_lds_dwordx4 v[230:231], off
	s_mov_b32 m0, s9
	s_nop 0
	global_load_lds_dwordx4 v[232:233], off
	s_waitcnt vmcnt(8)
	s_waitcnt lgkmcnt(0)
	s_setprio 1
	s_barrier
	v_mfma_f32_16x16x32_bf16 v[60:63], v[156:159], v[194:197], v[60:63]
	v_mfma_f32_16x16x32_bf16 v[56:59], v[164:167], v[194:197], v[56:59]
	v_mfma_f32_16x16x32_bf16 v[40:43], v[164:167], v[202:205], v[40:43]
	v_mfma_f32_16x16x32_bf16 v[44:47], v[156:159], v[202:205], v[44:47]
	v_mfma_f32_16x16x32_bf16 v[28:31], v[156:159], v[210:213], v[28:31]
	v_mfma_f32_16x16x32_bf16 v[24:27], v[164:167], v[210:213], v[24:27]
	v_mfma_f32_16x16x32_bf16 v[8:11], v[164:167], v[218:221], v[8:11]
	v_mfma_f32_16x16x32_bf16 v[12:15], v[156:159], v[218:221], v[12:15]
	v_mfma_f32_16x16x32_bf16 v[60:63], v[160:163], v[198:201], v[60:63]
	v_mfma_f32_16x16x32_bf16 v[56:59], v[168:171], v[198:201], v[56:59]
	v_mfma_f32_16x16x32_bf16 v[40:43], v[168:171], v[206:209], v[40:43]
	v_mfma_f32_16x16x32_bf16 v[44:47], v[160:163], v[206:209], v[44:47]
	v_mfma_f32_16x16x32_bf16 v[28:31], v[160:163], v[214:217], v[28:31]
	v_mfma_f32_16x16x32_bf16 v[24:27], v[168:171], v[214:217], v[24:27]
	v_mfma_f32_16x16x32_bf16 v[8:11], v[168:171], v[222:225], v[8:11]
	v_mfma_f32_16x16x32_bf16 v[12:15], v[160:163], v[222:225], v[12:15]
	s_setprio 0
	s_setprio 1
	v_mfma_f32_16x16x32_bf16 v[52:55], v[172:175], v[194:197], v[52:55]
	v_mfma_f32_16x16x32_bf16 v[48:51], v[180:183], v[194:197], v[48:51]
	v_mfma_f32_16x16x32_bf16 v[32:35], v[180:183], v[202:205], v[32:35]
	v_mfma_f32_16x16x32_bf16 v[36:39], v[172:175], v[202:205], v[36:39]
	v_mfma_f32_16x16x32_bf16 v[20:23], v[172:175], v[210:213], v[20:23]
	v_mfma_f32_16x16x32_bf16 v[16:19], v[180:183], v[210:213], v[16:19]
	v_mfma_f32_16x16x32_bf16 v[0:3], v[180:183], v[218:221], v[0:3]
	v_mfma_f32_16x16x32_bf16 v[4:7], v[172:175], v[218:221], v[4:7]
	v_mfma_f32_16x16x32_bf16 v[52:55], v[176:179], v[198:201], v[52:55]
	v_mfma_f32_16x16x32_bf16 v[48:51], v[190:193], v[198:201], v[48:51]
	v_mfma_f32_16x16x32_bf16 v[32:35], v[190:193], v[206:209], v[32:35]
	v_mfma_f32_16x16x32_bf16 v[36:39], v[176:179], v[206:209], v[36:39]
	v_mfma_f32_16x16x32_bf16 v[20:23], v[176:179], v[214:217], v[20:23]
	v_mfma_f32_16x16x32_bf16 v[16:19], v[190:193], v[214:217], v[16:19]
	v_mfma_f32_16x16x32_bf16 v[0:3], v[190:193], v[222:225], v[0:3]
	v_mfma_f32_16x16x32_bf16 v[4:7], v[176:179], v[222:225], v[4:7]
	s_barrier
; #define PG8_STAGE(bufoff, gbase, voff) do { _Pragma("unroll") for (int _i = 0; _i < 2; ++_i) \
;         __builtin_amdgcn_global_load_lds((const unsigned*)((const char*)(gbase) + (voff)[_i]), (PG8_LAS unsigned*)(lds + (bufoff) + ldsw + _i * 8192), 16, 0, 0); } while (0)
; #define PG8_LDA(dst, b, h) do { _Pragma("unroll") for (int m = 0; m < 4; ++m) _Pragma("unroll") for (int k = 0; k < 2; ++k) dst[m][k] = *(const PG8_LAS bf16x8*)(lds + PG8_SA(b, h) + aoff + m * 2048 + k * 1024); } while (0)
; #define PG8_LDB(dst, b, h) do { _Pragma("unroll") for (int n = 0; n < 2; ++n) _Pragma("unroll") for (int k = 0; k < 2; ++k) dst[n][k] = *(const PG8_LAS bf16x8*)(lds + PG8_SB(b, h) + boff + n * 2048 + k * 1024); } while (0)
; #define PG8_MMA(ai, bj, At, Bt) do { __builtin_amdgcn_s_setprio(1); _Pragma("unroll") for (int m = 0; m < 4; ++m) _Pragma("unroll") for (int n = 0; n < 2; ++n) _Pragma("unroll") for (int k = 0; k < 2; ++k) \
;         acc[ai][bj][m][n] = __builtin_amdgcn_mfma_f32_16x16x32_bf16(Bt[n][k], At[m][k], acc[ai][bj][m][n], 0, 0, 0); __builtin_amdgcn_s_setprio(0); } while (0)
; #define PG8_WAIT_V(n) asm volatile("s_waitcnt vmcnt(" #n ")" ::: "memory")
; #define PG8_WAIT_L(n) asm volatile("s_waitcnt lgkmcnt(" #n ")" ::: "memory")
; #define PG8_BAR __builtin_amdgcn_s_barrier()
; #define PG8_SCHED __builtin_amdgcn_sched_barrier(0)
; template <class Epi, class Sched, bool ALIGN_EPI = false, bool SP2 = false>
; __device__ __forceinline__ void gemm_phase(PG8_LAS unsigned char* lds, const Gemm g, const Sched& S, const Epi& E) {
;     ...
;             PG8_LDB(B0, 1, 0); PG8_LDB(B1, 1, 1); PG8_SCHED; PG8_LDA(At, 1, 0); PG8_STAGE(PG8_SA(0, 1), a2 + hstepA, voffA);
;             PG8_WAIT_V(8); PG8_WAIT_L(0); PG8_BAR; PG8_MMA(0, 0, At, B0); PG8_MMA(0, 1, At, B1); PG8_BAR; PG8_SCHED;
	s_setprio 0
	s_add_i32 s53, 0, 0x18000
	v_add_u32_e32 v155, s53, v150
	s_add_i32 s54, 0, 0x1c000
	ds_read_b128 v[156:159], v155
	ds_read_b128 v[160:163], v155 offset:1024
	ds_read_b128 v[164:167], v155 offset:2048
	ds_read_b128 v[168:171], v155 offset:3072
	v_add_u32_e32 v155, s54, v150
	ds_read_b128 v[172:175], v155
	ds_read_b128 v[176:179], v155 offset:1024
	ds_read_b128 v[180:183], v155 offset:2048
	ds_read_b128 v[190:193], v155 offset:3072
	s_add_u32 s44, s44, 0x80000
	s_addc_u32 s45, s45, 0
	s_mov_b32 m0, s10
	v_lshl_add_u64 v[234:235], s[44:45], 0, v[128:129]
	ds_read_b128 v[194:197], v154 offset:32768
	ds_read_b128 v[198:201], v154 offset:33792
	ds_read_b128 v[202:205], v154 offset:34816
	ds_read_b128 v[206:209], v154 offset:35840
	ds_read_b128 v[210:213], v154 offset:36864
	ds_read_b128 v[214:217], v154 offset:37888
	ds_read_b128 v[218:221], v154 offset:38912
	ds_read_b128 v[222:225], v154 offset:39936
	global_load_lds_dwordx4 v[234:235], off
	v_lshl_add_u64 v[234:235], s[44:45], 0, v[132:133]
	s_mov_b32 m0, s11
	s_nop 0
	global_load_lds_dwordx4 v[234:235], off
	s_waitcnt vmcnt(8)
	s_waitcnt lgkmcnt(0)
	s_setprio 1
	s_barrier
	v_mfma_f32_16x16x32_bf16 v[124:127], v[156:159], v[194:197], v[124:127]
	v_mfma_f32_16x16x32_bf16 v[120:123], v[164:167], v[194:197], v[120:123]
	v_mfma_f32_16x16x32_bf16 v[104:107], v[164:167], v[202:205], v[104:107]
	v_mfma_f32_16x16x32_bf16 v[108:111], v[156:159], v[202:205], v[108:111]
	v_mfma_f32_16x16x32_bf16 v[92:95], v[156:159], v[210:213], v[92:95]
	v_mfma_f32_16x16x32_bf16 v[88:91], v[164:167], v[210:213], v[88:91]
	v_mfma_f32_16x16x32_bf16 v[72:75], v[164:167], v[218:221], v[72:75]
	v_mfma_f32_16x16x32_bf16 v[76:79], v[156:159], v[218:221], v[76:79]
	v_mfma_f32_16x16x32_bf16 v[124:127], v[160:163], v[198:201], v[124:127]
	v_mfma_f32_16x16x32_bf16 v[120:123], v[168:171], v[198:201], v[120:123]
	v_mfma_f32_16x16x32_bf16 v[104:107], v[168:171], v[206:209], v[104:107]
	v_mfma_f32_16x16x32_bf16 v[108:111], v[160:163], v[206:209], v[108:111]
	v_mfma_f32_16x16x32_bf16 v[92:95], v[160:163], v[214:217], v[92:95]
	v_mfma_f32_16x16x32_bf16 v[88:91], v[168:171], v[214:217], v[88:91]
	v_mfma_f32_16x16x32_bf16 v[72:75], v[168:171], v[222:225], v[72:75]
	v_mfma_f32_16x16x32_bf16 v[76:79], v[160:163], v[222:225], v[76:79]
	s_setprio 0
	s_setprio 1
	v_mfma_f32_16x16x32_bf16 v[116:119], v[172:175], v[194:197], v[116:119]
	v_mfma_f32_16x16x32_bf16 v[112:115], v[180:183], v[194:197], v[112:115]
	v_mfma_f32_16x16x32_bf16 v[96:99], v[180:183], v[202:205], v[96:99]
	v_mfma_f32_16x16x32_bf16 v[100:103], v[172:175], v[202:205], v[100:103]
	v_mfma_f32_16x16x32_bf16 v[84:87], v[172:175], v[210:213], v[84:87]
	v_mfma_f32_16x16x32_bf16 v[80:83], v[180:183], v[210:213], v[80:83]
	v_mfma_f32_16x16x32_bf16 v[64:67], v[180:183], v[218:221], v[64:67]
	v_mfma_f32_16x16x32_bf16 v[68:71], v[172:175], v[218:221], v[68:71]
	v_mfma_f32_16x16x32_bf16 v[116:119], v[176:179], v[198:201], v[116:119]
	v_mfma_f32_16x16x32_bf16 v[112:115], v[190:193], v[198:201], v[112:115]
	v_mfma_f32_16x16x32_bf16 v[96:99], v[190:193], v[206:209], v[96:99]
	v_mfma_f32_16x16x32_bf16 v[100:103], v[176:179], v[206:209], v[100:103]
	v_mfma_f32_16x16x32_bf16 v[84:87], v[176:179], v[214:217], v[84:87]
	v_mfma_f32_16x16x32_bf16 v[80:83], v[190:193], v[214:217], v[80:83]
	v_mfma_f32_16x16x32_bf16 v[64:67], v[190:193], v[222:225], v[64:67]
	v_mfma_f32_16x16x32_bf16 v[68:71], v[176:179], v[222:225], v[68:71]
	s_barrier
; #define PG8_STAGE(bufoff, gbase, voff) do { _Pragma("unroll") for (int _i = 0; _i < 2; ++_i) \
;         __builtin_amdgcn_global_load_lds((const unsigned*)((const char*)(gbase) + (voff)[_i]), (PG8_LAS unsigned*)(lds + (bufoff) + ldsw + _i * 8192), 16, 0, 0); } while (0)
; #define PG8_LDA(dst, b, h) do { _Pragma("unroll") for (int m = 0; m < 4; ++m) _Pragma("unroll") for (int k = 0; k < 2; ++k) dst[m][k] = *(const PG8_LAS bf16x8*)(lds + PG8_SA(b, h) + aoff + m * 2048 + k * 1024); } while (0)
; #define PG8_MMA(ai, bj, At, Bt) do { __builtin_amdgcn_s_setprio(1); _Pragma("unroll") for (int m = 0; m < 4; ++m) _Pragma("unroll") for (int n = 0; n < 2; ++n) _Pragma("unroll") for (int k = 0; k < 2; ++k) \
;         acc[ai][bj][m][n] = __builtin_amdgcn_mfma_f32_16x16x32_bf16(Bt[n][k], At[m][k], acc[ai][bj][m][n], 0, 0, 0); __builtin_amdgcn_s_setprio(0); } while (0)
; #define PG8_WAIT_V(n) asm volatile("s_waitcnt vmcnt(" #n ")" ::: "memory")
; #define PG8_WAIT_L(n) asm volatile("s_waitcnt lgkmcnt(" #n ")" ::: "memory")
; #define PG8_BAR __builtin_amdgcn_s_barrier()
; #define PG8_SCHED __builtin_amdgcn_sched_barrier(0)
; template <class Epi, class Sched, bool ALIGN_EPI = false, bool SP2 = false>
; __device__ __forceinline__ void gemm_phase(PG8_LAS unsigned char* lds, const Gemm g, const Sched& S, const Epi& E) {
;     ...
;             PG8_LDA(At, 1, 1); PG8_STAGE(PG8_SB(1, 0), b3, voffB); PG8_STAGE(PG8_SB(1, 1), b3 + hstepB, voffB); PG8_STAGE(PG8_SA(1, 0), a3, voffA);
;             PG8_WAIT_V(8); PG8_WAIT_L(0); PG8_BAR; PG8_MMA(1, 0, At, B0); PG8_MMA(1, 1, At, B1); PG8_BAR; PG8_SCHED;
	s_setprio 0
	s_add_i32 s44, s53, s7
	v_lshl_add_u64 v[226:227], v[226:227], 0, s[16:17]
	s_mov_b32 m0, s44
	ds_read_b128 v[194:197], v154 offset:49152
	ds_read_b128 v[198:201], v154 offset:50176
	ds_read_b128 v[202:205], v154 offset:51200
	ds_read_b128 v[206:209], v154 offset:52224
	ds_read_b128 v[210:213], v154 offset:53248
	ds_read_b128 v[214:217], v154 offset:54272
	ds_read_b128 v[218:221], v154 offset:55296
	ds_read_b128 v[222:225], v154 offset:56320
	global_load_lds_dwordx4 v[226:227], off
	s_add_i32 m0, s44, 0x2000
	s_add_u32 s42, s42, 0x80080
	v_lshl_add_u64 v[226:227], v[228:229], 0, s[16:17]
	s_addc_u32 s43, s43, 0
	s_add_i32 s44, s54, s7
	global_load_lds_dwordx4 v[226:227], off
	v_lshl_add_u64 v[226:227], s[42:43], 0, v[130:131]
	s_mov_b32 m0, s44
	s_nop 0
	global_load_lds_dwordx4 v[226:227], off
	v_lshl_add_u64 v[226:227], s[42:43], 0, v[134:135]
	s_add_i32 m0, s44, 0x2000
	s_nop 0
	global_load_lds_dwordx4 v[226:227], off
	v_lshl_add_u64 v[226:227], v[230:231], 0, s[16:17]
	s_mov_b32 m0, s48
	s_nop 0
	global_load_lds_dwordx4 v[226:227], off
	v_lshl_add_u64 v[226:227], v[232:233], 0, s[16:17]
	s_mov_b32 m0, s49
	s_nop 0
	global_load_lds_dwordx4 v[226:227], off
	s_waitcnt vmcnt(8)
	s_waitcnt lgkmcnt(0)
	s_setprio 1
	s_barrier
	v_mfma_f32_16x16x32_bf16 v[60:63], v[156:159], v[194:197], v[60:63]
	v_mfma_f32_16x16x32_bf16 v[56:59], v[164:167], v[194:197], v[56:59]
	v_mfma_f32_16x16x32_bf16 v[40:43], v[164:167], v[202:205], v[40:43]
	v_mfma_f32_16x16x32_bf16 v[44:47], v[156:159], v[202:205], v[44:47]
	v_mfma_f32_16x16x32_bf16 v[28:31], v[156:159], v[210:213], v[28:31]
	v_mfma_f32_16x16x32_bf16 v[24:27], v[164:167], v[210:213], v[24:27]
	v_mfma_f32_16x16x32_bf16 v[8:11], v[164:167], v[218:221], v[8:11]
	v_mfma_f32_16x16x32_bf16 v[12:15], v[156:159], v[218:221], v[12:15]
	v_mfma_f32_16x16x32_bf16 v[60:63], v[160:163], v[198:201], v[60:63]
	v_mfma_f32_16x16x32_bf16 v[56:59], v[168:171], v[198:201], v[56:59]
	v_mfma_f32_16x16x32_bf16 v[40:43], v[168:171], v[206:209], v[40:43]
	v_mfma_f32_16x16x32_bf16 v[44:47], v[160:163], v[206:209], v[44:47]
	v_mfma_f32_16x16x32_bf16 v[28:31], v[160:163], v[214:217], v[28:31]
	v_mfma_f32_16x16x32_bf16 v[24:27], v[168:171], v[214:217], v[24:27]
	v_mfma_f32_16x16x32_bf16 v[8:11], v[168:171], v[222:225], v[8:11]
	v_mfma_f32_16x16x32_bf16 v[12:15], v[160:163], v[222:225], v[12:15]
	s_setprio 0
	s_setprio 1
	v_mfma_f32_16x16x32_bf16 v[52:55], v[172:175], v[194:197], v[52:55]
	v_mfma_f32_16x16x32_bf16 v[48:51], v[180:183], v[194:197], v[48:51]
	v_mfma_f32_16x16x32_bf16 v[32:35], v[180:183], v[202:205], v[32:35]
	v_mfma_f32_16x16x32_bf16 v[36:39], v[172:175], v[202:205], v[36:39]
	v_mfma_f32_16x16x32_bf16 v[20:23], v[172:175], v[210:213], v[20:23]
	v_mfma_f32_16x16x32_bf16 v[16:19], v[180:183], v[210:213], v[16:19]
	v_mfma_f32_16x16x32_bf16 v[0:3], v[180:183], v[218:221], v[0:3]
	v_mfma_f32_16x16x32_bf16 v[4:7], v[172:175], v[218:221], v[4:7]
	v_mfma_f32_16x16x32_bf16 v[52:55], v[176:179], v[198:201], v[52:55]
	v_mfma_f32_16x16x32_bf16 v[48:51], v[190:193], v[198:201], v[48:51]
	v_mfma_f32_16x16x32_bf16 v[32:35], v[190:193], v[206:209], v[32:35]
	v_mfma_f32_16x16x32_bf16 v[36:39], v[176:179], v[206:209], v[36:39]
	v_mfma_f32_16x16x32_bf16 v[20:23], v[176:179], v[214:217], v[20:23]
	v_mfma_f32_16x16x32_bf16 v[16:19], v[190:193], v[214:217], v[16:19]
	v_mfma_f32_16x16x32_bf16 v[0:3], v[190:193], v[222:225], v[0:3]
	v_mfma_f32_16x16x32_bf16 v[4:7], v[176:179], v[222:225], v[4:7]
	s_barrier
	s_setprio 0
	s_add_i32 s35, s35, 2
	s_add_u32 s40, s40, 0x100
	s_addc_u32 s41, s41, 0
	s_add_u32 s21, s21, 0x100
	s_addc_u32 s23, s23, 0
	s_cmp_gt_u32 s35, 29
	s_cbranch_scc0 .LBB0_3058

; #define PG8_STAGE(bufoff, gbase, voff) do { _Pragma("unroll") for (int _i = 0; _i < 2; ++_i) \
;         __builtin_amdgcn_global_load_lds((const unsigned*)((const char*)(gbase) + (voff)[_i]), (PG8_LAS unsigned*)(lds + (bufoff) + ldsw + _i * 8192), 16, 0, 0); } while (0)
; #define PG8_LDA(dst, b, h) do { _Pragma("unroll") for (int m = 0; m < 4; ++m) _Pragma("unroll") for (int k = 0; k < 2; ++k) dst[m][k] = *(const PG8_LAS bf16x8*)(lds + PG8_SA(b, h) + aoff + m * 2048 + k * 1024); } while (0)
; #define PG8_LDB(dst, b, h) do { _Pragma("unroll") for (int n = 0; n < 2; ++n) _Pragma("unroll") for (int k = 0; k < 2; ++k) dst[n][k] = *(const PG8_LAS bf16x8*)(lds + PG8_SB(b, h) + boff + n * 2048 + k * 1024); } while (0)
; #define PG8_MMA(ai, bj, At, Bt) do { __builtin_amdgcn_s_setprio(1); _Pragma("unroll") for (int m = 0; m < 4; ++m) _Pragma("unroll") for (int n = 0; n < 2; ++n) _Pragma("unroll") for (int k = 0; k < 2; ++k) \
;         acc[ai][bj][m][n] = __builtin_amdgcn_mfma_f32_16x16x32_bf16(Bt[n][k], At[m][k], acc[ai][bj][m][n], 0, 0, 0); __builtin_amdgcn_s_setprio(0); } while (0)
; #define PG8_WAIT_V(n) asm volatile("s_waitcnt vmcnt(" #n ")" ::: "memory")
; #define PG8_WAIT_L(n) asm volatile("s_waitcnt lgkmcnt(" #n ")" ::: "memory")
; #define PG8_BAR __builtin_amdgcn_s_barrier()
; template <class Epi, class Sched, bool ALIGN_EPI = false, bool SP2 = false>
; __device__ __forceinline__ void gemm_phase(PG8_LAS unsigned char* lds, const Gemm g, const Sched& S, const Epi& E) {
;     ...
;             const char* a1 = cA + (size_t)(t + 1) * kstA;
;             const char* a2 = last ? nA : cA + (size_t)(t + 2) * kstA; const char* b2 = last ? nB : cB + (size_t)(t + 2) * kstep;
;             const char* a3 = a2 + kstA; const char* b3 = b2 + kstep;
;             if (last && has_next) S.a_ready(nxt);
;             if constexpr (SP2) {
;             PG8_LDB(B0, 0, 0); PG8_LDB(B1, 0, 1); PG8_SCHED; PG8_LDA(At, 0, 0); PG8_STAGE(PG8_SA(1, 1), a1 + hstepA, voffA);
;             PG8_WAIT_V(8); PG8_WAIT_L(0); PG8_BAR; PG8_MMA(0, 0, At, B0); PG8_MMA(0, 1, At, B1); PG8_BAR; PG8_SCHED;
;             PG8_LDA(At, 0, 1); PG8_STAGE(PG8_SB(0, 0), b2, voffB); PG8_STAGE(PG8_SB(0, 1), b2 + hstepB, voffB); PG8_STAGE(PG8_SA(0, 0), a2, voffA);
;             PG8_WAIT_V(8); PG8_WAIT_L(0); PG8_BAR; PG8_MMA(1, 0, At, B0); PG8_MMA(1, 1, At, B1); PG8_BAR; PG8_SCHED;
.LBB0_3147:
	v_add_u32_e32 v176, s64, v178
	ds_read_b128 v[164:167], v176
	ds_read_b128 v[168:171], v176 offset:1024
	ds_read_b128 v[172:175], v176 offset:2048
	ds_read_b128 v[190:193], v176 offset:3072
	v_add_u32_e32 v176, s65, v178
	ds_read_b128 v[194:197], v176
	ds_read_b128 v[198:201], v176 offset:1024
	ds_read_b128 v[202:205], v176 offset:2048
	ds_read_b128 v[206:209], v176 offset:3072
	s_add_u32 s12, s20, s46
	s_addc_u32 s13, s21, s47
	s_cmp_eq_u32 s7, s5
	s_cselect_b32 s52, s42, s12
	s_cselect_b32 s53, s43, s13
	s_cselect_b32 s51, s45, s4
	s_cselect_b32 s50, s44, s1
	s_add_u32 s48, s52, 0x8000
	s_addc_u32 s49, s53, 0
	v_lshl_add_u64 v[176:177], s[20:21], 0, v[162:163]
	s_add_i32 m0, s55, 0xc000
	ds_read_b128 v[210:213], v180
	ds_read_b128 v[214:217], v180 offset:1024
	ds_read_b128 v[218:221], v180 offset:2048
	ds_read_b128 v[222:225], v180 offset:3072
	ds_read_b128 v[226:229], v180 offset:4096
	ds_read_b128 v[230:233], v180 offset:5120
	ds_read_b128 v[234:237], v180 offset:6144
	ds_read_b128 v[238:241], v180 offset:7168
	global_load_lds_dwordx4 v[176:177], off
	v_lshl_add_u64 v[176:177], s[20:21], 0, v[160:161]
	s_add_i32 m0, s55, 0xe000
	s_nop 0
	global_load_lds_dwordx4 v[176:177], off
	s_waitcnt vmcnt(8)
	s_waitcnt lgkmcnt(0)
	s_setprio 1
	s_barrier
	v_mfma_f32_16x16x32_bf16 v[124:127], v[164:167], v[210:213], v[124:127]
	v_mfma_f32_16x16x32_bf16 v[120:123], v[172:175], v[210:213], v[120:123]
	v_mfma_f32_16x16x32_bf16 v[112:115], v[172:175], v[218:221], v[112:115]
	v_mfma_f32_16x16x32_bf16 v[116:119], v[164:167], v[218:221], v[116:119]
	v_mfma_f32_16x16x32_bf16 v[108:111], v[164:167], v[226:229], v[108:111]
	v_mfma_f32_16x16x32_bf16 v[104:107], v[172:175], v[226:229], v[104:107]
	v_mfma_f32_16x16x32_bf16 v[96:99], v[172:175], v[234:237], v[96:99]
	v_mfma_f32_16x16x32_bf16 v[100:103], v[164:167], v[234:237], v[100:103]
	v_mfma_f32_16x16x32_bf16 v[124:127], v[168:171], v[214:217], v[124:127]
	v_mfma_f32_16x16x32_bf16 v[120:123], v[190:193], v[214:217], v[120:123]
	v_mfma_f32_16x16x32_bf16 v[112:115], v[190:193], v[222:225], v[112:115]
	v_mfma_f32_16x16x32_bf16 v[116:119], v[168:171], v[222:225], v[116:119]
	v_mfma_f32_16x16x32_bf16 v[108:111], v[168:171], v[230:233], v[108:111]
	v_mfma_f32_16x16x32_bf16 v[104:107], v[190:193], v[230:233], v[104:107]
	v_mfma_f32_16x16x32_bf16 v[96:99], v[190:193], v[238:241], v[96:99]
	v_mfma_f32_16x16x32_bf16 v[100:103], v[168:171], v[238:241], v[100:103]
	s_setprio 0
	s_setprio 1
	v_mfma_f32_16x16x32_bf16 v[92:95], v[194:197], v[210:213], v[92:95]
	v_mfma_f32_16x16x32_bf16 v[88:91], v[202:205], v[210:213], v[88:91]
	v_mfma_f32_16x16x32_bf16 v[80:83], v[202:205], v[218:221], v[80:83]
	v_mfma_f32_16x16x32_bf16 v[84:87], v[194:197], v[218:221], v[84:87]
	v_mfma_f32_16x16x32_bf16 v[76:79], v[194:197], v[226:229], v[76:79]
	v_mfma_f32_16x16x32_bf16 v[72:75], v[202:205], v[226:229], v[72:75]
	v_mfma_f32_16x16x32_bf16 v[64:67], v[202:205], v[234:237], v[64:67]
	v_mfma_f32_16x16x32_bf16 v[68:71], v[194:197], v[234:237], v[68:71]
	v_mfma_f32_16x16x32_bf16 v[92:95], v[198:201], v[214:217], v[92:95]
	v_mfma_f32_16x16x32_bf16 v[88:91], v[206:209], v[214:217], v[88:91]
	v_mfma_f32_16x16x32_bf16 v[80:83], v[206:209], v[222:225], v[80:83]
	v_mfma_f32_16x16x32_bf16 v[84:87], v[198:201], v[222:225], v[84:87]
	v_mfma_f32_16x16x32_bf16 v[76:79], v[198:201], v[230:233], v[76:79]
	v_mfma_f32_16x16x32_bf16 v[72:75], v[206:209], v[230:233], v[72:75]
	v_mfma_f32_16x16x32_bf16 v[64:67], v[206:209], v[238:241], v[64:67]
	v_mfma_f32_16x16x32_bf16 v[68:71], v[198:201], v[238:241], v[68:71]
	s_barrier
	s_setprio 0
	s_add_i32 s12, s64, s54
	v_lshl_add_u64 v[176:177], s[50:51], 0, v[130:131]
	s_mov_b32 m0, s12
	ds_read_b128 v[210:213], v180 offset:16384
	ds_read_b128 v[214:217], v180 offset:17408
	ds_read_b128 v[218:221], v180 offset:18432
	ds_read_b128 v[222:225], v180 offset:19456
	ds_read_b128 v[226:229], v180 offset:20480
	ds_read_b128 v[230:233], v180 offset:21504
	ds_read_b128 v[234:237], v180 offset:22528
	ds_read_b128 v[238:241], v180 offset:23552
	global_load_lds_dwordx4 v[176:177], off
	s_add_i32 m0, s12, 0x2000
	s_add_u32 s12, s50, 0x160000
	v_lshl_add_u64 v[182:183], s[50:51], 0, v[134:135]
	s_addc_u32 s13, s51, 0
	s_add_i32 s17, s65, s54
	global_load_lds_dwordx4 v[182:183], off
	v_lshl_add_u64 v[242:243], s[12:13], 0, v[130:131]
	s_mov_b32 m0, s17
	s_nop 0
	global_load_lds_dwordx4 v[242:243], off
	v_lshl_add_u64 v[242:243], s[12:13], 0, v[134:135]
	s_add_i32 m0, s17, 0x2000
	s_nop 0
	global_load_lds_dwordx4 v[242:243], off
	v_lshl_add_u64 v[242:243], s[52:53], 0, v[128:129]
	s_mov_b32 m0, s55
	s_nop 0
	global_load_lds_dwordx4 v[242:243], off
	v_lshl_add_u64 v[242:243], s[52:53], 0, v[132:133]
	s_mov_b32 m0, s56
	s_nop 0
	global_load_lds_dwordx4 v[242:243], off
	s_waitcnt vmcnt(8)
	s_waitcnt lgkmcnt(0)
	s_setprio 1
	s_barrier
; #define PG8_STAGE(bufoff, gbase, voff) do { _Pragma("unroll") for (int _i = 0; _i < 2; ++_i) \
;         __builtin_amdgcn_global_load_lds((const unsigned*)((const char*)(gbase) + (voff)[_i]), (PG8_LAS unsigned*)(lds + (bufoff) + ldsw + _i * 8192), 16, 0, 0); } while (0)
; #define PG8_LDA(dst, b, h) do { _Pragma("unroll") for (int m = 0; m < 4; ++m) _Pragma("unroll") for (int k = 0; k < 2; ++k) dst[m][k] = *(const PG8_LAS bf16x8*)(lds + PG8_SA(b, h) + aoff + m * 2048 + k * 1024); } while (0)
; #define PG8_LDB(dst, b, h) do { _Pragma("unroll") for (int n = 0; n < 2; ++n) _Pragma("unroll") for (int k = 0; k < 2; ++k) dst[n][k] = *(const PG8_LAS bf16x8*)(lds + PG8_SB(b, h) + boff + n * 2048 + k * 1024); } while (0)
; #define PG8_MMA(ai, bj, At, Bt) do { __builtin_amdgcn_s_setprio(1); _Pragma("unroll") for (int m = 0; m < 4; ++m) _Pragma("unroll") for (int n = 0; n < 2; ++n) _Pragma("unroll") for (int k = 0; k < 2; ++k) \
;         acc[ai][bj][m][n] = __builtin_amdgcn_mfma_f32_16x16x32_bf16(Bt[n][k], At[m][k], acc[ai][bj][m][n], 0, 0, 0); __builtin_amdgcn_s_setprio(0); } while (0)
; #define PG8_WAIT_V(n) asm volatile("s_waitcnt vmcnt(" #n ")" ::: "memory")
; #define PG8_WAIT_L(n) asm volatile("s_waitcnt lgkmcnt(" #n ")" ::: "memory")
; #define PG8_BAR __builtin_amdgcn_s_barrier()
; #define PG8_SCHED __builtin_amdgcn_sched_barrier(0)
; template <class Epi, class Sched, bool ALIGN_EPI = false, bool SP2 = false>
; __device__ __forceinline__ void gemm_phase(PG8_LAS unsigned char* lds, const Gemm g, const Sched& S, const Epi& E) {
;     ...
;             PG8_WAIT_V(8); PG8_WAIT_L(0); PG8_BAR; PG8_MMA(1, 0, At, B0); PG8_MMA(1, 1, At, B1); PG8_BAR; PG8_SCHED;
;             PG8_LDB(B0, 1, 0); PG8_LDB(B1, 1, 1); PG8_SCHED; PG8_LDA(At, 1, 0); PG8_STAGE(PG8_SA(0, 1), a2 + hstepA, voffA);
;             PG8_WAIT_V(8); PG8_WAIT_L(0); PG8_BAR; PG8_MMA(0, 0, At, B0); PG8_MMA(0, 1, At, B1); PG8_BAR; PG8_SCHED;
	v_mfma_f32_16x16x32_bf16 v[60:63], v[164:167], v[210:213], v[60:63]
	v_mfma_f32_16x16x32_bf16 v[56:59], v[172:175], v[210:213], v[56:59]
	v_mfma_f32_16x16x32_bf16 v[48:51], v[172:175], v[218:221], v[48:51]
	v_mfma_f32_16x16x32_bf16 v[52:55], v[164:167], v[218:221], v[52:55]
	v_mfma_f32_16x16x32_bf16 v[44:47], v[164:167], v[226:229], v[44:47]
	v_mfma_f32_16x16x32_bf16 v[40:43], v[172:175], v[226:229], v[40:43]
	v_mfma_f32_16x16x32_bf16 v[32:35], v[172:175], v[234:237], v[32:35]
	v_mfma_f32_16x16x32_bf16 v[36:39], v[164:167], v[234:237], v[36:39]
	v_mfma_f32_16x16x32_bf16 v[60:63], v[168:171], v[214:217], v[60:63]
	v_mfma_f32_16x16x32_bf16 v[56:59], v[190:193], v[214:217], v[56:59]
	v_mfma_f32_16x16x32_bf16 v[48:51], v[190:193], v[222:225], v[48:51]
	v_mfma_f32_16x16x32_bf16 v[52:55], v[168:171], v[222:225], v[52:55]
	v_mfma_f32_16x16x32_bf16 v[44:47], v[168:171], v[230:233], v[44:47]
	v_mfma_f32_16x16x32_bf16 v[40:43], v[190:193], v[230:233], v[40:43]
	v_mfma_f32_16x16x32_bf16 v[32:35], v[190:193], v[238:241], v[32:35]
	v_mfma_f32_16x16x32_bf16 v[36:39], v[168:171], v[238:241], v[36:39]
	s_setprio 0
	s_setprio 1
	v_mfma_f32_16x16x32_bf16 v[28:31], v[194:197], v[210:213], v[28:31]
	v_mfma_f32_16x16x32_bf16 v[24:27], v[202:205], v[210:213], v[24:27]
	v_mfma_f32_16x16x32_bf16 v[16:19], v[202:205], v[218:221], v[16:19]
	v_mfma_f32_16x16x32_bf16 v[20:23], v[194:197], v[218:221], v[20:23]
	v_mfma_f32_16x16x32_bf16 v[12:15], v[194:197], v[226:229], v[12:15]
	v_mfma_f32_16x16x32_bf16 v[8:11], v[202:205], v[226:229], v[8:11]
	v_mfma_f32_16x16x32_bf16 v[0:3], v[202:205], v[234:237], v[0:3]
	v_mfma_f32_16x16x32_bf16 v[4:7], v[194:197], v[234:237], v[4:7]
	v_mfma_f32_16x16x32_bf16 v[28:31], v[198:201], v[214:217], v[28:31]
	v_mfma_f32_16x16x32_bf16 v[24:27], v[206:209], v[214:217], v[24:27]
	v_mfma_f32_16x16x32_bf16 v[16:19], v[206:209], v[222:225], v[16:19]
	v_mfma_f32_16x16x32_bf16 v[20:23], v[198:201], v[222:225], v[20:23]
	v_mfma_f32_16x16x32_bf16 v[12:15], v[198:201], v[230:233], v[12:15]
	v_mfma_f32_16x16x32_bf16 v[8:11], v[206:209], v[230:233], v[8:11]
	v_mfma_f32_16x16x32_bf16 v[0:3], v[206:209], v[238:241], v[0:3]
	v_mfma_f32_16x16x32_bf16 v[4:7], v[198:201], v[238:241], v[4:7]
	s_barrier
	s_setprio 0
	s_add_i32 s17, 0, 0x18000
	v_add_u32_e32 v181, s17, v178
	s_add_i32 s19, 0, 0x1c000
	ds_read_b128 v[164:167], v181
	ds_read_b128 v[168:171], v181 offset:1024
	ds_read_b128 v[172:175], v181 offset:2048
	ds_read_b128 v[190:193], v181 offset:3072
	v_add_u32_e32 v181, s19, v178
	ds_read_b128 v[194:197], v181
	ds_read_b128 v[198:201], v181 offset:1024
	ds_read_b128 v[202:205], v181 offset:2048
	ds_read_b128 v[206:209], v181 offset:3072
	s_add_u32 s12, s52, 0x4000
	s_addc_u32 s13, s53, 0
	s_mov_b32 m0, s57
	v_lshl_add_u64 v[242:243], s[12:13], 0, v[128:129]
	ds_read_b128 v[210:213], v180 offset:32768
	ds_read_b128 v[214:217], v180 offset:33792
	ds_read_b128 v[218:221], v180 offset:34816
	ds_read_b128 v[222:225], v180 offset:35840
	ds_read_b128 v[226:229], v180 offset:36864
	ds_read_b128 v[230:233], v180 offset:37888
	ds_read_b128 v[234:237], v180 offset:38912
	ds_read_b128 v[238:241], v180 offset:39936
	global_load_lds_dwordx4 v[242:243], off
	v_lshl_add_u64 v[242:243], s[12:13], 0, v[132:133]
	s_mov_b32 m0, s58
	s_nop 0
	global_load_lds_dwordx4 v[242:243], off
	s_waitcnt vmcnt(8)
	s_waitcnt lgkmcnt(0)
	s_setprio 1
	s_barrier
	v_mfma_f32_16x16x32_bf16 v[124:127], v[164:167], v[210:213], v[124:127]
	v_mfma_f32_16x16x32_bf16 v[120:123], v[172:175], v[210:213], v[120:123]
	v_mfma_f32_16x16x32_bf16 v[112:115], v[172:175], v[218:221], v[112:115]
	v_mfma_f32_16x16x32_bf16 v[116:119], v[164:167], v[218:221], v[116:119]
	v_mfma_f32_16x16x32_bf16 v[108:111], v[164:167], v[226:229], v[108:111]
	v_mfma_f32_16x16x32_bf16 v[104:107], v[172:175], v[226:229], v[104:107]
	v_mfma_f32_16x16x32_bf16 v[96:99], v[172:175], v[234:237], v[96:99]
	v_mfma_f32_16x16x32_bf16 v[100:103], v[164:167], v[234:237], v[100:103]
	v_mfma_f32_16x16x32_bf16 v[124:127], v[168:171], v[214:217], v[124:127]
	v_mfma_f32_16x16x32_bf16 v[120:123], v[190:193], v[214:217], v[120:123]
	v_mfma_f32_16x16x32_bf16 v[112:115], v[190:193], v[222:225], v[112:115]
	v_mfma_f32_16x16x32_bf16 v[116:119], v[168:171], v[222:225], v[116:119]
	v_mfma_f32_16x16x32_bf16 v[108:111], v[168:171], v[230:233], v[108:111]
	v_mfma_f32_16x16x32_bf16 v[104:107], v[190:193], v[230:233], v[104:107]
	v_mfma_f32_16x16x32_bf16 v[96:99], v[190:193], v[238:241], v[96:99]
	v_mfma_f32_16x16x32_bf16 v[100:103], v[168:171], v[238:241], v[100:103]
	s_setprio 0
	s_setprio 1
	v_mfma_f32_16x16x32_bf16 v[92:95], v[194:197], v[210:213], v[92:95]
	v_mfma_f32_16x16x32_bf16 v[88:91], v[202:205], v[210:213], v[88:91]
	v_mfma_f32_16x16x32_bf16 v[80:83], v[202:205], v[218:221], v[80:83]
	v_mfma_f32_16x16x32_bf16 v[84:87], v[194:197], v[218:221], v[84:87]
	v_mfma_f32_16x16x32_bf16 v[76:79], v[194:197], v[226:229], v[76:79]
	v_mfma_f32_16x16x32_bf16 v[72:75], v[202:205], v[226:229], v[72:75]
	v_mfma_f32_16x16x32_bf16 v[64:67], v[202:205], v[234:237], v[64:67]
	v_mfma_f32_16x16x32_bf16 v[68:71], v[194:197], v[234:237], v[68:71]
	v_mfma_f32_16x16x32_bf16 v[92:95], v[198:201], v[214:217], v[92:95]
	v_mfma_f32_16x16x32_bf16 v[88:91], v[206:209], v[214:217], v[88:91]
	v_mfma_f32_16x16x32_bf16 v[80:83], v[206:209], v[222:225], v[80:83]
	v_mfma_f32_16x16x32_bf16 v[84:87], v[198:201], v[222:225], v[84:87]
	v_mfma_f32_16x16x32_bf16 v[76:79], v[198:201], v[230:233], v[76:79]
	v_mfma_f32_16x16x32_bf16 v[72:75], v[206:209], v[230:233], v[72:75]
	v_mfma_f32_16x16x32_bf16 v[64:67], v[206:209], v[238:241], v[64:67]
	v_mfma_f32_16x16x32_bf16 v[68:71], v[198:201], v[238:241], v[68:71]
	s_barrier
; #define PG8_STAGE(bufoff, gbase, voff) do { _Pragma("unroll") for (int _i = 0; _i < 2; ++_i) \
;         __builtin_amdgcn_global_load_lds((const unsigned*)((const char*)(gbase) + (voff)[_i]), (PG8_LAS unsigned*)(lds + (bufoff) + ldsw + _i * 8192), 16, 0, 0); } while (0)
; #define PG8_LDA(dst, b, h) do { _Pragma("unroll") for (int m = 0; m < 4; ++m) _Pragma("unroll") for (int k = 0; k < 2; ++k) dst[m][k] = *(const PG8_LAS bf16x8*)(lds + PG8_SA(b, h) + aoff + m * 2048 + k * 1024); } while (0)
; #define PG8_WAIT_V(n) asm volatile("s_waitcnt vmcnt(" #n ")" ::: "memory")
; template <class Epi, class Sched, bool ALIGN_EPI = false, bool SP2 = false>
; __device__ __forceinline__ void gemm_phase(PG8_LAS unsigned char* lds, const Gemm g, const Sched& S, const Epi& E) {
;     ...
;             PG8_LDA(At, 1, 1); PG8_STAGE(PG8_SB(1, 0), b3, voffB); PG8_STAGE(PG8_SB(1, 1), b3 + hstepB, voffB); PG8_STAGE(PG8_SA(1, 0), a3, voffA);
;             PG8_WAIT_V(8); PG8_WAIT_L(0); PG8_BAR; PG8_MMA(1, 0, At, B0); PG8_MMA(1, 1, At, B1); PG8_BAR; PG8_SCHED;
;             } else {
;             PG8_LDB(B0, 0, 0); PG8_SCHED; PG8_LDA(At, 0, 0); PG8_STAGE(PG8_SA(1, 1), a1 + hstepA, voffA);
;             PG8_WAIT_L(8); PG8_BAR; PG8_WAIT_L(0); PG8_MMA(0, 0, At, B0); PG8_BAR; PG8_SCHED;
;             PG8_LDB(B1, 0, 1); PG8_STAGE(PG8_SB(0, 0), b2, voffB);
;             PG8_BAR; PG8_WAIT_L(0); PG8_MMA(0, 1, At, B1); PG8_BAR;
;             PG8_LDA(At, 0, 1); PG8_STAGE(PG8_SA(0, 0), a2, voffA);
;             PG8_BAR; PG8_WAIT_L(0); PG8_MMA(1, 0, At, B0); PG8_BAR; PG8_SCHED;
;             PG8_STAGE(PG8_SB(0, 1), b2 + hstepB, voffB);
;             PG8_WAIT_V(6); PG8_BAR; PG8_MMA(1, 1, At, B1); PG8_BAR;
;             PG8_LDB(B0, 1, 0); PG8_SCHED; PG8_LDA(At, 1, 0); PG8_STAGE(PG8_SA(0, 1), a2 + hstepA, voffA);
;             PG8_WAIT_L(8); PG8_BAR; PG8_WAIT_L(0); PG8_MMA(0, 0, At, B0); PG8_BAR; PG8_SCHED;
;             PG8_LDB(B1, 1, 1); PG8_STAGE(PG8_SB(1, 0), b3, voffB);
;             PG8_BAR; PG8_WAIT_L(0); PG8_MMA(0, 1, At, B1); PG8_BAR;
;             PG8_LDA(At, 1, 1); PG8_STAGE(PG8_SA(1, 0), a3, voffA);
;             PG8_BAR; PG8_WAIT_L(0); PG8_MMA(1, 0, At, B0); PG8_BAR; PG8_SCHED;
;             PG8_STAGE(PG8_SB(1, 1), b3 + hstepB, voffB);
;             PG8_WAIT_V(6); PG8_BAR; PG8_MMA(1, 1, At, B1); PG8_BAR;
;             }
;         }
;         if constexpr (ALIGN_EPI) { if (wr == 0) PG8_BAR; }
	s_setprio 0
	s_add_i32 s12, s17, s54
	v_lshl_add_u64 v[176:177], v[176:177], 0, s[30:31]
	s_mov_b32 m0, s12
	ds_read_b128 v[210:213], v180 offset:49152
	ds_read_b128 v[214:217], v180 offset:50176
	ds_read_b128 v[218:221], v180 offset:51200
	ds_read_b128 v[222:225], v180 offset:52224
	ds_read_b128 v[226:229], v180 offset:53248
	ds_read_b128 v[230:233], v180 offset:54272
	ds_read_b128 v[234:237], v180 offset:55296
	ds_read_b128 v[238:241], v180 offset:56320
	global_load_lds_dwordx4 v[176:177], off
	s_add_i32 m0, s12, 0x2000
	s_add_u32 s12, s50, 0x160080
	v_lshl_add_u64 v[176:177], v[182:183], 0, s[30:31]
	s_addc_u32 s13, s51, 0
	s_add_i32 s17, s19, s54
	global_load_lds_dwordx4 v[176:177], off
	v_lshl_add_u64 v[176:177], s[12:13], 0, v[130:131]
	s_mov_b32 m0, s17
	s_nop 0
	global_load_lds_dwordx4 v[176:177], off
	v_lshl_add_u64 v[176:177], s[12:13], 0, v[134:135]
	s_add_i32 m0, s17, 0x2000
	s_nop 0
	global_load_lds_dwordx4 v[176:177], off
	v_lshl_add_u64 v[176:177], s[48:49], 0, v[128:129]
	s_mov_b32 m0, s62
	s_nop 0
	global_load_lds_dwordx4 v[176:177], off
	v_lshl_add_u64 v[176:177], s[48:49], 0, v[132:133]
	s_mov_b32 m0, s63
	s_nop 0
	global_load_lds_dwordx4 v[176:177], off
	s_waitcnt vmcnt(8)
	s_waitcnt lgkmcnt(0)
	s_setprio 1
	s_barrier
	v_mfma_f32_16x16x32_bf16 v[60:63], v[164:167], v[210:213], v[60:63]
	v_mfma_f32_16x16x32_bf16 v[56:59], v[172:175], v[210:213], v[56:59]
	v_mfma_f32_16x16x32_bf16 v[48:51], v[172:175], v[218:221], v[48:51]
	v_mfma_f32_16x16x32_bf16 v[52:55], v[164:167], v[218:221], v[52:55]
	v_mfma_f32_16x16x32_bf16 v[44:47], v[164:167], v[226:229], v[44:47]
	v_mfma_f32_16x16x32_bf16 v[40:43], v[172:175], v[226:229], v[40:43]
	v_mfma_f32_16x16x32_bf16 v[32:35], v[172:175], v[234:237], v[32:35]
	v_mfma_f32_16x16x32_bf16 v[36:39], v[164:167], v[234:237], v[36:39]
	v_mfma_f32_16x16x32_bf16 v[60:63], v[168:171], v[214:217], v[60:63]
	v_mfma_f32_16x16x32_bf16 v[56:59], v[190:193], v[214:217], v[56:59]
	v_mfma_f32_16x16x32_bf16 v[48:51], v[190:193], v[222:225], v[48:51]
	v_mfma_f32_16x16x32_bf16 v[52:55], v[168:171], v[222:225], v[52:55]
	v_mfma_f32_16x16x32_bf16 v[44:47], v[168:171], v[230:233], v[44:47]
	v_mfma_f32_16x16x32_bf16 v[40:43], v[190:193], v[230:233], v[40:43]
	v_mfma_f32_16x16x32_bf16 v[32:35], v[190:193], v[238:241], v[32:35]
	v_mfma_f32_16x16x32_bf16 v[36:39], v[168:171], v[238:241], v[36:39]
	s_setprio 0
	s_setprio 1
	v_mfma_f32_16x16x32_bf16 v[28:31], v[194:197], v[210:213], v[28:31]
	v_mfma_f32_16x16x32_bf16 v[24:27], v[202:205], v[210:213], v[24:27]
	v_mfma_f32_16x16x32_bf16 v[16:19], v[202:205], v[218:221], v[16:19]
	v_mfma_f32_16x16x32_bf16 v[20:23], v[194:197], v[218:221], v[20:23]
	v_mfma_f32_16x16x32_bf16 v[12:15], v[194:197], v[226:229], v[12:15]
	v_mfma_f32_16x16x32_bf16 v[8:11], v[202:205], v[226:229], v[8:11]
	v_mfma_f32_16x16x32_bf16 v[0:3], v[202:205], v[234:237], v[0:3]
	v_mfma_f32_16x16x32_bf16 v[4:7], v[194:197], v[234:237], v[4:7]
	v_mfma_f32_16x16x32_bf16 v[28:31], v[198:201], v[214:217], v[28:31]
	v_mfma_f32_16x16x32_bf16 v[24:27], v[206:209], v[214:217], v[24:27]
	v_mfma_f32_16x16x32_bf16 v[16:19], v[206:209], v[222:225], v[16:19]
	v_mfma_f32_16x16x32_bf16 v[20:23], v[198:201], v[222:225], v[20:23]
	v_mfma_f32_16x16x32_bf16 v[12:15], v[198:201], v[230:233], v[12:15]
	v_mfma_f32_16x16x32_bf16 v[8:11], v[206:209], v[230:233], v[8:11]
	v_mfma_f32_16x16x32_bf16 v[0:3], v[206:209], v[238:241], v[0:3]
	v_mfma_f32_16x16x32_bf16 v[4:7], v[198:201], v[238:241], v[4:7]
	s_barrier
	s_setprio 0
	s_add_i32 s12, s5, 2
	s_add_u32 s46, s46, 0x10000
	s_addc_u32 s47, s47, 0
	s_add_u32 s1, s1, 0x100
	s_addc_u32 s4, s4, 0
	v_lshl_add_u64 v[162:163], v[162:163], 0, s[38:39]
	v_lshl_add_u64 v[160:161], v[160:161], 0, s[38:39]
	s_cmp_ge_i32 s5, s7
	s_mov_b32 s5, s12
	s_cbranch_scc0 .LBB0_3147
	s_and_b64 vcc, exec, s[36:37]
	s_cbranch_vccz .LBB0_3150
	s_barrier
